# plus phases 5/7 residual epilogue: f16-copy dwordx2 store pairs merged into dwordx4 (permlane16 swap)
# speedup vs baseline: 1.0056x; 1.0056x over previous
; #define GL_LOAD(s_, kt_) if (VAR != 1) { a##s_##0 = GL_A(0, kt_); a##s_##1 = GL_A(1, kt_); a##s_##2 = GL_A(2, kt_); a##s_##3 = GL_A(3, kt_); b##s_##0 = GL_B(0, kt_); b##s_##1 = GL_B(1, kt_); b##s_##2 = GL_B(2, kt_); b##s_##3 = GL_B(3, kt_); }
; #define LDS_STORE(s_, buf_) if (VAR != 2) { LDS_ST1(sA, 0, buf_, a##s_##0) LDS_ST1(sA, 1, buf_, a##s_##1) LDS_ST1(sA, 2, buf_, a##s_##2) LDS_ST1(sA, 3, buf_, a##s_##3) LDS_ST1(sB, 0, buf_, b##s_##0) LDS_ST1(sB, 1, buf_, b##s_##1) LDS_ST1(sB, 2, buf_, b##s_##2) LDS_ST1(sB, 3, buf_, b##s_##3) }
;     ...
;   uint4 a00 = {}, a01 = {}, a02 = {}, a03 = {}, b00 = {}, b01 = {}, b02 = {}, b03 = {}, a10 = {}, a11 = {}, a12 = {}, a13 = {}, b10 = {}, b11 = {}, b12 = {}, b13 = {};
;   constexpr int nk = NK;
;   const int sw0 = (g ^ ((lr >> 1) & 7)) << 4, sw1 = sw0 ^ 64;
;   const int r0 = tid >> 3, kc = tid & 7, kcs = kc ^ ((r0 >> 1) & 7);
;     ...
;   GL_LOAD(0, 0)
;   GL_LOAD(1, 1)
;   LDS_STORE(0, 0)
;   if (VAR != 4) __syncthreads();
; #pragma unroll
;   for (int kt = 0; kt < nk; kt += 2) {
;     if (kt + 2 < nk) { GL_LOAD(0, kt + 2) }
;     MMA_TILE(0)
;     LDS_STORE(1, 1)
;     if (VAR != 4) __syncthreads();
.LBB0_1249:
	s_ashr_i32 s6, s1, 3
	s_andn2_b32 s6, s6, 63
	s_and_b32 s7, s10, 56
	s_or_b32 s6, s6, s7
	s_bfe_u32 s7, s1, 0x30003
	s_or_b32 s6, s6, s7
	s_cmpk_gt_i32 s6, 0x7f
	s_cbranch_scc1 .LBB0_1248
	s_lshl_b32 s6, s6, 7
	s_ashr_i32 s7, s6, 31
	v_mov_b32_e32 v20, v148
	s_and_b32 s11, s9, 0x380
	s_lshl_b64 s[12:13], s[6:7], 11
	v_readlane_b32 s14, v253, 19
	v_readlane_b32 s15, v253, 20
	v_ashrrev_i32_e32 v16, 3, v20
	s_add_u32 s12, s14, s12
	v_ashrrev_i32_e32 v17, 31, v16
	v_add_u32_e32 v18, 32, v16
	s_addc_u32 s13, s15, s13
	v_lshlrev_b64 v[8:9], 11, v[16:17]
	v_lshlrev_b32_e32 v17, 4, v20
	v_ashrrev_i32_e32 v19, 31, v18
	v_add_u32_e32 v54, 64, v16
	s_waitcnt lgkmcnt(0)
	v_lshl_add_u64 v[0:1], s[12:13], 0, v[8:9]
	v_and_b32_e32 v150, 0x70, v17
	v_lshlrev_b64 v[10:11], 11, v[18:19]
	v_ashrrev_i32_e32 v55, 31, v54
	v_add_u32_e32 v58, 0x60, v16
	s_lshl_b32 s7, s11, 11
	v_lshl_add_u64 v[0:1], v[0:1], 0, v[150:151]
	v_lshl_add_u64 v[2:3], s[12:13], 0, v[10:11]
	v_lshlrev_b64 v[12:13], 11, v[54:55]
	v_ashrrev_i32_e32 v59, 31, v58
	s_add_u32 s14, s2, s7
	global_load_dwordx4 v[22:25], v[0:1], off
	v_lshl_add_u64 v[2:3], v[2:3], 0, v[150:151]
	v_lshl_add_u64 v[4:5], s[12:13], 0, v[12:13]
	v_lshlrev_b64 v[14:15], 11, v[58:59]
	s_addc_u32 s15, s8, 0
	global_load_dwordx4 v[26:29], v[2:3], off
	v_lshl_add_u64 v[4:5], v[4:5], 0, v[150:151]
	v_lshl_add_u64 v[6:7], s[12:13], 0, v[14:15]
	global_load_dwordx4 v[30:33], v[4:5], off
	v_lshl_add_u64 v[6:7], v[6:7], 0, v[150:151]
	v_lshl_add_u64 v[8:9], s[14:15], 0, v[8:9]
	global_load_dwordx4 v[34:37], v[6:7], off
	v_lshl_add_u64 v[8:9], v[8:9], 0, v[150:151]
	v_lshl_add_u64 v[10:11], s[14:15], 0, v[10:11]
	global_load_dwordx4 v[38:41], v[8:9], off
	v_lshl_add_u64 v[10:11], v[10:11], 0, v[150:151]
	v_lshl_add_u64 v[12:13], s[14:15], 0, v[12:13]
	global_load_dwordx4 v[42:45], v[10:11], off
	v_lshl_add_u64 v[12:13], v[12:13], 0, v[150:151]
	v_lshl_add_u64 v[14:15], s[14:15], 0, v[14:15]
	global_load_dwordx4 v[46:49], v[12:13], off
	v_lshl_add_u64 v[14:15], v[14:15], 0, v[150:151]
	global_load_dwordx4 v[50:53], v[14:15], off
	v_lshlrev_b32_e32 v21, 3, v20
	v_and_b32_e32 v55, 48, v20
	v_and_b32_e32 v19, 15, v20
	v_lshrrev_b32_e32 v59, 1, v20
	s_waitcnt vmcnt(10)
	v_lshlrev_b32_e32 v60, 7, v20
	v_and_b32_e32 v90, 0x70, v21
	v_bitop3_b32 v134, v21, v55, s23 bitop3:0x6c
	v_bitop3_b32 v21, v17, s23, v20 bitop3:0x48
	v_and_or_b32 v91, v59, s24, v19
	v_and_b32_e32 v130, 0x2780, v60
	v_lshl_or_b32 v20, v18, 7, v21
	v_lshl_or_b32 v18, v58, 7, v21
	global_load_dwordx4 v[58:61], v[0:1], off offset:128
	global_load_dwordx4 v[62:65], v[2:3], off offset:128
	global_load_dwordx4 v[66:69], v[4:5], off offset:128
	global_load_dwordx4 v[70:73], v[6:7], off offset:128
	global_load_dwordx4 v[74:77], v[8:9], off offset:128
	global_load_dwordx4 v[78:81], v[10:11], off offset:128
	global_load_dwordx4 v[82:85], v[12:13], off offset:128
	global_load_dwordx4 v[86:89], v[14:15], off offset:128
	v_lshl_or_b32 v19, v16, 7, v21
	v_or_b32_e32 v16, v130, v134
	v_lshl_or_b32 v17, v54, 7, v21
	v_lshlrev_b32_e32 v54, 7, v91
	v_bitop3_b32 v21, v54, v90, v55 bitop3:0xf6
	v_readlane_b32 s12, v254, 55
	v_readlane_b32 s13, v254, 56
	v_readlane_b32 s14, v254, 57
	v_readlane_b32 s15, v254, 58
	s_waitcnt vmcnt(15)
	ds_write_b128 v19, v[22:25]
	s_waitcnt vmcnt(14)
	ds_write_b128 v20, v[26:29]
	s_waitcnt vmcnt(13)
	ds_write_b128 v17, v[30:33]
	s_waitcnt vmcnt(12)
	ds_write_b128 v18, v[34:37]
	s_waitcnt vmcnt(11)
	ds_write_b128 v19, v[38:41] offset:32768
	s_waitcnt vmcnt(10)
	ds_write_b128 v20, v[42:45] offset:32768
	s_waitcnt vmcnt(9)
	ds_write_b128 v17, v[46:49] offset:32768
	s_waitcnt vmcnt(8)
	ds_write_b128 v18, v[50:53] offset:32768
	s_waitcnt lgkmcnt(0)
	s_barrier
	s_setprio 1
	ds_read_b128 v[22:25], v16 offset:32768
	ds_read_b128 v[30:33], v21
	s_waitcnt lgkmcnt(0)
	v_mfma_f32_16x16x32_f16 v[38:41], v[22:25], v[30:33], 0
	ds_read_b128 v[26:29], v16 offset:34816
	ds_read_b128 v[34:37], v21 offset:2048
	s_waitcnt lgkmcnt(0)
	v_mfma_f32_16x16x32_f16 v[94:97], v[22:25], v[34:37], 0
	ds_read_b128 v[42:45], v16 offset:36864
	ds_read_b128 v[106:109], v21 offset:4096
	s_waitcnt lgkmcnt(0)
	v_mfma_f32_16x16x32_f16 v[114:117], v[22:25], v[106:109], 0
	ds_read_b128 v[50:53], v16 offset:38912
	ds_read_b128 v[110:113], v21 offset:6144
	s_waitcnt lgkmcnt(0)
	v_mfma_f32_16x16x32_f16 v[126:129], v[22:25], v[110:113], 0
	v_xor_b32_e32 v22, 64, v134
	v_mfma_f32_16x16x32_f16 v[46:49], v[26:29], v[30:33], 0
	v_or_b32_e32 v22, v130, v22
	v_mfma_f32_16x16x32_f16 v[90:93], v[42:45], v[30:33], 0
	ds_read_b128 v[130:133], v22 offset:32768
	v_mfma_f32_16x16x32_f16 v[30:33], v[50:53], v[30:33], 0
	ds_read_b128 v[142:145], v22 offset:36864
	v_mfma_f32_16x16x32_f16 v[98:101], v[26:29], v[34:37], 0
	ds_read_b128 v[154:157], v22 offset:38912
	v_mfma_f32_16x16x32_f16 v[102:105], v[42:45], v[34:37], 0
	v_bitop3_b32 v23, v54, v134, 64 bitop3:0xf6
	v_mfma_f32_16x16x32_f16 v[34:37], v[50:53], v[34:37], 0
	ds_read_b128 v[134:137], v23
	v_mfma_f32_16x16x32_f16 v[118:121], v[26:29], v[106:109], 0
	ds_read_b128 v[138:141], v23 offset:2048
	v_mfma_f32_16x16x32_f16 v[122:125], v[42:45], v[106:109], 0
	s_waitcnt vmcnt(7)
	ds_write_b128 v19, v[58:61] offset:16384
	v_mfma_f32_16x16x32_f16 v[106:109], v[50:53], v[106:109], 0
	s_waitcnt vmcnt(6)
	ds_write_b128 v20, v[62:65] offset:16384
	v_mfma_f32_16x16x32_f16 v[24:27], v[26:29], v[110:113], 0
	s_waitcnt vmcnt(5)
	ds_write_b128 v17, v[66:69] offset:16384
	v_mfma_f32_16x16x32_f16 v[42:45], v[42:45], v[110:113], 0
	s_waitcnt vmcnt(4)
	ds_write_b128 v18, v[70:73] offset:16384
	v_mfma_f32_16x16x32_f16 v[50:53], v[50:53], v[110:113], 0
	ds_read_b128 v[110:113], v22 offset:34816
	s_waitcnt lgkmcnt(6)
; #define GL_LOAD(s_, kt_) if (VAR != 1) { a##s_##0 = GL_A(0, kt_); a##s_##1 = GL_A(1, kt_); a##s_##2 = GL_A(2, kt_); a##s_##3 = GL_A(3, kt_); b##s_##0 = GL_B(0, kt_); b##s_##1 = GL_B(1, kt_); b##s_##2 = GL_B(2, kt_); b##s_##3 = GL_B(3, kt_); }
; #define LDS_STORE(s_, buf_) if (VAR != 2) { LDS_ST1(sA, 0, buf_, a##s_##0) LDS_ST1(sA, 1, buf_, a##s_##1) LDS_ST1(sA, 2, buf_, a##s_##2) LDS_ST1(sA, 3, buf_, a##s_##3) LDS_ST1(sB, 0, buf_, b##s_##0) LDS_ST1(sB, 1, buf_, b##s_##1) LDS_ST1(sB, 2, buf_, b##s_##2) LDS_ST1(sB, 3, buf_, b##s_##3) }
;     ...
;   GL_LOAD(0, 0)
;   GL_LOAD(1, 1)
;   LDS_STORE(0, 0)
;   if (VAR != 4) __syncthreads();
; #pragma unroll
;   for (int kt = 0; kt < nk; kt += 2) {
;     if (kt + 2 < nk) { GL_LOAD(0, kt + 2) }
;     MMA_TILE(0)
;     LDS_STORE(1, 1)
;     if (VAR != 4) __syncthreads();
;     if (kt + 3 < nk) { GL_LOAD(1, kt + 3) }
;     MMA_TILE(1)
;     if (kt + 2 < nk) { LDS_STORE(0, 0) }
;     if (VAR != 4) __syncthreads();
	v_mfma_f32_16x16x32_f16 v[38:41], v[130:133], v[134:137], v[38:41]
	s_waitcnt vmcnt(3)
	ds_write_b128 v19, v[74:77] offset:49152
	v_mfma_f32_16x16x32_f16 v[90:93], v[142:145], v[134:137], v[90:93]
	s_waitcnt vmcnt(2)
	ds_write_b128 v20, v[78:81] offset:49152
	v_mfma_f32_16x16x32_f16 v[28:31], v[154:157], v[134:137], v[30:33]
	s_waitcnt vmcnt(1)
	ds_write_b128 v17, v[82:85] offset:49152
	s_waitcnt lgkmcnt(8)
	v_mfma_f32_16x16x32_f16 v[94:97], v[130:133], v[138:141], v[94:97]
	s_waitcnt vmcnt(0)
	ds_write_b128 v18, v[86:89] offset:49152
	v_mfma_f32_16x16x32_f16 v[102:105], v[142:145], v[138:141], v[102:105]
	v_mfma_f32_16x16x32_f16 v[32:35], v[154:157], v[138:141], v[34:37]
	s_waitcnt lgkmcnt(4)
	v_mfma_f32_16x16x32_f16 v[46:49], v[110:113], v[134:137], v[46:49]
	ds_read_b128 v[134:137], v23 offset:4096
	v_mfma_f32_16x16x32_f16 v[98:101], v[110:113], v[138:141], v[98:101]
	ds_read_b128 v[138:141], v23 offset:6144
	s_waitcnt lgkmcnt(1)
	v_mfma_f32_16x16x32_f16 v[114:117], v[130:133], v[134:137], v[114:117]
	s_waitcnt lgkmcnt(0)
	v_mfma_f32_16x16x32_f16 v[126:129], v[130:133], v[138:141], v[126:129]
	global_load_dwordx4 v[130:133], v[0:1], off offset:256
	v_mfma_f32_16x16x32_f16 v[118:121], v[110:113], v[134:137], v[118:121]
	v_mfma_f32_16x16x32_f16 v[24:27], v[110:113], v[138:141], v[24:27]
	v_mfma_f32_16x16x32_f16 v[122:125], v[142:145], v[134:137], v[122:125]
	v_mfma_f32_16x16x32_f16 v[106:109], v[154:157], v[134:137], v[106:109]
	global_load_dwordx4 v[134:137], v[2:3], off offset:256
	global_load_dwordx4 v[158:161], v[4:5], off offset:256
	global_load_dwordx4 v[162:165], v[6:7], off offset:256
	global_load_dwordx4 v[110:113], v[8:9], off offset:256
	global_load_dwordx4 v[166:169], v[10:11], off offset:256
	global_load_dwordx4 v[190:193], v[12:13], off offset:256
	global_load_dwordx4 v[194:197], v[14:15], off offset:256
	s_waitcnt lgkmcnt(0)
	s_barrier
	v_mfma_f32_16x16x32_f16 v[42:45], v[142:145], v[138:141], v[42:45]
	ds_read_b128 v[58:61], v16 offset:49152
	v_mfma_f32_16x16x32_f16 v[50:53], v[154:157], v[138:141], v[50:53]
	ds_read_b128 v[62:65], v16 offset:51200
	ds_read_b128 v[66:69], v21 offset:16384
	s_waitcnt lgkmcnt(0)
	v_mfma_f32_16x16x32_f16 v[36:39], v[58:61], v[66:69], v[38:41]
	ds_read_b128 v[70:73], v21 offset:18432
	v_mfma_f32_16x16x32_f16 v[46:49], v[62:65], v[66:69], v[46:49]
	ds_read_b128 v[74:77], v16 offset:53248
	s_waitcnt lgkmcnt(0)
	v_mfma_f32_16x16x32_f16 v[82:85], v[74:77], v[66:69], v[90:93]
	ds_read_b128 v[78:81], v16 offset:55296
	s_waitcnt lgkmcnt(0)
	v_mfma_f32_16x16x32_f16 v[28:31], v[78:81], v[66:69], v[28:31]
	v_mfma_f32_16x16x32_f16 v[66:69], v[58:61], v[70:73], v[94:97]
	s_nop 2
	ds_read_b128 v[94:97], v21 offset:22528
	s_waitcnt vmcnt(7)
	ds_write_b128 v19, v[130:133]
	v_mfma_f32_16x16x32_f16 v[86:89], v[62:65], v[70:73], v[98:101]
	s_waitcnt vmcnt(6)
	ds_write_b128 v20, v[134:137]
	s_waitcnt vmcnt(5)
	ds_write_b128 v17, v[158:161]
	v_mfma_f32_16x16x32_f16 v[90:93], v[74:77], v[70:73], v[102:105]
	s_waitcnt vmcnt(4)
	ds_write_b128 v18, v[162:165]
	s_waitcnt vmcnt(3)
	ds_write_b128 v19, v[110:113] offset:32768
	v_mfma_f32_16x16x32_f16 v[32:35], v[78:81], v[70:73], v[32:35]
	ds_read_b128 v[70:73], v21 offset:20480
	s_waitcnt lgkmcnt(0)
	v_mfma_f32_16x16x32_f16 v[98:101], v[58:61], v[70:73], v[114:117]
	s_waitcnt vmcnt(2)
	ds_write_b128 v20, v[166:169] offset:32768
	v_mfma_f32_16x16x32_f16 v[58:61], v[58:61], v[94:97], v[126:129]
	s_waitcnt vmcnt(1)
	ds_write_b128 v17, v[190:193] offset:32768
	v_mfma_f32_16x16x32_f16 v[102:105], v[62:65], v[70:73], v[118:121]
	s_nop 2
	ds_read_b128 v[118:121], v22 offset:55296
	v_mfma_f32_16x16x32_f16 v[24:27], v[62:65], v[94:97], v[24:27]
	ds_read_b128 v[62:65], v22 offset:49152
	v_mfma_f32_16x16x32_f16 v[114:117], v[74:77], v[70:73], v[122:125]
	s_waitcnt vmcnt(0)
	ds_write_b128 v18, v[194:197] offset:32768
	v_mfma_f32_16x16x32_f16 v[40:43], v[74:77], v[94:97], v[42:45]
	ds_read_b128 v[74:77], v22 offset:51200
	v_mfma_f32_16x16x32_f16 v[70:73], v[78:81], v[70:73], v[106:109]
	s_nop 2
	ds_read_b128 v[106:109], v22 offset:53248
	v_mfma_f32_16x16x32_f16 v[50:53], v[78:81], v[94:97], v[50:53]
	ds_read_b128 v[78:81], v23 offset:16384
	s_waitcnt lgkmcnt(0)
	v_mfma_f32_16x16x32_f16 v[36:39], v[62:65], v[78:81], v[36:39]
	ds_read_b128 v[94:97], v23 offset:18432
	s_waitcnt lgkmcnt(0)
	v_mfma_f32_16x16x32_f16 v[66:69], v[62:65], v[94:97], v[66:69]
	v_mfma_f32_16x16x32_f16 v[44:47], v[74:77], v[78:81], v[46:49]
	v_mfma_f32_16x16x32_f16 v[82:85], v[106:109], v[78:81], v[82:85]
	v_mfma_f32_16x16x32_f16 v[28:31], v[118:121], v[78:81], v[28:31]
	v_mfma_f32_16x16x32_f16 v[78:81], v[74:77], v[94:97], v[86:89]
	v_mfma_f32_16x16x32_f16 v[86:89], v[106:109], v[94:97], v[90:93]
	s_nop 2
	ds_read_b128 v[90:93], v23 offset:20480
	v_mfma_f32_16x16x32_f16 v[32:35], v[118:121], v[94:97], v[32:35]
	ds_read_b128 v[94:97], v23 offset:22528
	s_waitcnt lgkmcnt(1)
	v_mfma_f32_16x16x32_f16 v[98:101], v[62:65], v[90:93], v[98:101]
	s_waitcnt lgkmcnt(0)
	v_mfma_f32_16x16x32_f16 v[58:61], v[62:65], v[94:97], v[58:61]
	global_load_dwordx4 v[62:65], v[0:1], off offset:384
	v_mfma_f32_16x16x32_f16 v[102:105], v[74:77], v[90:93], v[102:105]
	v_mfma_f32_16x16x32_f16 v[24:27], v[74:77], v[94:97], v[24:27]
	v_mfma_f32_16x16x32_f16 v[114:117], v[106:109], v[90:93], v[114:117]
	v_mfma_f32_16x16x32_f16 v[40:43], v[106:109], v[94:97], v[40:43]
	v_mfma_f32_16x16x32_f16 v[70:73], v[118:121], v[90:93], v[70:73]
	global_load_dwordx4 v[90:93], v[2:3], off offset:384
	global_load_dwordx4 v[122:125], v[4:5], off offset:384
	global_load_dwordx4 v[126:129], v[6:7], off offset:384
	global_load_dwordx4 v[74:77], v[8:9], off offset:384
	global_load_dwordx4 v[138:141], v[10:11], off offset:384
	global_load_dwordx4 v[142:145], v[12:13], off offset:384
	global_load_dwordx4 v[154:157], v[14:15], off offset:384
	s_waitcnt lgkmcnt(0)
	s_barrier
; #define GL_LOAD(s_, kt_) if (VAR != 1) { a##s_##0 = GL_A(0, kt_); a##s_##1 = GL_A(1, kt_); a##s_##2 = GL_A(2, kt_); a##s_##3 = GL_A(3, kt_); b##s_##0 = GL_B(0, kt_); b##s_##1 = GL_B(1, kt_); b##s_##2 = GL_B(2, kt_); b##s_##3 = GL_B(3, kt_); }
; #define LDS_STORE(s_, buf_) if (VAR != 2) { LDS_ST1(sA, 0, buf_, a##s_##0) LDS_ST1(sA, 1, buf_, a##s_##1) LDS_ST1(sA, 2, buf_, a##s_##2) LDS_ST1(sA, 3, buf_, a##s_##3) LDS_ST1(sB, 0, buf_, b##s_##0) LDS_ST1(sB, 1, buf_, b##s_##1) LDS_ST1(sB, 2, buf_, b##s_##2) LDS_ST1(sB, 3, buf_, b##s_##3) }
;     ...
;   GL_LOAD(0, 0)
;   GL_LOAD(1, 1)
;   LDS_STORE(0, 0)
;   if (VAR != 4) __syncthreads();
; #pragma unroll
;   for (int kt = 0; kt < nk; kt += 2) {
;     if (kt + 2 < nk) { GL_LOAD(0, kt + 2) }
;     MMA_TILE(0)
;     LDS_STORE(1, 1)
;     if (VAR != 4) __syncthreads();
;     if (kt + 3 < nk) { GL_LOAD(1, kt + 3) }
;     MMA_TILE(1)
;     if (kt + 2 < nk) { LDS_STORE(0, 0) }
;     if (VAR != 4) __syncthreads();
	v_mfma_f32_16x16x32_f16 v[48:51], v[118:121], v[94:97], v[50:53]
	ds_read_b128 v[106:109], v16 offset:32768
	ds_read_b128 v[94:97], v21
	s_waitcnt lgkmcnt(0)
	v_mfma_f32_16x16x32_f16 v[36:39], v[106:109], v[94:97], v[36:39]
	ds_read_b128 v[52:55], v16 offset:34816
	ds_read_b128 v[110:113], v21 offset:2048
	s_waitcnt lgkmcnt(0)
	v_mfma_f32_16x16x32_f16 v[66:69], v[106:109], v[110:113], v[66:69]
	ds_read_b128 v[118:121], v16 offset:36864
	v_mfma_f32_16x16x32_f16 v[44:47], v[52:55], v[94:97], v[44:47]
	ds_read_b128 v[130:133], v16 offset:38912
	v_mfma_f32_16x16x32_f16 v[78:81], v[52:55], v[110:113], v[78:81]
	s_waitcnt vmcnt(7)
	ds_write_b128 v19, v[62:65] offset:16384
	s_waitcnt lgkmcnt(2)
	v_mfma_f32_16x16x32_f16 v[82:85], v[118:121], v[94:97], v[82:85]
	s_waitcnt vmcnt(6)
	ds_write_b128 v20, v[90:93] offset:16384
	v_mfma_f32_16x16x32_f16 v[86:89], v[118:121], v[110:113], v[86:89]
	s_waitcnt vmcnt(5)
	ds_write_b128 v17, v[122:125] offset:16384
	s_waitcnt lgkmcnt(3)
	v_mfma_f32_16x16x32_f16 v[28:31], v[130:133], v[94:97], v[28:31]
	ds_read_b128 v[94:97], v21 offset:4096
	v_mfma_f32_16x16x32_f16 v[32:35], v[130:133], v[110:113], v[32:35]
	ds_read_b128 v[110:113], v21 offset:6144
	s_waitcnt lgkmcnt(1)
	v_mfma_f32_16x16x32_f16 v[98:101], v[106:109], v[94:97], v[98:101]
	s_waitcnt vmcnt(4)
	ds_write_b128 v18, v[126:129] offset:16384
	s_waitcnt lgkmcnt(1)
	v_mfma_f32_16x16x32_f16 v[58:61], v[106:109], v[110:113], v[58:61]
	ds_read_b128 v[106:109], v23
	v_mfma_f32_16x16x32_f16 v[102:105], v[52:55], v[94:97], v[102:105]
	s_waitcnt vmcnt(3)
	ds_write_b128 v19, v[74:77] offset:49152
	v_mfma_f32_16x16x32_f16 v[24:27], v[52:55], v[110:113], v[24:27]
	ds_read_b128 v[52:55], v22 offset:32768
	v_mfma_f32_16x16x32_f16 v[114:117], v[118:121], v[94:97], v[114:117]
	s_waitcnt vmcnt(2)
	ds_write_b128 v20, v[138:141] offset:49152
	v_mfma_f32_16x16x32_f16 v[40:43], v[118:121], v[110:113], v[40:43]
	ds_read_b128 v[118:121], v22 offset:36864
	v_mfma_f32_16x16x32_f16 v[70:73], v[130:133], v[94:97], v[70:73]
	ds_read_b128 v[94:97], v22 offset:34816
	v_mfma_f32_16x16x32_f16 v[48:51], v[130:133], v[110:113], v[48:51]
	ds_read_b128 v[110:113], v23 offset:2048
	s_waitcnt lgkmcnt(4)
	v_mfma_f32_16x16x32_f16 v[36:39], v[52:55], v[106:109], v[36:39]
	ds_read_b128 v[130:133], v22 offset:38912
	s_waitcnt lgkmcnt(1)
	v_mfma_f32_16x16x32_f16 v[66:69], v[52:55], v[110:113], v[66:69]
	s_waitcnt vmcnt(1)
	ds_write_b128 v17, v[142:145] offset:49152
	v_mfma_f32_16x16x32_f16 v[44:47], v[94:97], v[106:109], v[44:47]
	s_waitcnt vmcnt(0)
	ds_write_b128 v18, v[154:157] offset:49152
	v_mfma_f32_16x16x32_f16 v[78:81], v[94:97], v[110:113], v[78:81]
	v_mfma_f32_16x16x32_f16 v[82:85], v[118:121], v[106:109], v[82:85]
	v_mfma_f32_16x16x32_f16 v[86:89], v[118:121], v[110:113], v[86:89]
	s_waitcnt lgkmcnt(2)
	v_mfma_f32_16x16x32_f16 v[28:31], v[130:133], v[106:109], v[28:31]
	ds_read_b128 v[106:109], v23 offset:4096
	v_mfma_f32_16x16x32_f16 v[32:35], v[130:133], v[110:113], v[32:35]
	ds_read_b128 v[110:113], v23 offset:6144
	s_waitcnt lgkmcnt(1)
	v_mfma_f32_16x16x32_f16 v[98:101], v[52:55], v[106:109], v[98:101]
	s_waitcnt lgkmcnt(0)
	v_mfma_f32_16x16x32_f16 v[52:55], v[52:55], v[110:113], v[58:61]
	s_nop 2
	global_load_dwordx4 v[58:61], v[0:1], off offset:512
	v_mfma_f32_16x16x32_f16 v[102:105], v[94:97], v[106:109], v[102:105]
	v_mfma_f32_16x16x32_f16 v[24:27], v[94:97], v[110:113], v[24:27]
	v_mfma_f32_16x16x32_f16 v[114:117], v[118:121], v[106:109], v[114:117]
	v_mfma_f32_16x16x32_f16 v[40:43], v[118:121], v[110:113], v[40:43]
	v_mfma_f32_16x16x32_f16 v[70:73], v[130:133], v[106:109], v[70:73]
	global_load_dwordx4 v[106:109], v[2:3], off offset:512
	global_load_dwordx4 v[134:137], v[4:5], off offset:512
	global_load_dwordx4 v[158:161], v[6:7], off offset:512
	global_load_dwordx4 v[94:97], v[8:9], off offset:512
	global_load_dwordx4 v[162:165], v[10:11], off offset:512
	global_load_dwordx4 v[166:169], v[12:13], off offset:512
	global_load_dwordx4 v[190:193], v[14:15], off offset:512
	s_waitcnt lgkmcnt(0)
	s_barrier
	v_mfma_f32_16x16x32_f16 v[48:51], v[130:133], v[110:113], v[48:51]
	ds_read_b128 v[62:65], v16 offset:49152
	ds_read_b128 v[90:93], v21 offset:16384
	s_waitcnt lgkmcnt(0)
	v_mfma_f32_16x16x32_f16 v[36:39], v[62:65], v[90:93], v[36:39]
	ds_read_b128 v[74:77], v16 offset:51200
	ds_read_b128 v[110:113], v21 offset:18432
	s_waitcnt lgkmcnt(0)
	v_mfma_f32_16x16x32_f16 v[66:69], v[62:65], v[110:113], v[66:69]
	ds_read_b128 v[118:121], v16 offset:53248
	v_mfma_f32_16x16x32_f16 v[44:47], v[74:77], v[90:93], v[44:47]
	ds_read_b128 v[122:125], v16 offset:55296
	v_mfma_f32_16x16x32_f16 v[78:81], v[74:77], v[110:113], v[78:81]
	s_waitcnt vmcnt(7)
	ds_write_b128 v19, v[58:61]
	s_waitcnt lgkmcnt(2)
	v_mfma_f32_16x16x32_f16 v[82:85], v[118:121], v[90:93], v[82:85]
	s_waitcnt vmcnt(6)
	ds_write_b128 v20, v[106:109]
	v_mfma_f32_16x16x32_f16 v[86:89], v[118:121], v[110:113], v[86:89]
	s_waitcnt vmcnt(5)
	ds_write_b128 v17, v[134:137]
	s_waitcnt lgkmcnt(3)
	v_mfma_f32_16x16x32_f16 v[28:31], v[122:125], v[90:93], v[28:31]
	ds_read_b128 v[90:93], v21 offset:20480
	v_mfma_f32_16x16x32_f16 v[32:35], v[122:125], v[110:113], v[32:35]
	ds_read_b128 v[110:113], v21 offset:22528
	s_waitcnt lgkmcnt(1)
	v_mfma_f32_16x16x32_f16 v[98:101], v[62:65], v[90:93], v[98:101]
	s_waitcnt vmcnt(4)
	ds_write_b128 v18, v[158:161]
	s_waitcnt lgkmcnt(1)
	v_mfma_f32_16x16x32_f16 v[52:55], v[62:65], v[110:113], v[52:55]
	ds_read_b128 v[62:65], v22 offset:49152
	v_mfma_f32_16x16x32_f16 v[102:105], v[74:77], v[90:93], v[102:105]
	s_waitcnt vmcnt(3)
; #define GL_LOAD(s_, kt_) if (VAR != 1) { a##s_##0 = GL_A(0, kt_); a##s_##1 = GL_A(1, kt_); a##s_##2 = GL_A(2, kt_); a##s_##3 = GL_A(3, kt_); b##s_##0 = GL_B(0, kt_); b##s_##1 = GL_B(1, kt_); b##s_##2 = GL_B(2, kt_); b##s_##3 = GL_B(3, kt_); }
; #define LDS_STORE(s_, buf_) if (VAR != 2) { LDS_ST1(sA, 0, buf_, a##s_##0) LDS_ST1(sA, 1, buf_, a##s_##1) LDS_ST1(sA, 2, buf_, a##s_##2) LDS_ST1(sA, 3, buf_, a##s_##3) LDS_ST1(sB, 0, buf_, b##s_##0) LDS_ST1(sB, 1, buf_, b##s_##1) LDS_ST1(sB, 2, buf_, b##s_##2) LDS_ST1(sB, 3, buf_, b##s_##3) }
;     ...
;   GL_LOAD(0, 0)
;   GL_LOAD(1, 1)
;   LDS_STORE(0, 0)
;   if (VAR != 4) __syncthreads();
; #pragma unroll
;   for (int kt = 0; kt < nk; kt += 2) {
;     if (kt + 2 < nk) { GL_LOAD(0, kt + 2) }
;     MMA_TILE(0)
;     LDS_STORE(1, 1)
;     if (VAR != 4) __syncthreads();
;     if (kt + 3 < nk) { GL_LOAD(1, kt + 3) }
;     MMA_TILE(1)
;     if (kt + 2 < nk) { LDS_STORE(0, 0) }
;     if (VAR != 4) __syncthreads();
	ds_write_b128 v19, v[94:97] offset:32768
	v_mfma_f32_16x16x32_f16 v[24:27], v[74:77], v[110:113], v[24:27]
	ds_read_b128 v[74:77], v22 offset:51200
	v_mfma_f32_16x16x32_f16 v[114:117], v[118:121], v[90:93], v[114:117]
	s_waitcnt vmcnt(2)
	ds_write_b128 v20, v[162:165] offset:32768
	v_mfma_f32_16x16x32_f16 v[40:43], v[118:121], v[110:113], v[40:43]
	ds_read_b128 v[118:121], v22 offset:53248
	v_mfma_f32_16x16x32_f16 v[70:73], v[122:125], v[90:93], v[70:73]
	ds_read_b128 v[90:93], v23 offset:16384
	v_mfma_f32_16x16x32_f16 v[48:51], v[122:125], v[110:113], v[48:51]
	ds_read_b128 v[110:113], v23 offset:18432
	s_waitcnt lgkmcnt(1)
	v_mfma_f32_16x16x32_f16 v[36:39], v[62:65], v[90:93], v[36:39]
	ds_read_b128 v[122:125], v22 offset:55296
	s_waitcnt lgkmcnt(1)
	v_mfma_f32_16x16x32_f16 v[66:69], v[62:65], v[110:113], v[66:69]
	s_waitcnt vmcnt(1)
	ds_write_b128 v17, v[166:169] offset:32768
	v_mfma_f32_16x16x32_f16 v[44:47], v[74:77], v[90:93], v[44:47]
	s_waitcnt vmcnt(0)
	ds_write_b128 v18, v[190:193] offset:32768
	v_mfma_f32_16x16x32_f16 v[78:81], v[74:77], v[110:113], v[78:81]
	v_mfma_f32_16x16x32_f16 v[82:85], v[118:121], v[90:93], v[82:85]
	v_mfma_f32_16x16x32_f16 v[86:89], v[118:121], v[110:113], v[86:89]
	s_waitcnt lgkmcnt(2)
	v_mfma_f32_16x16x32_f16 v[28:31], v[122:125], v[90:93], v[28:31]
	ds_read_b128 v[90:93], v23 offset:20480
	v_mfma_f32_16x16x32_f16 v[32:35], v[122:125], v[110:113], v[32:35]
	ds_read_b128 v[110:113], v23 offset:22528
	s_waitcnt lgkmcnt(1)
	v_mfma_f32_16x16x32_f16 v[98:101], v[62:65], v[90:93], v[98:101]
	s_waitcnt lgkmcnt(0)
	v_mfma_f32_16x16x32_f16 v[52:55], v[62:65], v[110:113], v[52:55]
	global_load_dwordx4 v[62:65], v[0:1], off offset:640
	v_mfma_f32_16x16x32_f16 v[102:105], v[74:77], v[90:93], v[102:105]
	v_mfma_f32_16x16x32_f16 v[24:27], v[74:77], v[110:113], v[24:27]
	v_mfma_f32_16x16x32_f16 v[114:117], v[118:121], v[90:93], v[114:117]
	v_mfma_f32_16x16x32_f16 v[40:43], v[118:121], v[110:113], v[40:43]
	v_mfma_f32_16x16x32_f16 v[70:73], v[122:125], v[90:93], v[70:73]
	global_load_dwordx4 v[90:93], v[2:3], off offset:640
	global_load_dwordx4 v[126:129], v[4:5], off offset:640
	global_load_dwordx4 v[130:133], v[6:7], off offset:640
	global_load_dwordx4 v[74:77], v[8:9], off offset:640
	global_load_dwordx4 v[138:141], v[10:11], off offset:640
	global_load_dwordx4 v[142:145], v[12:13], off offset:640
	global_load_dwordx4 v[154:157], v[14:15], off offset:640
	s_waitcnt lgkmcnt(0)
	s_barrier
	v_mfma_f32_16x16x32_f16 v[48:51], v[122:125], v[110:113], v[48:51]
	ds_read_b128 v[58:61], v16 offset:32768
	ds_read_b128 v[106:109], v21
	s_waitcnt lgkmcnt(0)
	v_mfma_f32_16x16x32_f16 v[36:39], v[58:61], v[106:109], v[36:39]
	ds_read_b128 v[94:97], v16 offset:34816
	ds_read_b128 v[110:113], v21 offset:2048
	s_waitcnt lgkmcnt(0)
	v_mfma_f32_16x16x32_f16 v[66:69], v[58:61], v[110:113], v[66:69]
	ds_read_b128 v[118:121], v16 offset:36864
	v_mfma_f32_16x16x32_f16 v[44:47], v[94:97], v[106:109], v[44:47]
	ds_read_b128 v[122:125], v16 offset:38912
	v_mfma_f32_16x16x32_f16 v[78:81], v[94:97], v[110:113], v[78:81]
	s_waitcnt vmcnt(7)
	ds_write_b128 v19, v[62:65] offset:16384
	s_waitcnt lgkmcnt(2)
	v_mfma_f32_16x16x32_f16 v[82:85], v[118:121], v[106:109], v[82:85]
	s_waitcnt vmcnt(6)
	ds_write_b128 v20, v[90:93] offset:16384
	v_mfma_f32_16x16x32_f16 v[86:89], v[118:121], v[110:113], v[86:89]
	s_waitcnt vmcnt(5)
	ds_write_b128 v17, v[126:129] offset:16384
	s_waitcnt lgkmcnt(3)
	v_mfma_f32_16x16x32_f16 v[28:31], v[122:125], v[106:109], v[28:31]
	ds_read_b128 v[106:109], v21 offset:4096
	v_mfma_f32_16x16x32_f16 v[32:35], v[122:125], v[110:113], v[32:35]
	ds_read_b128 v[110:113], v21 offset:6144
	s_waitcnt lgkmcnt(1)
	v_mfma_f32_16x16x32_f16 v[98:101], v[58:61], v[106:109], v[98:101]
	s_waitcnt vmcnt(4)
	ds_write_b128 v18, v[130:133] offset:16384
	s_waitcnt lgkmcnt(1)
	v_mfma_f32_16x16x32_f16 v[52:55], v[58:61], v[110:113], v[52:55]
	ds_read_b128 v[58:61], v22 offset:32768
	v_mfma_f32_16x16x32_f16 v[102:105], v[94:97], v[106:109], v[102:105]
	s_waitcnt vmcnt(3)
	ds_write_b128 v19, v[74:77] offset:49152
	v_mfma_f32_16x16x32_f16 v[24:27], v[94:97], v[110:113], v[24:27]
	ds_read_b128 v[94:97], v22 offset:34816
	v_mfma_f32_16x16x32_f16 v[114:117], v[118:121], v[106:109], v[114:117]
	s_waitcnt vmcnt(2)
	ds_write_b128 v20, v[138:141] offset:49152
	v_mfma_f32_16x16x32_f16 v[40:43], v[118:121], v[110:113], v[40:43]
	ds_read_b128 v[118:121], v22 offset:36864
	v_mfma_f32_16x16x32_f16 v[70:73], v[122:125], v[106:109], v[70:73]
	ds_read_b128 v[106:109], v23
	v_mfma_f32_16x16x32_f16 v[48:51], v[122:125], v[110:113], v[48:51]
	ds_read_b128 v[110:113], v23 offset:2048
	s_waitcnt lgkmcnt(1)
	v_mfma_f32_16x16x32_f16 v[36:39], v[58:61], v[106:109], v[36:39]
	ds_read_b128 v[122:125], v22 offset:38912
	s_waitcnt lgkmcnt(1)
	v_mfma_f32_16x16x32_f16 v[66:69], v[58:61], v[110:113], v[66:69]
	s_waitcnt vmcnt(1)
	ds_write_b128 v17, v[142:145] offset:49152
	v_mfma_f32_16x16x32_f16 v[44:47], v[94:97], v[106:109], v[44:47]
	s_waitcnt vmcnt(0)
	ds_write_b128 v18, v[154:157] offset:49152
	v_mfma_f32_16x16x32_f16 v[78:81], v[94:97], v[110:113], v[78:81]
	v_mfma_f32_16x16x32_f16 v[82:85], v[118:121], v[106:109], v[82:85]
	v_mfma_f32_16x16x32_f16 v[86:89], v[118:121], v[110:113], v[86:89]
	s_waitcnt lgkmcnt(2)
	v_mfma_f32_16x16x32_f16 v[28:31], v[122:125], v[106:109], v[28:31]
	ds_read_b128 v[106:109], v23 offset:4096
	v_mfma_f32_16x16x32_f16 v[32:35], v[122:125], v[110:113], v[32:35]
	ds_read_b128 v[110:113], v23 offset:6144
	s_waitcnt lgkmcnt(1)
	v_mfma_f32_16x16x32_f16 v[98:101], v[58:61], v[106:109], v[98:101]
	s_waitcnt lgkmcnt(0)
	v_mfma_f32_16x16x32_f16 v[52:55], v[58:61], v[110:113], v[52:55]
	global_load_dwordx4 v[58:61], v[0:1], off offset:768
	v_mfma_f32_16x16x32_f16 v[102:105], v[94:97], v[106:109], v[102:105]
	v_mfma_f32_16x16x32_f16 v[24:27], v[94:97], v[110:113], v[24:27]
	v_mfma_f32_16x16x32_f16 v[114:117], v[118:121], v[106:109], v[114:117]
	v_mfma_f32_16x16x32_f16 v[40:43], v[118:121], v[110:113], v[40:43]
	v_mfma_f32_16x16x32_f16 v[70:73], v[122:125], v[106:109], v[70:73]
	global_load_dwordx4 v[106:109], v[2:3], off offset:768
	global_load_dwordx4 v[134:137], v[4:5], off offset:768
	global_load_dwordx4 v[158:161], v[6:7], off offset:768
	global_load_dwordx4 v[94:97], v[8:9], off offset:768
	global_load_dwordx4 v[162:165], v[10:11], off offset:768
	global_load_dwordx4 v[166:169], v[12:13], off offset:768
	global_load_dwordx4 v[190:193], v[14:15], off offset:768
	s_waitcnt lgkmcnt(0)
	s_barrier
; #define GL_LOAD(s_, kt_) if (VAR != 1) { a##s_##0 = GL_A(0, kt_); a##s_##1 = GL_A(1, kt_); a##s_##2 = GL_A(2, kt_); a##s_##3 = GL_A(3, kt_); b##s_##0 = GL_B(0, kt_); b##s_##1 = GL_B(1, kt_); b##s_##2 = GL_B(2, kt_); b##s_##3 = GL_B(3, kt_); }
; #define LDS_STORE(s_, buf_) if (VAR != 2) { LDS_ST1(sA, 0, buf_, a##s_##0) LDS_ST1(sA, 1, buf_, a##s_##1) LDS_ST1(sA, 2, buf_, a##s_##2) LDS_ST1(sA, 3, buf_, a##s_##3) LDS_ST1(sB, 0, buf_, b##s_##0) LDS_ST1(sB, 1, buf_, b##s_##1) LDS_ST1(sB, 2, buf_, b##s_##2) LDS_ST1(sB, 3, buf_, b##s_##3) }
;     ...
;   GL_LOAD(0, 0)
;   GL_LOAD(1, 1)
;   LDS_STORE(0, 0)
;   if (VAR != 4) __syncthreads();
; #pragma unroll
;   for (int kt = 0; kt < nk; kt += 2) {
;     if (kt + 2 < nk) { GL_LOAD(0, kt + 2) }
;     MMA_TILE(0)
;     LDS_STORE(1, 1)
;     if (VAR != 4) __syncthreads();
;     if (kt + 3 < nk) { GL_LOAD(1, kt + 3) }
;     MMA_TILE(1)
;     if (kt + 2 < nk) { LDS_STORE(0, 0) }
;     if (VAR != 4) __syncthreads();
	v_mfma_f32_16x16x32_f16 v[48:51], v[122:125], v[110:113], v[48:51]
	ds_read_b128 v[62:65], v16 offset:49152
	ds_read_b128 v[90:93], v21 offset:16384
	s_waitcnt lgkmcnt(0)
	v_mfma_f32_16x16x32_f16 v[36:39], v[62:65], v[90:93], v[36:39]
	ds_read_b128 v[74:77], v16 offset:51200
	ds_read_b128 v[110:113], v21 offset:18432
	s_waitcnt lgkmcnt(0)
	v_mfma_f32_16x16x32_f16 v[66:69], v[62:65], v[110:113], v[66:69]
	ds_read_b128 v[118:121], v16 offset:53248
	v_mfma_f32_16x16x32_f16 v[44:47], v[74:77], v[90:93], v[44:47]
	ds_read_b128 v[122:125], v16 offset:55296
	v_mfma_f32_16x16x32_f16 v[78:81], v[74:77], v[110:113], v[78:81]
	s_waitcnt vmcnt(7)
	ds_write_b128 v19, v[58:61]
	s_waitcnt lgkmcnt(2)
	v_mfma_f32_16x16x32_f16 v[82:85], v[118:121], v[90:93], v[82:85]
	s_waitcnt vmcnt(6)
	ds_write_b128 v20, v[106:109]
	v_mfma_f32_16x16x32_f16 v[86:89], v[118:121], v[110:113], v[86:89]
	s_waitcnt vmcnt(5)
	ds_write_b128 v17, v[134:137]
	s_waitcnt lgkmcnt(3)
	v_mfma_f32_16x16x32_f16 v[28:31], v[122:125], v[90:93], v[28:31]
	ds_read_b128 v[90:93], v21 offset:20480
	v_mfma_f32_16x16x32_f16 v[32:35], v[122:125], v[110:113], v[32:35]
	ds_read_b128 v[110:113], v21 offset:22528
	s_waitcnt lgkmcnt(1)
	v_mfma_f32_16x16x32_f16 v[98:101], v[62:65], v[90:93], v[98:101]
	s_waitcnt vmcnt(4)
	ds_write_b128 v18, v[158:161]
	s_waitcnt lgkmcnt(1)
	v_mfma_f32_16x16x32_f16 v[52:55], v[62:65], v[110:113], v[52:55]
	ds_read_b128 v[62:65], v22 offset:49152
	v_mfma_f32_16x16x32_f16 v[102:105], v[74:77], v[90:93], v[102:105]
	s_waitcnt vmcnt(3)
	ds_write_b128 v19, v[94:97] offset:32768
	v_mfma_f32_16x16x32_f16 v[24:27], v[74:77], v[110:113], v[24:27]
	ds_read_b128 v[74:77], v22 offset:51200
	v_mfma_f32_16x16x32_f16 v[114:117], v[118:121], v[90:93], v[114:117]
	s_waitcnt vmcnt(2)
	ds_write_b128 v20, v[162:165] offset:32768
	v_mfma_f32_16x16x32_f16 v[40:43], v[118:121], v[110:113], v[40:43]
	ds_read_b128 v[118:121], v22 offset:53248
	v_mfma_f32_16x16x32_f16 v[70:73], v[122:125], v[90:93], v[70:73]
	ds_read_b128 v[90:93], v23 offset:16384
	v_mfma_f32_16x16x32_f16 v[48:51], v[122:125], v[110:113], v[48:51]
	ds_read_b128 v[110:113], v23 offset:18432
	s_waitcnt lgkmcnt(1)
	v_mfma_f32_16x16x32_f16 v[36:39], v[62:65], v[90:93], v[36:39]
	ds_read_b128 v[122:125], v22 offset:55296
	s_waitcnt lgkmcnt(1)
	v_mfma_f32_16x16x32_f16 v[66:69], v[62:65], v[110:113], v[66:69]
	s_waitcnt vmcnt(1)
	ds_write_b128 v17, v[166:169] offset:32768
	v_mfma_f32_16x16x32_f16 v[44:47], v[74:77], v[90:93], v[44:47]
	s_waitcnt vmcnt(0)
	ds_write_b128 v18, v[190:193] offset:32768
	v_mfma_f32_16x16x32_f16 v[78:81], v[74:77], v[110:113], v[78:81]
	v_mfma_f32_16x16x32_f16 v[82:85], v[118:121], v[90:93], v[82:85]
	v_mfma_f32_16x16x32_f16 v[86:89], v[118:121], v[110:113], v[86:89]
	s_waitcnt lgkmcnt(2)
	v_mfma_f32_16x16x32_f16 v[28:31], v[122:125], v[90:93], v[28:31]
	ds_read_b128 v[90:93], v23 offset:20480
	v_mfma_f32_16x16x32_f16 v[32:35], v[122:125], v[110:113], v[32:35]
	ds_read_b128 v[110:113], v23 offset:22528
	s_waitcnt lgkmcnt(1)
	v_mfma_f32_16x16x32_f16 v[98:101], v[62:65], v[90:93], v[98:101]
	s_waitcnt lgkmcnt(0)
	v_mfma_f32_16x16x32_f16 v[52:55], v[62:65], v[110:113], v[52:55]
	global_load_dwordx4 v[62:65], v[0:1], off offset:896
	v_mfma_f32_16x16x32_f16 v[102:105], v[74:77], v[90:93], v[102:105]
	v_mfma_f32_16x16x32_f16 v[24:27], v[74:77], v[110:113], v[24:27]
	v_mfma_f32_16x16x32_f16 v[114:117], v[118:121], v[90:93], v[114:117]
	v_mfma_f32_16x16x32_f16 v[40:43], v[118:121], v[110:113], v[40:43]
	v_mfma_f32_16x16x32_f16 v[70:73], v[122:125], v[90:93], v[70:73]
	global_load_dwordx4 v[90:93], v[2:3], off offset:896
	global_load_dwordx4 v[126:129], v[4:5], off offset:896
	global_load_dwordx4 v[130:133], v[6:7], off offset:896
	global_load_dwordx4 v[74:77], v[8:9], off offset:896
	global_load_dwordx4 v[138:141], v[10:11], off offset:896
	global_load_dwordx4 v[142:145], v[12:13], off offset:896
	global_load_dwordx4 v[154:157], v[14:15], off offset:896
	s_waitcnt lgkmcnt(0)
	s_barrier
	v_mfma_f32_16x16x32_f16 v[48:51], v[122:125], v[110:113], v[48:51]
	ds_read_b128 v[58:61], v16 offset:32768
	ds_read_b128 v[106:109], v21
	s_waitcnt lgkmcnt(0)
	v_mfma_f32_16x16x32_f16 v[36:39], v[58:61], v[106:109], v[36:39]
	ds_read_b128 v[94:97], v16 offset:34816
	ds_read_b128 v[110:113], v21 offset:2048
	s_waitcnt lgkmcnt(0)
	v_mfma_f32_16x16x32_f16 v[66:69], v[58:61], v[110:113], v[66:69]
	ds_read_b128 v[118:121], v16 offset:36864
	v_mfma_f32_16x16x32_f16 v[44:47], v[94:97], v[106:109], v[44:47]
	ds_read_b128 v[122:125], v16 offset:38912
	v_mfma_f32_16x16x32_f16 v[78:81], v[94:97], v[110:113], v[78:81]
	s_waitcnt vmcnt(7)
	ds_write_b128 v19, v[62:65] offset:16384
	s_waitcnt lgkmcnt(2)
	v_mfma_f32_16x16x32_f16 v[82:85], v[118:121], v[106:109], v[82:85]
	s_waitcnt vmcnt(6)
	ds_write_b128 v20, v[90:93] offset:16384
	v_mfma_f32_16x16x32_f16 v[86:89], v[118:121], v[110:113], v[86:89]
	s_waitcnt vmcnt(5)
	ds_write_b128 v17, v[126:129] offset:16384
	s_waitcnt lgkmcnt(3)
	v_mfma_f32_16x16x32_f16 v[28:31], v[122:125], v[106:109], v[28:31]
	ds_read_b128 v[106:109], v21 offset:4096
	v_mfma_f32_16x16x32_f16 v[32:35], v[122:125], v[110:113], v[32:35]
	ds_read_b128 v[110:113], v21 offset:6144
	s_waitcnt lgkmcnt(1)
	v_mfma_f32_16x16x32_f16 v[98:101], v[58:61], v[106:109], v[98:101]
	s_waitcnt vmcnt(4)
	ds_write_b128 v18, v[130:133] offset:16384
	s_waitcnt lgkmcnt(1)
	v_mfma_f32_16x16x32_f16 v[52:55], v[58:61], v[110:113], v[52:55]
	ds_read_b128 v[58:61], v22 offset:32768
	v_mfma_f32_16x16x32_f16 v[102:105], v[94:97], v[106:109], v[102:105]
	s_waitcnt vmcnt(3)
; #define GL_LOAD(s_, kt_) if (VAR != 1) { a##s_##0 = GL_A(0, kt_); a##s_##1 = GL_A(1, kt_); a##s_##2 = GL_A(2, kt_); a##s_##3 = GL_A(3, kt_); b##s_##0 = GL_B(0, kt_); b##s_##1 = GL_B(1, kt_); b##s_##2 = GL_B(2, kt_); b##s_##3 = GL_B(3, kt_); }
; #define LDS_STORE(s_, buf_) if (VAR != 2) { LDS_ST1(sA, 0, buf_, a##s_##0) LDS_ST1(sA, 1, buf_, a##s_##1) LDS_ST1(sA, 2, buf_, a##s_##2) LDS_ST1(sA, 3, buf_, a##s_##3) LDS_ST1(sB, 0, buf_, b##s_##0) LDS_ST1(sB, 1, buf_, b##s_##1) LDS_ST1(sB, 2, buf_, b##s_##2) LDS_ST1(sB, 3, buf_, b##s_##3) }
;     ...
;   GL_LOAD(0, 0)
;   GL_LOAD(1, 1)
;   LDS_STORE(0, 0)
;   if (VAR != 4) __syncthreads();
; #pragma unroll
;   for (int kt = 0; kt < nk; kt += 2) {
;     if (kt + 2 < nk) { GL_LOAD(0, kt + 2) }
;     MMA_TILE(0)
;     LDS_STORE(1, 1)
;     if (VAR != 4) __syncthreads();
;     if (kt + 3 < nk) { GL_LOAD(1, kt + 3) }
;     MMA_TILE(1)
;     if (kt + 2 < nk) { LDS_STORE(0, 0) }
;     if (VAR != 4) __syncthreads();
	ds_write_b128 v19, v[74:77] offset:49152
	v_mfma_f32_16x16x32_f16 v[24:27], v[94:97], v[110:113], v[24:27]
	ds_read_b128 v[94:97], v22 offset:34816
	v_mfma_f32_16x16x32_f16 v[114:117], v[118:121], v[106:109], v[114:117]
	s_waitcnt vmcnt(2)
	ds_write_b128 v20, v[138:141] offset:49152
	v_mfma_f32_16x16x32_f16 v[40:43], v[118:121], v[110:113], v[40:43]
	ds_read_b128 v[118:121], v22 offset:36864
	v_mfma_f32_16x16x32_f16 v[70:73], v[122:125], v[106:109], v[70:73]
	ds_read_b128 v[106:109], v23
	v_mfma_f32_16x16x32_f16 v[48:51], v[122:125], v[110:113], v[48:51]
	ds_read_b128 v[110:113], v23 offset:2048
	s_waitcnt lgkmcnt(1)
	v_mfma_f32_16x16x32_f16 v[36:39], v[58:61], v[106:109], v[36:39]
	ds_read_b128 v[122:125], v22 offset:38912
	s_waitcnt lgkmcnt(1)
	v_mfma_f32_16x16x32_f16 v[66:69], v[58:61], v[110:113], v[66:69]
	s_waitcnt vmcnt(1)
	ds_write_b128 v17, v[142:145] offset:49152
	v_mfma_f32_16x16x32_f16 v[44:47], v[94:97], v[106:109], v[44:47]
	s_waitcnt vmcnt(0)
	ds_write_b128 v18, v[154:157] offset:49152
	v_mfma_f32_16x16x32_f16 v[78:81], v[94:97], v[110:113], v[78:81]
	v_mfma_f32_16x16x32_f16 v[82:85], v[118:121], v[106:109], v[82:85]
	v_mfma_f32_16x16x32_f16 v[86:89], v[118:121], v[110:113], v[86:89]
	s_waitcnt lgkmcnt(2)
	v_mfma_f32_16x16x32_f16 v[28:31], v[122:125], v[106:109], v[28:31]
	ds_read_b128 v[106:109], v23 offset:4096
	v_mfma_f32_16x16x32_f16 v[32:35], v[122:125], v[110:113], v[32:35]
	ds_read_b128 v[110:113], v23 offset:6144
	s_waitcnt lgkmcnt(1)
	v_mfma_f32_16x16x32_f16 v[98:101], v[58:61], v[106:109], v[98:101]
	s_waitcnt lgkmcnt(0)
	v_mfma_f32_16x16x32_f16 v[52:55], v[58:61], v[110:113], v[52:55]
	global_load_dwordx4 v[58:61], v[0:1], off offset:1024
	v_mfma_f32_16x16x32_f16 v[102:105], v[94:97], v[106:109], v[102:105]
	v_mfma_f32_16x16x32_f16 v[24:27], v[94:97], v[110:113], v[24:27]
	v_mfma_f32_16x16x32_f16 v[114:117], v[118:121], v[106:109], v[114:117]
	v_mfma_f32_16x16x32_f16 v[40:43], v[118:121], v[110:113], v[40:43]
	v_mfma_f32_16x16x32_f16 v[70:73], v[122:125], v[106:109], v[70:73]
	global_load_dwordx4 v[106:109], v[2:3], off offset:1024
	global_load_dwordx4 v[134:137], v[4:5], off offset:1024
	global_load_dwordx4 v[158:161], v[6:7], off offset:1024
	global_load_dwordx4 v[94:97], v[8:9], off offset:1024
	global_load_dwordx4 v[162:165], v[10:11], off offset:1024
	global_load_dwordx4 v[166:169], v[12:13], off offset:1024
	global_load_dwordx4 v[190:193], v[14:15], off offset:1024
	s_waitcnt lgkmcnt(0)
	s_barrier
	v_mfma_f32_16x16x32_f16 v[48:51], v[122:125], v[110:113], v[48:51]
	ds_read_b128 v[62:65], v16 offset:49152
	ds_read_b128 v[90:93], v21 offset:16384
	s_waitcnt lgkmcnt(0)
	v_mfma_f32_16x16x32_f16 v[36:39], v[62:65], v[90:93], v[36:39]
	ds_read_b128 v[74:77], v16 offset:51200
	ds_read_b128 v[110:113], v21 offset:18432
	s_waitcnt lgkmcnt(0)
	v_mfma_f32_16x16x32_f16 v[66:69], v[62:65], v[110:113], v[66:69]
	ds_read_b128 v[118:121], v16 offset:53248
	v_mfma_f32_16x16x32_f16 v[44:47], v[74:77], v[90:93], v[44:47]
	ds_read_b128 v[122:125], v16 offset:55296
	v_mfma_f32_16x16x32_f16 v[78:81], v[74:77], v[110:113], v[78:81]
	s_waitcnt vmcnt(7)
	ds_write_b128 v19, v[58:61]
	s_waitcnt lgkmcnt(2)
	v_mfma_f32_16x16x32_f16 v[82:85], v[118:121], v[90:93], v[82:85]
	s_waitcnt vmcnt(6)
	ds_write_b128 v20, v[106:109]
	v_mfma_f32_16x16x32_f16 v[86:89], v[118:121], v[110:113], v[86:89]
	s_waitcnt vmcnt(5)
	ds_write_b128 v17, v[134:137]
	s_waitcnt lgkmcnt(3)
	v_mfma_f32_16x16x32_f16 v[28:31], v[122:125], v[90:93], v[28:31]
	ds_read_b128 v[90:93], v21 offset:20480
	v_mfma_f32_16x16x32_f16 v[32:35], v[122:125], v[110:113], v[32:35]
	ds_read_b128 v[110:113], v21 offset:22528
	s_waitcnt lgkmcnt(1)
	v_mfma_f32_16x16x32_f16 v[98:101], v[62:65], v[90:93], v[98:101]
	s_waitcnt vmcnt(4)
	ds_write_b128 v18, v[158:161]
	s_waitcnt lgkmcnt(1)
	v_mfma_f32_16x16x32_f16 v[52:55], v[62:65], v[110:113], v[52:55]
	ds_read_b128 v[62:65], v22 offset:49152
	v_mfma_f32_16x16x32_f16 v[102:105], v[74:77], v[90:93], v[102:105]
	s_waitcnt vmcnt(3)
	ds_write_b128 v19, v[94:97] offset:32768
	v_mfma_f32_16x16x32_f16 v[24:27], v[74:77], v[110:113], v[24:27]
	ds_read_b128 v[74:77], v22 offset:51200
	v_mfma_f32_16x16x32_f16 v[114:117], v[118:121], v[90:93], v[114:117]
	s_waitcnt vmcnt(2)
	ds_write_b128 v20, v[162:165] offset:32768
	v_mfma_f32_16x16x32_f16 v[40:43], v[118:121], v[110:113], v[40:43]
	ds_read_b128 v[118:121], v22 offset:53248
	v_mfma_f32_16x16x32_f16 v[70:73], v[122:125], v[90:93], v[70:73]
	ds_read_b128 v[90:93], v23 offset:16384
	v_mfma_f32_16x16x32_f16 v[48:51], v[122:125], v[110:113], v[48:51]
	ds_read_b128 v[110:113], v23 offset:18432
	s_waitcnt lgkmcnt(1)
	v_mfma_f32_16x16x32_f16 v[36:39], v[62:65], v[90:93], v[36:39]
	ds_read_b128 v[122:125], v22 offset:55296
	s_waitcnt lgkmcnt(1)
	v_mfma_f32_16x16x32_f16 v[66:69], v[62:65], v[110:113], v[66:69]
	s_waitcnt vmcnt(1)
	ds_write_b128 v17, v[166:169] offset:32768
	v_mfma_f32_16x16x32_f16 v[44:47], v[74:77], v[90:93], v[44:47]
	s_waitcnt vmcnt(0)
	ds_write_b128 v18, v[190:193] offset:32768
	v_mfma_f32_16x16x32_f16 v[78:81], v[74:77], v[110:113], v[78:81]
	v_mfma_f32_16x16x32_f16 v[82:85], v[118:121], v[90:93], v[82:85]
	v_mfma_f32_16x16x32_f16 v[86:89], v[118:121], v[110:113], v[86:89]
	s_waitcnt lgkmcnt(2)
	v_mfma_f32_16x16x32_f16 v[28:31], v[122:125], v[90:93], v[28:31]
	ds_read_b128 v[90:93], v23 offset:20480
	v_mfma_f32_16x16x32_f16 v[32:35], v[122:125], v[110:113], v[32:35]
	ds_read_b128 v[110:113], v23 offset:22528
	s_waitcnt lgkmcnt(1)
	v_mfma_f32_16x16x32_f16 v[98:101], v[62:65], v[90:93], v[98:101]
	s_waitcnt lgkmcnt(0)
	v_mfma_f32_16x16x32_f16 v[52:55], v[62:65], v[110:113], v[52:55]
	global_load_dwordx4 v[62:65], v[0:1], off offset:1152
	v_mfma_f32_16x16x32_f16 v[102:105], v[74:77], v[90:93], v[102:105]
	v_mfma_f32_16x16x32_f16 v[24:27], v[74:77], v[110:113], v[24:27]
	v_mfma_f32_16x16x32_f16 v[114:117], v[118:121], v[90:93], v[114:117]
	v_mfma_f32_16x16x32_f16 v[40:43], v[118:121], v[110:113], v[40:43]
	v_mfma_f32_16x16x32_f16 v[70:73], v[122:125], v[90:93], v[70:73]
	global_load_dwordx4 v[90:93], v[2:3], off offset:1152
	global_load_dwordx4 v[126:129], v[4:5], off offset:1152
	global_load_dwordx4 v[130:133], v[6:7], off offset:1152
	global_load_dwordx4 v[74:77], v[8:9], off offset:1152
	global_load_dwordx4 v[138:141], v[10:11], off offset:1152
	global_load_dwordx4 v[142:145], v[12:13], off offset:1152
	global_load_dwordx4 v[154:157], v[14:15], off offset:1152
	s_waitcnt lgkmcnt(0)
	s_barrier
; #define GL_LOAD(s_, kt_) if (VAR != 1) { a##s_##0 = GL_A(0, kt_); a##s_##1 = GL_A(1, kt_); a##s_##2 = GL_A(2, kt_); a##s_##3 = GL_A(3, kt_); b##s_##0 = GL_B(0, kt_); b##s_##1 = GL_B(1, kt_); b##s_##2 = GL_B(2, kt_); b##s_##3 = GL_B(3, kt_); }
; #define LDS_STORE(s_, buf_) if (VAR != 2) { LDS_ST1(sA, 0, buf_, a##s_##0) LDS_ST1(sA, 1, buf_, a##s_##1) LDS_ST1(sA, 2, buf_, a##s_##2) LDS_ST1(sA, 3, buf_, a##s_##3) LDS_ST1(sB, 0, buf_, b##s_##0) LDS_ST1(sB, 1, buf_, b##s_##1) LDS_ST1(sB, 2, buf_, b##s_##2) LDS_ST1(sB, 3, buf_, b##s_##3) }
;     ...
;   GL_LOAD(0, 0)
;   GL_LOAD(1, 1)
;   LDS_STORE(0, 0)
;   if (VAR != 4) __syncthreads();
; #pragma unroll
;   for (int kt = 0; kt < nk; kt += 2) {
;     if (kt + 2 < nk) { GL_LOAD(0, kt + 2) }
;     MMA_TILE(0)
;     LDS_STORE(1, 1)
;     if (VAR != 4) __syncthreads();
;     if (kt + 3 < nk) { GL_LOAD(1, kt + 3) }
;     MMA_TILE(1)
;     if (kt + 2 < nk) { LDS_STORE(0, 0) }
;     if (VAR != 4) __syncthreads();
	v_mfma_f32_16x16x32_f16 v[48:51], v[122:125], v[110:113], v[48:51]
	ds_read_b128 v[58:61], v16 offset:32768
	ds_read_b128 v[106:109], v21
	s_waitcnt lgkmcnt(0)
	v_mfma_f32_16x16x32_f16 v[36:39], v[58:61], v[106:109], v[36:39]
	ds_read_b128 v[94:97], v16 offset:34816
	ds_read_b128 v[110:113], v21 offset:2048
	s_waitcnt lgkmcnt(0)
	v_mfma_f32_16x16x32_f16 v[66:69], v[58:61], v[110:113], v[66:69]
	ds_read_b128 v[118:121], v16 offset:36864
	v_mfma_f32_16x16x32_f16 v[44:47], v[94:97], v[106:109], v[44:47]
	ds_read_b128 v[122:125], v16 offset:38912
	v_mfma_f32_16x16x32_f16 v[78:81], v[94:97], v[110:113], v[78:81]
	s_waitcnt vmcnt(7)
	ds_write_b128 v19, v[62:65] offset:16384
	s_waitcnt lgkmcnt(2)
	v_mfma_f32_16x16x32_f16 v[82:85], v[118:121], v[106:109], v[82:85]
	s_waitcnt vmcnt(6)
	ds_write_b128 v20, v[90:93] offset:16384
	v_mfma_f32_16x16x32_f16 v[86:89], v[118:121], v[110:113], v[86:89]
	s_waitcnt vmcnt(5)
	ds_write_b128 v17, v[126:129] offset:16384
	s_waitcnt lgkmcnt(3)
	v_mfma_f32_16x16x32_f16 v[28:31], v[122:125], v[106:109], v[28:31]
	ds_read_b128 v[106:109], v21 offset:4096
	v_mfma_f32_16x16x32_f16 v[32:35], v[122:125], v[110:113], v[32:35]
	ds_read_b128 v[110:113], v21 offset:6144
	s_waitcnt lgkmcnt(1)
	v_mfma_f32_16x16x32_f16 v[98:101], v[58:61], v[106:109], v[98:101]
	s_waitcnt vmcnt(4)
	ds_write_b128 v18, v[130:133] offset:16384
	s_waitcnt lgkmcnt(1)
	v_mfma_f32_16x16x32_f16 v[52:55], v[58:61], v[110:113], v[52:55]
	ds_read_b128 v[58:61], v22 offset:32768
	v_mfma_f32_16x16x32_f16 v[102:105], v[94:97], v[106:109], v[102:105]
	s_waitcnt vmcnt(3)
	ds_write_b128 v19, v[74:77] offset:49152
	v_mfma_f32_16x16x32_f16 v[24:27], v[94:97], v[110:113], v[24:27]
	ds_read_b128 v[94:97], v22 offset:34816
	v_mfma_f32_16x16x32_f16 v[114:117], v[118:121], v[106:109], v[114:117]
	s_waitcnt vmcnt(2)
	ds_write_b128 v20, v[138:141] offset:49152
	v_mfma_f32_16x16x32_f16 v[40:43], v[118:121], v[110:113], v[40:43]
	ds_read_b128 v[118:121], v22 offset:36864
	v_mfma_f32_16x16x32_f16 v[70:73], v[122:125], v[106:109], v[70:73]
	ds_read_b128 v[106:109], v23
	v_mfma_f32_16x16x32_f16 v[48:51], v[122:125], v[110:113], v[48:51]
	ds_read_b128 v[110:113], v23 offset:2048
	s_waitcnt lgkmcnt(1)
	v_mfma_f32_16x16x32_f16 v[36:39], v[58:61], v[106:109], v[36:39]
	ds_read_b128 v[122:125], v22 offset:38912
	s_waitcnt lgkmcnt(1)
	v_mfma_f32_16x16x32_f16 v[66:69], v[58:61], v[110:113], v[66:69]
	s_waitcnt vmcnt(1)
	ds_write_b128 v17, v[142:145] offset:49152
	v_mfma_f32_16x16x32_f16 v[44:47], v[94:97], v[106:109], v[44:47]
	s_waitcnt vmcnt(0)
	ds_write_b128 v18, v[154:157] offset:49152
	v_mfma_f32_16x16x32_f16 v[78:81], v[94:97], v[110:113], v[78:81]
	v_mfma_f32_16x16x32_f16 v[82:85], v[118:121], v[106:109], v[82:85]
	v_mfma_f32_16x16x32_f16 v[86:89], v[118:121], v[110:113], v[86:89]
	s_waitcnt lgkmcnt(2)
	v_mfma_f32_16x16x32_f16 v[28:31], v[122:125], v[106:109], v[28:31]
	ds_read_b128 v[106:109], v23 offset:4096
	v_mfma_f32_16x16x32_f16 v[32:35], v[122:125], v[110:113], v[32:35]
	ds_read_b128 v[110:113], v23 offset:6144
	s_waitcnt lgkmcnt(1)
	v_mfma_f32_16x16x32_f16 v[98:101], v[58:61], v[106:109], v[98:101]
	s_waitcnt lgkmcnt(0)
	v_mfma_f32_16x16x32_f16 v[52:55], v[58:61], v[110:113], v[52:55]
	global_load_dwordx4 v[58:61], v[0:1], off offset:1280
	v_mfma_f32_16x16x32_f16 v[102:105], v[94:97], v[106:109], v[102:105]
	v_mfma_f32_16x16x32_f16 v[24:27], v[94:97], v[110:113], v[24:27]
	v_mfma_f32_16x16x32_f16 v[114:117], v[118:121], v[106:109], v[114:117]
	v_mfma_f32_16x16x32_f16 v[40:43], v[118:121], v[110:113], v[40:43]
	v_mfma_f32_16x16x32_f16 v[70:73], v[122:125], v[106:109], v[70:73]
	global_load_dwordx4 v[106:109], v[2:3], off offset:1280
	global_load_dwordx4 v[134:137], v[4:5], off offset:1280
	global_load_dwordx4 v[158:161], v[6:7], off offset:1280
	global_load_dwordx4 v[94:97], v[8:9], off offset:1280
	global_load_dwordx4 v[162:165], v[10:11], off offset:1280
	global_load_dwordx4 v[166:169], v[12:13], off offset:1280
	global_load_dwordx4 v[190:193], v[14:15], off offset:1280
	s_waitcnt lgkmcnt(0)
	s_barrier
	v_mfma_f32_16x16x32_f16 v[48:51], v[122:125], v[110:113], v[48:51]
	ds_read_b128 v[62:65], v16 offset:49152
	ds_read_b128 v[90:93], v21 offset:16384
	s_waitcnt lgkmcnt(0)
	v_mfma_f32_16x16x32_f16 v[36:39], v[62:65], v[90:93], v[36:39]
	ds_read_b128 v[74:77], v16 offset:51200
	ds_read_b128 v[110:113], v21 offset:18432
	s_waitcnt lgkmcnt(0)
	v_mfma_f32_16x16x32_f16 v[66:69], v[62:65], v[110:113], v[66:69]
	ds_read_b128 v[118:121], v16 offset:53248
	v_mfma_f32_16x16x32_f16 v[44:47], v[74:77], v[90:93], v[44:47]
	ds_read_b128 v[122:125], v16 offset:55296
	v_mfma_f32_16x16x32_f16 v[78:81], v[74:77], v[110:113], v[78:81]
	s_waitcnt vmcnt(7)
	ds_write_b128 v19, v[58:61]
	s_waitcnt lgkmcnt(2)
	v_mfma_f32_16x16x32_f16 v[82:85], v[118:121], v[90:93], v[82:85]
	s_waitcnt vmcnt(6)
	ds_write_b128 v20, v[106:109]
	v_mfma_f32_16x16x32_f16 v[86:89], v[118:121], v[110:113], v[86:89]
	s_waitcnt vmcnt(5)
	ds_write_b128 v17, v[134:137]
	s_waitcnt lgkmcnt(3)
	v_mfma_f32_16x16x32_f16 v[28:31], v[122:125], v[90:93], v[28:31]
	ds_read_b128 v[90:93], v21 offset:20480
	v_mfma_f32_16x16x32_f16 v[32:35], v[122:125], v[110:113], v[32:35]
	ds_read_b128 v[110:113], v21 offset:22528
	s_waitcnt lgkmcnt(1)
	v_mfma_f32_16x16x32_f16 v[98:101], v[62:65], v[90:93], v[98:101]
	s_waitcnt vmcnt(4)
	ds_write_b128 v18, v[158:161]
	s_waitcnt lgkmcnt(1)
	v_mfma_f32_16x16x32_f16 v[52:55], v[62:65], v[110:113], v[52:55]
	ds_read_b128 v[62:65], v22 offset:49152
	v_mfma_f32_16x16x32_f16 v[102:105], v[74:77], v[90:93], v[102:105]
	s_waitcnt vmcnt(3)
; #define GL_LOAD(s_, kt_) if (VAR != 1) { a##s_##0 = GL_A(0, kt_); a##s_##1 = GL_A(1, kt_); a##s_##2 = GL_A(2, kt_); a##s_##3 = GL_A(3, kt_); b##s_##0 = GL_B(0, kt_); b##s_##1 = GL_B(1, kt_); b##s_##2 = GL_B(2, kt_); b##s_##3 = GL_B(3, kt_); }
; #define LDS_STORE(s_, buf_) if (VAR != 2) { LDS_ST1(sA, 0, buf_, a##s_##0) LDS_ST1(sA, 1, buf_, a##s_##1) LDS_ST1(sA, 2, buf_, a##s_##2) LDS_ST1(sA, 3, buf_, a##s_##3) LDS_ST1(sB, 0, buf_, b##s_##0) LDS_ST1(sB, 1, buf_, b##s_##1) LDS_ST1(sB, 2, buf_, b##s_##2) LDS_ST1(sB, 3, buf_, b##s_##3) }
;     ...
;   GL_LOAD(0, 0)
;   GL_LOAD(1, 1)
;   LDS_STORE(0, 0)
;   if (VAR != 4) __syncthreads();
; #pragma unroll
;   for (int kt = 0; kt < nk; kt += 2) {
;     if (kt + 2 < nk) { GL_LOAD(0, kt + 2) }
;     MMA_TILE(0)
;     LDS_STORE(1, 1)
;     if (VAR != 4) __syncthreads();
;     if (kt + 3 < nk) { GL_LOAD(1, kt + 3) }
;     MMA_TILE(1)
;     if (kt + 2 < nk) { LDS_STORE(0, 0) }
;     if (VAR != 4) __syncthreads();
	ds_write_b128 v19, v[94:97] offset:32768
	v_mfma_f32_16x16x32_f16 v[24:27], v[74:77], v[110:113], v[24:27]
	ds_read_b128 v[74:77], v22 offset:51200
	v_mfma_f32_16x16x32_f16 v[114:117], v[118:121], v[90:93], v[114:117]
	s_waitcnt vmcnt(2)
	ds_write_b128 v20, v[162:165] offset:32768
	v_mfma_f32_16x16x32_f16 v[40:43], v[118:121], v[110:113], v[40:43]
	ds_read_b128 v[118:121], v22 offset:53248
	v_mfma_f32_16x16x32_f16 v[70:73], v[122:125], v[90:93], v[70:73]
	ds_read_b128 v[90:93], v23 offset:16384
	v_mfma_f32_16x16x32_f16 v[48:51], v[122:125], v[110:113], v[48:51]
	ds_read_b128 v[110:113], v23 offset:18432
	s_waitcnt lgkmcnt(1)
	v_mfma_f32_16x16x32_f16 v[36:39], v[62:65], v[90:93], v[36:39]
	ds_read_b128 v[122:125], v22 offset:55296
	s_waitcnt lgkmcnt(1)
	v_mfma_f32_16x16x32_f16 v[66:69], v[62:65], v[110:113], v[66:69]
	s_waitcnt vmcnt(1)
	ds_write_b128 v17, v[166:169] offset:32768
	v_mfma_f32_16x16x32_f16 v[44:47], v[74:77], v[90:93], v[44:47]
	s_waitcnt vmcnt(0)
	ds_write_b128 v18, v[190:193] offset:32768
	v_mfma_f32_16x16x32_f16 v[78:81], v[74:77], v[110:113], v[78:81]
	v_mfma_f32_16x16x32_f16 v[82:85], v[118:121], v[90:93], v[82:85]
	v_mfma_f32_16x16x32_f16 v[86:89], v[118:121], v[110:113], v[86:89]
	s_waitcnt lgkmcnt(2)
	v_mfma_f32_16x16x32_f16 v[28:31], v[122:125], v[90:93], v[28:31]
	ds_read_b128 v[90:93], v23 offset:20480
	v_mfma_f32_16x16x32_f16 v[32:35], v[122:125], v[110:113], v[32:35]
	ds_read_b128 v[110:113], v23 offset:22528
	s_waitcnt lgkmcnt(1)
	v_mfma_f32_16x16x32_f16 v[98:101], v[62:65], v[90:93], v[98:101]
	s_waitcnt lgkmcnt(0)
	v_mfma_f32_16x16x32_f16 v[52:55], v[62:65], v[110:113], v[52:55]
	global_load_dwordx4 v[62:65], v[0:1], off offset:1408
	v_mfma_f32_16x16x32_f16 v[102:105], v[74:77], v[90:93], v[102:105]
	v_mfma_f32_16x16x32_f16 v[24:27], v[74:77], v[110:113], v[24:27]
	v_mfma_f32_16x16x32_f16 v[114:117], v[118:121], v[90:93], v[114:117]
	v_mfma_f32_16x16x32_f16 v[40:43], v[118:121], v[110:113], v[40:43]
	v_mfma_f32_16x16x32_f16 v[70:73], v[122:125], v[90:93], v[70:73]
	global_load_dwordx4 v[90:93], v[2:3], off offset:1408
	global_load_dwordx4 v[126:129], v[4:5], off offset:1408
	global_load_dwordx4 v[130:133], v[6:7], off offset:1408
	global_load_dwordx4 v[74:77], v[8:9], off offset:1408
	global_load_dwordx4 v[138:141], v[10:11], off offset:1408
	global_load_dwordx4 v[142:145], v[12:13], off offset:1408
	global_load_dwordx4 v[154:157], v[14:15], off offset:1408
	s_waitcnt lgkmcnt(0)
	s_barrier
	v_mfma_f32_16x16x32_f16 v[48:51], v[122:125], v[110:113], v[48:51]
	ds_read_b128 v[58:61], v16 offset:32768
	ds_read_b128 v[106:109], v21
	s_waitcnt lgkmcnt(0)
	v_mfma_f32_16x16x32_f16 v[36:39], v[58:61], v[106:109], v[36:39]
	ds_read_b128 v[94:97], v16 offset:34816
	ds_read_b128 v[110:113], v21 offset:2048
	s_waitcnt lgkmcnt(0)
	v_mfma_f32_16x16x32_f16 v[66:69], v[58:61], v[110:113], v[66:69]
	ds_read_b128 v[118:121], v16 offset:36864
	v_mfma_f32_16x16x32_f16 v[44:47], v[94:97], v[106:109], v[44:47]
	ds_read_b128 v[122:125], v16 offset:38912
	v_mfma_f32_16x16x32_f16 v[78:81], v[94:97], v[110:113], v[78:81]
	s_waitcnt vmcnt(7)
	ds_write_b128 v19, v[62:65] offset:16384
	s_waitcnt lgkmcnt(2)
	v_mfma_f32_16x16x32_f16 v[82:85], v[118:121], v[106:109], v[82:85]
	s_waitcnt vmcnt(6)
	ds_write_b128 v20, v[90:93] offset:16384
	v_mfma_f32_16x16x32_f16 v[86:89], v[118:121], v[110:113], v[86:89]
	s_waitcnt vmcnt(5)
	ds_write_b128 v17, v[126:129] offset:16384
	s_waitcnt lgkmcnt(3)
	v_mfma_f32_16x16x32_f16 v[28:31], v[122:125], v[106:109], v[28:31]
	ds_read_b128 v[106:109], v21 offset:4096
	v_mfma_f32_16x16x32_f16 v[32:35], v[122:125], v[110:113], v[32:35]
	ds_read_b128 v[110:113], v21 offset:6144
	s_waitcnt lgkmcnt(1)
	v_mfma_f32_16x16x32_f16 v[98:101], v[58:61], v[106:109], v[98:101]
	s_waitcnt vmcnt(4)
	ds_write_b128 v18, v[130:133] offset:16384
	s_waitcnt lgkmcnt(1)
	v_mfma_f32_16x16x32_f16 v[52:55], v[58:61], v[110:113], v[52:55]
	ds_read_b128 v[58:61], v22 offset:32768
	v_mfma_f32_16x16x32_f16 v[102:105], v[94:97], v[106:109], v[102:105]
	s_waitcnt vmcnt(3)
	ds_write_b128 v19, v[74:77] offset:49152
	v_mfma_f32_16x16x32_f16 v[24:27], v[94:97], v[110:113], v[24:27]
	ds_read_b128 v[94:97], v22 offset:34816
	v_mfma_f32_16x16x32_f16 v[114:117], v[118:121], v[106:109], v[114:117]
	s_waitcnt vmcnt(2)
	ds_write_b128 v20, v[138:141] offset:49152
	v_mfma_f32_16x16x32_f16 v[40:43], v[118:121], v[110:113], v[40:43]
	ds_read_b128 v[118:121], v22 offset:36864
	v_mfma_f32_16x16x32_f16 v[70:73], v[122:125], v[106:109], v[70:73]
	ds_read_b128 v[106:109], v23
	v_mfma_f32_16x16x32_f16 v[48:51], v[122:125], v[110:113], v[48:51]
	ds_read_b128 v[110:113], v23 offset:2048
	s_waitcnt lgkmcnt(1)
	v_mfma_f32_16x16x32_f16 v[36:39], v[58:61], v[106:109], v[36:39]
	ds_read_b128 v[122:125], v22 offset:38912
	s_waitcnt lgkmcnt(1)
	v_mfma_f32_16x16x32_f16 v[66:69], v[58:61], v[110:113], v[66:69]
	s_waitcnt vmcnt(1)
	ds_write_b128 v17, v[142:145] offset:49152
	v_mfma_f32_16x16x32_f16 v[44:47], v[94:97], v[106:109], v[44:47]
	s_waitcnt vmcnt(0)
	ds_write_b128 v18, v[154:157] offset:49152
	v_mfma_f32_16x16x32_f16 v[78:81], v[94:97], v[110:113], v[78:81]
	v_mfma_f32_16x16x32_f16 v[82:85], v[118:121], v[106:109], v[82:85]
	v_mfma_f32_16x16x32_f16 v[86:89], v[118:121], v[110:113], v[86:89]
	s_waitcnt lgkmcnt(2)
	v_mfma_f32_16x16x32_f16 v[28:31], v[122:125], v[106:109], v[28:31]
	ds_read_b128 v[106:109], v23 offset:4096
	v_mfma_f32_16x16x32_f16 v[32:35], v[122:125], v[110:113], v[32:35]
	ds_read_b128 v[110:113], v23 offset:6144
	s_waitcnt lgkmcnt(1)
	v_mfma_f32_16x16x32_f16 v[98:101], v[58:61], v[106:109], v[98:101]
	s_waitcnt lgkmcnt(0)
	v_mfma_f32_16x16x32_f16 v[52:55], v[58:61], v[110:113], v[52:55]
	global_load_dwordx4 v[58:61], v[0:1], off offset:1536
	v_mfma_f32_16x16x32_f16 v[102:105], v[94:97], v[106:109], v[102:105]
	v_mfma_f32_16x16x32_f16 v[24:27], v[94:97], v[110:113], v[24:27]
	v_mfma_f32_16x16x32_f16 v[114:117], v[118:121], v[106:109], v[114:117]
	v_mfma_f32_16x16x32_f16 v[40:43], v[118:121], v[110:113], v[40:43]
	v_mfma_f32_16x16x32_f16 v[70:73], v[122:125], v[106:109], v[70:73]
	global_load_dwordx4 v[106:109], v[2:3], off offset:1536
	global_load_dwordx4 v[134:137], v[4:5], off offset:1536
	global_load_dwordx4 v[158:161], v[6:7], off offset:1536
	global_load_dwordx4 v[94:97], v[8:9], off offset:1536
	global_load_dwordx4 v[162:165], v[10:11], off offset:1536
	global_load_dwordx4 v[166:169], v[12:13], off offset:1536
	global_load_dwordx4 v[190:193], v[14:15], off offset:1536
	s_waitcnt lgkmcnt(0)
	s_barrier
; #define GL_LOAD(s_, kt_) if (VAR != 1) { a##s_##0 = GL_A(0, kt_); a##s_##1 = GL_A(1, kt_); a##s_##2 = GL_A(2, kt_); a##s_##3 = GL_A(3, kt_); b##s_##0 = GL_B(0, kt_); b##s_##1 = GL_B(1, kt_); b##s_##2 = GL_B(2, kt_); b##s_##3 = GL_B(3, kt_); }
; #define LDS_STORE(s_, buf_) if (VAR != 2) { LDS_ST1(sA, 0, buf_, a##s_##0) LDS_ST1(sA, 1, buf_, a##s_##1) LDS_ST1(sA, 2, buf_, a##s_##2) LDS_ST1(sA, 3, buf_, a##s_##3) LDS_ST1(sB, 0, buf_, b##s_##0) LDS_ST1(sB, 1, buf_, b##s_##1) LDS_ST1(sB, 2, buf_, b##s_##2) LDS_ST1(sB, 3, buf_, b##s_##3) }
;     ...
;   GL_LOAD(0, 0)
;   GL_LOAD(1, 1)
;   LDS_STORE(0, 0)
;   if (VAR != 4) __syncthreads();
; #pragma unroll
;   for (int kt = 0; kt < nk; kt += 2) {
;     if (kt + 2 < nk) { GL_LOAD(0, kt + 2) }
;     MMA_TILE(0)
;     LDS_STORE(1, 1)
;     if (VAR != 4) __syncthreads();
;     if (kt + 3 < nk) { GL_LOAD(1, kt + 3) }
;     MMA_TILE(1)
;     if (kt + 2 < nk) { LDS_STORE(0, 0) }
;     if (VAR != 4) __syncthreads();
	v_mfma_f32_16x16x32_f16 v[48:51], v[122:125], v[110:113], v[48:51]
	ds_read_b128 v[62:65], v16 offset:49152
	ds_read_b128 v[90:93], v21 offset:16384
	s_waitcnt lgkmcnt(0)
	v_mfma_f32_16x16x32_f16 v[36:39], v[62:65], v[90:93], v[36:39]
	ds_read_b128 v[74:77], v16 offset:51200
	ds_read_b128 v[110:113], v21 offset:18432
	s_waitcnt lgkmcnt(0)
	v_mfma_f32_16x16x32_f16 v[66:69], v[62:65], v[110:113], v[66:69]
	ds_read_b128 v[118:121], v16 offset:53248
	v_mfma_f32_16x16x32_f16 v[44:47], v[74:77], v[90:93], v[44:47]
	ds_read_b128 v[122:125], v16 offset:55296
	v_mfma_f32_16x16x32_f16 v[78:81], v[74:77], v[110:113], v[78:81]
	s_waitcnt vmcnt(7)
	ds_write_b128 v19, v[58:61]
	s_waitcnt lgkmcnt(2)
	v_mfma_f32_16x16x32_f16 v[82:85], v[118:121], v[90:93], v[82:85]
	s_waitcnt vmcnt(6)
	ds_write_b128 v20, v[106:109]
	v_mfma_f32_16x16x32_f16 v[86:89], v[118:121], v[110:113], v[86:89]
	s_waitcnt vmcnt(5)
	ds_write_b128 v17, v[134:137]
	s_waitcnt lgkmcnt(3)
	v_mfma_f32_16x16x32_f16 v[28:31], v[122:125], v[90:93], v[28:31]
	ds_read_b128 v[90:93], v21 offset:20480
	v_mfma_f32_16x16x32_f16 v[32:35], v[122:125], v[110:113], v[32:35]
	ds_read_b128 v[110:113], v21 offset:22528
	s_waitcnt lgkmcnt(1)
	v_mfma_f32_16x16x32_f16 v[98:101], v[62:65], v[90:93], v[98:101]
	s_waitcnt vmcnt(4)
	ds_write_b128 v18, v[158:161]
	s_waitcnt lgkmcnt(1)
	v_mfma_f32_16x16x32_f16 v[52:55], v[62:65], v[110:113], v[52:55]
	ds_read_b128 v[62:65], v22 offset:49152
	v_mfma_f32_16x16x32_f16 v[102:105], v[74:77], v[90:93], v[102:105]
	s_waitcnt vmcnt(3)
	ds_write_b128 v19, v[94:97] offset:32768
	v_mfma_f32_16x16x32_f16 v[24:27], v[74:77], v[110:113], v[24:27]
	ds_read_b128 v[74:77], v22 offset:51200
	v_mfma_f32_16x16x32_f16 v[114:117], v[118:121], v[90:93], v[114:117]
	s_waitcnt vmcnt(2)
	ds_write_b128 v20, v[162:165] offset:32768
	v_mfma_f32_16x16x32_f16 v[40:43], v[118:121], v[110:113], v[40:43]
	ds_read_b128 v[118:121], v22 offset:53248
	v_mfma_f32_16x16x32_f16 v[70:73], v[122:125], v[90:93], v[70:73]
	ds_read_b128 v[90:93], v23 offset:16384
	v_mfma_f32_16x16x32_f16 v[48:51], v[122:125], v[110:113], v[48:51]
	ds_read_b128 v[110:113], v23 offset:18432
	s_waitcnt lgkmcnt(1)
	v_mfma_f32_16x16x32_f16 v[36:39], v[62:65], v[90:93], v[36:39]
	ds_read_b128 v[122:125], v22 offset:55296
	s_waitcnt lgkmcnt(1)
	v_mfma_f32_16x16x32_f16 v[66:69], v[62:65], v[110:113], v[66:69]
	s_waitcnt vmcnt(1)
	ds_write_b128 v17, v[166:169] offset:32768
	v_mfma_f32_16x16x32_f16 v[44:47], v[74:77], v[90:93], v[44:47]
	s_waitcnt vmcnt(0)
	ds_write_b128 v18, v[190:193] offset:32768
	v_mfma_f32_16x16x32_f16 v[78:81], v[74:77], v[110:113], v[78:81]
	v_mfma_f32_16x16x32_f16 v[82:85], v[118:121], v[90:93], v[82:85]
	v_mfma_f32_16x16x32_f16 v[86:89], v[118:121], v[110:113], v[86:89]
	s_waitcnt lgkmcnt(2)
	v_mfma_f32_16x16x32_f16 v[28:31], v[122:125], v[90:93], v[28:31]
	ds_read_b128 v[90:93], v23 offset:20480
	v_mfma_f32_16x16x32_f16 v[32:35], v[122:125], v[110:113], v[32:35]
	ds_read_b128 v[110:113], v23 offset:22528
	s_waitcnt lgkmcnt(1)
	v_mfma_f32_16x16x32_f16 v[98:101], v[62:65], v[90:93], v[98:101]
	s_waitcnt lgkmcnt(0)
	v_mfma_f32_16x16x32_f16 v[52:55], v[62:65], v[110:113], v[52:55]
	global_load_dwordx4 v[62:65], v[0:1], off offset:1664
	v_mfma_f32_16x16x32_f16 v[102:105], v[74:77], v[90:93], v[102:105]
	v_mfma_f32_16x16x32_f16 v[24:27], v[74:77], v[110:113], v[24:27]
	v_mfma_f32_16x16x32_f16 v[114:117], v[118:121], v[90:93], v[114:117]
	v_mfma_f32_16x16x32_f16 v[40:43], v[118:121], v[110:113], v[40:43]
	v_mfma_f32_16x16x32_f16 v[70:73], v[122:125], v[90:93], v[70:73]
	global_load_dwordx4 v[90:93], v[2:3], off offset:1664
	global_load_dwordx4 v[126:129], v[4:5], off offset:1664
	global_load_dwordx4 v[130:133], v[6:7], off offset:1664
	global_load_dwordx4 v[74:77], v[8:9], off offset:1664
	global_load_dwordx4 v[138:141], v[10:11], off offset:1664
	global_load_dwordx4 v[142:145], v[12:13], off offset:1664
	global_load_dwordx4 v[154:157], v[14:15], off offset:1664
	s_waitcnt lgkmcnt(0)
	s_barrier
	v_mfma_f32_16x16x32_f16 v[48:51], v[122:125], v[110:113], v[48:51]
	ds_read_b128 v[58:61], v16 offset:32768
	ds_read_b128 v[106:109], v21
	s_waitcnt lgkmcnt(0)
	v_mfma_f32_16x16x32_f16 v[36:39], v[58:61], v[106:109], v[36:39]
	ds_read_b128 v[94:97], v16 offset:34816
	ds_read_b128 v[110:113], v21 offset:2048
	s_waitcnt lgkmcnt(0)
	v_mfma_f32_16x16x32_f16 v[66:69], v[58:61], v[110:113], v[66:69]
	ds_read_b128 v[118:121], v16 offset:36864
	v_mfma_f32_16x16x32_f16 v[44:47], v[94:97], v[106:109], v[44:47]
	ds_read_b128 v[122:125], v16 offset:38912
	v_mfma_f32_16x16x32_f16 v[78:81], v[94:97], v[110:113], v[78:81]
	s_waitcnt vmcnt(7)
	ds_write_b128 v19, v[62:65] offset:16384
	s_waitcnt lgkmcnt(2)
	v_mfma_f32_16x16x32_f16 v[82:85], v[118:121], v[106:109], v[82:85]
	s_waitcnt vmcnt(6)
	ds_write_b128 v20, v[90:93] offset:16384
	v_mfma_f32_16x16x32_f16 v[86:89], v[118:121], v[110:113], v[86:89]
	s_waitcnt vmcnt(5)
	ds_write_b128 v17, v[126:129] offset:16384
	s_waitcnt lgkmcnt(3)
	v_mfma_f32_16x16x32_f16 v[28:31], v[122:125], v[106:109], v[28:31]
	ds_read_b128 v[106:109], v21 offset:4096
	v_mfma_f32_16x16x32_f16 v[32:35], v[122:125], v[110:113], v[32:35]
	ds_read_b128 v[110:113], v21 offset:6144
	s_waitcnt lgkmcnt(1)
	v_mfma_f32_16x16x32_f16 v[98:101], v[58:61], v[106:109], v[98:101]
	s_waitcnt vmcnt(4)
	ds_write_b128 v18, v[130:133] offset:16384
	s_waitcnt lgkmcnt(1)
	v_mfma_f32_16x16x32_f16 v[52:55], v[58:61], v[110:113], v[52:55]
	ds_read_b128 v[58:61], v22 offset:32768
	v_mfma_f32_16x16x32_f16 v[102:105], v[94:97], v[106:109], v[102:105]
	s_waitcnt vmcnt(3)
; #define GL_LOAD(s_, kt_) if (VAR != 1) { a##s_##0 = GL_A(0, kt_); a##s_##1 = GL_A(1, kt_); a##s_##2 = GL_A(2, kt_); a##s_##3 = GL_A(3, kt_); b##s_##0 = GL_B(0, kt_); b##s_##1 = GL_B(1, kt_); b##s_##2 = GL_B(2, kt_); b##s_##3 = GL_B(3, kt_); }
; #define LDS_STORE(s_, buf_) if (VAR != 2) { LDS_ST1(sA, 0, buf_, a##s_##0) LDS_ST1(sA, 1, buf_, a##s_##1) LDS_ST1(sA, 2, buf_, a##s_##2) LDS_ST1(sA, 3, buf_, a##s_##3) LDS_ST1(sB, 0, buf_, b##s_##0) LDS_ST1(sB, 1, buf_, b##s_##1) LDS_ST1(sB, 2, buf_, b##s_##2) LDS_ST1(sB, 3, buf_, b##s_##3) }
;     ...
;   GL_LOAD(0, 0)
;   GL_LOAD(1, 1)
;   LDS_STORE(0, 0)
;   if (VAR != 4) __syncthreads();
; #pragma unroll
;   for (int kt = 0; kt < nk; kt += 2) {
;     if (kt + 2 < nk) { GL_LOAD(0, kt + 2) }
;     MMA_TILE(0)
;     LDS_STORE(1, 1)
;     if (VAR != 4) __syncthreads();
;     if (kt + 3 < nk) { GL_LOAD(1, kt + 3) }
;     MMA_TILE(1)
;     if (kt + 2 < nk) { LDS_STORE(0, 0) }
;     if (VAR != 4) __syncthreads();
	ds_write_b128 v19, v[74:77] offset:49152
	v_mfma_f32_16x16x32_f16 v[24:27], v[94:97], v[110:113], v[24:27]
	ds_read_b128 v[94:97], v22 offset:34816
	v_mfma_f32_16x16x32_f16 v[114:117], v[118:121], v[106:109], v[114:117]
	s_waitcnt vmcnt(2)
	ds_write_b128 v20, v[138:141] offset:49152
	v_mfma_f32_16x16x32_f16 v[40:43], v[118:121], v[110:113], v[40:43]
	ds_read_b128 v[118:121], v22 offset:36864
	v_mfma_f32_16x16x32_f16 v[70:73], v[122:125], v[106:109], v[70:73]
	ds_read_b128 v[106:109], v23
	v_mfma_f32_16x16x32_f16 v[48:51], v[122:125], v[110:113], v[48:51]
	ds_read_b128 v[110:113], v23 offset:2048
	s_waitcnt lgkmcnt(1)
	v_mfma_f32_16x16x32_f16 v[36:39], v[58:61], v[106:109], v[36:39]
	ds_read_b128 v[122:125], v22 offset:38912
	s_waitcnt lgkmcnt(1)
	v_mfma_f32_16x16x32_f16 v[66:69], v[58:61], v[110:113], v[66:69]
	s_waitcnt vmcnt(1)
	ds_write_b128 v17, v[142:145] offset:49152
	v_mfma_f32_16x16x32_f16 v[44:47], v[94:97], v[106:109], v[44:47]
	s_waitcnt vmcnt(0)
	ds_write_b128 v18, v[154:157] offset:49152
	v_mfma_f32_16x16x32_f16 v[78:81], v[94:97], v[110:113], v[78:81]
	v_mfma_f32_16x16x32_f16 v[82:85], v[118:121], v[106:109], v[82:85]
	v_mfma_f32_16x16x32_f16 v[86:89], v[118:121], v[110:113], v[86:89]
	s_waitcnt lgkmcnt(2)
	v_mfma_f32_16x16x32_f16 v[28:31], v[122:125], v[106:109], v[28:31]
	ds_read_b128 v[106:109], v23 offset:4096
	v_mfma_f32_16x16x32_f16 v[32:35], v[122:125], v[110:113], v[32:35]
	ds_read_b128 v[110:113], v23 offset:6144
	s_waitcnt lgkmcnt(1)
	v_mfma_f32_16x16x32_f16 v[98:101], v[58:61], v[106:109], v[98:101]
	s_waitcnt lgkmcnt(0)
	v_mfma_f32_16x16x32_f16 v[52:55], v[58:61], v[110:113], v[52:55]
	global_load_dwordx4 v[58:61], v[0:1], off offset:1792
	v_mfma_f32_16x16x32_f16 v[102:105], v[94:97], v[106:109], v[102:105]
	v_mfma_f32_16x16x32_f16 v[24:27], v[94:97], v[110:113], v[24:27]
	v_mfma_f32_16x16x32_f16 v[114:117], v[118:121], v[106:109], v[114:117]
	v_mfma_f32_16x16x32_f16 v[40:43], v[118:121], v[110:113], v[40:43]
	v_mfma_f32_16x16x32_f16 v[70:73], v[122:125], v[106:109], v[70:73]
	global_load_dwordx4 v[106:109], v[2:3], off offset:1792
	global_load_dwordx4 v[134:137], v[4:5], off offset:1792
	global_load_dwordx4 v[158:161], v[6:7], off offset:1792
	global_load_dwordx4 v[94:97], v[8:9], off offset:1792
	global_load_dwordx4 v[162:165], v[10:11], off offset:1792
	global_load_dwordx4 v[166:169], v[12:13], off offset:1792
	global_load_dwordx4 v[190:193], v[14:15], off offset:1792
	s_waitcnt lgkmcnt(0)
	s_barrier
	v_mfma_f32_16x16x32_f16 v[48:51], v[122:125], v[110:113], v[48:51]
	ds_read_b128 v[62:65], v16 offset:49152
	ds_read_b128 v[90:93], v21 offset:16384
	s_waitcnt lgkmcnt(0)
	v_mfma_f32_16x16x32_f16 v[36:39], v[62:65], v[90:93], v[36:39]
	ds_read_b128 v[74:77], v16 offset:51200
	ds_read_b128 v[110:113], v21 offset:18432
	s_waitcnt lgkmcnt(0)
	v_mfma_f32_16x16x32_f16 v[66:69], v[62:65], v[110:113], v[66:69]
	ds_read_b128 v[118:121], v16 offset:53248
	v_mfma_f32_16x16x32_f16 v[44:47], v[74:77], v[90:93], v[44:47]
	ds_read_b128 v[122:125], v16 offset:55296
	v_mfma_f32_16x16x32_f16 v[78:81], v[74:77], v[110:113], v[78:81]
	v_or_b32_e32 v130, s11, v56
	s_waitcnt lgkmcnt(1)
	v_mfma_f32_16x16x32_f16 v[82:85], v[118:121], v[90:93], v[82:85]
	v_lshrrev_b32_e32 v150, 4, v130
	v_mfma_f32_16x16x32_f16 v[86:89], v[118:121], v[110:113], v[86:89]
	s_waitcnt vmcnt(7)
	ds_write_b128 v19, v[58:61]
	s_waitcnt lgkmcnt(1)
	v_mfma_f32_16x16x32_f16 v[28:31], v[122:125], v[90:93], v[28:31]
	ds_read_b128 v[90:93], v21 offset:20480
	v_mfma_f32_16x16x32_f16 v[32:35], v[122:125], v[110:113], v[32:35]
	ds_read_b128 v[110:113], v21 offset:22528
	s_waitcnt lgkmcnt(1)
	v_mfma_f32_16x16x32_f16 v[98:101], v[62:65], v[90:93], v[98:101]
	s_waitcnt vmcnt(6)
	ds_write_b128 v20, v[106:109]
	s_waitcnt lgkmcnt(1)
	v_mfma_f32_16x16x32_f16 v[52:55], v[62:65], v[110:113], v[52:55]
	ds_read_b128 v[62:65], v22 offset:49152
	v_mfma_f32_16x16x32_f16 v[102:105], v[74:77], v[90:93], v[102:105]
	s_waitcnt vmcnt(5)
	ds_write_b128 v17, v[134:137]
	v_mfma_f32_16x16x32_f16 v[24:27], v[74:77], v[110:113], v[24:27]
	ds_read_b128 v[74:77], v22 offset:51200
	v_mfma_f32_16x16x32_f16 v[114:117], v[118:121], v[90:93], v[114:117]
	s_waitcnt vmcnt(4)
	ds_write_b128 v18, v[158:161]
	v_mfma_f32_16x16x32_f16 v[40:43], v[118:121], v[110:113], v[40:43]
	ds_read_b128 v[118:121], v22 offset:53248
	v_mfma_f32_16x16x32_f16 v[70:73], v[122:125], v[90:93], v[70:73]
	ds_read_b128 v[90:93], v23 offset:16384
	v_mfma_f32_16x16x32_f16 v[48:51], v[122:125], v[110:113], v[48:51]
	ds_read_b128 v[110:113], v23 offset:18432
	s_waitcnt lgkmcnt(1)
	v_mfma_f32_16x16x32_f16 v[36:39], v[62:65], v[90:93], v[36:39]
	ds_read_b128 v[122:125], v22 offset:55296
	s_waitcnt lgkmcnt(1)
	v_mfma_f32_16x16x32_f16 v[66:69], v[62:65], v[110:113], v[66:69]
	s_waitcnt vmcnt(3)
	ds_write_b128 v19, v[94:97] offset:32768
	v_mfma_f32_16x16x32_f16 v[44:47], v[74:77], v[90:93], v[44:47]
	s_waitcnt vmcnt(2)
	ds_write_b128 v20, v[162:165] offset:32768
	v_mfma_f32_16x16x32_f16 v[78:81], v[74:77], v[110:113], v[78:81]
	s_waitcnt vmcnt(1)
	ds_write_b128 v17, v[166:169] offset:32768
	v_mfma_f32_16x16x32_f16 v[82:85], v[118:121], v[90:93], v[82:85]
	s_waitcnt vmcnt(0)
	ds_write_b128 v18, v[190:193] offset:32768
	v_mfma_f32_16x16x32_f16 v[86:89], v[118:121], v[110:113], v[86:89]
	s_waitcnt lgkmcnt(4)
	v_mfma_f32_16x16x32_f16 v[28:31], v[122:125], v[90:93], v[28:31]
	ds_read_b128 v[90:93], v23 offset:20480
	v_mfma_f32_16x16x32_f16 v[32:35], v[122:125], v[110:113], v[32:35]
	ds_read_b128 v[110:113], v23 offset:22528
	s_waitcnt lgkmcnt(1)
	v_mfma_f32_16x16x32_f16 v[98:101], v[62:65], v[90:93], v[98:101]
	s_waitcnt lgkmcnt(0)
	v_mfma_f32_16x16x32_f16 v[52:55], v[62:65], v[110:113], v[52:55]
	global_load_dwordx4 v[62:65], v[0:1], off offset:1920
	global_load_dwordx4 v[0:3], v[2:3], off offset:1920
	v_mfma_f32_16x16x32_f16 v[102:105], v[74:77], v[90:93], v[102:105]
	v_mfma_f32_16x16x32_f16 v[24:27], v[74:77], v[110:113], v[24:27]
	v_mfma_f32_16x16x32_f16 v[114:117], v[118:121], v[90:93], v[114:117]
	v_mfma_f32_16x16x32_f16 v[40:43], v[118:121], v[110:113], v[40:43]
	v_mfma_f32_16x16x32_f16 v[70:73], v[122:125], v[90:93], v[70:73]
	global_load_dwordx4 v[90:93], v[4:5], off offset:1920
	global_load_dwordx4 v[4:7], v[6:7], off offset:1920
	global_load_dwordx4 v[74:77], v[8:9], off offset:1920
	global_load_dwordx4 v[8:11], v[10:11], off offset:1920
	global_load_dwordx4 v[126:129], v[12:13], off offset:1920
	global_load_dwordx4 v[12:15], v[14:15], off offset:1920
	s_waitcnt lgkmcnt(0)
	s_barrier
; #define GL_LOAD(s_, kt_) if (VAR != 1) { a##s_##0 = GL_A(0, kt_); a##s_##1 = GL_A(1, kt_); a##s_##2 = GL_A(2, kt_); a##s_##3 = GL_A(3, kt_); b##s_##0 = GL_B(0, kt_); b##s_##1 = GL_B(1, kt_); b##s_##2 = GL_B(2, kt_); b##s_##3 = GL_B(3, kt_); }
; #define LDS_STORE(s_, buf_) if (VAR != 2) { LDS_ST1(sA, 0, buf_, a##s_##0) LDS_ST1(sA, 1, buf_, a##s_##1) LDS_ST1(sA, 2, buf_, a##s_##2) LDS_ST1(sA, 3, buf_, a##s_##3) LDS_ST1(sB, 0, buf_, b##s_##0) LDS_ST1(sB, 1, buf_, b##s_##1) LDS_ST1(sB, 2, buf_, b##s_##2) LDS_ST1(sB, 3, buf_, b##s_##3) }
;     ...
;   GL_LOAD(0, 0)
;   GL_LOAD(1, 1)
;   LDS_STORE(0, 0)
;   if (VAR != 4) __syncthreads();
; #pragma unroll
;   for (int kt = 0; kt < nk; kt += 2) {
;     if (kt + 2 < nk) { GL_LOAD(0, kt + 2) }
;     MMA_TILE(0)
;     LDS_STORE(1, 1)
;     if (VAR != 4) __syncthreads();
;     if (kt + 3 < nk) { GL_LOAD(1, kt + 3) }
;     MMA_TILE(1)
;     if (kt + 2 < nk) { LDS_STORE(0, 0) }
;     if (VAR != 4) __syncthreads();
	ds_read_b128 v[58:61], v16 offset:32768
	v_mfma_f32_16x16x32_f16 v[48:51], v[122:125], v[110:113], v[48:51]
	ds_read_b128 v[94:97], v16 offset:34816
	ds_read_b128 v[106:109], v21
	ds_read_b128 v[110:113], v21 offset:2048
	ds_read_b128 v[118:121], v16 offset:36864
	ds_read_b128 v[122:125], v16 offset:38912
	s_waitcnt lgkmcnt(3)
	v_mfma_f32_16x16x32_f16 v[36:39], v[58:61], v[106:109], v[36:39]
	v_mfma_f32_16x16x32_f16 v[44:47], v[94:97], v[106:109], v[44:47]
	s_waitcnt lgkmcnt(1)
	v_mfma_f32_16x16x32_f16 v[82:85], v[118:121], v[106:109], v[82:85]
	s_waitcnt lgkmcnt(0)
	v_mfma_f32_16x16x32_f16 v[28:31], v[122:125], v[106:109], v[28:31]
	v_mfma_f32_16x16x32_f16 v[66:69], v[58:61], v[110:113], v[66:69]
	v_mfma_f32_16x16x32_f16 v[78:81], v[94:97], v[110:113], v[78:81]
	v_mfma_f32_16x16x32_f16 v[86:89], v[118:121], v[110:113], v[86:89]
	v_mfma_f32_16x16x32_f16 v[32:35], v[122:125], v[110:113], v[32:35]
	ds_read_b128 v[106:109], v21 offset:4096
	ds_read_b128 v[110:113], v21 offset:6144
	s_waitcnt lgkmcnt(1)
	v_mfma_f32_16x16x32_f16 v[98:101], v[58:61], v[106:109], v[98:101]
	v_mfma_f32_16x16x32_f16 v[102:105], v[94:97], v[106:109], v[102:105]
	v_mfma_f32_16x16x32_f16 v[114:117], v[118:121], v[106:109], v[114:117]
	v_mfma_f32_16x16x32_f16 v[70:73], v[122:125], v[106:109], v[70:73]
	s_waitcnt lgkmcnt(0)
	v_mfma_f32_16x16x32_f16 v[52:55], v[58:61], v[110:113], v[52:55]
	ds_read_b128 v[58:61], v22 offset:32768
	v_mfma_f32_16x16x32_f16 v[24:27], v[94:97], v[110:113], v[24:27]
	v_mfma_f32_16x16x32_f16 v[40:43], v[118:121], v[110:113], v[40:43]
	v_mfma_f32_16x16x32_f16 v[48:51], v[122:125], v[110:113], v[48:51]
	ds_read_b128 v[94:97], v22 offset:34816
	ds_read_b128 v[106:109], v23
	ds_read_b128 v[110:113], v23 offset:2048
	ds_read_b128 v[118:121], v22 offset:36864
	ds_read_b128 v[122:125], v22 offset:38912
	s_waitcnt lgkmcnt(3)
	v_mfma_f32_16x16x32_f16 v[36:39], v[58:61], v[106:109], v[36:39]
	v_mfma_f32_16x16x32_f16 v[44:47], v[94:97], v[106:109], v[44:47]
	s_waitcnt lgkmcnt(1)
	v_mfma_f32_16x16x32_f16 v[82:85], v[118:121], v[106:109], v[82:85]
	s_waitcnt lgkmcnt(0)
	v_mfma_f32_16x16x32_f16 v[28:31], v[122:125], v[106:109], v[28:31]
	v_mfma_f32_16x16x32_f16 v[66:69], v[58:61], v[110:113], v[66:69]
	v_mfma_f32_16x16x32_f16 v[78:81], v[94:97], v[110:113], v[78:81]
	v_mfma_f32_16x16x32_f16 v[86:89], v[118:121], v[110:113], v[86:89]
	v_mfma_f32_16x16x32_f16 v[32:35], v[122:125], v[110:113], v[32:35]
	ds_read_b128 v[106:109], v23 offset:4096
	ds_read_b128 v[110:113], v23 offset:6144
	s_waitcnt vmcnt(7)
	ds_write_b128 v19, v[62:65] offset:16384
	s_waitcnt vmcnt(6)
	ds_write_b128 v20, v[0:3] offset:16384
	s_waitcnt vmcnt(5)
	ds_write_b128 v17, v[90:93] offset:16384
	s_waitcnt vmcnt(4)
	ds_write_b128 v18, v[4:7] offset:16384
	s_waitcnt vmcnt(3)
	ds_write_b128 v19, v[74:77] offset:49152
	s_waitcnt vmcnt(2)
	ds_write_b128 v20, v[8:11] offset:49152
	s_waitcnt lgkmcnt(7)
	v_mfma_f32_16x16x32_f16 v[98:101], v[58:61], v[106:109], v[98:101]
	s_waitcnt vmcnt(1)
	ds_write_b128 v17, v[126:129] offset:49152
	s_waitcnt vmcnt(0)
	ds_write_b128 v18, v[12:15] offset:49152
	s_waitcnt lgkmcnt(0)
	s_barrier
	v_mfma_f32_16x16x32_f16 v[52:55], v[58:61], v[110:113], v[52:55]
	ds_read_b128 v[8:11], v16 offset:49152
	v_mfma_f32_16x16x32_f16 v[0:3], v[94:97], v[110:113], v[24:27]
	v_mfma_f32_16x16x32_f16 v[4:7], v[118:121], v[110:113], v[40:43]
	v_mfma_f32_16x16x32_f16 v[12:15], v[122:125], v[110:113], v[48:51]
	s_nop 0
	ds_read_b128 v[24:27], v16 offset:51200
	ds_read_b128 v[40:43], v21 offset:16384
	ds_read_b128 v[48:51], v21 offset:18432
	ds_read_b128 v[58:61], v16 offset:53248
	ds_read_b128 v[16:19], v16 offset:55296
	v_mfma_f32_16x16x32_f16 v[102:105], v[94:97], v[106:109], v[102:105]
	v_mfma_f32_16x16x32_f16 v[114:117], v[118:121], v[106:109], v[114:117]
	v_mfma_f32_16x16x32_f16 v[70:73], v[122:125], v[106:109], v[70:73]
	s_waitcnt lgkmcnt(3)
	v_mfma_f32_16x16x32_f16 v[36:39], v[8:11], v[40:43], v[36:39]
	v_mfma_f32_16x16x32_f16 v[44:47], v[24:27], v[40:43], v[44:47]
	s_waitcnt lgkmcnt(1)
	v_mfma_f32_16x16x32_f16 v[62:65], v[58:61], v[40:43], v[82:85]
	ds_read_b128 v[74:77], v21 offset:20480
	s_nop 1
	ds_read_b128 v[82:85], v21 offset:22528
	s_waitcnt lgkmcnt(2)
	v_mfma_f32_16x16x32_f16 v[28:31], v[16:19], v[40:43], v[28:31]
	ds_read_b128 v[40:43], v23 offset:16384
	ds_read_b128 v[90:93], v23 offset:18432
	ds_read_b128 v[94:97], v22 offset:49152
	ds_read_b128 v[106:109], v22 offset:51200
	ds_read_b128 v[110:113], v23 offset:20480
	ds_read_b128 v[118:121], v23 offset:22528
	ds_read_b128 v[122:125], v22 offset:53248
	ds_read_b128 v[126:129], v22 offset:55296
	s_waitcnt lgkmcnt(0)
	v_mfma_f32_16x16x32_f16 v[20:23], v[24:27], v[48:51], v[78:81]
	s_barrier
; DI unsigned pack2(float lo, float hi) { f2_t v = {lo, hi}; h2_t b = __builtin_convertvector(v, h2_t); return __builtin_bit_cast(unsigned, b); }
; DI void epi_residual(const f32x4 (&v)[4][4], int row0, int col0, const float* xsrc, float* x, bf16_t* xb, float* ssq_out, bool write_xb, bool write_ssq) {
;     ...
;   for (int mt = 0; mt < 4; ++mt) {
;     const int row = row0 + mt * 16 + lr;
;     float ss = 0.f;
; #pragma unroll
;     for (int nt = 0; nt < 4; ++nt) {
;       const int col = col0 + nt * 16 + 4 * g;
;       float4* px = (float4*)(x + (size_t)row * DM + col);
;       float4 o = *(const float4*)(xsrc + (size_t)row * DM + col);
;       o.x += v[mt][nt][0]; o.y += v[mt][nt][1]; o.z += v[mt][nt][2]; o.w += v[mt][nt][3];
;       *px = o;
;       ss += (o.x * o.x + o.y * o.y) + (o.z * o.z + o.w * o.w);
;       if (write_xb) *(uint2*)(xb + (size_t)row * DM + col) = make_uint2(pack2(o.x, o.y), pack2(o.z, o.w));
;     }
;     if (write_ssq) {
;       ss += __shfl_xor(ss, 16); ss += __shfl_xor(ss, 32);
;       if (g == 0) ssq_out[(size_t)row * 16 + (col0 >> 6)] = ss;
;     }
	s_setprio 0
	v_mfma_f32_16x16x32_f16 v[78:81], v[58:61], v[48:51], v[86:89]
	s_nop 2
	v_add_u32_e32 v86, s6, v57
	v_mov_b32_e32 v87, v148
	v_mfma_f32_16x16x32_f16 v[66:69], v[8:11], v[48:51], v[66:69]
	v_readlane_b32 s6, v254, 41
	v_bfe_u32 v134, v87, 4, 2
	v_mfma_f32_16x16x32_f16 v[32:35], v[16:19], v[48:51], v[32:35]
	v_and_or_b32 v50, v87, 15, v86
	v_ashrrev_i32_e32 v51, 31, v50
	v_lshl_or_b32 v135, v134, 2, v130
	v_readlane_b32 s7, v254, 42
	v_lshlrev_b64 v[130:131], 12, v[50:51]
	v_lshl_add_u64 v[132:133], s[4:5], 0, v[130:131]
	v_lshl_add_u64 v[48:49], s[6:7], 0, v[150:151]
	v_lshlrev_b32_e32 v150, 2, v135
	v_lshl_add_u64 v[132:133], v[132:133], 0, v[150:151]
	v_mfma_f32_16x16x32_f16 v[86:89], v[8:11], v[74:77], v[98:101]
	v_readlane_b32 s6, v254, 43
	v_readlane_b32 s7, v254, 44
	v_cmp_eq_u32_e32 vcc, 0, v134
	v_mfma_f32_16x16x32_f16 v[98:101], v[24:27], v[74:77], v[102:105]
	v_mfma_f32_16x16x32_f16 v[102:105], v[58:61], v[74:77], v[114:117]
	s_nop 2
	global_load_dwordx4 v[114:117], v[132:133], off
	v_mfma_f32_16x16x32_f16 v[36:39], v[94:97], v[40:43], v[36:39]
	v_mfma_f32_16x16x32_f16 v[70:73], v[16:19], v[74:77], v[70:73]
	v_lshlrev_b64 v[76:77], 11, v[50:51]
	v_lshl_add_u64 v[74:75], s[12:13], 0, v[130:131]
	v_lshl_add_u64 v[76:77], s[6:7], 0, v[76:77]
	v_mfma_f32_16x16x32_f16 v[8:11], v[8:11], v[82:85], v[52:55]
	v_lshl_add_u64 v[74:75], v[74:75], 0, v[150:151]
	s_waitcnt vmcnt(0)
	s_nop 0
	v_pk_add_f32 v[36:37], v[36:37], v[114:115]
	v_pk_add_f32 v[38:39], v[38:39], v[116:117]
	v_lshlrev_b32_e32 v52, 1, v135
	v_mov_b32_e32 v53, v151
	v_cvt_pk_f16_f32 v54, v36, v37
	v_cvt_pk_f16_f32 v55, v38, v39
	v_lshl_add_u64 v[76:77], v[76:77], 0, v[52:53]
	global_store_dwordx4 v[74:75], v[36:39], off
	v_mov_b32_e32 v136, v54
	v_mov_b32_e32 v137, v55
	v_mfma_f32_16x16x32_f16 v[0:3], v[24:27], v[82:85], v[0:3]
	v_mul_f32_e64 v54, v36, v36
	v_mul_f32_e64 v55, v37, v37
	v_mfma_f32_16x16x32_f16 v[24:27], v[106:109], v[40:43], v[44:47]
	s_nop 2
	global_load_dwordx4 v[44:47], v[132:133], off offset:64
	v_mfma_f32_16x16x32_f16 v[4:7], v[58:61], v[82:85], v[4:7]
	s_waitcnt vmcnt(0)
	s_nop 1
	v_pk_add_f32 v[24:25], v[24:25], v[44:45]
	v_pk_add_f32 v[26:27], v[26:27], v[46:47]
	v_cvt_pk_f16_f32 v44, v24, v25
	v_cvt_pk_f16_f32 v45, v26, v27
	global_store_dwordx4 v[74:75], v[24:27], off offset:64
	v_mov_b32_e32 v138, v44
	v_mov_b32_e32 v139, v45
	v_and_b32_e32 v144, 16, v148
	v_lshrrev_b32_e32 v145, 1, v144
	v_add_u32_e32 v144, v144, v145
	v_mov_b32_e32 v145, 0
	v_lshl_add_u64 v[144:145], v[144:145], 0, v[76:77]
	v_permlane16_swap_b32_e32 v136, v138
	v_permlane16_swap_b32_e32 v137, v139
	global_store_dwordx4 v[144:145], v[136:139], off
	v_mfma_f32_16x16x32_f16 v[58:61], v[16:19], v[82:85], v[12:15]
	s_nop 2
	global_load_dwordx4 v[12:15], v[132:133], off offset:128
	v_mfma_f32_16x16x32_f16 v[16:19], v[122:125], v[40:43], v[62:65]
	v_mfma_f32_16x16x32_f16 v[44:47], v[94:97], v[90:93], v[66:69]
	s_nop 2
	v_mul_f32_e64 v66, v26, v26
	v_mul_f32_e64 v67, v27, v27
	v_mfma_f32_16x16x32_f16 v[32:35], v[126:129], v[90:93], v[32:35]
	s_waitcnt vmcnt(0)
	v_pk_add_f32 v[12:13], v[16:17], v[12:13]
	v_pk_add_f32 v[14:15], v[18:19], v[14:15]
	v_mfma_f32_16x16x32_f16 v[16:19], v[126:129], v[40:43], v[28:31]
	global_store_dwordx4 v[74:75], v[12:15], off offset:128
	s_nop 1
	v_cvt_pk_f16_f32 v28, v12, v13
	v_cvt_pk_f16_f32 v29, v14, v15
	v_mov_b32_e32 v140, v28
	v_mov_b32_e32 v141, v29
	global_load_dwordx4 v[28:31], v[132:133], off offset:192
	v_mfma_f32_16x16x32_f16 v[40:43], v[106:109], v[90:93], v[20:23]
	v_mul_f32_e64 v12, v12, v12
	v_mul_f32_e64 v13, v13, v13
	v_pk_mul_f32 v[14:15], v[14:15], v[14:15]
	v_add_f32_e32 v12, v12, v13
	v_pk_mul_f32 v[20:21], v[38:39], v[38:39]
	v_pk_mul_f32 v[22:23], v[24:25], v[24:25]
	v_add_f32_e32 v14, v14, v15
	v_add_f32_e32 v12, v12, v14
	v_mfma_f32_16x16x32_f16 v[36:39], v[122:125], v[90:93], v[78:81]
	s_waitcnt vmcnt(0)
	v_pk_add_f32 v[62:63], v[16:17], v[28:29]
	v_add_f32_e32 v16, v20, v21
	v_add_f32_e32 v17, v54, v55
	v_pk_add_f32 v[64:65], v[18:19], v[30:31]
	v_add_f32_e32 v16, v17, v16
	v_add_f32_e32 v17, v66, v67
	v_add_f32_e32 v18, v22, v23
	v_add_f32_e32 v17, v18, v17
	global_store_dwordx4 v[74:75], v[62:65], off offset:192
	v_pk_mul_f32 v[68:69], v[62:63], v[62:63]
	v_pk_mul_f32 v[74:75], v[64:65], v[64:65]
	v_add_f32_e32 v54, v16, v17
	v_add_f32_e32 v54, v54, v12
	v_mfma_f32_16x16x32_f16 v[12:15], v[94:97], v[118:121], v[8:11]
	s_nop 2
	v_add_f32_e32 v8, v74, v75
	v_add_f32_e32 v9, v68, v69
	v_add_f32_e32 v55, v9, v8
	v_mfma_f32_16x16x32_f16 v[8:11], v[106:109], v[118:121], v[0:3]
	s_nop 2
	v_add_f32_e32 v2, v54, v55
	ds_bpermute_b32 v3, v189, v2
	v_cvt_pk_f16_f32 v0, v62, v63
	v_cvt_pk_f16_f32 v1, v64, v65
	v_mfma_f32_16x16x32_f16 v[28:31], v[94:97], v[110:113], v[86:89]
	v_mov_b32_e32 v142, v0
	v_mov_b32_e32 v143, v1
	v_and_b32_e32 v144, 16, v148
	v_lshrrev_b32_e32 v145, 1, v144
	v_add_u32_e32 v144, v144, v145
	v_mov_b32_e32 v145, 0
	v_lshl_add_u64 v[144:145], v[144:145], 0, v[76:77]
	v_permlane16_swap_b32_e32 v140, v142
	v_permlane16_swap_b32_e32 v141, v143
	global_store_dwordx4 v[144:145], v[140:143], off offset:64
	s_waitcnt lgkmcnt(0)
	v_add_f32_e32 v54, v2, v3
	ds_bpermute_b32 v55, v188, v54
	v_mfma_f32_16x16x32_f16 v[24:27], v[106:109], v[110:113], v[98:101]
	v_mfma_f32_16x16x32_f16 v[20:23], v[122:125], v[110:113], v[102:105]
	v_mfma_f32_16x16x32_f16 v[16:19], v[126:129], v[110:113], v[70:73]
	v_mfma_f32_16x16x32_f16 v[4:7], v[122:125], v[118:121], v[4:7]
	v_mfma_f32_16x16x32_f16 v[0:3], v[126:129], v[118:121], v[58:61]
	s_and_saveexec_b64 s[6:7], vcc
	s_cbranch_execz .LBB0_1252
	s_waitcnt lgkmcnt(0)
	v_add_f32_e32 v58, v54, v55
	v_lshlrev_b64 v[54:55], 6, v[50:51]
	v_lshl_add_u64 v[54:55], v[48:49], 0, v[54:55]
	global_store_dword v[54:55], v58, off
; DI unsigned pack2(float lo, float hi) { f2_t v = {lo, hi}; h2_t b = __builtin_convertvector(v, h2_t); return __builtin_bit_cast(unsigned, b); }
; DI void epi_residual(const f32x4 (&v)[4][4], int row0, int col0, const float* xsrc, float* x, bf16_t* xb, float* ssq_out, bool write_xb, bool write_ssq) {
;     ...
;   for (int mt = 0; mt < 4; ++mt) {
;     const int row = row0 + mt * 16 + lr;
;     float ss = 0.f;
; #pragma unroll
;     for (int nt = 0; nt < 4; ++nt) {
;       const int col = col0 + nt * 16 + 4 * g;
;       float4* px = (float4*)(x + (size_t)row * DM + col);
;       float4 o = *(const float4*)(xsrc + (size_t)row * DM + col);
;       o.x += v[mt][nt][0]; o.y += v[mt][nt][1]; o.z += v[mt][nt][2]; o.w += v[mt][nt][3];
;       *px = o;
;       ss += (o.x * o.x + o.y * o.y) + (o.z * o.z + o.w * o.w);
;       if (write_xb) *(uint2*)(xb + (size_t)row * DM + col) = make_uint2(pack2(o.x, o.y), pack2(o.z, o.w));
;     }
;     if (write_ssq) {
;       ss += __shfl_xor(ss, 16); ss += __shfl_xor(ss, 32);
;       if (g == 0) ssq_out[(size_t)row * 16 + (col0 >> 6)] = ss;
;     }
.LBB0_1252:
	s_or_b64 exec, exec, s[6:7]
	v_or_b32_e32 v54, 16, v50
	s_waitcnt lgkmcnt(0)
	v_ashrrev_i32_e32 v55, 31, v54
	v_lshlrev_b64 v[62:63], 12, v[54:55]
	v_lshl_add_u64 v[58:59], s[4:5], 0, v[62:63]
	v_lshl_add_u64 v[64:65], v[58:59], 0, v[150:151]
	global_load_dwordx4 v[58:61], v[64:65], off
	v_readlane_b32 s12, v254, 55
	v_readlane_b32 s6, v254, 43
	v_lshlrev_b64 v[66:67], 11, v[54:55]
	v_readlane_b32 s13, v254, 56
	v_readlane_b32 s7, v254, 44
	v_readlane_b32 s14, v254, 57
	v_lshl_add_u64 v[62:63], s[12:13], 0, v[62:63]
	v_lshl_add_u64 v[66:67], s[6:7], 0, v[66:67]
	v_lshl_add_u64 v[62:63], v[62:63], 0, v[150:151]
	v_lshl_add_u64 v[66:67], v[66:67], 0, v[52:53]
	v_readlane_b32 s15, v254, 58
	s_waitcnt vmcnt(0)
	v_pk_add_f32 v[44:45], v[44:45], v[58:59]
	v_pk_add_f32 v[46:47], v[46:47], v[60:61]
	v_cvt_pk_f16_f32 v58, v44, v45
	v_cvt_pk_f16_f32 v59, v46, v47
	global_store_dwordx4 v[62:63], v[44:47], off
	v_mov_b32_e32 v136, v58
	v_mov_b32_e32 v137, v59
	global_load_dwordx4 v[58:61], v[64:65], off offset:64
	v_pk_mul_f32 v[44:45], v[44:45], v[44:45]
	v_pk_mul_f32 v[46:47], v[46:47], v[46:47]
	v_add_f32_e32 v44, v44, v45
	v_add_f32_e32 v46, v46, v47
	v_add_f32_e32 v44, v44, v46
	s_waitcnt vmcnt(0)
	v_pk_add_f32 v[40:41], v[40:41], v[58:59]
	v_pk_add_f32 v[42:43], v[42:43], v[60:61]
	v_cvt_pk_f16_f32 v58, v40, v41
	v_cvt_pk_f16_f32 v59, v42, v43
	global_store_dwordx4 v[62:63], v[40:43], off offset:64
	v_mov_b32_e32 v138, v58
	v_mov_b32_e32 v139, v59
	v_and_b32_e32 v144, 16, v148
	v_lshrrev_b32_e32 v145, 1, v144
	v_add_u32_e32 v144, v144, v145
	v_mov_b32_e32 v145, 0
	v_lshl_add_u64 v[144:145], v[144:145], 0, v[66:67]
	v_permlane16_swap_b32_e32 v136, v138
	v_permlane16_swap_b32_e32 v137, v139
	global_store_dwordx4 v[144:145], v[136:139], off
	global_load_dwordx4 v[58:61], v[64:65], off offset:128
	v_pk_mul_f32 v[40:41], v[40:41], v[40:41]
	v_pk_mul_f32 v[42:43], v[42:43], v[42:43]
	v_add_f32_e32 v40, v40, v41
	v_add_f32_e32 v42, v42, v43
	v_add_f32_e32 v40, v40, v42
	v_add_f32_e32 v40, v44, v40
	s_waitcnt vmcnt(0)
	v_pk_add_f32 v[36:37], v[36:37], v[58:59]
	v_pk_add_f32 v[38:39], v[38:39], v[60:61]
	v_cvt_pk_f16_f32 v58, v36, v37
	v_cvt_pk_f16_f32 v59, v38, v39
	global_store_dwordx4 v[62:63], v[36:39], off offset:128
	v_mov_b32_e32 v140, v58
	v_mov_b32_e32 v141, v59
	global_load_dwordx4 v[58:61], v[64:65], off offset:192
	v_pk_mul_f32 v[36:37], v[36:37], v[36:37]
	v_pk_mul_f32 v[38:39], v[38:39], v[38:39]
	v_add_f32_e32 v36, v36, v37
	v_add_f32_e32 v38, v38, v39
	v_add_f32_e32 v36, v36, v38
	v_add_f32_e32 v40, v40, v36
	s_waitcnt vmcnt(0)
	v_pk_add_f32 v[36:37], v[32:33], v[58:59]
	v_pk_add_f32 v[38:39], v[34:35], v[60:61]
	v_pk_mul_f32 v[32:33], v[36:37], v[36:37]
	v_pk_mul_f32 v[34:35], v[38:39], v[38:39]
	v_add_f32_e32 v32, v32, v33
	v_add_f32_e32 v34, v34, v35
	v_add_f32_e32 v32, v32, v34
	v_add_f32_e32 v32, v40, v32
	ds_bpermute_b32 v33, v189, v32
	v_cvt_pk_f16_f32 v34, v36, v37
	v_cvt_pk_f16_f32 v35, v38, v39
	global_store_dwordx4 v[62:63], v[36:39], off offset:192
	v_mov_b32_e32 v142, v34
	v_mov_b32_e32 v143, v35
	v_and_b32_e32 v144, 16, v148
	v_lshrrev_b32_e32 v145, 1, v144
	v_add_u32_e32 v144, v144, v145
	v_mov_b32_e32 v145, 0
	v_lshl_add_u64 v[144:145], v[144:145], 0, v[66:67]
	v_permlane16_swap_b32_e32 v140, v142
	v_permlane16_swap_b32_e32 v141, v143
	global_store_dwordx4 v[144:145], v[140:143], off offset:64
	s_waitcnt lgkmcnt(0)
	v_add_f32_e32 v32, v32, v33
	ds_bpermute_b32 v33, v188, v32
	s_and_saveexec_b64 s[6:7], vcc
	s_cbranch_execz .LBB0_1254
	s_waitcnt lgkmcnt(0)
	v_add_f32_e32 v34, v32, v33
	v_lshlrev_b64 v[32:33], 6, v[54:55]
	v_lshl_add_u64 v[32:33], v[48:49], 0, v[32:33]
	global_store_dword v[32:33], v34, off
.LBB0_1254:
	s_or_b64 exec, exec, s[6:7]
	v_or_b32_e32 v32, 32, v50
	s_waitcnt lgkmcnt(0)
	v_ashrrev_i32_e32 v33, 31, v32
	v_lshlrev_b64 v[38:39], 12, v[32:33]
	v_lshl_add_u64 v[34:35], s[4:5], 0, v[38:39]
	v_lshl_add_u64 v[40:41], v[34:35], 0, v[150:151]
	global_load_dwordx4 v[34:37], v[40:41], off
	v_readlane_b32 s12, v254, 55
	v_readlane_b32 s6, v254, 43
	v_lshlrev_b64 v[42:43], 11, v[32:33]
	v_readlane_b32 s13, v254, 56
	v_readlane_b32 s7, v254, 44
	v_mov_b32_e32 v53, v151
	v_lshl_add_u64 v[38:39], s[12:13], 0, v[38:39]
	v_lshl_add_u64 v[42:43], s[6:7], 0, v[42:43]
	v_lshl_add_u64 v[38:39], v[38:39], 0, v[150:151]
	v_lshl_add_u64 v[42:43], v[42:43], 0, v[52:53]
	v_readlane_b32 s14, v254, 57
	v_readlane_b32 s15, v254, 58
	s_waitcnt vmcnt(0)
	v_pk_add_f32 v[28:29], v[28:29], v[34:35]
	v_pk_add_f32 v[30:31], v[30:31], v[36:37]
	v_cvt_pk_f16_f32 v34, v28, v29
	v_cvt_pk_f16_f32 v35, v30, v31
	global_store_dwordx4 v[38:39], v[28:31], off
	v_mov_b32_e32 v136, v34
	v_mov_b32_e32 v137, v35
	global_load_dwordx4 v[34:37], v[40:41], off offset:64
	v_pk_mul_f32 v[28:29], v[28:29], v[28:29]
	v_pk_mul_f32 v[30:31], v[30:31], v[30:31]
	v_add_f32_e32 v28, v28, v29
	v_add_f32_e32 v30, v30, v31
	v_add_f32_e32 v28, v28, v30
	s_waitcnt vmcnt(0)
	v_pk_add_f32 v[24:25], v[24:25], v[34:35]
	v_pk_add_f32 v[26:27], v[26:27], v[36:37]
	v_cvt_pk_f16_f32 v34, v24, v25
	v_cvt_pk_f16_f32 v35, v26, v27
	global_store_dwordx4 v[38:39], v[24:27], off offset:64
	v_mov_b32_e32 v138, v34
	v_mov_b32_e32 v139, v35
	v_and_b32_e32 v144, 16, v148
	v_lshrrev_b32_e32 v145, 1, v144
	v_add_u32_e32 v144, v144, v145
	v_mov_b32_e32 v145, 0
	v_lshl_add_u64 v[144:145], v[144:145], 0, v[42:43]
	v_permlane16_swap_b32_e32 v136, v138
	v_permlane16_swap_b32_e32 v137, v139
	global_store_dwordx4 v[144:145], v[136:139], off
	global_load_dwordx4 v[34:37], v[40:41], off offset:128
	v_pk_mul_f32 v[24:25], v[24:25], v[24:25]
	v_pk_mul_f32 v[26:27], v[26:27], v[26:27]
	v_add_f32_e32 v24, v24, v25
	v_add_f32_e32 v26, v26, v27
	v_add_f32_e32 v24, v24, v26
	v_add_f32_e32 v24, v28, v24
	s_waitcnt vmcnt(0)
; DI unsigned pack2(float lo, float hi) { f2_t v = {lo, hi}; h2_t b = __builtin_convertvector(v, h2_t); return __builtin_bit_cast(unsigned, b); }
; DI void epi_residual(const f32x4 (&v)[4][4], int row0, int col0, const float* xsrc, float* x, bf16_t* xb, float* ssq_out, bool write_xb, bool write_ssq) {
;     ...
;   for (int mt = 0; mt < 4; ++mt) {
;     const int row = row0 + mt * 16 + lr;
;     float ss = 0.f;
; #pragma unroll
;     for (int nt = 0; nt < 4; ++nt) {
;       const int col = col0 + nt * 16 + 4 * g;
;       float4* px = (float4*)(x + (size_t)row * DM + col);
;       float4 o = *(const float4*)(xsrc + (size_t)row * DM + col);
;       o.x += v[mt][nt][0]; o.y += v[mt][nt][1]; o.z += v[mt][nt][2]; o.w += v[mt][nt][3];
;       *px = o;
;       ss += (o.x * o.x + o.y * o.y) + (o.z * o.z + o.w * o.w);
;       if (write_xb) *(uint2*)(xb + (size_t)row * DM + col) = make_uint2(pack2(o.x, o.y), pack2(o.z, o.w));
;     }
;     if (write_ssq) {
;       ss += __shfl_xor(ss, 16); ss += __shfl_xor(ss, 32);
;       if (g == 0) ssq_out[(size_t)row * 16 + (col0 >> 6)] = ss;
;     }
	v_pk_add_f32 v[20:21], v[20:21], v[34:35]
	v_pk_add_f32 v[22:23], v[22:23], v[36:37]
	v_cvt_pk_f16_f32 v34, v20, v21
	v_cvt_pk_f16_f32 v35, v22, v23
	global_store_dwordx4 v[38:39], v[20:23], off offset:128
	v_mov_b32_e32 v140, v34
	v_mov_b32_e32 v141, v35
	global_load_dwordx4 v[34:37], v[40:41], off offset:192
	v_pk_mul_f32 v[20:21], v[20:21], v[20:21]
	v_pk_mul_f32 v[22:23], v[22:23], v[22:23]
	v_add_f32_e32 v20, v20, v21
	v_add_f32_e32 v22, v22, v23
	v_add_f32_e32 v20, v20, v22
	v_add_f32_e32 v24, v24, v20
	s_waitcnt vmcnt(0)
	v_pk_add_f32 v[20:21], v[16:17], v[34:35]
	v_pk_add_f32 v[22:23], v[18:19], v[36:37]
	v_pk_mul_f32 v[16:17], v[20:21], v[20:21]
	v_pk_mul_f32 v[18:19], v[22:23], v[22:23]
	v_add_f32_e32 v16, v16, v17
	v_add_f32_e32 v18, v18, v19
	v_add_f32_e32 v16, v16, v18
	v_add_f32_e32 v16, v24, v16
	ds_bpermute_b32 v17, v189, v16
	v_cvt_pk_f16_f32 v18, v20, v21
	v_cvt_pk_f16_f32 v19, v22, v23
	global_store_dwordx4 v[38:39], v[20:23], off offset:192
	v_mov_b32_e32 v142, v18
	v_mov_b32_e32 v143, v19
	v_and_b32_e32 v144, 16, v148
	v_lshrrev_b32_e32 v145, 1, v144
	v_add_u32_e32 v144, v144, v145
	v_mov_b32_e32 v145, 0
	v_lshl_add_u64 v[144:145], v[144:145], 0, v[42:43]
	v_permlane16_swap_b32_e32 v140, v142
	v_permlane16_swap_b32_e32 v141, v143
	global_store_dwordx4 v[144:145], v[140:143], off offset:64
	s_waitcnt lgkmcnt(0)
	v_add_f32_e32 v16, v16, v17
	ds_bpermute_b32 v17, v188, v16
	s_and_saveexec_b64 s[6:7], vcc
	s_cbranch_execz .LBB0_1256
	s_waitcnt lgkmcnt(0)
	v_add_f32_e32 v18, v16, v17
	v_lshlrev_b64 v[16:17], 6, v[32:33]
	v_lshl_add_u64 v[16:17], v[48:49], 0, v[16:17]
	global_store_dword v[16:17], v18, off
.LBB0_1256:
	s_or_b64 exec, exec, s[6:7]
	v_or_b32_e32 v16, 48, v50
	s_waitcnt lgkmcnt(0)
	v_ashrrev_i32_e32 v17, 31, v16
	v_lshlrev_b64 v[22:23], 12, v[16:17]
	v_lshl_add_u64 v[18:19], s[4:5], 0, v[22:23]
	v_lshl_add_u64 v[24:25], v[18:19], 0, v[150:151]
	global_load_dwordx4 v[18:21], v[24:25], off
	v_readlane_b32 s12, v254, 55
	v_readlane_b32 s6, v254, 43
	v_lshlrev_b64 v[26:27], 11, v[16:17]
	v_readlane_b32 s13, v254, 56
	v_readlane_b32 s7, v254, 44
	v_readlane_b32 s14, v254, 57
	v_lshl_add_u64 v[22:23], s[12:13], 0, v[22:23]
	v_lshl_add_u64 v[26:27], s[6:7], 0, v[26:27]
	v_lshl_add_u64 v[22:23], v[22:23], 0, v[150:151]
	v_lshl_add_u64 v[26:27], v[26:27], 0, v[52:53]
	v_readlane_b32 s15, v254, 58
	s_waitcnt vmcnt(0)
	v_pk_add_f32 v[12:13], v[12:13], v[18:19]
	v_pk_add_f32 v[14:15], v[14:15], v[20:21]
	v_cvt_pk_f16_f32 v18, v12, v13
	v_cvt_pk_f16_f32 v19, v14, v15
	global_store_dwordx4 v[22:23], v[12:15], off
	v_mov_b32_e32 v136, v18
	v_mov_b32_e32 v137, v19
	global_load_dwordx4 v[18:21], v[24:25], off offset:64
	v_pk_mul_f32 v[12:13], v[12:13], v[12:13]
	v_pk_mul_f32 v[14:15], v[14:15], v[14:15]
	v_add_f32_e32 v12, v12, v13
	v_add_f32_e32 v14, v14, v15
	v_add_f32_e32 v12, v12, v14
	s_waitcnt vmcnt(0)
	v_pk_add_f32 v[8:9], v[8:9], v[18:19]
	v_pk_add_f32 v[10:11], v[10:11], v[20:21]
	v_cvt_pk_f16_f32 v18, v8, v9
	v_cvt_pk_f16_f32 v19, v10, v11
	global_store_dwordx4 v[22:23], v[8:11], off offset:64
	v_mov_b32_e32 v138, v18
	v_mov_b32_e32 v139, v19
	v_and_b32_e32 v144, 16, v148
	v_lshrrev_b32_e32 v145, 1, v144
	v_add_u32_e32 v144, v144, v145
	v_mov_b32_e32 v145, 0
	v_lshl_add_u64 v[144:145], v[144:145], 0, v[26:27]
	v_permlane16_swap_b32_e32 v136, v138
	v_permlane16_swap_b32_e32 v137, v139
	global_store_dwordx4 v[144:145], v[136:139], off
	global_load_dwordx4 v[18:21], v[24:25], off offset:128
	v_pk_mul_f32 v[8:9], v[8:9], v[8:9]
	v_pk_mul_f32 v[10:11], v[10:11], v[10:11]
	v_add_f32_e32 v8, v8, v9
	v_add_f32_e32 v10, v10, v11
	v_add_f32_e32 v8, v8, v10
	v_add_f32_e32 v8, v12, v8
	s_waitcnt vmcnt(0)
	v_pk_add_f32 v[4:5], v[4:5], v[18:19]
	v_pk_add_f32 v[6:7], v[6:7], v[20:21]
	v_cvt_pk_f16_f32 v18, v4, v5
	v_cvt_pk_f16_f32 v19, v6, v7
	global_store_dwordx4 v[22:23], v[4:7], off offset:128
	v_mov_b32_e32 v140, v18
	v_mov_b32_e32 v141, v19
	global_load_dwordx4 v[18:21], v[24:25], off offset:192
	v_pk_mul_f32 v[4:5], v[4:5], v[4:5]
	v_pk_mul_f32 v[6:7], v[6:7], v[6:7]
	v_add_f32_e32 v4, v4, v5
	v_add_f32_e32 v6, v6, v7
	v_add_f32_e32 v4, v4, v6
	v_add_f32_e32 v8, v8, v4
	s_waitcnt vmcnt(0)
	v_pk_add_f32 v[4:5], v[0:1], v[18:19]
	v_pk_add_f32 v[6:7], v[2:3], v[20:21]
	v_pk_mul_f32 v[0:1], v[4:5], v[4:5]
	v_pk_mul_f32 v[2:3], v[6:7], v[6:7]
	v_add_f32_e32 v0, v0, v1
	v_add_f32_e32 v2, v2, v3
	v_add_f32_e32 v0, v0, v2
	v_add_f32_e32 v0, v8, v0
	ds_bpermute_b32 v1, v189, v0
	v_cvt_pk_f16_f32 v2, v4, v5
	v_cvt_pk_f16_f32 v3, v6, v7
	global_store_dwordx4 v[22:23], v[4:7], off offset:192
	v_mov_b32_e32 v142, v2
	v_mov_b32_e32 v143, v3
	v_and_b32_e32 v144, 16, v148
	v_lshrrev_b32_e32 v145, 1, v144
	v_add_u32_e32 v144, v144, v145
	v_mov_b32_e32 v145, 0
	v_lshl_add_u64 v[144:145], v[144:145], 0, v[26:27]
	v_permlane16_swap_b32_e32 v140, v142
	v_permlane16_swap_b32_e32 v141, v143
	global_store_dwordx4 v[144:145], v[140:143], off offset:64
	s_waitcnt lgkmcnt(0)
	v_add_f32_e32 v0, v0, v1
	ds_bpermute_b32 v1, v188, v0
	s_and_saveexec_b64 s[6:7], vcc
	s_cbranch_execz .LBB0_1247
	s_waitcnt lgkmcnt(0)
	v_add_f32_e32 v2, v0, v1
	v_lshlrev_b64 v[0:1], 6, v[16:17]
	v_lshl_add_u64 v[0:1], v[48:49], 0, v[0:1]
	global_store_dword v[0:1], v2, off
	s_branch .LBB0_1247

; DI int BIDX() { int b = blockIdx.x; asm volatile("" : "+s"(b)); return b; }
; #define GL_LOAD(s_, kt_) if (VAR != 1) { a##s_##0 = GL_A(0, kt_); a##s_##1 = GL_A(1, kt_); a##s_##2 = GL_A(2, kt_); a##s_##3 = GL_A(3, kt_); b##s_##0 = GL_B(0, kt_); b##s_##1 = GL_B(1, kt_); b##s_##2 = GL_B(2, kt_); b##s_##3 = GL_B(3, kt_); }
; #define LDS_STORE(s_, buf_) if (VAR != 2) { LDS_ST1(sA, 0, buf_, a##s_##0) LDS_ST1(sA, 1, buf_, a##s_##1) LDS_ST1(sA, 2, buf_, a##s_##2) LDS_ST1(sA, 3, buf_, a##s_##3) LDS_ST1(sB, 0, buf_, b##s_##0) LDS_ST1(sB, 1, buf_, b##s_##1) LDS_ST1(sB, 2, buf_, b##s_##2) LDS_ST1(sB, 3, buf_, b##s_##3) }
; DI int tile_groups(int MT, int NT) { return (MT >> 6) * ((NT + 7) >> 3) * 512; }
;     ...
;   GL_LOAD(0, 0)
;   GL_LOAD(1, 1)
;   LDS_STORE(0, 0)
;   if (VAR != 4) __syncthreads();
; #pragma unroll
;   for (int kt = 0; kt < nk; kt += 2) {
;     if (kt + 2 < nk) { GL_LOAD(0, kt + 2) }
;     MMA_TILE(0)
;     LDS_STORE(1, 1)
;     if (VAR != 4) __syncthreads();
;     if (kt + 3 < nk) { GL_LOAD(1, kt + 3) }
; DI void phase_resgemm(const Params& P, const bf16_t* A, int K, const bf16_t* Wt, float* ssq_out, const float* xsrc, char* smem) {
;     ...
;   for (int vb = BIDX(); vb < tile_groups(128, 8); vb += gridDim.x) {
;     int tm, tn; if (!tile_of(vb, 128, 8, tm, tn)) continue;
;     const int m0 = tm * 128, n0 = tn * 128;
;     f32x4 acc[4][4]; zero_acc(acc);
;     if (K == 1024) gemm_kloop<false, true, 16>(acc, A + (size_t)m0 * K, K, Wt + (size_t)n0 * K, K, smem);
;     else gemm_kloop<false, true, 64>(acc, A + (size_t)m0 * K, K, Wt + (size_t)n0 * K, K, smem);
.LBB0_1371:
	s_ashr_i32 s1, s2, 3
	s_andn2_b32 s1, s1, 63
	s_and_b32 s4, s9, 56
	s_or_b32 s1, s1, s4
	s_bfe_u32 s4, s2, 0x30003
	s_or_b32 s1, s1, s4
	s_cmpk_gt_i32 s1, 0x7f
	s_cbranch_scc1 .LBB0_1370
	s_lshl_b32 s4, s1, 7
	s_ashr_i32 s5, s4, 31
	v_mov_b32_e32 v58, v148
	s_and_b32 s10, s8, 0x380
	s_lshl_b64 s[12:13], s[4:5], 13
	s_add_u32 s12, s34, s12
	v_ashrrev_i32_e32 v16, 3, v58
	v_ashrrev_i32_e32 v17, 31, v16
	v_add_u32_e32 v18, 32, v16
	s_addc_u32 s13, s35, s13
	v_lshlrev_b64 v[6:7], 13, v[16:17]
	v_lshlrev_b32_e32 v17, 4, v58
	v_ashrrev_i32_e32 v19, 31, v18
	v_add_u32_e32 v20, 64, v16
	s_waitcnt lgkmcnt(0)
	v_lshl_add_u64 v[0:1], s[12:13], 0, v[6:7]
	v_and_b32_e32 v150, 0x70, v17
	v_lshlrev_b64 v[8:9], 13, v[18:19]
	v_ashrrev_i32_e32 v21, 31, v20
	v_add_u32_e32 v54, 0x60, v16
	s_lshl_b32 s1, s10, 13
	v_lshl_add_u64 v[0:1], v[0:1], 0, v[150:151]
	v_lshl_add_u64 v[2:3], s[12:13], 0, v[8:9]
	v_lshlrev_b64 v[46:47], 13, v[20:21]
	v_ashrrev_i32_e32 v55, 31, v54
	s_add_u32 s14, s6, s1
	global_load_dwordx4 v[22:25], v[0:1], off
	v_lshl_add_u64 v[2:3], v[2:3], 0, v[150:151]
	v_lshl_add_u64 v[4:5], s[12:13], 0, v[46:47]
	v_lshlrev_b64 v[50:51], 13, v[54:55]
	s_addc_u32 s15, s7, 0
	global_load_dwordx4 v[26:29], v[2:3], off
	v_lshl_add_u64 v[4:5], v[4:5], 0, v[150:151]
	v_lshl_add_u64 v[10:11], s[12:13], 0, v[50:51]
	global_load_dwordx4 v[30:33], v[4:5], off
	v_lshl_add_u64 v[14:15], v[10:11], 0, v[150:151]
	v_lshl_add_u64 v[6:7], s[14:15], 0, v[6:7]
	global_load_dwordx4 v[34:37], v[14:15], off
	v_lshl_add_u64 v[10:11], v[6:7], 0, v[150:151]
	v_lshl_add_u64 v[6:7], s[14:15], 0, v[8:9]
	global_load_dwordx4 v[38:41], v[10:11], off
	v_lshl_add_u64 v[12:13], v[6:7], 0, v[150:151]
	v_lshl_add_u64 v[6:7], s[14:15], 0, v[46:47]
	global_load_dwordx4 v[42:45], v[12:13], off
	v_lshl_add_u64 v[8:9], v[6:7], 0, v[150:151]
	v_lshl_add_u64 v[6:7], s[14:15], 0, v[50:51]
	global_load_dwordx4 v[46:49], v[8:9], off
	v_lshl_add_u64 v[6:7], v[6:7], 0, v[150:151]
	global_load_dwordx4 v[50:53], v[6:7], off
	v_and_b32_e32 v19, 15, v58
	v_lshlrev_b32_e32 v21, 3, v58
	v_and_b32_e32 v55, 48, v58
	v_lshrrev_b32_e32 v59, 1, v58
	s_waitcnt vmcnt(10)
	v_lshlrev_b32_e32 v60, 7, v58
	v_and_b32_e32 v90, 0x70, v21
	v_bitop3_b32 v134, v21, v55, s23 bitop3:0x6c
	v_bitop3_b32 v21, v17, s23, v58 bitop3:0x48
	v_and_or_b32 v91, v59, s24, v19
	v_and_b32_e32 v130, 0x2780, v60
	global_load_dwordx4 v[58:61], v[0:1], off offset:128
	global_load_dwordx4 v[62:65], v[2:3], off offset:128
	global_load_dwordx4 v[66:69], v[4:5], off offset:128
	global_load_dwordx4 v[70:73], v[14:15], off offset:128
	global_load_dwordx4 v[74:77], v[10:11], off offset:128
	global_load_dwordx4 v[78:81], v[12:13], off offset:128
	global_load_dwordx4 v[82:85], v[8:9], off offset:128
	global_load_dwordx4 v[86:89], v[6:7], off offset:128
	v_lshl_or_b32 v17, v16, 7, v21
	v_or_b32_e32 v16, v130, v134
	v_lshl_or_b32 v18, v18, 7, v21
	v_lshl_or_b32 v19, v20, 7, v21
	v_lshl_or_b32 v20, v54, 7, v21
	v_lshlrev_b32_e32 v54, 7, v91
	v_bitop3_b32 v21, v54, v90, v55 bitop3:0xf6
	s_movk_i32 s1, 0x1000
	v_readlane_b32 s12, v254, 55
	v_readlane_b32 s13, v254, 56
	v_readlane_b32 s14, v254, 57
	v_readlane_b32 s15, v254, 58
	s_waitcnt vmcnt(15)
	ds_write_b128 v17, v[22:25]
	s_waitcnt vmcnt(14)
	ds_write_b128 v18, v[26:29]
	s_waitcnt vmcnt(13)
	ds_write_b128 v19, v[30:33]
	s_waitcnt vmcnt(12)
	ds_write_b128 v20, v[34:37]
	s_waitcnt vmcnt(11)
	ds_write_b128 v17, v[38:41] offset:32768
	s_waitcnt vmcnt(10)
	ds_write_b128 v18, v[42:45] offset:32768
	s_waitcnt vmcnt(9)
	ds_write_b128 v19, v[46:49] offset:32768
	s_waitcnt vmcnt(8)
	ds_write_b128 v20, v[50:53] offset:32768
	s_waitcnt lgkmcnt(0)
	s_barrier
	s_setprio 1
	ds_read_b128 v[22:25], v16 offset:32768
	ds_read_b128 v[30:33], v21
	s_waitcnt lgkmcnt(0)
	v_mfma_f32_16x16x32_f16 v[38:41], v[22:25], v[30:33], 0
	ds_read_b128 v[26:29], v16 offset:34816
	ds_read_b128 v[34:37], v21 offset:2048
	s_waitcnt lgkmcnt(0)
	v_mfma_f32_16x16x32_f16 v[94:97], v[22:25], v[34:37], 0
	ds_read_b128 v[42:45], v16 offset:36864
	ds_read_b128 v[106:109], v21 offset:4096
	s_waitcnt lgkmcnt(0)
	v_mfma_f32_16x16x32_f16 v[114:117], v[22:25], v[106:109], 0
	ds_read_b128 v[50:53], v16 offset:38912
	ds_read_b128 v[110:113], v21 offset:6144
	s_waitcnt lgkmcnt(0)
	v_mfma_f32_16x16x32_f16 v[126:129], v[22:25], v[110:113], 0
	v_xor_b32_e32 v22, 64, v134
	v_mfma_f32_16x16x32_f16 v[46:49], v[26:29], v[30:33], 0
	v_or_b32_e32 v22, v130, v22
	v_mfma_f32_16x16x32_f16 v[90:93], v[42:45], v[30:33], 0
	ds_read_b128 v[130:133], v22 offset:32768
	v_mfma_f32_16x16x32_f16 v[30:33], v[50:53], v[30:33], 0
	ds_read_b128 v[142:145], v22 offset:36864
	v_mfma_f32_16x16x32_f16 v[98:101], v[26:29], v[34:37], 0
	ds_read_b128 v[154:157], v22 offset:38912
	v_mfma_f32_16x16x32_f16 v[102:105], v[42:45], v[34:37], 0
	v_bitop3_b32 v23, v54, v134, 64 bitop3:0xf6
	v_mfma_f32_16x16x32_f16 v[34:37], v[50:53], v[34:37], 0
	ds_read_b128 v[134:137], v23
	v_mfma_f32_16x16x32_f16 v[118:121], v[26:29], v[106:109], 0
	ds_read_b128 v[138:141], v23 offset:2048
	v_mfma_f32_16x16x32_f16 v[122:125], v[42:45], v[106:109], 0
	s_waitcnt vmcnt(7)
	ds_write_b128 v17, v[58:61] offset:16384
	v_mfma_f32_16x16x32_f16 v[106:109], v[50:53], v[106:109], 0
	s_waitcnt vmcnt(6)
	ds_write_b128 v18, v[62:65] offset:16384
	v_mfma_f32_16x16x32_f16 v[24:27], v[26:29], v[110:113], 0
	s_waitcnt vmcnt(5)
	ds_write_b128 v19, v[66:69] offset:16384
	v_mfma_f32_16x16x32_f16 v[42:45], v[42:45], v[110:113], 0
	s_waitcnt vmcnt(4)
	ds_write_b128 v20, v[70:73] offset:16384
	v_mfma_f32_16x16x32_f16 v[50:53], v[50:53], v[110:113], 0
	ds_read_b128 v[110:113], v22 offset:34816
	s_waitcnt lgkmcnt(6)
; #define GL_LOAD(s_, kt_) if (VAR != 1) { a##s_##0 = GL_A(0, kt_); a##s_##1 = GL_A(1, kt_); a##s_##2 = GL_A(2, kt_); a##s_##3 = GL_A(3, kt_); b##s_##0 = GL_B(0, kt_); b##s_##1 = GL_B(1, kt_); b##s_##2 = GL_B(2, kt_); b##s_##3 = GL_B(3, kt_); }
; #define LDS_STORE(s_, buf_) if (VAR != 2) { LDS_ST1(sA, 0, buf_, a##s_##0) LDS_ST1(sA, 1, buf_, a##s_##1) LDS_ST1(sA, 2, buf_, a##s_##2) LDS_ST1(sA, 3, buf_, a##s_##3) LDS_ST1(sB, 0, buf_, b##s_##0) LDS_ST1(sB, 1, buf_, b##s_##1) LDS_ST1(sB, 2, buf_, b##s_##2) LDS_ST1(sB, 3, buf_, b##s_##3) }
;     ...
;   GL_LOAD(0, 0)
;   GL_LOAD(1, 1)
;   LDS_STORE(0, 0)
;   if (VAR != 4) __syncthreads();
; #pragma unroll
;   for (int kt = 0; kt < nk; kt += 2) {
;     if (kt + 2 < nk) { GL_LOAD(0, kt + 2) }
;     MMA_TILE(0)
;     LDS_STORE(1, 1)
;     if (VAR != 4) __syncthreads();
;     if (kt + 3 < nk) { GL_LOAD(1, kt + 3) }
;     MMA_TILE(1)
;     if (kt + 2 < nk) { LDS_STORE(0, 0) }
;     if (VAR != 4) __syncthreads();
	v_mfma_f32_16x16x32_f16 v[38:41], v[130:133], v[134:137], v[38:41]
	s_waitcnt vmcnt(3)
	ds_write_b128 v17, v[74:77] offset:49152
	v_mfma_f32_16x16x32_f16 v[90:93], v[142:145], v[134:137], v[90:93]
	s_waitcnt vmcnt(2)
	ds_write_b128 v18, v[78:81] offset:49152
	v_mfma_f32_16x16x32_f16 v[28:31], v[154:157], v[134:137], v[30:33]
	s_waitcnt vmcnt(1)
	ds_write_b128 v19, v[82:85] offset:49152
	s_waitcnt lgkmcnt(8)
	v_mfma_f32_16x16x32_f16 v[94:97], v[130:133], v[138:141], v[94:97]
	s_waitcnt vmcnt(0)
	ds_write_b128 v20, v[86:89] offset:49152
	v_mfma_f32_16x16x32_f16 v[102:105], v[142:145], v[138:141], v[102:105]
	v_mfma_f32_16x16x32_f16 v[32:35], v[154:157], v[138:141], v[34:37]
	s_waitcnt lgkmcnt(4)
	v_mfma_f32_16x16x32_f16 v[46:49], v[110:113], v[134:137], v[46:49]
	ds_read_b128 v[134:137], v23 offset:4096
	v_mfma_f32_16x16x32_f16 v[98:101], v[110:113], v[138:141], v[98:101]
	ds_read_b128 v[138:141], v23 offset:6144
	s_waitcnt lgkmcnt(1)
	v_mfma_f32_16x16x32_f16 v[114:117], v[130:133], v[134:137], v[114:117]
	s_waitcnt lgkmcnt(0)
	v_mfma_f32_16x16x32_f16 v[126:129], v[130:133], v[138:141], v[126:129]
	global_load_dwordx4 v[130:133], v[0:1], off offset:256
	v_mfma_f32_16x16x32_f16 v[118:121], v[110:113], v[134:137], v[118:121]
	v_mfma_f32_16x16x32_f16 v[24:27], v[110:113], v[138:141], v[24:27]
	v_mfma_f32_16x16x32_f16 v[122:125], v[142:145], v[134:137], v[122:125]
	v_mfma_f32_16x16x32_f16 v[106:109], v[154:157], v[134:137], v[106:109]
	global_load_dwordx4 v[134:137], v[2:3], off offset:256
	global_load_dwordx4 v[158:161], v[4:5], off offset:256
	global_load_dwordx4 v[162:165], v[14:15], off offset:256
	global_load_dwordx4 v[110:113], v[10:11], off offset:256
	global_load_dwordx4 v[166:169], v[12:13], off offset:256
	global_load_dwordx4 v[190:193], v[8:9], off offset:256
	global_load_dwordx4 v[194:197], v[6:7], off offset:256
	s_waitcnt lgkmcnt(0)
	s_barrier
	v_mfma_f32_16x16x32_f16 v[42:45], v[142:145], v[138:141], v[42:45]
	ds_read_b128 v[58:61], v16 offset:49152
	v_mfma_f32_16x16x32_f16 v[50:53], v[154:157], v[138:141], v[50:53]
	ds_read_b128 v[62:65], v16 offset:51200
	ds_read_b128 v[66:69], v21 offset:16384
	s_waitcnt lgkmcnt(0)
	v_mfma_f32_16x16x32_f16 v[36:39], v[58:61], v[66:69], v[38:41]
	ds_read_b128 v[70:73], v21 offset:18432
	v_mfma_f32_16x16x32_f16 v[46:49], v[62:65], v[66:69], v[46:49]
	ds_read_b128 v[74:77], v16 offset:53248
	s_waitcnt lgkmcnt(0)
	v_mfma_f32_16x16x32_f16 v[82:85], v[74:77], v[66:69], v[90:93]
	ds_read_b128 v[78:81], v16 offset:55296
	s_waitcnt lgkmcnt(0)
	v_mfma_f32_16x16x32_f16 v[28:31], v[78:81], v[66:69], v[28:31]
	v_mfma_f32_16x16x32_f16 v[66:69], v[58:61], v[70:73], v[94:97]
	s_nop 2
	ds_read_b128 v[94:97], v21 offset:22528
	s_waitcnt vmcnt(7)
	ds_write_b128 v17, v[130:133]
	v_mfma_f32_16x16x32_f16 v[86:89], v[62:65], v[70:73], v[98:101]
	s_waitcnt vmcnt(6)
	ds_write_b128 v18, v[134:137]
	s_waitcnt vmcnt(5)
	ds_write_b128 v19, v[158:161]
	v_mfma_f32_16x16x32_f16 v[90:93], v[74:77], v[70:73], v[102:105]
	s_waitcnt vmcnt(4)
	ds_write_b128 v20, v[162:165]
	s_waitcnt vmcnt(3)
	ds_write_b128 v17, v[110:113] offset:32768
	v_mfma_f32_16x16x32_f16 v[32:35], v[78:81], v[70:73], v[32:35]
	ds_read_b128 v[70:73], v21 offset:20480
	s_waitcnt lgkmcnt(0)
	v_mfma_f32_16x16x32_f16 v[98:101], v[58:61], v[70:73], v[114:117]
	s_waitcnt vmcnt(2)
	ds_write_b128 v18, v[166:169] offset:32768
	v_mfma_f32_16x16x32_f16 v[58:61], v[58:61], v[94:97], v[126:129]
	s_waitcnt vmcnt(1)
	ds_write_b128 v19, v[190:193] offset:32768
	v_mfma_f32_16x16x32_f16 v[102:105], v[62:65], v[70:73], v[118:121]
	s_nop 2
	ds_read_b128 v[118:121], v22 offset:55296
	v_mfma_f32_16x16x32_f16 v[24:27], v[62:65], v[94:97], v[24:27]
	ds_read_b128 v[62:65], v22 offset:49152
	v_mfma_f32_16x16x32_f16 v[114:117], v[74:77], v[70:73], v[122:125]
	s_waitcnt vmcnt(0)
	ds_write_b128 v20, v[194:197] offset:32768
	v_mfma_f32_16x16x32_f16 v[40:43], v[74:77], v[94:97], v[42:45]
	ds_read_b128 v[74:77], v22 offset:51200
	v_mfma_f32_16x16x32_f16 v[70:73], v[78:81], v[70:73], v[106:109]
	s_nop 2
	ds_read_b128 v[106:109], v22 offset:53248
	v_mfma_f32_16x16x32_f16 v[50:53], v[78:81], v[94:97], v[50:53]
	ds_read_b128 v[78:81], v23 offset:16384
	s_waitcnt lgkmcnt(0)
	v_mfma_f32_16x16x32_f16 v[36:39], v[62:65], v[78:81], v[36:39]
	ds_read_b128 v[94:97], v23 offset:18432
	s_waitcnt lgkmcnt(0)
	v_mfma_f32_16x16x32_f16 v[66:69], v[62:65], v[94:97], v[66:69]
	v_mfma_f32_16x16x32_f16 v[44:47], v[74:77], v[78:81], v[46:49]
	v_mfma_f32_16x16x32_f16 v[82:85], v[106:109], v[78:81], v[82:85]
	v_mfma_f32_16x16x32_f16 v[28:31], v[118:121], v[78:81], v[28:31]
	v_mfma_f32_16x16x32_f16 v[78:81], v[74:77], v[94:97], v[86:89]
	v_mfma_f32_16x16x32_f16 v[86:89], v[106:109], v[94:97], v[90:93]
	s_nop 2
	ds_read_b128 v[90:93], v23 offset:20480
	v_mfma_f32_16x16x32_f16 v[32:35], v[118:121], v[94:97], v[32:35]
	ds_read_b128 v[94:97], v23 offset:22528
	s_waitcnt lgkmcnt(1)
	v_mfma_f32_16x16x32_f16 v[98:101], v[62:65], v[90:93], v[98:101]
	s_waitcnt lgkmcnt(0)
	v_mfma_f32_16x16x32_f16 v[58:61], v[62:65], v[94:97], v[58:61]
	global_load_dwordx4 v[62:65], v[0:1], off offset:384
	v_mfma_f32_16x16x32_f16 v[102:105], v[74:77], v[90:93], v[102:105]
	v_mfma_f32_16x16x32_f16 v[24:27], v[74:77], v[94:97], v[24:27]
	v_mfma_f32_16x16x32_f16 v[114:117], v[106:109], v[90:93], v[114:117]
	v_mfma_f32_16x16x32_f16 v[40:43], v[106:109], v[94:97], v[40:43]
	v_mfma_f32_16x16x32_f16 v[70:73], v[118:121], v[90:93], v[70:73]
	global_load_dwordx4 v[90:93], v[2:3], off offset:384
	global_load_dwordx4 v[122:125], v[4:5], off offset:384
	global_load_dwordx4 v[126:129], v[14:15], off offset:384
	global_load_dwordx4 v[74:77], v[10:11], off offset:384
	global_load_dwordx4 v[138:141], v[12:13], off offset:384
	global_load_dwordx4 v[142:145], v[8:9], off offset:384
	global_load_dwordx4 v[154:157], v[6:7], off offset:384
	s_waitcnt lgkmcnt(0)
	s_barrier
; #define GL_LOAD(s_, kt_) if (VAR != 1) { a##s_##0 = GL_A(0, kt_); a##s_##1 = GL_A(1, kt_); a##s_##2 = GL_A(2, kt_); a##s_##3 = GL_A(3, kt_); b##s_##0 = GL_B(0, kt_); b##s_##1 = GL_B(1, kt_); b##s_##2 = GL_B(2, kt_); b##s_##3 = GL_B(3, kt_); }
; #define LDS_STORE(s_, buf_) if (VAR != 2) { LDS_ST1(sA, 0, buf_, a##s_##0) LDS_ST1(sA, 1, buf_, a##s_##1) LDS_ST1(sA, 2, buf_, a##s_##2) LDS_ST1(sA, 3, buf_, a##s_##3) LDS_ST1(sB, 0, buf_, b##s_##0) LDS_ST1(sB, 1, buf_, b##s_##1) LDS_ST1(sB, 2, buf_, b##s_##2) LDS_ST1(sB, 3, buf_, b##s_##3) }
;     ...
;   GL_LOAD(0, 0)
;   GL_LOAD(1, 1)
;   LDS_STORE(0, 0)
;   if (VAR != 4) __syncthreads();
; #pragma unroll
;   for (int kt = 0; kt < nk; kt += 2) {
;     if (kt + 2 < nk) { GL_LOAD(0, kt + 2) }
;     MMA_TILE(0)
;     LDS_STORE(1, 1)
;     if (VAR != 4) __syncthreads();
;     if (kt + 3 < nk) { GL_LOAD(1, kt + 3) }
;     MMA_TILE(1)
;     if (kt + 2 < nk) { LDS_STORE(0, 0) }
;     if (VAR != 4) __syncthreads();
	v_mfma_f32_16x16x32_f16 v[48:51], v[118:121], v[94:97], v[50:53]
	ds_read_b128 v[106:109], v16 offset:32768
	ds_read_b128 v[94:97], v21
	s_waitcnt lgkmcnt(0)
	v_mfma_f32_16x16x32_f16 v[36:39], v[106:109], v[94:97], v[36:39]
	ds_read_b128 v[52:55], v16 offset:34816
	ds_read_b128 v[110:113], v21 offset:2048
	s_waitcnt lgkmcnt(0)
	v_mfma_f32_16x16x32_f16 v[66:69], v[106:109], v[110:113], v[66:69]
	ds_read_b128 v[118:121], v16 offset:36864
	v_mfma_f32_16x16x32_f16 v[44:47], v[52:55], v[94:97], v[44:47]
	ds_read_b128 v[130:133], v16 offset:38912
	v_mfma_f32_16x16x32_f16 v[78:81], v[52:55], v[110:113], v[78:81]
	s_waitcnt vmcnt(7)
	ds_write_b128 v17, v[62:65] offset:16384
	s_waitcnt lgkmcnt(2)
	v_mfma_f32_16x16x32_f16 v[82:85], v[118:121], v[94:97], v[82:85]
	s_waitcnt vmcnt(6)
	ds_write_b128 v18, v[90:93] offset:16384
	v_mfma_f32_16x16x32_f16 v[86:89], v[118:121], v[110:113], v[86:89]
	s_waitcnt vmcnt(5)
	ds_write_b128 v19, v[122:125] offset:16384
	s_waitcnt lgkmcnt(3)
	v_mfma_f32_16x16x32_f16 v[28:31], v[130:133], v[94:97], v[28:31]
	ds_read_b128 v[94:97], v21 offset:4096
	v_mfma_f32_16x16x32_f16 v[32:35], v[130:133], v[110:113], v[32:35]
	ds_read_b128 v[110:113], v21 offset:6144
	s_waitcnt lgkmcnt(1)
	v_mfma_f32_16x16x32_f16 v[98:101], v[106:109], v[94:97], v[98:101]
	s_waitcnt vmcnt(4)
	ds_write_b128 v20, v[126:129] offset:16384
	s_waitcnt lgkmcnt(1)
	v_mfma_f32_16x16x32_f16 v[58:61], v[106:109], v[110:113], v[58:61]
	ds_read_b128 v[106:109], v23
	v_mfma_f32_16x16x32_f16 v[102:105], v[52:55], v[94:97], v[102:105]
	s_waitcnt vmcnt(3)
	ds_write_b128 v17, v[74:77] offset:49152
	v_mfma_f32_16x16x32_f16 v[24:27], v[52:55], v[110:113], v[24:27]
	ds_read_b128 v[52:55], v22 offset:32768
	v_mfma_f32_16x16x32_f16 v[114:117], v[118:121], v[94:97], v[114:117]
	s_waitcnt vmcnt(2)
	ds_write_b128 v18, v[138:141] offset:49152
	v_mfma_f32_16x16x32_f16 v[40:43], v[118:121], v[110:113], v[40:43]
	ds_read_b128 v[118:121], v22 offset:36864
	v_mfma_f32_16x16x32_f16 v[70:73], v[130:133], v[94:97], v[70:73]
	ds_read_b128 v[94:97], v22 offset:34816
	v_mfma_f32_16x16x32_f16 v[48:51], v[130:133], v[110:113], v[48:51]
	ds_read_b128 v[110:113], v23 offset:2048
	s_waitcnt lgkmcnt(4)
	v_mfma_f32_16x16x32_f16 v[36:39], v[52:55], v[106:109], v[36:39]
	ds_read_b128 v[130:133], v22 offset:38912
	s_waitcnt lgkmcnt(1)
	v_mfma_f32_16x16x32_f16 v[66:69], v[52:55], v[110:113], v[66:69]
	s_waitcnt vmcnt(1)
	ds_write_b128 v19, v[142:145] offset:49152
	v_mfma_f32_16x16x32_f16 v[44:47], v[94:97], v[106:109], v[44:47]
	s_waitcnt vmcnt(0)
	ds_write_b128 v20, v[154:157] offset:49152
	v_mfma_f32_16x16x32_f16 v[78:81], v[94:97], v[110:113], v[78:81]
	v_mfma_f32_16x16x32_f16 v[82:85], v[118:121], v[106:109], v[82:85]
	v_mfma_f32_16x16x32_f16 v[86:89], v[118:121], v[110:113], v[86:89]
	s_waitcnt lgkmcnt(2)
	v_mfma_f32_16x16x32_f16 v[28:31], v[130:133], v[106:109], v[28:31]
	ds_read_b128 v[106:109], v23 offset:4096
	v_mfma_f32_16x16x32_f16 v[32:35], v[130:133], v[110:113], v[32:35]
	ds_read_b128 v[110:113], v23 offset:6144
	s_waitcnt lgkmcnt(1)
	v_mfma_f32_16x16x32_f16 v[98:101], v[52:55], v[106:109], v[98:101]
	s_waitcnt lgkmcnt(0)
	v_mfma_f32_16x16x32_f16 v[52:55], v[52:55], v[110:113], v[58:61]
	s_nop 2
	global_load_dwordx4 v[58:61], v[0:1], off offset:512
	v_mfma_f32_16x16x32_f16 v[102:105], v[94:97], v[106:109], v[102:105]
	v_mfma_f32_16x16x32_f16 v[24:27], v[94:97], v[110:113], v[24:27]
	v_mfma_f32_16x16x32_f16 v[114:117], v[118:121], v[106:109], v[114:117]
	v_mfma_f32_16x16x32_f16 v[40:43], v[118:121], v[110:113], v[40:43]
	v_mfma_f32_16x16x32_f16 v[70:73], v[130:133], v[106:109], v[70:73]
	global_load_dwordx4 v[106:109], v[2:3], off offset:512
	global_load_dwordx4 v[134:137], v[4:5], off offset:512
	global_load_dwordx4 v[158:161], v[14:15], off offset:512
	global_load_dwordx4 v[94:97], v[10:11], off offset:512
	global_load_dwordx4 v[162:165], v[12:13], off offset:512
	global_load_dwordx4 v[166:169], v[8:9], off offset:512
	global_load_dwordx4 v[190:193], v[6:7], off offset:512
	s_waitcnt lgkmcnt(0)
	s_barrier
	v_mfma_f32_16x16x32_f16 v[48:51], v[130:133], v[110:113], v[48:51]
	ds_read_b128 v[62:65], v16 offset:49152
	ds_read_b128 v[90:93], v21 offset:16384
	s_waitcnt lgkmcnt(0)
	v_mfma_f32_16x16x32_f16 v[36:39], v[62:65], v[90:93], v[36:39]
	ds_read_b128 v[74:77], v16 offset:51200
	ds_read_b128 v[110:113], v21 offset:18432
	s_waitcnt lgkmcnt(0)
	v_mfma_f32_16x16x32_f16 v[66:69], v[62:65], v[110:113], v[66:69]
	ds_read_b128 v[118:121], v16 offset:53248
	v_mfma_f32_16x16x32_f16 v[44:47], v[74:77], v[90:93], v[44:47]
	ds_read_b128 v[122:125], v16 offset:55296
	v_mfma_f32_16x16x32_f16 v[78:81], v[74:77], v[110:113], v[78:81]
	s_waitcnt vmcnt(7)
	ds_write_b128 v17, v[58:61]
	s_waitcnt lgkmcnt(2)
	v_mfma_f32_16x16x32_f16 v[82:85], v[118:121], v[90:93], v[82:85]
	s_waitcnt vmcnt(6)
	ds_write_b128 v18, v[106:109]
	v_mfma_f32_16x16x32_f16 v[86:89], v[118:121], v[110:113], v[86:89]
	s_waitcnt vmcnt(5)
	ds_write_b128 v19, v[134:137]
	s_waitcnt lgkmcnt(3)
	v_mfma_f32_16x16x32_f16 v[28:31], v[122:125], v[90:93], v[28:31]
	ds_read_b128 v[90:93], v21 offset:20480
	v_mfma_f32_16x16x32_f16 v[32:35], v[122:125], v[110:113], v[32:35]
	ds_read_b128 v[110:113], v21 offset:22528
	s_waitcnt lgkmcnt(1)
	v_mfma_f32_16x16x32_f16 v[98:101], v[62:65], v[90:93], v[98:101]
	s_waitcnt vmcnt(4)
	ds_write_b128 v20, v[158:161]
	s_waitcnt lgkmcnt(1)
	v_mfma_f32_16x16x32_f16 v[52:55], v[62:65], v[110:113], v[52:55]
	ds_read_b128 v[62:65], v22 offset:49152
	v_mfma_f32_16x16x32_f16 v[102:105], v[74:77], v[90:93], v[102:105]
	s_waitcnt vmcnt(3)
; #define GL_LOAD(s_, kt_) if (VAR != 1) { a##s_##0 = GL_A(0, kt_); a##s_##1 = GL_A(1, kt_); a##s_##2 = GL_A(2, kt_); a##s_##3 = GL_A(3, kt_); b##s_##0 = GL_B(0, kt_); b##s_##1 = GL_B(1, kt_); b##s_##2 = GL_B(2, kt_); b##s_##3 = GL_B(3, kt_); }
; #define LDS_STORE(s_, buf_) if (VAR != 2) { LDS_ST1(sA, 0, buf_, a##s_##0) LDS_ST1(sA, 1, buf_, a##s_##1) LDS_ST1(sA, 2, buf_, a##s_##2) LDS_ST1(sA, 3, buf_, a##s_##3) LDS_ST1(sB, 0, buf_, b##s_##0) LDS_ST1(sB, 1, buf_, b##s_##1) LDS_ST1(sB, 2, buf_, b##s_##2) LDS_ST1(sB, 3, buf_, b##s_##3) }
;     ...
;   GL_LOAD(0, 0)
;   GL_LOAD(1, 1)
;   LDS_STORE(0, 0)
;   if (VAR != 4) __syncthreads();
; #pragma unroll
;   for (int kt = 0; kt < nk; kt += 2) {
;     if (kt + 2 < nk) { GL_LOAD(0, kt + 2) }
;     MMA_TILE(0)
;     LDS_STORE(1, 1)
;     if (VAR != 4) __syncthreads();
;     if (kt + 3 < nk) { GL_LOAD(1, kt + 3) }
;     MMA_TILE(1)
;     if (kt + 2 < nk) { LDS_STORE(0, 0) }
;     if (VAR != 4) __syncthreads();
	ds_write_b128 v17, v[94:97] offset:32768
	v_mfma_f32_16x16x32_f16 v[24:27], v[74:77], v[110:113], v[24:27]
	ds_read_b128 v[74:77], v22 offset:51200
	v_mfma_f32_16x16x32_f16 v[114:117], v[118:121], v[90:93], v[114:117]
	s_waitcnt vmcnt(2)
	ds_write_b128 v18, v[162:165] offset:32768
	v_mfma_f32_16x16x32_f16 v[40:43], v[118:121], v[110:113], v[40:43]
	ds_read_b128 v[118:121], v22 offset:53248
	v_mfma_f32_16x16x32_f16 v[70:73], v[122:125], v[90:93], v[70:73]
	ds_read_b128 v[90:93], v23 offset:16384
	v_mfma_f32_16x16x32_f16 v[48:51], v[122:125], v[110:113], v[48:51]
	ds_read_b128 v[110:113], v23 offset:18432
	s_waitcnt lgkmcnt(1)
	v_mfma_f32_16x16x32_f16 v[36:39], v[62:65], v[90:93], v[36:39]
	ds_read_b128 v[122:125], v22 offset:55296
	s_waitcnt lgkmcnt(1)
	v_mfma_f32_16x16x32_f16 v[66:69], v[62:65], v[110:113], v[66:69]
	s_waitcnt vmcnt(1)
	ds_write_b128 v19, v[166:169] offset:32768
	v_mfma_f32_16x16x32_f16 v[44:47], v[74:77], v[90:93], v[44:47]
	s_waitcnt vmcnt(0)
	ds_write_b128 v20, v[190:193] offset:32768
	v_mfma_f32_16x16x32_f16 v[78:81], v[74:77], v[110:113], v[78:81]
	v_mfma_f32_16x16x32_f16 v[82:85], v[118:121], v[90:93], v[82:85]
	v_mfma_f32_16x16x32_f16 v[86:89], v[118:121], v[110:113], v[86:89]
	s_waitcnt lgkmcnt(2)
	v_mfma_f32_16x16x32_f16 v[28:31], v[122:125], v[90:93], v[28:31]
	ds_read_b128 v[90:93], v23 offset:20480
	v_mfma_f32_16x16x32_f16 v[32:35], v[122:125], v[110:113], v[32:35]
	ds_read_b128 v[110:113], v23 offset:22528
	s_waitcnt lgkmcnt(1)
	v_mfma_f32_16x16x32_f16 v[98:101], v[62:65], v[90:93], v[98:101]
	s_waitcnt lgkmcnt(0)
	v_mfma_f32_16x16x32_f16 v[52:55], v[62:65], v[110:113], v[52:55]
	global_load_dwordx4 v[62:65], v[0:1], off offset:640
	v_mfma_f32_16x16x32_f16 v[102:105], v[74:77], v[90:93], v[102:105]
	v_mfma_f32_16x16x32_f16 v[24:27], v[74:77], v[110:113], v[24:27]
	v_mfma_f32_16x16x32_f16 v[114:117], v[118:121], v[90:93], v[114:117]
	v_mfma_f32_16x16x32_f16 v[40:43], v[118:121], v[110:113], v[40:43]
	v_mfma_f32_16x16x32_f16 v[70:73], v[122:125], v[90:93], v[70:73]
	global_load_dwordx4 v[90:93], v[2:3], off offset:640
	global_load_dwordx4 v[126:129], v[4:5], off offset:640
	global_load_dwordx4 v[130:133], v[14:15], off offset:640
	global_load_dwordx4 v[74:77], v[10:11], off offset:640
	global_load_dwordx4 v[138:141], v[12:13], off offset:640
	global_load_dwordx4 v[142:145], v[8:9], off offset:640
	global_load_dwordx4 v[154:157], v[6:7], off offset:640
	s_waitcnt lgkmcnt(0)
	s_barrier
	v_mfma_f32_16x16x32_f16 v[48:51], v[122:125], v[110:113], v[48:51]
	ds_read_b128 v[58:61], v16 offset:32768
	ds_read_b128 v[106:109], v21
	s_waitcnt lgkmcnt(0)
	v_mfma_f32_16x16x32_f16 v[36:39], v[58:61], v[106:109], v[36:39]
	ds_read_b128 v[94:97], v16 offset:34816
	ds_read_b128 v[110:113], v21 offset:2048
	s_waitcnt lgkmcnt(0)
	v_mfma_f32_16x16x32_f16 v[66:69], v[58:61], v[110:113], v[66:69]
	ds_read_b128 v[118:121], v16 offset:36864
	v_mfma_f32_16x16x32_f16 v[44:47], v[94:97], v[106:109], v[44:47]
	ds_read_b128 v[122:125], v16 offset:38912
	v_mfma_f32_16x16x32_f16 v[78:81], v[94:97], v[110:113], v[78:81]
	s_waitcnt vmcnt(7)
	ds_write_b128 v17, v[62:65] offset:16384
	s_waitcnt lgkmcnt(2)
	v_mfma_f32_16x16x32_f16 v[82:85], v[118:121], v[106:109], v[82:85]
	s_waitcnt vmcnt(6)
	ds_write_b128 v18, v[90:93] offset:16384
	v_mfma_f32_16x16x32_f16 v[86:89], v[118:121], v[110:113], v[86:89]
	s_waitcnt vmcnt(5)
	ds_write_b128 v19, v[126:129] offset:16384
	s_waitcnt lgkmcnt(3)
	v_mfma_f32_16x16x32_f16 v[28:31], v[122:125], v[106:109], v[28:31]
	ds_read_b128 v[106:109], v21 offset:4096
	v_mfma_f32_16x16x32_f16 v[32:35], v[122:125], v[110:113], v[32:35]
	ds_read_b128 v[110:113], v21 offset:6144
	s_waitcnt lgkmcnt(1)
	v_mfma_f32_16x16x32_f16 v[98:101], v[58:61], v[106:109], v[98:101]
	s_waitcnt vmcnt(4)
	ds_write_b128 v20, v[130:133] offset:16384
	s_waitcnt lgkmcnt(1)
	v_mfma_f32_16x16x32_f16 v[52:55], v[58:61], v[110:113], v[52:55]
	ds_read_b128 v[58:61], v22 offset:32768
	v_mfma_f32_16x16x32_f16 v[102:105], v[94:97], v[106:109], v[102:105]
	s_waitcnt vmcnt(3)
	ds_write_b128 v17, v[74:77] offset:49152
	v_mfma_f32_16x16x32_f16 v[24:27], v[94:97], v[110:113], v[24:27]
	ds_read_b128 v[94:97], v22 offset:34816
	v_mfma_f32_16x16x32_f16 v[114:117], v[118:121], v[106:109], v[114:117]
	s_waitcnt vmcnt(2)
	ds_write_b128 v18, v[138:141] offset:49152
	v_mfma_f32_16x16x32_f16 v[40:43], v[118:121], v[110:113], v[40:43]
	ds_read_b128 v[118:121], v22 offset:36864
	v_mfma_f32_16x16x32_f16 v[70:73], v[122:125], v[106:109], v[70:73]
	ds_read_b128 v[106:109], v23
	v_mfma_f32_16x16x32_f16 v[48:51], v[122:125], v[110:113], v[48:51]
	ds_read_b128 v[110:113], v23 offset:2048
	s_waitcnt lgkmcnt(1)
	v_mfma_f32_16x16x32_f16 v[36:39], v[58:61], v[106:109], v[36:39]
	ds_read_b128 v[122:125], v22 offset:38912
	s_waitcnt lgkmcnt(1)
	v_mfma_f32_16x16x32_f16 v[66:69], v[58:61], v[110:113], v[66:69]
	s_waitcnt vmcnt(1)
	ds_write_b128 v19, v[142:145] offset:49152
	v_mfma_f32_16x16x32_f16 v[44:47], v[94:97], v[106:109], v[44:47]
	s_waitcnt vmcnt(0)
	ds_write_b128 v20, v[154:157] offset:49152
	v_mfma_f32_16x16x32_f16 v[78:81], v[94:97], v[110:113], v[78:81]
	v_mfma_f32_16x16x32_f16 v[82:85], v[118:121], v[106:109], v[82:85]
	v_mfma_f32_16x16x32_f16 v[86:89], v[118:121], v[110:113], v[86:89]
	s_waitcnt lgkmcnt(2)
	v_mfma_f32_16x16x32_f16 v[28:31], v[122:125], v[106:109], v[28:31]
	ds_read_b128 v[106:109], v23 offset:4096
	v_mfma_f32_16x16x32_f16 v[32:35], v[122:125], v[110:113], v[32:35]
	ds_read_b128 v[110:113], v23 offset:6144
	s_waitcnt lgkmcnt(1)
	v_mfma_f32_16x16x32_f16 v[98:101], v[58:61], v[106:109], v[98:101]
	s_waitcnt lgkmcnt(0)
	v_mfma_f32_16x16x32_f16 v[52:55], v[58:61], v[110:113], v[52:55]
	global_load_dwordx4 v[58:61], v[0:1], off offset:768
	v_mfma_f32_16x16x32_f16 v[102:105], v[94:97], v[106:109], v[102:105]
	v_mfma_f32_16x16x32_f16 v[24:27], v[94:97], v[110:113], v[24:27]
	v_mfma_f32_16x16x32_f16 v[114:117], v[118:121], v[106:109], v[114:117]
	v_mfma_f32_16x16x32_f16 v[40:43], v[118:121], v[110:113], v[40:43]
	v_mfma_f32_16x16x32_f16 v[70:73], v[122:125], v[106:109], v[70:73]
	global_load_dwordx4 v[106:109], v[2:3], off offset:768
	global_load_dwordx4 v[134:137], v[4:5], off offset:768
	global_load_dwordx4 v[158:161], v[14:15], off offset:768
	global_load_dwordx4 v[94:97], v[10:11], off offset:768
	global_load_dwordx4 v[162:165], v[12:13], off offset:768
	global_load_dwordx4 v[166:169], v[8:9], off offset:768
	global_load_dwordx4 v[190:193], v[6:7], off offset:768
	s_waitcnt lgkmcnt(0)
	s_barrier
; #define GL_LOAD(s_, kt_) if (VAR != 1) { a##s_##0 = GL_A(0, kt_); a##s_##1 = GL_A(1, kt_); a##s_##2 = GL_A(2, kt_); a##s_##3 = GL_A(3, kt_); b##s_##0 = GL_B(0, kt_); b##s_##1 = GL_B(1, kt_); b##s_##2 = GL_B(2, kt_); b##s_##3 = GL_B(3, kt_); }
; #define LDS_STORE(s_, buf_) if (VAR != 2) { LDS_ST1(sA, 0, buf_, a##s_##0) LDS_ST1(sA, 1, buf_, a##s_##1) LDS_ST1(sA, 2, buf_, a##s_##2) LDS_ST1(sA, 3, buf_, a##s_##3) LDS_ST1(sB, 0, buf_, b##s_##0) LDS_ST1(sB, 1, buf_, b##s_##1) LDS_ST1(sB, 2, buf_, b##s_##2) LDS_ST1(sB, 3, buf_, b##s_##3) }
;     ...
;   GL_LOAD(0, 0)
;   GL_LOAD(1, 1)
;   LDS_STORE(0, 0)
;   if (VAR != 4) __syncthreads();
; #pragma unroll
;   for (int kt = 0; kt < nk; kt += 2) {
;     if (kt + 2 < nk) { GL_LOAD(0, kt + 2) }
;     MMA_TILE(0)
;     LDS_STORE(1, 1)
;     if (VAR != 4) __syncthreads();
;     if (kt + 3 < nk) { GL_LOAD(1, kt + 3) }
;     MMA_TILE(1)
;     if (kt + 2 < nk) { LDS_STORE(0, 0) }
;     if (VAR != 4) __syncthreads();
	v_mfma_f32_16x16x32_f16 v[48:51], v[122:125], v[110:113], v[48:51]
	ds_read_b128 v[62:65], v16 offset:49152
	ds_read_b128 v[90:93], v21 offset:16384
	s_waitcnt lgkmcnt(0)
	v_mfma_f32_16x16x32_f16 v[36:39], v[62:65], v[90:93], v[36:39]
	ds_read_b128 v[74:77], v16 offset:51200
	ds_read_b128 v[110:113], v21 offset:18432
	s_waitcnt lgkmcnt(0)
	v_mfma_f32_16x16x32_f16 v[66:69], v[62:65], v[110:113], v[66:69]
	ds_read_b128 v[118:121], v16 offset:53248
	v_mfma_f32_16x16x32_f16 v[44:47], v[74:77], v[90:93], v[44:47]
	ds_read_b128 v[122:125], v16 offset:55296
	v_mfma_f32_16x16x32_f16 v[78:81], v[74:77], v[110:113], v[78:81]
	s_waitcnt vmcnt(7)
	ds_write_b128 v17, v[58:61]
	s_waitcnt lgkmcnt(2)
	v_mfma_f32_16x16x32_f16 v[82:85], v[118:121], v[90:93], v[82:85]
	s_waitcnt vmcnt(6)
	ds_write_b128 v18, v[106:109]
	v_mfma_f32_16x16x32_f16 v[86:89], v[118:121], v[110:113], v[86:89]
	s_waitcnt vmcnt(5)
	ds_write_b128 v19, v[134:137]
	s_waitcnt lgkmcnt(3)
	v_mfma_f32_16x16x32_f16 v[28:31], v[122:125], v[90:93], v[28:31]
	ds_read_b128 v[90:93], v21 offset:20480
	v_mfma_f32_16x16x32_f16 v[32:35], v[122:125], v[110:113], v[32:35]
	ds_read_b128 v[110:113], v21 offset:22528
	s_waitcnt lgkmcnt(1)
	v_mfma_f32_16x16x32_f16 v[98:101], v[62:65], v[90:93], v[98:101]
	s_waitcnt vmcnt(4)
	ds_write_b128 v20, v[158:161]
	s_waitcnt lgkmcnt(1)
	v_mfma_f32_16x16x32_f16 v[52:55], v[62:65], v[110:113], v[52:55]
	ds_read_b128 v[62:65], v22 offset:49152
	v_mfma_f32_16x16x32_f16 v[102:105], v[74:77], v[90:93], v[102:105]
	s_waitcnt vmcnt(3)
	ds_write_b128 v17, v[94:97] offset:32768
	v_mfma_f32_16x16x32_f16 v[24:27], v[74:77], v[110:113], v[24:27]
	ds_read_b128 v[74:77], v22 offset:51200
	v_mfma_f32_16x16x32_f16 v[114:117], v[118:121], v[90:93], v[114:117]
	s_waitcnt vmcnt(2)
	ds_write_b128 v18, v[162:165] offset:32768
	v_mfma_f32_16x16x32_f16 v[40:43], v[118:121], v[110:113], v[40:43]
	ds_read_b128 v[118:121], v22 offset:53248
	v_mfma_f32_16x16x32_f16 v[70:73], v[122:125], v[90:93], v[70:73]
	ds_read_b128 v[90:93], v23 offset:16384
	v_mfma_f32_16x16x32_f16 v[48:51], v[122:125], v[110:113], v[48:51]
	ds_read_b128 v[110:113], v23 offset:18432
	s_waitcnt lgkmcnt(1)
	v_mfma_f32_16x16x32_f16 v[36:39], v[62:65], v[90:93], v[36:39]
	ds_read_b128 v[122:125], v22 offset:55296
	s_waitcnt lgkmcnt(1)
	v_mfma_f32_16x16x32_f16 v[66:69], v[62:65], v[110:113], v[66:69]
	s_waitcnt vmcnt(1)
	ds_write_b128 v19, v[166:169] offset:32768
	v_mfma_f32_16x16x32_f16 v[44:47], v[74:77], v[90:93], v[44:47]
	s_waitcnt vmcnt(0)
	ds_write_b128 v20, v[190:193] offset:32768
	v_mfma_f32_16x16x32_f16 v[78:81], v[74:77], v[110:113], v[78:81]
	v_mfma_f32_16x16x32_f16 v[82:85], v[118:121], v[90:93], v[82:85]
	v_mfma_f32_16x16x32_f16 v[86:89], v[118:121], v[110:113], v[86:89]
	s_waitcnt lgkmcnt(2)
	v_mfma_f32_16x16x32_f16 v[28:31], v[122:125], v[90:93], v[28:31]
	ds_read_b128 v[90:93], v23 offset:20480
	v_mfma_f32_16x16x32_f16 v[32:35], v[122:125], v[110:113], v[32:35]
	ds_read_b128 v[110:113], v23 offset:22528
	s_waitcnt lgkmcnt(1)
	v_mfma_f32_16x16x32_f16 v[98:101], v[62:65], v[90:93], v[98:101]
	s_waitcnt lgkmcnt(0)
	v_mfma_f32_16x16x32_f16 v[52:55], v[62:65], v[110:113], v[52:55]
	global_load_dwordx4 v[62:65], v[0:1], off offset:896
	v_mfma_f32_16x16x32_f16 v[102:105], v[74:77], v[90:93], v[102:105]
	v_mfma_f32_16x16x32_f16 v[24:27], v[74:77], v[110:113], v[24:27]
	v_mfma_f32_16x16x32_f16 v[114:117], v[118:121], v[90:93], v[114:117]
	v_mfma_f32_16x16x32_f16 v[40:43], v[118:121], v[110:113], v[40:43]
	v_mfma_f32_16x16x32_f16 v[70:73], v[122:125], v[90:93], v[70:73]
	global_load_dwordx4 v[90:93], v[2:3], off offset:896
	global_load_dwordx4 v[126:129], v[4:5], off offset:896
	global_load_dwordx4 v[130:133], v[14:15], off offset:896
	global_load_dwordx4 v[74:77], v[10:11], off offset:896
	global_load_dwordx4 v[138:141], v[12:13], off offset:896
	global_load_dwordx4 v[142:145], v[8:9], off offset:896
	global_load_dwordx4 v[154:157], v[6:7], off offset:896
	s_waitcnt lgkmcnt(0)
	s_barrier
	v_mfma_f32_16x16x32_f16 v[48:51], v[122:125], v[110:113], v[48:51]
	ds_read_b128 v[58:61], v16 offset:32768
	ds_read_b128 v[106:109], v21
	s_waitcnt lgkmcnt(0)
	v_mfma_f32_16x16x32_f16 v[36:39], v[58:61], v[106:109], v[36:39]
	ds_read_b128 v[94:97], v16 offset:34816
	ds_read_b128 v[110:113], v21 offset:2048
	s_waitcnt lgkmcnt(0)
	v_mfma_f32_16x16x32_f16 v[66:69], v[58:61], v[110:113], v[66:69]
	ds_read_b128 v[118:121], v16 offset:36864
	v_mfma_f32_16x16x32_f16 v[44:47], v[94:97], v[106:109], v[44:47]
	ds_read_b128 v[122:125], v16 offset:38912
	v_mfma_f32_16x16x32_f16 v[78:81], v[94:97], v[110:113], v[78:81]
	s_waitcnt vmcnt(7)
	ds_write_b128 v17, v[62:65] offset:16384
	s_waitcnt lgkmcnt(2)
	v_mfma_f32_16x16x32_f16 v[82:85], v[118:121], v[106:109], v[82:85]
	s_waitcnt vmcnt(6)
	ds_write_b128 v18, v[90:93] offset:16384
	v_mfma_f32_16x16x32_f16 v[86:89], v[118:121], v[110:113], v[86:89]
	s_waitcnt vmcnt(5)
	ds_write_b128 v19, v[126:129] offset:16384
	s_waitcnt lgkmcnt(3)
	v_mfma_f32_16x16x32_f16 v[28:31], v[122:125], v[106:109], v[28:31]
	ds_read_b128 v[106:109], v21 offset:4096
	v_mfma_f32_16x16x32_f16 v[32:35], v[122:125], v[110:113], v[32:35]
	ds_read_b128 v[110:113], v21 offset:6144
	s_waitcnt lgkmcnt(1)
	v_mfma_f32_16x16x32_f16 v[98:101], v[58:61], v[106:109], v[98:101]
	s_waitcnt vmcnt(4)
	ds_write_b128 v20, v[130:133] offset:16384
	s_waitcnt lgkmcnt(1)
	v_mfma_f32_16x16x32_f16 v[52:55], v[58:61], v[110:113], v[52:55]
	ds_read_b128 v[58:61], v22 offset:32768
	v_mfma_f32_16x16x32_f16 v[102:105], v[94:97], v[106:109], v[102:105]
	s_waitcnt vmcnt(3)
; #define GL_LOAD(s_, kt_) if (VAR != 1) { a##s_##0 = GL_A(0, kt_); a##s_##1 = GL_A(1, kt_); a##s_##2 = GL_A(2, kt_); a##s_##3 = GL_A(3, kt_); b##s_##0 = GL_B(0, kt_); b##s_##1 = GL_B(1, kt_); b##s_##2 = GL_B(2, kt_); b##s_##3 = GL_B(3, kt_); }
; #define LDS_STORE(s_, buf_) if (VAR != 2) { LDS_ST1(sA, 0, buf_, a##s_##0) LDS_ST1(sA, 1, buf_, a##s_##1) LDS_ST1(sA, 2, buf_, a##s_##2) LDS_ST1(sA, 3, buf_, a##s_##3) LDS_ST1(sB, 0, buf_, b##s_##0) LDS_ST1(sB, 1, buf_, b##s_##1) LDS_ST1(sB, 2, buf_, b##s_##2) LDS_ST1(sB, 3, buf_, b##s_##3) }
;     ...
;   GL_LOAD(0, 0)
;   GL_LOAD(1, 1)
;   LDS_STORE(0, 0)
;   if (VAR != 4) __syncthreads();
; #pragma unroll
;   for (int kt = 0; kt < nk; kt += 2) {
;     if (kt + 2 < nk) { GL_LOAD(0, kt + 2) }
;     MMA_TILE(0)
;     LDS_STORE(1, 1)
;     if (VAR != 4) __syncthreads();
;     if (kt + 3 < nk) { GL_LOAD(1, kt + 3) }
;     MMA_TILE(1)
;     if (kt + 2 < nk) { LDS_STORE(0, 0) }
;     if (VAR != 4) __syncthreads();
	ds_write_b128 v17, v[74:77] offset:49152
	v_mfma_f32_16x16x32_f16 v[24:27], v[94:97], v[110:113], v[24:27]
	ds_read_b128 v[94:97], v22 offset:34816
	v_mfma_f32_16x16x32_f16 v[114:117], v[118:121], v[106:109], v[114:117]
	s_waitcnt vmcnt(2)
	ds_write_b128 v18, v[138:141] offset:49152
	v_mfma_f32_16x16x32_f16 v[40:43], v[118:121], v[110:113], v[40:43]
	ds_read_b128 v[118:121], v22 offset:36864
	v_mfma_f32_16x16x32_f16 v[70:73], v[122:125], v[106:109], v[70:73]
	ds_read_b128 v[106:109], v23
	v_mfma_f32_16x16x32_f16 v[48:51], v[122:125], v[110:113], v[48:51]
	ds_read_b128 v[110:113], v23 offset:2048
	s_waitcnt lgkmcnt(1)
	v_mfma_f32_16x16x32_f16 v[36:39], v[58:61], v[106:109], v[36:39]
	ds_read_b128 v[122:125], v22 offset:38912
	s_waitcnt lgkmcnt(1)
	v_mfma_f32_16x16x32_f16 v[66:69], v[58:61], v[110:113], v[66:69]
	s_waitcnt vmcnt(1)
	ds_write_b128 v19, v[142:145] offset:49152
	v_mfma_f32_16x16x32_f16 v[44:47], v[94:97], v[106:109], v[44:47]
	s_waitcnt vmcnt(0)
	ds_write_b128 v20, v[154:157] offset:49152
	v_mfma_f32_16x16x32_f16 v[78:81], v[94:97], v[110:113], v[78:81]
	v_mfma_f32_16x16x32_f16 v[82:85], v[118:121], v[106:109], v[82:85]
	v_mfma_f32_16x16x32_f16 v[86:89], v[118:121], v[110:113], v[86:89]
	s_waitcnt lgkmcnt(2)
	v_mfma_f32_16x16x32_f16 v[28:31], v[122:125], v[106:109], v[28:31]
	ds_read_b128 v[106:109], v23 offset:4096
	v_mfma_f32_16x16x32_f16 v[32:35], v[122:125], v[110:113], v[32:35]
	ds_read_b128 v[110:113], v23 offset:6144
	s_waitcnt lgkmcnt(1)
	v_mfma_f32_16x16x32_f16 v[98:101], v[58:61], v[106:109], v[98:101]
	s_waitcnt lgkmcnt(0)
	v_mfma_f32_16x16x32_f16 v[52:55], v[58:61], v[110:113], v[52:55]
	global_load_dwordx4 v[58:61], v[0:1], off offset:1024
	v_mfma_f32_16x16x32_f16 v[102:105], v[94:97], v[106:109], v[102:105]
	v_mfma_f32_16x16x32_f16 v[24:27], v[94:97], v[110:113], v[24:27]
	v_mfma_f32_16x16x32_f16 v[114:117], v[118:121], v[106:109], v[114:117]
	v_mfma_f32_16x16x32_f16 v[40:43], v[118:121], v[110:113], v[40:43]
	v_mfma_f32_16x16x32_f16 v[70:73], v[122:125], v[106:109], v[70:73]
	global_load_dwordx4 v[106:109], v[2:3], off offset:1024
	global_load_dwordx4 v[134:137], v[4:5], off offset:1024
	global_load_dwordx4 v[158:161], v[14:15], off offset:1024
	global_load_dwordx4 v[94:97], v[10:11], off offset:1024
	global_load_dwordx4 v[162:165], v[12:13], off offset:1024
	global_load_dwordx4 v[166:169], v[8:9], off offset:1024
	global_load_dwordx4 v[190:193], v[6:7], off offset:1024
	s_waitcnt lgkmcnt(0)
	s_barrier
	v_mfma_f32_16x16x32_f16 v[48:51], v[122:125], v[110:113], v[48:51]
	ds_read_b128 v[62:65], v16 offset:49152
	ds_read_b128 v[90:93], v21 offset:16384
	s_waitcnt lgkmcnt(0)
	v_mfma_f32_16x16x32_f16 v[36:39], v[62:65], v[90:93], v[36:39]
	ds_read_b128 v[74:77], v16 offset:51200
	ds_read_b128 v[110:113], v21 offset:18432
	s_waitcnt lgkmcnt(0)
	v_mfma_f32_16x16x32_f16 v[66:69], v[62:65], v[110:113], v[66:69]
	ds_read_b128 v[118:121], v16 offset:53248
	v_mfma_f32_16x16x32_f16 v[44:47], v[74:77], v[90:93], v[44:47]
	ds_read_b128 v[122:125], v16 offset:55296
	v_mfma_f32_16x16x32_f16 v[78:81], v[74:77], v[110:113], v[78:81]
	s_waitcnt vmcnt(7)
	ds_write_b128 v17, v[58:61]
	s_waitcnt lgkmcnt(2)
	v_mfma_f32_16x16x32_f16 v[82:85], v[118:121], v[90:93], v[82:85]
	s_waitcnt vmcnt(6)
	ds_write_b128 v18, v[106:109]
	v_mfma_f32_16x16x32_f16 v[86:89], v[118:121], v[110:113], v[86:89]
	s_waitcnt vmcnt(5)
	ds_write_b128 v19, v[134:137]
	s_waitcnt lgkmcnt(3)
	v_mfma_f32_16x16x32_f16 v[28:31], v[122:125], v[90:93], v[28:31]
	ds_read_b128 v[90:93], v21 offset:20480
	v_mfma_f32_16x16x32_f16 v[32:35], v[122:125], v[110:113], v[32:35]
	ds_read_b128 v[110:113], v21 offset:22528
	s_waitcnt lgkmcnt(1)
	v_mfma_f32_16x16x32_f16 v[98:101], v[62:65], v[90:93], v[98:101]
	s_waitcnt vmcnt(4)
	ds_write_b128 v20, v[158:161]
	s_waitcnt lgkmcnt(1)
	v_mfma_f32_16x16x32_f16 v[52:55], v[62:65], v[110:113], v[52:55]
	ds_read_b128 v[62:65], v22 offset:49152
	v_mfma_f32_16x16x32_f16 v[102:105], v[74:77], v[90:93], v[102:105]
	s_waitcnt vmcnt(3)
	ds_write_b128 v17, v[94:97] offset:32768
	v_mfma_f32_16x16x32_f16 v[24:27], v[74:77], v[110:113], v[24:27]
	ds_read_b128 v[74:77], v22 offset:51200
	v_mfma_f32_16x16x32_f16 v[114:117], v[118:121], v[90:93], v[114:117]
	s_waitcnt vmcnt(2)
	ds_write_b128 v18, v[162:165] offset:32768
	v_mfma_f32_16x16x32_f16 v[40:43], v[118:121], v[110:113], v[40:43]
	ds_read_b128 v[118:121], v22 offset:53248
	v_mfma_f32_16x16x32_f16 v[70:73], v[122:125], v[90:93], v[70:73]
	ds_read_b128 v[90:93], v23 offset:16384
	v_mfma_f32_16x16x32_f16 v[48:51], v[122:125], v[110:113], v[48:51]
	ds_read_b128 v[110:113], v23 offset:18432
	s_waitcnt lgkmcnt(1)
	v_mfma_f32_16x16x32_f16 v[36:39], v[62:65], v[90:93], v[36:39]
	ds_read_b128 v[122:125], v22 offset:55296
	s_waitcnt lgkmcnt(1)
	v_mfma_f32_16x16x32_f16 v[66:69], v[62:65], v[110:113], v[66:69]
	s_waitcnt vmcnt(1)
	ds_write_b128 v19, v[166:169] offset:32768
	v_mfma_f32_16x16x32_f16 v[44:47], v[74:77], v[90:93], v[44:47]
	s_waitcnt vmcnt(0)
	ds_write_b128 v20, v[190:193] offset:32768
	v_mfma_f32_16x16x32_f16 v[78:81], v[74:77], v[110:113], v[78:81]
	v_mfma_f32_16x16x32_f16 v[82:85], v[118:121], v[90:93], v[82:85]
	v_mfma_f32_16x16x32_f16 v[86:89], v[118:121], v[110:113], v[86:89]
	s_waitcnt lgkmcnt(2)
	v_mfma_f32_16x16x32_f16 v[28:31], v[122:125], v[90:93], v[28:31]
	ds_read_b128 v[90:93], v23 offset:20480
	v_mfma_f32_16x16x32_f16 v[32:35], v[122:125], v[110:113], v[32:35]
	ds_read_b128 v[110:113], v23 offset:22528
	s_waitcnt lgkmcnt(1)
	v_mfma_f32_16x16x32_f16 v[98:101], v[62:65], v[90:93], v[98:101]
	s_waitcnt lgkmcnt(0)
	v_mfma_f32_16x16x32_f16 v[52:55], v[62:65], v[110:113], v[52:55]
	global_load_dwordx4 v[62:65], v[0:1], off offset:1152
	v_mfma_f32_16x16x32_f16 v[102:105], v[74:77], v[90:93], v[102:105]
	v_mfma_f32_16x16x32_f16 v[24:27], v[74:77], v[110:113], v[24:27]
	v_mfma_f32_16x16x32_f16 v[114:117], v[118:121], v[90:93], v[114:117]
	v_mfma_f32_16x16x32_f16 v[40:43], v[118:121], v[110:113], v[40:43]
	v_mfma_f32_16x16x32_f16 v[70:73], v[122:125], v[90:93], v[70:73]
	global_load_dwordx4 v[90:93], v[2:3], off offset:1152
	global_load_dwordx4 v[126:129], v[4:5], off offset:1152
	global_load_dwordx4 v[130:133], v[14:15], off offset:1152
	global_load_dwordx4 v[74:77], v[10:11], off offset:1152
	global_load_dwordx4 v[138:141], v[12:13], off offset:1152
	global_load_dwordx4 v[142:145], v[8:9], off offset:1152
	global_load_dwordx4 v[154:157], v[6:7], off offset:1152
	s_waitcnt lgkmcnt(0)
	s_barrier
; #define GL_LOAD(s_, kt_) if (VAR != 1) { a##s_##0 = GL_A(0, kt_); a##s_##1 = GL_A(1, kt_); a##s_##2 = GL_A(2, kt_); a##s_##3 = GL_A(3, kt_); b##s_##0 = GL_B(0, kt_); b##s_##1 = GL_B(1, kt_); b##s_##2 = GL_B(2, kt_); b##s_##3 = GL_B(3, kt_); }
; #define LDS_STORE(s_, buf_) if (VAR != 2) { LDS_ST1(sA, 0, buf_, a##s_##0) LDS_ST1(sA, 1, buf_, a##s_##1) LDS_ST1(sA, 2, buf_, a##s_##2) LDS_ST1(sA, 3, buf_, a##s_##3) LDS_ST1(sB, 0, buf_, b##s_##0) LDS_ST1(sB, 1, buf_, b##s_##1) LDS_ST1(sB, 2, buf_, b##s_##2) LDS_ST1(sB, 3, buf_, b##s_##3) }
;     ...
;   GL_LOAD(0, 0)
;   GL_LOAD(1, 1)
;   LDS_STORE(0, 0)
;   if (VAR != 4) __syncthreads();
; #pragma unroll
;   for (int kt = 0; kt < nk; kt += 2) {
;     if (kt + 2 < nk) { GL_LOAD(0, kt + 2) }
;     MMA_TILE(0)
;     LDS_STORE(1, 1)
;     if (VAR != 4) __syncthreads();
;     if (kt + 3 < nk) { GL_LOAD(1, kt + 3) }
;     MMA_TILE(1)
;     if (kt + 2 < nk) { LDS_STORE(0, 0) }
;     if (VAR != 4) __syncthreads();
	v_mfma_f32_16x16x32_f16 v[48:51], v[122:125], v[110:113], v[48:51]
	ds_read_b128 v[58:61], v16 offset:32768
	ds_read_b128 v[106:109], v21
	s_waitcnt lgkmcnt(0)
	v_mfma_f32_16x16x32_f16 v[36:39], v[58:61], v[106:109], v[36:39]
	ds_read_b128 v[94:97], v16 offset:34816
	ds_read_b128 v[110:113], v21 offset:2048
	s_waitcnt lgkmcnt(0)
	v_mfma_f32_16x16x32_f16 v[66:69], v[58:61], v[110:113], v[66:69]
	ds_read_b128 v[118:121], v16 offset:36864
	v_mfma_f32_16x16x32_f16 v[44:47], v[94:97], v[106:109], v[44:47]
	ds_read_b128 v[122:125], v16 offset:38912
	v_mfma_f32_16x16x32_f16 v[78:81], v[94:97], v[110:113], v[78:81]
	s_waitcnt vmcnt(7)
	ds_write_b128 v17, v[62:65] offset:16384
	s_waitcnt lgkmcnt(2)
	v_mfma_f32_16x16x32_f16 v[82:85], v[118:121], v[106:109], v[82:85]
	s_waitcnt vmcnt(6)
	ds_write_b128 v18, v[90:93] offset:16384
	v_mfma_f32_16x16x32_f16 v[86:89], v[118:121], v[110:113], v[86:89]
	s_waitcnt vmcnt(5)
	ds_write_b128 v19, v[126:129] offset:16384
	s_waitcnt lgkmcnt(3)
	v_mfma_f32_16x16x32_f16 v[28:31], v[122:125], v[106:109], v[28:31]
	ds_read_b128 v[106:109], v21 offset:4096
	v_mfma_f32_16x16x32_f16 v[32:35], v[122:125], v[110:113], v[32:35]
	ds_read_b128 v[110:113], v21 offset:6144
	s_waitcnt lgkmcnt(1)
	v_mfma_f32_16x16x32_f16 v[98:101], v[58:61], v[106:109], v[98:101]
	s_waitcnt vmcnt(4)
	ds_write_b128 v20, v[130:133] offset:16384
	s_waitcnt lgkmcnt(1)
	v_mfma_f32_16x16x32_f16 v[52:55], v[58:61], v[110:113], v[52:55]
	ds_read_b128 v[58:61], v22 offset:32768
	v_mfma_f32_16x16x32_f16 v[102:105], v[94:97], v[106:109], v[102:105]
	s_waitcnt vmcnt(3)
	ds_write_b128 v17, v[74:77] offset:49152
	v_mfma_f32_16x16x32_f16 v[24:27], v[94:97], v[110:113], v[24:27]
	ds_read_b128 v[94:97], v22 offset:34816
	v_mfma_f32_16x16x32_f16 v[114:117], v[118:121], v[106:109], v[114:117]
	s_waitcnt vmcnt(2)
	ds_write_b128 v18, v[138:141] offset:49152
	v_mfma_f32_16x16x32_f16 v[40:43], v[118:121], v[110:113], v[40:43]
	ds_read_b128 v[118:121], v22 offset:36864
	v_mfma_f32_16x16x32_f16 v[70:73], v[122:125], v[106:109], v[70:73]
	ds_read_b128 v[106:109], v23
	v_mfma_f32_16x16x32_f16 v[48:51], v[122:125], v[110:113], v[48:51]
	ds_read_b128 v[110:113], v23 offset:2048
	s_waitcnt lgkmcnt(1)
	v_mfma_f32_16x16x32_f16 v[36:39], v[58:61], v[106:109], v[36:39]
	ds_read_b128 v[122:125], v22 offset:38912
	s_waitcnt lgkmcnt(1)
	v_mfma_f32_16x16x32_f16 v[66:69], v[58:61], v[110:113], v[66:69]
	s_waitcnt vmcnt(1)
	ds_write_b128 v19, v[142:145] offset:49152
	v_mfma_f32_16x16x32_f16 v[44:47], v[94:97], v[106:109], v[44:47]
	s_waitcnt vmcnt(0)
	ds_write_b128 v20, v[154:157] offset:49152
	v_mfma_f32_16x16x32_f16 v[78:81], v[94:97], v[110:113], v[78:81]
	v_mfma_f32_16x16x32_f16 v[82:85], v[118:121], v[106:109], v[82:85]
	v_mfma_f32_16x16x32_f16 v[86:89], v[118:121], v[110:113], v[86:89]
	s_waitcnt lgkmcnt(2)
	v_mfma_f32_16x16x32_f16 v[28:31], v[122:125], v[106:109], v[28:31]
	ds_read_b128 v[106:109], v23 offset:4096
	v_mfma_f32_16x16x32_f16 v[32:35], v[122:125], v[110:113], v[32:35]
	ds_read_b128 v[110:113], v23 offset:6144
	s_waitcnt lgkmcnt(1)
	v_mfma_f32_16x16x32_f16 v[98:101], v[58:61], v[106:109], v[98:101]
	s_waitcnt lgkmcnt(0)
	v_mfma_f32_16x16x32_f16 v[52:55], v[58:61], v[110:113], v[52:55]
	global_load_dwordx4 v[58:61], v[0:1], off offset:1280
	v_mfma_f32_16x16x32_f16 v[102:105], v[94:97], v[106:109], v[102:105]
	v_mfma_f32_16x16x32_f16 v[24:27], v[94:97], v[110:113], v[24:27]
	v_mfma_f32_16x16x32_f16 v[114:117], v[118:121], v[106:109], v[114:117]
	v_mfma_f32_16x16x32_f16 v[40:43], v[118:121], v[110:113], v[40:43]
	v_mfma_f32_16x16x32_f16 v[70:73], v[122:125], v[106:109], v[70:73]
	global_load_dwordx4 v[106:109], v[2:3], off offset:1280
	global_load_dwordx4 v[134:137], v[4:5], off offset:1280
	global_load_dwordx4 v[158:161], v[14:15], off offset:1280
	global_load_dwordx4 v[94:97], v[10:11], off offset:1280
	global_load_dwordx4 v[162:165], v[12:13], off offset:1280
	global_load_dwordx4 v[166:169], v[8:9], off offset:1280
	global_load_dwordx4 v[190:193], v[6:7], off offset:1280
	s_waitcnt lgkmcnt(0)
	s_barrier
	v_mfma_f32_16x16x32_f16 v[48:51], v[122:125], v[110:113], v[48:51]
	ds_read_b128 v[62:65], v16 offset:49152
	ds_read_b128 v[90:93], v21 offset:16384
	s_waitcnt lgkmcnt(0)
	v_mfma_f32_16x16x32_f16 v[36:39], v[62:65], v[90:93], v[36:39]
	ds_read_b128 v[74:77], v16 offset:51200
	ds_read_b128 v[110:113], v21 offset:18432
	s_waitcnt lgkmcnt(0)
	v_mfma_f32_16x16x32_f16 v[66:69], v[62:65], v[110:113], v[66:69]
	ds_read_b128 v[118:121], v16 offset:53248
	v_mfma_f32_16x16x32_f16 v[44:47], v[74:77], v[90:93], v[44:47]
	ds_read_b128 v[122:125], v16 offset:55296
	v_mfma_f32_16x16x32_f16 v[78:81], v[74:77], v[110:113], v[78:81]
	s_waitcnt vmcnt(7)
	ds_write_b128 v17, v[58:61]
	s_waitcnt lgkmcnt(2)
	v_mfma_f32_16x16x32_f16 v[82:85], v[118:121], v[90:93], v[82:85]
	s_waitcnt vmcnt(6)
	ds_write_b128 v18, v[106:109]
	v_mfma_f32_16x16x32_f16 v[86:89], v[118:121], v[110:113], v[86:89]
	s_waitcnt vmcnt(5)
	ds_write_b128 v19, v[134:137]
	s_waitcnt lgkmcnt(3)
	v_mfma_f32_16x16x32_f16 v[28:31], v[122:125], v[90:93], v[28:31]
	ds_read_b128 v[90:93], v21 offset:20480
	v_mfma_f32_16x16x32_f16 v[32:35], v[122:125], v[110:113], v[32:35]
	ds_read_b128 v[110:113], v21 offset:22528
	s_waitcnt lgkmcnt(1)
	v_mfma_f32_16x16x32_f16 v[98:101], v[62:65], v[90:93], v[98:101]
	s_waitcnt vmcnt(4)
	ds_write_b128 v20, v[158:161]
	s_waitcnt lgkmcnt(1)
	v_mfma_f32_16x16x32_f16 v[52:55], v[62:65], v[110:113], v[52:55]
	ds_read_b128 v[62:65], v22 offset:49152
	v_mfma_f32_16x16x32_f16 v[102:105], v[74:77], v[90:93], v[102:105]
	s_waitcnt vmcnt(3)
; #define GL_LOAD(s_, kt_) if (VAR != 1) { a##s_##0 = GL_A(0, kt_); a##s_##1 = GL_A(1, kt_); a##s_##2 = GL_A(2, kt_); a##s_##3 = GL_A(3, kt_); b##s_##0 = GL_B(0, kt_); b##s_##1 = GL_B(1, kt_); b##s_##2 = GL_B(2, kt_); b##s_##3 = GL_B(3, kt_); }
; #define LDS_STORE(s_, buf_) if (VAR != 2) { LDS_ST1(sA, 0, buf_, a##s_##0) LDS_ST1(sA, 1, buf_, a##s_##1) LDS_ST1(sA, 2, buf_, a##s_##2) LDS_ST1(sA, 3, buf_, a##s_##3) LDS_ST1(sB, 0, buf_, b##s_##0) LDS_ST1(sB, 1, buf_, b##s_##1) LDS_ST1(sB, 2, buf_, b##s_##2) LDS_ST1(sB, 3, buf_, b##s_##3) }
;     ...
;   GL_LOAD(0, 0)
;   GL_LOAD(1, 1)
;   LDS_STORE(0, 0)
;   if (VAR != 4) __syncthreads();
; #pragma unroll
;   for (int kt = 0; kt < nk; kt += 2) {
;     if (kt + 2 < nk) { GL_LOAD(0, kt + 2) }
;     MMA_TILE(0)
;     LDS_STORE(1, 1)
;     if (VAR != 4) __syncthreads();
;     if (kt + 3 < nk) { GL_LOAD(1, kt + 3) }
;     MMA_TILE(1)
;     if (kt + 2 < nk) { LDS_STORE(0, 0) }
;     if (VAR != 4) __syncthreads();
	ds_write_b128 v17, v[94:97] offset:32768
	v_mfma_f32_16x16x32_f16 v[24:27], v[74:77], v[110:113], v[24:27]
	ds_read_b128 v[74:77], v22 offset:51200
	v_mfma_f32_16x16x32_f16 v[114:117], v[118:121], v[90:93], v[114:117]
	s_waitcnt vmcnt(2)
	ds_write_b128 v18, v[162:165] offset:32768
	v_mfma_f32_16x16x32_f16 v[40:43], v[118:121], v[110:113], v[40:43]
	ds_read_b128 v[118:121], v22 offset:53248
	v_mfma_f32_16x16x32_f16 v[70:73], v[122:125], v[90:93], v[70:73]
	ds_read_b128 v[90:93], v23 offset:16384
	v_mfma_f32_16x16x32_f16 v[48:51], v[122:125], v[110:113], v[48:51]
	ds_read_b128 v[110:113], v23 offset:18432
	s_waitcnt lgkmcnt(1)
	v_mfma_f32_16x16x32_f16 v[36:39], v[62:65], v[90:93], v[36:39]
	ds_read_b128 v[122:125], v22 offset:55296
	s_waitcnt lgkmcnt(1)
	v_mfma_f32_16x16x32_f16 v[66:69], v[62:65], v[110:113], v[66:69]
	s_waitcnt vmcnt(1)
	ds_write_b128 v19, v[166:169] offset:32768
	v_mfma_f32_16x16x32_f16 v[44:47], v[74:77], v[90:93], v[44:47]
	s_waitcnt vmcnt(0)
	ds_write_b128 v20, v[190:193] offset:32768
	v_mfma_f32_16x16x32_f16 v[78:81], v[74:77], v[110:113], v[78:81]
	v_mfma_f32_16x16x32_f16 v[82:85], v[118:121], v[90:93], v[82:85]
	v_mfma_f32_16x16x32_f16 v[86:89], v[118:121], v[110:113], v[86:89]
	s_waitcnt lgkmcnt(2)
	v_mfma_f32_16x16x32_f16 v[28:31], v[122:125], v[90:93], v[28:31]
	ds_read_b128 v[90:93], v23 offset:20480
	v_mfma_f32_16x16x32_f16 v[32:35], v[122:125], v[110:113], v[32:35]
	ds_read_b128 v[110:113], v23 offset:22528
	s_waitcnt lgkmcnt(1)
	v_mfma_f32_16x16x32_f16 v[98:101], v[62:65], v[90:93], v[98:101]
	s_waitcnt lgkmcnt(0)
	v_mfma_f32_16x16x32_f16 v[52:55], v[62:65], v[110:113], v[52:55]
	global_load_dwordx4 v[62:65], v[0:1], off offset:1408
	v_mfma_f32_16x16x32_f16 v[102:105], v[74:77], v[90:93], v[102:105]
	v_mfma_f32_16x16x32_f16 v[24:27], v[74:77], v[110:113], v[24:27]
	v_mfma_f32_16x16x32_f16 v[114:117], v[118:121], v[90:93], v[114:117]
	v_mfma_f32_16x16x32_f16 v[40:43], v[118:121], v[110:113], v[40:43]
	v_mfma_f32_16x16x32_f16 v[70:73], v[122:125], v[90:93], v[70:73]
	global_load_dwordx4 v[90:93], v[2:3], off offset:1408
	global_load_dwordx4 v[126:129], v[4:5], off offset:1408
	global_load_dwordx4 v[130:133], v[14:15], off offset:1408
	global_load_dwordx4 v[74:77], v[10:11], off offset:1408
	global_load_dwordx4 v[138:141], v[12:13], off offset:1408
	global_load_dwordx4 v[142:145], v[8:9], off offset:1408
	global_load_dwordx4 v[154:157], v[6:7], off offset:1408
	s_waitcnt lgkmcnt(0)
	s_barrier
	v_mfma_f32_16x16x32_f16 v[48:51], v[122:125], v[110:113], v[48:51]
	ds_read_b128 v[58:61], v16 offset:32768
	ds_read_b128 v[106:109], v21
	s_waitcnt lgkmcnt(0)
	v_mfma_f32_16x16x32_f16 v[36:39], v[58:61], v[106:109], v[36:39]
	ds_read_b128 v[94:97], v16 offset:34816
	ds_read_b128 v[110:113], v21 offset:2048
	s_waitcnt lgkmcnt(0)
	v_mfma_f32_16x16x32_f16 v[66:69], v[58:61], v[110:113], v[66:69]
	ds_read_b128 v[118:121], v16 offset:36864
	v_mfma_f32_16x16x32_f16 v[44:47], v[94:97], v[106:109], v[44:47]
	ds_read_b128 v[122:125], v16 offset:38912
	v_mfma_f32_16x16x32_f16 v[78:81], v[94:97], v[110:113], v[78:81]
	s_waitcnt vmcnt(7)
	ds_write_b128 v17, v[62:65] offset:16384
	s_waitcnt lgkmcnt(2)
	v_mfma_f32_16x16x32_f16 v[82:85], v[118:121], v[106:109], v[82:85]
	s_waitcnt vmcnt(6)
	ds_write_b128 v18, v[90:93] offset:16384
	v_mfma_f32_16x16x32_f16 v[86:89], v[118:121], v[110:113], v[86:89]
	s_waitcnt vmcnt(5)
	ds_write_b128 v19, v[126:129] offset:16384
	s_waitcnt lgkmcnt(3)
	v_mfma_f32_16x16x32_f16 v[28:31], v[122:125], v[106:109], v[28:31]
	ds_read_b128 v[106:109], v21 offset:4096
	v_mfma_f32_16x16x32_f16 v[32:35], v[122:125], v[110:113], v[32:35]
	ds_read_b128 v[110:113], v21 offset:6144
	s_waitcnt lgkmcnt(1)
	v_mfma_f32_16x16x32_f16 v[98:101], v[58:61], v[106:109], v[98:101]
	s_waitcnt vmcnt(4)
	ds_write_b128 v20, v[130:133] offset:16384
	s_waitcnt lgkmcnt(1)
	v_mfma_f32_16x16x32_f16 v[52:55], v[58:61], v[110:113], v[52:55]
	ds_read_b128 v[58:61], v22 offset:32768
	v_mfma_f32_16x16x32_f16 v[102:105], v[94:97], v[106:109], v[102:105]
	s_waitcnt vmcnt(3)
	ds_write_b128 v17, v[74:77] offset:49152
	v_mfma_f32_16x16x32_f16 v[24:27], v[94:97], v[110:113], v[24:27]
	ds_read_b128 v[94:97], v22 offset:34816
	v_mfma_f32_16x16x32_f16 v[114:117], v[118:121], v[106:109], v[114:117]
	s_waitcnt vmcnt(2)
	ds_write_b128 v18, v[138:141] offset:49152
	v_mfma_f32_16x16x32_f16 v[40:43], v[118:121], v[110:113], v[40:43]
	ds_read_b128 v[118:121], v22 offset:36864
	v_mfma_f32_16x16x32_f16 v[70:73], v[122:125], v[106:109], v[70:73]
	ds_read_b128 v[106:109], v23
	v_mfma_f32_16x16x32_f16 v[48:51], v[122:125], v[110:113], v[48:51]
	ds_read_b128 v[110:113], v23 offset:2048
	s_waitcnt lgkmcnt(1)
	v_mfma_f32_16x16x32_f16 v[36:39], v[58:61], v[106:109], v[36:39]
	ds_read_b128 v[122:125], v22 offset:38912
	s_waitcnt lgkmcnt(1)
	v_mfma_f32_16x16x32_f16 v[66:69], v[58:61], v[110:113], v[66:69]
	s_waitcnt vmcnt(1)
	ds_write_b128 v19, v[142:145] offset:49152
	v_mfma_f32_16x16x32_f16 v[44:47], v[94:97], v[106:109], v[44:47]
	s_waitcnt vmcnt(0)
	ds_write_b128 v20, v[154:157] offset:49152
	v_mfma_f32_16x16x32_f16 v[78:81], v[94:97], v[110:113], v[78:81]
	v_mfma_f32_16x16x32_f16 v[82:85], v[118:121], v[106:109], v[82:85]
	v_mfma_f32_16x16x32_f16 v[86:89], v[118:121], v[110:113], v[86:89]
	s_waitcnt lgkmcnt(2)
	v_mfma_f32_16x16x32_f16 v[28:31], v[122:125], v[106:109], v[28:31]
	ds_read_b128 v[106:109], v23 offset:4096
	v_mfma_f32_16x16x32_f16 v[32:35], v[122:125], v[110:113], v[32:35]
	ds_read_b128 v[110:113], v23 offset:6144
	s_waitcnt lgkmcnt(1)
	v_mfma_f32_16x16x32_f16 v[98:101], v[58:61], v[106:109], v[98:101]
	s_waitcnt lgkmcnt(0)
	v_mfma_f32_16x16x32_f16 v[52:55], v[58:61], v[110:113], v[52:55]
	global_load_dwordx4 v[58:61], v[0:1], off offset:1536
	v_mfma_f32_16x16x32_f16 v[102:105], v[94:97], v[106:109], v[102:105]
	v_mfma_f32_16x16x32_f16 v[24:27], v[94:97], v[110:113], v[24:27]
	v_mfma_f32_16x16x32_f16 v[114:117], v[118:121], v[106:109], v[114:117]
	v_mfma_f32_16x16x32_f16 v[40:43], v[118:121], v[110:113], v[40:43]
	v_mfma_f32_16x16x32_f16 v[70:73], v[122:125], v[106:109], v[70:73]
	global_load_dwordx4 v[106:109], v[2:3], off offset:1536
	global_load_dwordx4 v[134:137], v[4:5], off offset:1536
	global_load_dwordx4 v[158:161], v[14:15], off offset:1536
	global_load_dwordx4 v[94:97], v[10:11], off offset:1536
	global_load_dwordx4 v[162:165], v[12:13], off offset:1536
	global_load_dwordx4 v[166:169], v[8:9], off offset:1536
	global_load_dwordx4 v[190:193], v[6:7], off offset:1536
	s_waitcnt lgkmcnt(0)
	s_barrier
; #define GL_LOAD(s_, kt_) if (VAR != 1) { a##s_##0 = GL_A(0, kt_); a##s_##1 = GL_A(1, kt_); a##s_##2 = GL_A(2, kt_); a##s_##3 = GL_A(3, kt_); b##s_##0 = GL_B(0, kt_); b##s_##1 = GL_B(1, kt_); b##s_##2 = GL_B(2, kt_); b##s_##3 = GL_B(3, kt_); }
; #define LDS_STORE(s_, buf_) if (VAR != 2) { LDS_ST1(sA, 0, buf_, a##s_##0) LDS_ST1(sA, 1, buf_, a##s_##1) LDS_ST1(sA, 2, buf_, a##s_##2) LDS_ST1(sA, 3, buf_, a##s_##3) LDS_ST1(sB, 0, buf_, b##s_##0) LDS_ST1(sB, 1, buf_, b##s_##1) LDS_ST1(sB, 2, buf_, b##s_##2) LDS_ST1(sB, 3, buf_, b##s_##3) }
;     ...
;   GL_LOAD(0, 0)
;   GL_LOAD(1, 1)
;   LDS_STORE(0, 0)
;   if (VAR != 4) __syncthreads();
; #pragma unroll
;   for (int kt = 0; kt < nk; kt += 2) {
;     if (kt + 2 < nk) { GL_LOAD(0, kt + 2) }
;     MMA_TILE(0)
;     LDS_STORE(1, 1)
;     if (VAR != 4) __syncthreads();
;     if (kt + 3 < nk) { GL_LOAD(1, kt + 3) }
;     MMA_TILE(1)
;     if (kt + 2 < nk) { LDS_STORE(0, 0) }
;     if (VAR != 4) __syncthreads();
	v_mfma_f32_16x16x32_f16 v[48:51], v[122:125], v[110:113], v[48:51]
	ds_read_b128 v[62:65], v16 offset:49152
	ds_read_b128 v[90:93], v21 offset:16384
	s_waitcnt lgkmcnt(0)
	v_mfma_f32_16x16x32_f16 v[36:39], v[62:65], v[90:93], v[36:39]
	ds_read_b128 v[74:77], v16 offset:51200
	ds_read_b128 v[110:113], v21 offset:18432
	s_waitcnt lgkmcnt(0)
	v_mfma_f32_16x16x32_f16 v[66:69], v[62:65], v[110:113], v[66:69]
	ds_read_b128 v[118:121], v16 offset:53248
	v_mfma_f32_16x16x32_f16 v[44:47], v[74:77], v[90:93], v[44:47]
	ds_read_b128 v[122:125], v16 offset:55296
	v_mfma_f32_16x16x32_f16 v[78:81], v[74:77], v[110:113], v[78:81]
	s_waitcnt vmcnt(7)
	ds_write_b128 v17, v[58:61]
	s_waitcnt lgkmcnt(2)
	v_mfma_f32_16x16x32_f16 v[82:85], v[118:121], v[90:93], v[82:85]
	s_waitcnt vmcnt(6)
	ds_write_b128 v18, v[106:109]
	v_mfma_f32_16x16x32_f16 v[86:89], v[118:121], v[110:113], v[86:89]
	s_waitcnt vmcnt(5)
	ds_write_b128 v19, v[134:137]
	s_waitcnt lgkmcnt(3)
	v_mfma_f32_16x16x32_f16 v[28:31], v[122:125], v[90:93], v[28:31]
	ds_read_b128 v[90:93], v21 offset:20480
	v_mfma_f32_16x16x32_f16 v[32:35], v[122:125], v[110:113], v[32:35]
	ds_read_b128 v[110:113], v21 offset:22528
	s_waitcnt lgkmcnt(1)
	v_mfma_f32_16x16x32_f16 v[98:101], v[62:65], v[90:93], v[98:101]
	s_waitcnt vmcnt(4)
	ds_write_b128 v20, v[158:161]
	s_waitcnt lgkmcnt(1)
	v_mfma_f32_16x16x32_f16 v[52:55], v[62:65], v[110:113], v[52:55]
	ds_read_b128 v[62:65], v22 offset:49152
	v_mfma_f32_16x16x32_f16 v[102:105], v[74:77], v[90:93], v[102:105]
	s_waitcnt vmcnt(3)
	ds_write_b128 v17, v[94:97] offset:32768
	v_mfma_f32_16x16x32_f16 v[24:27], v[74:77], v[110:113], v[24:27]
	ds_read_b128 v[74:77], v22 offset:51200
	v_mfma_f32_16x16x32_f16 v[114:117], v[118:121], v[90:93], v[114:117]
	s_waitcnt vmcnt(2)
	ds_write_b128 v18, v[162:165] offset:32768
	v_mfma_f32_16x16x32_f16 v[40:43], v[118:121], v[110:113], v[40:43]
	ds_read_b128 v[118:121], v22 offset:53248
	v_mfma_f32_16x16x32_f16 v[70:73], v[122:125], v[90:93], v[70:73]
	ds_read_b128 v[90:93], v23 offset:16384
	v_mfma_f32_16x16x32_f16 v[48:51], v[122:125], v[110:113], v[48:51]
	ds_read_b128 v[110:113], v23 offset:18432
	s_waitcnt lgkmcnt(1)
	v_mfma_f32_16x16x32_f16 v[36:39], v[62:65], v[90:93], v[36:39]
	ds_read_b128 v[122:125], v22 offset:55296
	s_waitcnt lgkmcnt(1)
	v_mfma_f32_16x16x32_f16 v[66:69], v[62:65], v[110:113], v[66:69]
	s_waitcnt vmcnt(1)
	ds_write_b128 v19, v[166:169] offset:32768
	v_mfma_f32_16x16x32_f16 v[44:47], v[74:77], v[90:93], v[44:47]
	s_waitcnt vmcnt(0)
	ds_write_b128 v20, v[190:193] offset:32768
	v_mfma_f32_16x16x32_f16 v[78:81], v[74:77], v[110:113], v[78:81]
	v_mfma_f32_16x16x32_f16 v[82:85], v[118:121], v[90:93], v[82:85]
	v_mfma_f32_16x16x32_f16 v[86:89], v[118:121], v[110:113], v[86:89]
	s_waitcnt lgkmcnt(2)
	v_mfma_f32_16x16x32_f16 v[28:31], v[122:125], v[90:93], v[28:31]
	ds_read_b128 v[90:93], v23 offset:20480
	v_mfma_f32_16x16x32_f16 v[32:35], v[122:125], v[110:113], v[32:35]
	ds_read_b128 v[110:113], v23 offset:22528
	s_waitcnt lgkmcnt(1)
	v_mfma_f32_16x16x32_f16 v[98:101], v[62:65], v[90:93], v[98:101]
	s_waitcnt lgkmcnt(0)
	v_mfma_f32_16x16x32_f16 v[52:55], v[62:65], v[110:113], v[52:55]
	global_load_dwordx4 v[62:65], v[0:1], off offset:1664
	v_mfma_f32_16x16x32_f16 v[102:105], v[74:77], v[90:93], v[102:105]
	v_mfma_f32_16x16x32_f16 v[24:27], v[74:77], v[110:113], v[24:27]
	v_mfma_f32_16x16x32_f16 v[114:117], v[118:121], v[90:93], v[114:117]
	v_mfma_f32_16x16x32_f16 v[40:43], v[118:121], v[110:113], v[40:43]
	v_mfma_f32_16x16x32_f16 v[70:73], v[122:125], v[90:93], v[70:73]
	global_load_dwordx4 v[90:93], v[2:3], off offset:1664
	global_load_dwordx4 v[126:129], v[4:5], off offset:1664
	global_load_dwordx4 v[130:133], v[14:15], off offset:1664
	global_load_dwordx4 v[74:77], v[10:11], off offset:1664
	global_load_dwordx4 v[138:141], v[12:13], off offset:1664
	global_load_dwordx4 v[142:145], v[8:9], off offset:1664
	global_load_dwordx4 v[154:157], v[6:7], off offset:1664
	s_waitcnt lgkmcnt(0)
	s_barrier
	v_mfma_f32_16x16x32_f16 v[48:51], v[122:125], v[110:113], v[48:51]
	ds_read_b128 v[58:61], v16 offset:32768
	ds_read_b128 v[106:109], v21
	s_waitcnt lgkmcnt(0)
	v_mfma_f32_16x16x32_f16 v[36:39], v[58:61], v[106:109], v[36:39]
	ds_read_b128 v[94:97], v16 offset:34816
	ds_read_b128 v[110:113], v21 offset:2048
	s_waitcnt lgkmcnt(0)
	v_mfma_f32_16x16x32_f16 v[66:69], v[58:61], v[110:113], v[66:69]
	ds_read_b128 v[118:121], v16 offset:36864
	v_mfma_f32_16x16x32_f16 v[44:47], v[94:97], v[106:109], v[44:47]
	ds_read_b128 v[122:125], v16 offset:38912
	v_mfma_f32_16x16x32_f16 v[78:81], v[94:97], v[110:113], v[78:81]
	s_waitcnt vmcnt(7)
	ds_write_b128 v17, v[62:65] offset:16384
	s_waitcnt lgkmcnt(2)
	v_mfma_f32_16x16x32_f16 v[82:85], v[118:121], v[106:109], v[82:85]
	s_waitcnt vmcnt(6)
	ds_write_b128 v18, v[90:93] offset:16384
	v_mfma_f32_16x16x32_f16 v[86:89], v[118:121], v[110:113], v[86:89]
	s_waitcnt vmcnt(5)
	ds_write_b128 v19, v[126:129] offset:16384
	s_waitcnt lgkmcnt(3)
	v_mfma_f32_16x16x32_f16 v[28:31], v[122:125], v[106:109], v[28:31]
	ds_read_b128 v[106:109], v21 offset:4096
	v_mfma_f32_16x16x32_f16 v[32:35], v[122:125], v[110:113], v[32:35]
	ds_read_b128 v[110:113], v21 offset:6144
	s_waitcnt lgkmcnt(1)
	v_mfma_f32_16x16x32_f16 v[98:101], v[58:61], v[106:109], v[98:101]
	s_waitcnt vmcnt(4)
	ds_write_b128 v20, v[130:133] offset:16384
	s_waitcnt lgkmcnt(1)
	v_mfma_f32_16x16x32_f16 v[52:55], v[58:61], v[110:113], v[52:55]
	ds_read_b128 v[58:61], v22 offset:32768
	v_mfma_f32_16x16x32_f16 v[102:105], v[94:97], v[106:109], v[102:105]
	s_waitcnt vmcnt(3)
; #define GL_LOAD(s_, kt_) if (VAR != 1) { a##s_##0 = GL_A(0, kt_); a##s_##1 = GL_A(1, kt_); a##s_##2 = GL_A(2, kt_); a##s_##3 = GL_A(3, kt_); b##s_##0 = GL_B(0, kt_); b##s_##1 = GL_B(1, kt_); b##s_##2 = GL_B(2, kt_); b##s_##3 = GL_B(3, kt_); }
; #define LDS_STORE(s_, buf_) if (VAR != 2) { LDS_ST1(sA, 0, buf_, a##s_##0) LDS_ST1(sA, 1, buf_, a##s_##1) LDS_ST1(sA, 2, buf_, a##s_##2) LDS_ST1(sA, 3, buf_, a##s_##3) LDS_ST1(sB, 0, buf_, b##s_##0) LDS_ST1(sB, 1, buf_, b##s_##1) LDS_ST1(sB, 2, buf_, b##s_##2) LDS_ST1(sB, 3, buf_, b##s_##3) }
;     ...
;   GL_LOAD(0, 0)
;   GL_LOAD(1, 1)
;   LDS_STORE(0, 0)
;   if (VAR != 4) __syncthreads();
; #pragma unroll
;   for (int kt = 0; kt < nk; kt += 2) {
;     if (kt + 2 < nk) { GL_LOAD(0, kt + 2) }
;     MMA_TILE(0)
;     LDS_STORE(1, 1)
;     if (VAR != 4) __syncthreads();
;     if (kt + 3 < nk) { GL_LOAD(1, kt + 3) }
;     MMA_TILE(1)
;     if (kt + 2 < nk) { LDS_STORE(0, 0) }
;     if (VAR != 4) __syncthreads();
	ds_write_b128 v17, v[74:77] offset:49152
	v_mfma_f32_16x16x32_f16 v[24:27], v[94:97], v[110:113], v[24:27]
	ds_read_b128 v[94:97], v22 offset:34816
	v_mfma_f32_16x16x32_f16 v[114:117], v[118:121], v[106:109], v[114:117]
	s_waitcnt vmcnt(2)
	ds_write_b128 v18, v[138:141] offset:49152
	v_mfma_f32_16x16x32_f16 v[40:43], v[118:121], v[110:113], v[40:43]
	ds_read_b128 v[118:121], v22 offset:36864
	v_mfma_f32_16x16x32_f16 v[70:73], v[122:125], v[106:109], v[70:73]
	ds_read_b128 v[106:109], v23
	v_mfma_f32_16x16x32_f16 v[48:51], v[122:125], v[110:113], v[48:51]
	ds_read_b128 v[110:113], v23 offset:2048
	s_waitcnt lgkmcnt(1)
	v_mfma_f32_16x16x32_f16 v[36:39], v[58:61], v[106:109], v[36:39]
	ds_read_b128 v[122:125], v22 offset:38912
	s_waitcnt lgkmcnt(1)
	v_mfma_f32_16x16x32_f16 v[66:69], v[58:61], v[110:113], v[66:69]
	s_waitcnt vmcnt(1)
	ds_write_b128 v19, v[142:145] offset:49152
	v_mfma_f32_16x16x32_f16 v[44:47], v[94:97], v[106:109], v[44:47]
	s_waitcnt vmcnt(0)
	ds_write_b128 v20, v[154:157] offset:49152
	v_mfma_f32_16x16x32_f16 v[78:81], v[94:97], v[110:113], v[78:81]
	v_mfma_f32_16x16x32_f16 v[82:85], v[118:121], v[106:109], v[82:85]
	v_mfma_f32_16x16x32_f16 v[86:89], v[118:121], v[110:113], v[86:89]
	s_waitcnt lgkmcnt(2)
	v_mfma_f32_16x16x32_f16 v[28:31], v[122:125], v[106:109], v[28:31]
	ds_read_b128 v[106:109], v23 offset:4096
	v_mfma_f32_16x16x32_f16 v[32:35], v[122:125], v[110:113], v[32:35]
	ds_read_b128 v[110:113], v23 offset:6144
	s_waitcnt lgkmcnt(1)
	v_mfma_f32_16x16x32_f16 v[98:101], v[58:61], v[106:109], v[98:101]
	s_waitcnt lgkmcnt(0)
	v_mfma_f32_16x16x32_f16 v[52:55], v[58:61], v[110:113], v[52:55]
	global_load_dwordx4 v[58:61], v[0:1], off offset:1792
	v_mfma_f32_16x16x32_f16 v[102:105], v[94:97], v[106:109], v[102:105]
	v_mfma_f32_16x16x32_f16 v[24:27], v[94:97], v[110:113], v[24:27]
	v_mfma_f32_16x16x32_f16 v[114:117], v[118:121], v[106:109], v[114:117]
	v_mfma_f32_16x16x32_f16 v[40:43], v[118:121], v[110:113], v[40:43]
	v_mfma_f32_16x16x32_f16 v[70:73], v[122:125], v[106:109], v[70:73]
	global_load_dwordx4 v[106:109], v[2:3], off offset:1792
	global_load_dwordx4 v[134:137], v[4:5], off offset:1792
	global_load_dwordx4 v[158:161], v[14:15], off offset:1792
	global_load_dwordx4 v[94:97], v[10:11], off offset:1792
	global_load_dwordx4 v[162:165], v[12:13], off offset:1792
	global_load_dwordx4 v[166:169], v[8:9], off offset:1792
	global_load_dwordx4 v[190:193], v[6:7], off offset:1792
	s_waitcnt lgkmcnt(0)
	s_barrier
	v_mfma_f32_16x16x32_f16 v[48:51], v[122:125], v[110:113], v[48:51]
	ds_read_b128 v[62:65], v16 offset:49152
	ds_read_b128 v[90:93], v21 offset:16384
	s_waitcnt lgkmcnt(0)
	v_mfma_f32_16x16x32_f16 v[36:39], v[62:65], v[90:93], v[36:39]
	ds_read_b128 v[74:77], v16 offset:51200
	ds_read_b128 v[110:113], v21 offset:18432
	s_waitcnt lgkmcnt(0)
	v_mfma_f32_16x16x32_f16 v[66:69], v[62:65], v[110:113], v[66:69]
	ds_read_b128 v[118:121], v16 offset:53248
	v_mfma_f32_16x16x32_f16 v[44:47], v[74:77], v[90:93], v[44:47]
	ds_read_b128 v[122:125], v16 offset:55296
	v_mfma_f32_16x16x32_f16 v[78:81], v[74:77], v[110:113], v[78:81]
	s_waitcnt vmcnt(7)
	ds_write_b128 v17, v[58:61]
	s_waitcnt lgkmcnt(2)
	v_mfma_f32_16x16x32_f16 v[82:85], v[118:121], v[90:93], v[82:85]
	s_waitcnt vmcnt(6)
	ds_write_b128 v18, v[106:109]
	v_mfma_f32_16x16x32_f16 v[86:89], v[118:121], v[110:113], v[86:89]
	s_waitcnt vmcnt(5)
	ds_write_b128 v19, v[134:137]
	s_waitcnt lgkmcnt(3)
	v_mfma_f32_16x16x32_f16 v[28:31], v[122:125], v[90:93], v[28:31]
	ds_read_b128 v[90:93], v21 offset:20480
	v_mfma_f32_16x16x32_f16 v[32:35], v[122:125], v[110:113], v[32:35]
	ds_read_b128 v[110:113], v21 offset:22528
	s_waitcnt lgkmcnt(1)
	v_mfma_f32_16x16x32_f16 v[98:101], v[62:65], v[90:93], v[98:101]
	s_waitcnt vmcnt(4)
	ds_write_b128 v20, v[158:161]
	s_waitcnt lgkmcnt(1)
	v_mfma_f32_16x16x32_f16 v[52:55], v[62:65], v[110:113], v[52:55]
	ds_read_b128 v[62:65], v22 offset:49152
	v_mfma_f32_16x16x32_f16 v[102:105], v[74:77], v[90:93], v[102:105]
	s_waitcnt vmcnt(3)
	ds_write_b128 v17, v[94:97] offset:32768
	v_mfma_f32_16x16x32_f16 v[24:27], v[74:77], v[110:113], v[24:27]
	ds_read_b128 v[74:77], v22 offset:51200
	v_mfma_f32_16x16x32_f16 v[114:117], v[118:121], v[90:93], v[114:117]
	s_waitcnt vmcnt(2)
	ds_write_b128 v18, v[162:165] offset:32768
	v_mfma_f32_16x16x32_f16 v[40:43], v[118:121], v[110:113], v[40:43]
	ds_read_b128 v[118:121], v22 offset:53248
	v_mfma_f32_16x16x32_f16 v[70:73], v[122:125], v[90:93], v[70:73]
	ds_read_b128 v[90:93], v23 offset:16384
	v_mfma_f32_16x16x32_f16 v[48:51], v[122:125], v[110:113], v[48:51]
	ds_read_b128 v[110:113], v23 offset:18432
	s_waitcnt lgkmcnt(1)
	v_mfma_f32_16x16x32_f16 v[36:39], v[62:65], v[90:93], v[36:39]
	ds_read_b128 v[122:125], v22 offset:55296
	s_waitcnt lgkmcnt(1)
	v_mfma_f32_16x16x32_f16 v[66:69], v[62:65], v[110:113], v[66:69]
	s_waitcnt vmcnt(1)
	ds_write_b128 v19, v[166:169] offset:32768
	v_mfma_f32_16x16x32_f16 v[44:47], v[74:77], v[90:93], v[44:47]
	s_waitcnt vmcnt(0)
	ds_write_b128 v20, v[190:193] offset:32768
	v_mfma_f32_16x16x32_f16 v[78:81], v[74:77], v[110:113], v[78:81]
	v_mfma_f32_16x16x32_f16 v[82:85], v[118:121], v[90:93], v[82:85]
	v_mfma_f32_16x16x32_f16 v[86:89], v[118:121], v[110:113], v[86:89]
	s_waitcnt lgkmcnt(2)
	v_mfma_f32_16x16x32_f16 v[28:31], v[122:125], v[90:93], v[28:31]
	ds_read_b128 v[90:93], v23 offset:20480
	v_mfma_f32_16x16x32_f16 v[32:35], v[122:125], v[110:113], v[32:35]
	ds_read_b128 v[110:113], v23 offset:22528
	s_waitcnt lgkmcnt(1)
	v_mfma_f32_16x16x32_f16 v[98:101], v[62:65], v[90:93], v[98:101]
	s_waitcnt lgkmcnt(0)
	v_mfma_f32_16x16x32_f16 v[52:55], v[62:65], v[110:113], v[52:55]
	global_load_dwordx4 v[62:65], v[0:1], off offset:1920
	v_mfma_f32_16x16x32_f16 v[102:105], v[74:77], v[90:93], v[102:105]
	v_mfma_f32_16x16x32_f16 v[24:27], v[74:77], v[110:113], v[24:27]
	v_mfma_f32_16x16x32_f16 v[114:117], v[118:121], v[90:93], v[114:117]
	v_mfma_f32_16x16x32_f16 v[40:43], v[118:121], v[110:113], v[40:43]
	v_mfma_f32_16x16x32_f16 v[70:73], v[122:125], v[90:93], v[70:73]
	global_load_dwordx4 v[90:93], v[2:3], off offset:1920
	global_load_dwordx4 v[126:129], v[4:5], off offset:1920
	global_load_dwordx4 v[130:133], v[14:15], off offset:1920
	global_load_dwordx4 v[74:77], v[10:11], off offset:1920
	global_load_dwordx4 v[138:141], v[12:13], off offset:1920
	global_load_dwordx4 v[142:145], v[8:9], off offset:1920
	global_load_dwordx4 v[154:157], v[6:7], off offset:1920
	s_waitcnt lgkmcnt(0)
	s_barrier
; #define GL_LOAD(s_, kt_) if (VAR != 1) { a##s_##0 = GL_A(0, kt_); a##s_##1 = GL_A(1, kt_); a##s_##2 = GL_A(2, kt_); a##s_##3 = GL_A(3, kt_); b##s_##0 = GL_B(0, kt_); b##s_##1 = GL_B(1, kt_); b##s_##2 = GL_B(2, kt_); b##s_##3 = GL_B(3, kt_); }
; #define LDS_STORE(s_, buf_) if (VAR != 2) { LDS_ST1(sA, 0, buf_, a##s_##0) LDS_ST1(sA, 1, buf_, a##s_##1) LDS_ST1(sA, 2, buf_, a##s_##2) LDS_ST1(sA, 3, buf_, a##s_##3) LDS_ST1(sB, 0, buf_, b##s_##0) LDS_ST1(sB, 1, buf_, b##s_##1) LDS_ST1(sB, 2, buf_, b##s_##2) LDS_ST1(sB, 3, buf_, b##s_##3) }
;     ...
;   GL_LOAD(0, 0)
;   GL_LOAD(1, 1)
;   LDS_STORE(0, 0)
;   if (VAR != 4) __syncthreads();
; #pragma unroll
;   for (int kt = 0; kt < nk; kt += 2) {
;     if (kt + 2 < nk) { GL_LOAD(0, kt + 2) }
;     MMA_TILE(0)
;     LDS_STORE(1, 1)
;     if (VAR != 4) __syncthreads();
;     if (kt + 3 < nk) { GL_LOAD(1, kt + 3) }
;     MMA_TILE(1)
;     if (kt + 2 < nk) { LDS_STORE(0, 0) }
;     if (VAR != 4) __syncthreads();
	v_mfma_f32_16x16x32_f16 v[48:51], v[122:125], v[110:113], v[48:51]
	ds_read_b128 v[58:61], v16 offset:32768
	ds_read_b128 v[106:109], v21
	s_waitcnt lgkmcnt(0)
	v_mfma_f32_16x16x32_f16 v[36:39], v[58:61], v[106:109], v[36:39]
	ds_read_b128 v[94:97], v16 offset:34816
	ds_read_b128 v[110:113], v21 offset:2048
	s_waitcnt lgkmcnt(0)
	v_mfma_f32_16x16x32_f16 v[66:69], v[58:61], v[110:113], v[66:69]
	ds_read_b128 v[118:121], v16 offset:36864
	v_mfma_f32_16x16x32_f16 v[44:47], v[94:97], v[106:109], v[44:47]
	ds_read_b128 v[122:125], v16 offset:38912
	v_mfma_f32_16x16x32_f16 v[78:81], v[94:97], v[110:113], v[78:81]
	s_waitcnt vmcnt(7)
	ds_write_b128 v17, v[62:65] offset:16384
	s_waitcnt lgkmcnt(2)
	v_mfma_f32_16x16x32_f16 v[82:85], v[118:121], v[106:109], v[82:85]
	s_waitcnt vmcnt(6)
	ds_write_b128 v18, v[90:93] offset:16384
	v_mfma_f32_16x16x32_f16 v[86:89], v[118:121], v[110:113], v[86:89]
	s_waitcnt vmcnt(5)
	ds_write_b128 v19, v[126:129] offset:16384
	s_waitcnt lgkmcnt(3)
	v_mfma_f32_16x16x32_f16 v[28:31], v[122:125], v[106:109], v[28:31]
	ds_read_b128 v[106:109], v21 offset:4096
	v_mfma_f32_16x16x32_f16 v[32:35], v[122:125], v[110:113], v[32:35]
	ds_read_b128 v[110:113], v21 offset:6144
	s_waitcnt lgkmcnt(1)
	v_mfma_f32_16x16x32_f16 v[98:101], v[58:61], v[106:109], v[98:101]
	s_waitcnt vmcnt(4)
	ds_write_b128 v20, v[130:133] offset:16384
	s_waitcnt lgkmcnt(1)
	v_mfma_f32_16x16x32_f16 v[52:55], v[58:61], v[110:113], v[52:55]
	ds_read_b128 v[58:61], v22 offset:32768
	v_mfma_f32_16x16x32_f16 v[102:105], v[94:97], v[106:109], v[102:105]
	s_waitcnt vmcnt(3)
	ds_write_b128 v17, v[74:77] offset:49152
	v_mfma_f32_16x16x32_f16 v[24:27], v[94:97], v[110:113], v[24:27]
	ds_read_b128 v[94:97], v22 offset:34816
	v_mfma_f32_16x16x32_f16 v[114:117], v[118:121], v[106:109], v[114:117]
	s_waitcnt vmcnt(2)
	ds_write_b128 v18, v[138:141] offset:49152
	v_mfma_f32_16x16x32_f16 v[40:43], v[118:121], v[110:113], v[40:43]
	ds_read_b128 v[118:121], v22 offset:36864
	v_mfma_f32_16x16x32_f16 v[70:73], v[122:125], v[106:109], v[70:73]
	ds_read_b128 v[106:109], v23
	v_mfma_f32_16x16x32_f16 v[48:51], v[122:125], v[110:113], v[48:51]
	ds_read_b128 v[110:113], v23 offset:2048
	s_waitcnt lgkmcnt(1)
	v_mfma_f32_16x16x32_f16 v[36:39], v[58:61], v[106:109], v[36:39]
	ds_read_b128 v[122:125], v22 offset:38912
	s_waitcnt lgkmcnt(1)
	v_mfma_f32_16x16x32_f16 v[66:69], v[58:61], v[110:113], v[66:69]
	s_waitcnt vmcnt(1)
	ds_write_b128 v19, v[142:145] offset:49152
	v_mfma_f32_16x16x32_f16 v[44:47], v[94:97], v[106:109], v[44:47]
	s_waitcnt vmcnt(0)
	ds_write_b128 v20, v[154:157] offset:49152
	v_mfma_f32_16x16x32_f16 v[78:81], v[94:97], v[110:113], v[78:81]
	v_mfma_f32_16x16x32_f16 v[82:85], v[118:121], v[106:109], v[82:85]
	v_mfma_f32_16x16x32_f16 v[86:89], v[118:121], v[110:113], v[86:89]
	s_waitcnt lgkmcnt(2)
	v_mfma_f32_16x16x32_f16 v[28:31], v[122:125], v[106:109], v[28:31]
	ds_read_b128 v[106:109], v23 offset:4096
	v_mfma_f32_16x16x32_f16 v[32:35], v[122:125], v[110:113], v[32:35]
	ds_read_b128 v[110:113], v23 offset:6144
	s_waitcnt lgkmcnt(1)
	v_mfma_f32_16x16x32_f16 v[98:101], v[58:61], v[106:109], v[98:101]
	s_waitcnt lgkmcnt(0)
	v_mfma_f32_16x16x32_f16 v[52:55], v[58:61], v[110:113], v[52:55]
	global_load_dwordx4 v[58:61], v[0:1], off offset:2048
	v_mfma_f32_16x16x32_f16 v[102:105], v[94:97], v[106:109], v[102:105]
	v_mfma_f32_16x16x32_f16 v[24:27], v[94:97], v[110:113], v[24:27]
	v_mfma_f32_16x16x32_f16 v[114:117], v[118:121], v[106:109], v[114:117]
	v_mfma_f32_16x16x32_f16 v[40:43], v[118:121], v[110:113], v[40:43]
	v_mfma_f32_16x16x32_f16 v[70:73], v[122:125], v[106:109], v[70:73]
	global_load_dwordx4 v[106:109], v[2:3], off offset:2048
	global_load_dwordx4 v[134:137], v[4:5], off offset:2048
	global_load_dwordx4 v[158:161], v[14:15], off offset:2048
	global_load_dwordx4 v[94:97], v[10:11], off offset:2048
	global_load_dwordx4 v[162:165], v[12:13], off offset:2048
	global_load_dwordx4 v[166:169], v[8:9], off offset:2048
	global_load_dwordx4 v[190:193], v[6:7], off offset:2048
	s_waitcnt lgkmcnt(0)
	s_barrier
	v_mfma_f32_16x16x32_f16 v[48:51], v[122:125], v[110:113], v[48:51]
	ds_read_b128 v[62:65], v16 offset:49152
	ds_read_b128 v[90:93], v21 offset:16384
	s_waitcnt lgkmcnt(0)
	v_mfma_f32_16x16x32_f16 v[36:39], v[62:65], v[90:93], v[36:39]
	ds_read_b128 v[74:77], v16 offset:51200
	ds_read_b128 v[110:113], v21 offset:18432
	s_waitcnt lgkmcnt(0)
	v_mfma_f32_16x16x32_f16 v[66:69], v[62:65], v[110:113], v[66:69]
	ds_read_b128 v[118:121], v16 offset:53248
	v_mfma_f32_16x16x32_f16 v[44:47], v[74:77], v[90:93], v[44:47]
	ds_read_b128 v[122:125], v16 offset:55296
	v_mfma_f32_16x16x32_f16 v[78:81], v[74:77], v[110:113], v[78:81]
	s_waitcnt vmcnt(7)
	ds_write_b128 v17, v[58:61]
	s_waitcnt lgkmcnt(2)
	v_mfma_f32_16x16x32_f16 v[82:85], v[118:121], v[90:93], v[82:85]
	s_waitcnt vmcnt(6)
	ds_write_b128 v18, v[106:109]
	v_mfma_f32_16x16x32_f16 v[86:89], v[118:121], v[110:113], v[86:89]
	s_waitcnt vmcnt(5)
	ds_write_b128 v19, v[134:137]
	s_waitcnt lgkmcnt(3)
	v_mfma_f32_16x16x32_f16 v[28:31], v[122:125], v[90:93], v[28:31]
	ds_read_b128 v[90:93], v21 offset:20480
	v_mfma_f32_16x16x32_f16 v[32:35], v[122:125], v[110:113], v[32:35]
	ds_read_b128 v[110:113], v21 offset:22528
	s_waitcnt lgkmcnt(1)
	v_mfma_f32_16x16x32_f16 v[98:101], v[62:65], v[90:93], v[98:101]
	s_waitcnt vmcnt(4)
	ds_write_b128 v20, v[158:161]
	s_waitcnt lgkmcnt(1)
	v_mfma_f32_16x16x32_f16 v[52:55], v[62:65], v[110:113], v[52:55]
	ds_read_b128 v[62:65], v22 offset:49152
	v_mfma_f32_16x16x32_f16 v[102:105], v[74:77], v[90:93], v[102:105]
	s_waitcnt vmcnt(3)
; #define GL_LOAD(s_, kt_) if (VAR != 1) { a##s_##0 = GL_A(0, kt_); a##s_##1 = GL_A(1, kt_); a##s_##2 = GL_A(2, kt_); a##s_##3 = GL_A(3, kt_); b##s_##0 = GL_B(0, kt_); b##s_##1 = GL_B(1, kt_); b##s_##2 = GL_B(2, kt_); b##s_##3 = GL_B(3, kt_); }
; #define LDS_STORE(s_, buf_) if (VAR != 2) { LDS_ST1(sA, 0, buf_, a##s_##0) LDS_ST1(sA, 1, buf_, a##s_##1) LDS_ST1(sA, 2, buf_, a##s_##2) LDS_ST1(sA, 3, buf_, a##s_##3) LDS_ST1(sB, 0, buf_, b##s_##0) LDS_ST1(sB, 1, buf_, b##s_##1) LDS_ST1(sB, 2, buf_, b##s_##2) LDS_ST1(sB, 3, buf_, b##s_##3) }
;     ...
;   GL_LOAD(0, 0)
;   GL_LOAD(1, 1)
;   LDS_STORE(0, 0)
;   if (VAR != 4) __syncthreads();
; #pragma unroll
;   for (int kt = 0; kt < nk; kt += 2) {
;     if (kt + 2 < nk) { GL_LOAD(0, kt + 2) }
;     MMA_TILE(0)
;     LDS_STORE(1, 1)
;     if (VAR != 4) __syncthreads();
;     if (kt + 3 < nk) { GL_LOAD(1, kt + 3) }
;     MMA_TILE(1)
;     if (kt + 2 < nk) { LDS_STORE(0, 0) }
;     if (VAR != 4) __syncthreads();
	ds_write_b128 v17, v[94:97] offset:32768
	v_mfma_f32_16x16x32_f16 v[24:27], v[74:77], v[110:113], v[24:27]
	ds_read_b128 v[74:77], v22 offset:51200
	v_mfma_f32_16x16x32_f16 v[114:117], v[118:121], v[90:93], v[114:117]
	s_waitcnt vmcnt(2)
	ds_write_b128 v18, v[162:165] offset:32768
	v_mfma_f32_16x16x32_f16 v[40:43], v[118:121], v[110:113], v[40:43]
	ds_read_b128 v[118:121], v22 offset:53248
	v_mfma_f32_16x16x32_f16 v[70:73], v[122:125], v[90:93], v[70:73]
	ds_read_b128 v[90:93], v23 offset:16384
	v_mfma_f32_16x16x32_f16 v[48:51], v[122:125], v[110:113], v[48:51]
	ds_read_b128 v[110:113], v23 offset:18432
	s_waitcnt lgkmcnt(1)
	v_mfma_f32_16x16x32_f16 v[36:39], v[62:65], v[90:93], v[36:39]
	ds_read_b128 v[122:125], v22 offset:55296
	s_waitcnt lgkmcnt(1)
	v_mfma_f32_16x16x32_f16 v[66:69], v[62:65], v[110:113], v[66:69]
	s_waitcnt vmcnt(1)
	ds_write_b128 v19, v[166:169] offset:32768
	v_mfma_f32_16x16x32_f16 v[44:47], v[74:77], v[90:93], v[44:47]
	s_waitcnt vmcnt(0)
	ds_write_b128 v20, v[190:193] offset:32768
	v_mfma_f32_16x16x32_f16 v[78:81], v[74:77], v[110:113], v[78:81]
	v_mfma_f32_16x16x32_f16 v[82:85], v[118:121], v[90:93], v[82:85]
	v_mfma_f32_16x16x32_f16 v[86:89], v[118:121], v[110:113], v[86:89]
	s_waitcnt lgkmcnt(2)
	v_mfma_f32_16x16x32_f16 v[28:31], v[122:125], v[90:93], v[28:31]
	ds_read_b128 v[90:93], v23 offset:20480
	v_mfma_f32_16x16x32_f16 v[32:35], v[122:125], v[110:113], v[32:35]
	ds_read_b128 v[110:113], v23 offset:22528
	s_waitcnt lgkmcnt(1)
	v_mfma_f32_16x16x32_f16 v[98:101], v[62:65], v[90:93], v[98:101]
	s_waitcnt lgkmcnt(0)
	v_mfma_f32_16x16x32_f16 v[52:55], v[62:65], v[110:113], v[52:55]
	global_load_dwordx4 v[62:65], v[0:1], off offset:2176
	v_mfma_f32_16x16x32_f16 v[102:105], v[74:77], v[90:93], v[102:105]
	v_mfma_f32_16x16x32_f16 v[24:27], v[74:77], v[110:113], v[24:27]
	v_mfma_f32_16x16x32_f16 v[114:117], v[118:121], v[90:93], v[114:117]
	v_mfma_f32_16x16x32_f16 v[40:43], v[118:121], v[110:113], v[40:43]
	v_mfma_f32_16x16x32_f16 v[70:73], v[122:125], v[90:93], v[70:73]
	global_load_dwordx4 v[90:93], v[2:3], off offset:2176
	global_load_dwordx4 v[126:129], v[4:5], off offset:2176
	global_load_dwordx4 v[130:133], v[14:15], off offset:2176
	global_load_dwordx4 v[74:77], v[10:11], off offset:2176
	global_load_dwordx4 v[138:141], v[12:13], off offset:2176
	global_load_dwordx4 v[142:145], v[8:9], off offset:2176
	global_load_dwordx4 v[154:157], v[6:7], off offset:2176
	s_waitcnt lgkmcnt(0)
	s_barrier
	v_mfma_f32_16x16x32_f16 v[48:51], v[122:125], v[110:113], v[48:51]
	ds_read_b128 v[58:61], v16 offset:32768
	ds_read_b128 v[106:109], v21
	s_waitcnt lgkmcnt(0)
	v_mfma_f32_16x16x32_f16 v[36:39], v[58:61], v[106:109], v[36:39]
	ds_read_b128 v[94:97], v16 offset:34816
	ds_read_b128 v[110:113], v21 offset:2048
	s_waitcnt lgkmcnt(0)
	v_mfma_f32_16x16x32_f16 v[66:69], v[58:61], v[110:113], v[66:69]
	ds_read_b128 v[118:121], v16 offset:36864
	v_mfma_f32_16x16x32_f16 v[44:47], v[94:97], v[106:109], v[44:47]
	ds_read_b128 v[122:125], v16 offset:38912
	v_mfma_f32_16x16x32_f16 v[78:81], v[94:97], v[110:113], v[78:81]
	s_waitcnt vmcnt(7)
	ds_write_b128 v17, v[62:65] offset:16384
	s_waitcnt lgkmcnt(2)
	v_mfma_f32_16x16x32_f16 v[82:85], v[118:121], v[106:109], v[82:85]
	s_waitcnt vmcnt(6)
	ds_write_b128 v18, v[90:93] offset:16384
	v_mfma_f32_16x16x32_f16 v[86:89], v[118:121], v[110:113], v[86:89]
	s_waitcnt vmcnt(5)
	ds_write_b128 v19, v[126:129] offset:16384
	s_waitcnt lgkmcnt(3)
	v_mfma_f32_16x16x32_f16 v[28:31], v[122:125], v[106:109], v[28:31]
	ds_read_b128 v[106:109], v21 offset:4096
	v_mfma_f32_16x16x32_f16 v[32:35], v[122:125], v[110:113], v[32:35]
	ds_read_b128 v[110:113], v21 offset:6144
	s_waitcnt lgkmcnt(1)
	v_mfma_f32_16x16x32_f16 v[98:101], v[58:61], v[106:109], v[98:101]
	s_waitcnt vmcnt(4)
	ds_write_b128 v20, v[130:133] offset:16384
	s_waitcnt lgkmcnt(1)
	v_mfma_f32_16x16x32_f16 v[52:55], v[58:61], v[110:113], v[52:55]
	ds_read_b128 v[58:61], v22 offset:32768
	v_mfma_f32_16x16x32_f16 v[102:105], v[94:97], v[106:109], v[102:105]
	s_waitcnt vmcnt(3)
	ds_write_b128 v17, v[74:77] offset:49152
	v_mfma_f32_16x16x32_f16 v[24:27], v[94:97], v[110:113], v[24:27]
	ds_read_b128 v[94:97], v22 offset:34816
	v_mfma_f32_16x16x32_f16 v[114:117], v[118:121], v[106:109], v[114:117]
	s_waitcnt vmcnt(2)
	ds_write_b128 v18, v[138:141] offset:49152
	v_mfma_f32_16x16x32_f16 v[40:43], v[118:121], v[110:113], v[40:43]
	ds_read_b128 v[118:121], v22 offset:36864
	v_mfma_f32_16x16x32_f16 v[70:73], v[122:125], v[106:109], v[70:73]
	ds_read_b128 v[106:109], v23
	v_mfma_f32_16x16x32_f16 v[48:51], v[122:125], v[110:113], v[48:51]
	ds_read_b128 v[110:113], v23 offset:2048
	s_waitcnt lgkmcnt(1)
	v_mfma_f32_16x16x32_f16 v[36:39], v[58:61], v[106:109], v[36:39]
	ds_read_b128 v[122:125], v22 offset:38912
	s_waitcnt lgkmcnt(1)
	v_mfma_f32_16x16x32_f16 v[66:69], v[58:61], v[110:113], v[66:69]
	s_waitcnt vmcnt(1)
	ds_write_b128 v19, v[142:145] offset:49152
	v_mfma_f32_16x16x32_f16 v[44:47], v[94:97], v[106:109], v[44:47]
	s_waitcnt vmcnt(0)
	ds_write_b128 v20, v[154:157] offset:49152
	v_mfma_f32_16x16x32_f16 v[78:81], v[94:97], v[110:113], v[78:81]
	v_mfma_f32_16x16x32_f16 v[82:85], v[118:121], v[106:109], v[82:85]
	v_mfma_f32_16x16x32_f16 v[86:89], v[118:121], v[110:113], v[86:89]
	s_waitcnt lgkmcnt(2)
	v_mfma_f32_16x16x32_f16 v[28:31], v[122:125], v[106:109], v[28:31]
	ds_read_b128 v[106:109], v23 offset:4096
	v_mfma_f32_16x16x32_f16 v[32:35], v[122:125], v[110:113], v[32:35]
	ds_read_b128 v[110:113], v23 offset:6144
	s_waitcnt lgkmcnt(1)
	v_mfma_f32_16x16x32_f16 v[98:101], v[58:61], v[106:109], v[98:101]
	s_waitcnt lgkmcnt(0)
	v_mfma_f32_16x16x32_f16 v[52:55], v[58:61], v[110:113], v[52:55]
	global_load_dwordx4 v[58:61], v[0:1], off offset:2304
	v_mfma_f32_16x16x32_f16 v[102:105], v[94:97], v[106:109], v[102:105]
	v_mfma_f32_16x16x32_f16 v[24:27], v[94:97], v[110:113], v[24:27]
	v_mfma_f32_16x16x32_f16 v[114:117], v[118:121], v[106:109], v[114:117]
	v_mfma_f32_16x16x32_f16 v[40:43], v[118:121], v[110:113], v[40:43]
	v_mfma_f32_16x16x32_f16 v[70:73], v[122:125], v[106:109], v[70:73]
	global_load_dwordx4 v[106:109], v[2:3], off offset:2304
	global_load_dwordx4 v[134:137], v[4:5], off offset:2304
	global_load_dwordx4 v[158:161], v[14:15], off offset:2304
	global_load_dwordx4 v[94:97], v[10:11], off offset:2304
	global_load_dwordx4 v[162:165], v[12:13], off offset:2304
	global_load_dwordx4 v[166:169], v[8:9], off offset:2304
	global_load_dwordx4 v[190:193], v[6:7], off offset:2304
	s_waitcnt lgkmcnt(0)
	s_barrier
; #define GL_LOAD(s_, kt_) if (VAR != 1) { a##s_##0 = GL_A(0, kt_); a##s_##1 = GL_A(1, kt_); a##s_##2 = GL_A(2, kt_); a##s_##3 = GL_A(3, kt_); b##s_##0 = GL_B(0, kt_); b##s_##1 = GL_B(1, kt_); b##s_##2 = GL_B(2, kt_); b##s_##3 = GL_B(3, kt_); }
; #define LDS_STORE(s_, buf_) if (VAR != 2) { LDS_ST1(sA, 0, buf_, a##s_##0) LDS_ST1(sA, 1, buf_, a##s_##1) LDS_ST1(sA, 2, buf_, a##s_##2) LDS_ST1(sA, 3, buf_, a##s_##3) LDS_ST1(sB, 0, buf_, b##s_##0) LDS_ST1(sB, 1, buf_, b##s_##1) LDS_ST1(sB, 2, buf_, b##s_##2) LDS_ST1(sB, 3, buf_, b##s_##3) }
;     ...
;   GL_LOAD(0, 0)
;   GL_LOAD(1, 1)
;   LDS_STORE(0, 0)
;   if (VAR != 4) __syncthreads();
; #pragma unroll
;   for (int kt = 0; kt < nk; kt += 2) {
;     if (kt + 2 < nk) { GL_LOAD(0, kt + 2) }
;     MMA_TILE(0)
;     LDS_STORE(1, 1)
;     if (VAR != 4) __syncthreads();
;     if (kt + 3 < nk) { GL_LOAD(1, kt + 3) }
;     MMA_TILE(1)
;     if (kt + 2 < nk) { LDS_STORE(0, 0) }
;     if (VAR != 4) __syncthreads();
	v_mfma_f32_16x16x32_f16 v[48:51], v[122:125], v[110:113], v[48:51]
	ds_read_b128 v[62:65], v16 offset:49152
	ds_read_b128 v[90:93], v21 offset:16384
	s_waitcnt lgkmcnt(0)
	v_mfma_f32_16x16x32_f16 v[36:39], v[62:65], v[90:93], v[36:39]
	ds_read_b128 v[74:77], v16 offset:51200
	ds_read_b128 v[110:113], v21 offset:18432
	s_waitcnt lgkmcnt(0)
	v_mfma_f32_16x16x32_f16 v[66:69], v[62:65], v[110:113], v[66:69]
	ds_read_b128 v[118:121], v16 offset:53248
	v_mfma_f32_16x16x32_f16 v[44:47], v[74:77], v[90:93], v[44:47]
	ds_read_b128 v[122:125], v16 offset:55296
	v_mfma_f32_16x16x32_f16 v[78:81], v[74:77], v[110:113], v[78:81]
	s_waitcnt vmcnt(7)
	ds_write_b128 v17, v[58:61]
	s_waitcnt lgkmcnt(2)
	v_mfma_f32_16x16x32_f16 v[82:85], v[118:121], v[90:93], v[82:85]
	s_waitcnt vmcnt(6)
	ds_write_b128 v18, v[106:109]
	v_mfma_f32_16x16x32_f16 v[86:89], v[118:121], v[110:113], v[86:89]
	s_waitcnt vmcnt(5)
	ds_write_b128 v19, v[134:137]
	s_waitcnt lgkmcnt(3)
	v_mfma_f32_16x16x32_f16 v[28:31], v[122:125], v[90:93], v[28:31]
	ds_read_b128 v[90:93], v21 offset:20480
	v_mfma_f32_16x16x32_f16 v[32:35], v[122:125], v[110:113], v[32:35]
	ds_read_b128 v[110:113], v21 offset:22528
	s_waitcnt lgkmcnt(1)
	v_mfma_f32_16x16x32_f16 v[98:101], v[62:65], v[90:93], v[98:101]
	s_waitcnt vmcnt(4)
	ds_write_b128 v20, v[158:161]
	s_waitcnt lgkmcnt(1)
	v_mfma_f32_16x16x32_f16 v[52:55], v[62:65], v[110:113], v[52:55]
	ds_read_b128 v[62:65], v22 offset:49152
	v_mfma_f32_16x16x32_f16 v[102:105], v[74:77], v[90:93], v[102:105]
	s_waitcnt vmcnt(3)
	ds_write_b128 v17, v[94:97] offset:32768
	v_mfma_f32_16x16x32_f16 v[24:27], v[74:77], v[110:113], v[24:27]
	ds_read_b128 v[74:77], v22 offset:51200
	v_mfma_f32_16x16x32_f16 v[114:117], v[118:121], v[90:93], v[114:117]
	s_waitcnt vmcnt(2)
	ds_write_b128 v18, v[162:165] offset:32768
	v_mfma_f32_16x16x32_f16 v[40:43], v[118:121], v[110:113], v[40:43]
	ds_read_b128 v[118:121], v22 offset:53248
	v_mfma_f32_16x16x32_f16 v[70:73], v[122:125], v[90:93], v[70:73]
	ds_read_b128 v[90:93], v23 offset:16384
	v_mfma_f32_16x16x32_f16 v[48:51], v[122:125], v[110:113], v[48:51]
	ds_read_b128 v[110:113], v23 offset:18432
	s_waitcnt lgkmcnt(1)
	v_mfma_f32_16x16x32_f16 v[36:39], v[62:65], v[90:93], v[36:39]
	ds_read_b128 v[122:125], v22 offset:55296
	s_waitcnt lgkmcnt(1)
	v_mfma_f32_16x16x32_f16 v[66:69], v[62:65], v[110:113], v[66:69]
	s_waitcnt vmcnt(1)
	ds_write_b128 v19, v[166:169] offset:32768
	v_mfma_f32_16x16x32_f16 v[44:47], v[74:77], v[90:93], v[44:47]
	s_waitcnt vmcnt(0)
	ds_write_b128 v20, v[190:193] offset:32768
	v_mfma_f32_16x16x32_f16 v[78:81], v[74:77], v[110:113], v[78:81]
	v_mfma_f32_16x16x32_f16 v[82:85], v[118:121], v[90:93], v[82:85]
	v_mfma_f32_16x16x32_f16 v[86:89], v[118:121], v[110:113], v[86:89]
	s_waitcnt lgkmcnt(2)
	v_mfma_f32_16x16x32_f16 v[28:31], v[122:125], v[90:93], v[28:31]
	ds_read_b128 v[90:93], v23 offset:20480
	v_mfma_f32_16x16x32_f16 v[32:35], v[122:125], v[110:113], v[32:35]
	ds_read_b128 v[110:113], v23 offset:22528
	s_waitcnt lgkmcnt(1)
	v_mfma_f32_16x16x32_f16 v[98:101], v[62:65], v[90:93], v[98:101]
	s_waitcnt lgkmcnt(0)
	v_mfma_f32_16x16x32_f16 v[52:55], v[62:65], v[110:113], v[52:55]
	global_load_dwordx4 v[62:65], v[0:1], off offset:2432
	v_mfma_f32_16x16x32_f16 v[102:105], v[74:77], v[90:93], v[102:105]
	v_mfma_f32_16x16x32_f16 v[24:27], v[74:77], v[110:113], v[24:27]
	v_mfma_f32_16x16x32_f16 v[114:117], v[118:121], v[90:93], v[114:117]
	v_mfma_f32_16x16x32_f16 v[40:43], v[118:121], v[110:113], v[40:43]
	v_mfma_f32_16x16x32_f16 v[70:73], v[122:125], v[90:93], v[70:73]
	global_load_dwordx4 v[90:93], v[2:3], off offset:2432
	global_load_dwordx4 v[126:129], v[4:5], off offset:2432
	global_load_dwordx4 v[130:133], v[14:15], off offset:2432
	global_load_dwordx4 v[74:77], v[10:11], off offset:2432
	global_load_dwordx4 v[138:141], v[12:13], off offset:2432
	global_load_dwordx4 v[142:145], v[8:9], off offset:2432
	global_load_dwordx4 v[154:157], v[6:7], off offset:2432
	s_waitcnt lgkmcnt(0)
	s_barrier
	v_mfma_f32_16x16x32_f16 v[48:51], v[122:125], v[110:113], v[48:51]
	ds_read_b128 v[58:61], v16 offset:32768
	ds_read_b128 v[106:109], v21
	s_waitcnt lgkmcnt(0)
	v_mfma_f32_16x16x32_f16 v[36:39], v[58:61], v[106:109], v[36:39]
	ds_read_b128 v[94:97], v16 offset:34816
	ds_read_b128 v[110:113], v21 offset:2048
	s_waitcnt lgkmcnt(0)
	v_mfma_f32_16x16x32_f16 v[66:69], v[58:61], v[110:113], v[66:69]
	ds_read_b128 v[118:121], v16 offset:36864
	v_mfma_f32_16x16x32_f16 v[44:47], v[94:97], v[106:109], v[44:47]
	ds_read_b128 v[122:125], v16 offset:38912
	v_mfma_f32_16x16x32_f16 v[78:81], v[94:97], v[110:113], v[78:81]
	s_waitcnt vmcnt(7)
	ds_write_b128 v17, v[62:65] offset:16384
	s_waitcnt lgkmcnt(2)
	v_mfma_f32_16x16x32_f16 v[82:85], v[118:121], v[106:109], v[82:85]
	s_waitcnt vmcnt(6)
	ds_write_b128 v18, v[90:93] offset:16384
	v_mfma_f32_16x16x32_f16 v[86:89], v[118:121], v[110:113], v[86:89]
	s_waitcnt vmcnt(5)
	ds_write_b128 v19, v[126:129] offset:16384
	s_waitcnt lgkmcnt(3)
	v_mfma_f32_16x16x32_f16 v[28:31], v[122:125], v[106:109], v[28:31]
	ds_read_b128 v[106:109], v21 offset:4096
	v_mfma_f32_16x16x32_f16 v[32:35], v[122:125], v[110:113], v[32:35]
	ds_read_b128 v[110:113], v21 offset:6144
	s_waitcnt lgkmcnt(1)
	v_mfma_f32_16x16x32_f16 v[98:101], v[58:61], v[106:109], v[98:101]
	s_waitcnt vmcnt(4)
	ds_write_b128 v20, v[130:133] offset:16384
	s_waitcnt lgkmcnt(1)
	v_mfma_f32_16x16x32_f16 v[52:55], v[58:61], v[110:113], v[52:55]
	ds_read_b128 v[58:61], v22 offset:32768
	v_mfma_f32_16x16x32_f16 v[102:105], v[94:97], v[106:109], v[102:105]
	s_waitcnt vmcnt(3)
; #define GL_LOAD(s_, kt_) if (VAR != 1) { a##s_##0 = GL_A(0, kt_); a##s_##1 = GL_A(1, kt_); a##s_##2 = GL_A(2, kt_); a##s_##3 = GL_A(3, kt_); b##s_##0 = GL_B(0, kt_); b##s_##1 = GL_B(1, kt_); b##s_##2 = GL_B(2, kt_); b##s_##3 = GL_B(3, kt_); }
; #define LDS_STORE(s_, buf_) if (VAR != 2) { LDS_ST1(sA, 0, buf_, a##s_##0) LDS_ST1(sA, 1, buf_, a##s_##1) LDS_ST1(sA, 2, buf_, a##s_##2) LDS_ST1(sA, 3, buf_, a##s_##3) LDS_ST1(sB, 0, buf_, b##s_##0) LDS_ST1(sB, 1, buf_, b##s_##1) LDS_ST1(sB, 2, buf_, b##s_##2) LDS_ST1(sB, 3, buf_, b##s_##3) }
;     ...
;   GL_LOAD(0, 0)
;   GL_LOAD(1, 1)
;   LDS_STORE(0, 0)
;   if (VAR != 4) __syncthreads();
; #pragma unroll
;   for (int kt = 0; kt < nk; kt += 2) {
;     if (kt + 2 < nk) { GL_LOAD(0, kt + 2) }
;     MMA_TILE(0)
;     LDS_STORE(1, 1)
;     if (VAR != 4) __syncthreads();
;     if (kt + 3 < nk) { GL_LOAD(1, kt + 3) }
;     MMA_TILE(1)
;     if (kt + 2 < nk) { LDS_STORE(0, 0) }
;     if (VAR != 4) __syncthreads();
	ds_write_b128 v17, v[74:77] offset:49152
	v_mfma_f32_16x16x32_f16 v[24:27], v[94:97], v[110:113], v[24:27]
	ds_read_b128 v[94:97], v22 offset:34816
	v_mfma_f32_16x16x32_f16 v[114:117], v[118:121], v[106:109], v[114:117]
	s_waitcnt vmcnt(2)
	ds_write_b128 v18, v[138:141] offset:49152
	v_mfma_f32_16x16x32_f16 v[40:43], v[118:121], v[110:113], v[40:43]
	ds_read_b128 v[118:121], v22 offset:36864
	v_mfma_f32_16x16x32_f16 v[70:73], v[122:125], v[106:109], v[70:73]
	ds_read_b128 v[106:109], v23
	v_mfma_f32_16x16x32_f16 v[48:51], v[122:125], v[110:113], v[48:51]
	ds_read_b128 v[110:113], v23 offset:2048
	s_waitcnt lgkmcnt(1)
	v_mfma_f32_16x16x32_f16 v[36:39], v[58:61], v[106:109], v[36:39]
	ds_read_b128 v[122:125], v22 offset:38912
	s_waitcnt lgkmcnt(1)
	v_mfma_f32_16x16x32_f16 v[66:69], v[58:61], v[110:113], v[66:69]
	s_waitcnt vmcnt(1)
	ds_write_b128 v19, v[142:145] offset:49152
	v_mfma_f32_16x16x32_f16 v[44:47], v[94:97], v[106:109], v[44:47]
	s_waitcnt vmcnt(0)
	ds_write_b128 v20, v[154:157] offset:49152
	v_mfma_f32_16x16x32_f16 v[78:81], v[94:97], v[110:113], v[78:81]
	v_mfma_f32_16x16x32_f16 v[82:85], v[118:121], v[106:109], v[82:85]
	v_mfma_f32_16x16x32_f16 v[86:89], v[118:121], v[110:113], v[86:89]
	s_waitcnt lgkmcnt(2)
	v_mfma_f32_16x16x32_f16 v[28:31], v[122:125], v[106:109], v[28:31]
	ds_read_b128 v[106:109], v23 offset:4096
	v_mfma_f32_16x16x32_f16 v[32:35], v[122:125], v[110:113], v[32:35]
	ds_read_b128 v[110:113], v23 offset:6144
	s_waitcnt lgkmcnt(1)
	v_mfma_f32_16x16x32_f16 v[98:101], v[58:61], v[106:109], v[98:101]
	s_waitcnt lgkmcnt(0)
	v_mfma_f32_16x16x32_f16 v[52:55], v[58:61], v[110:113], v[52:55]
	global_load_dwordx4 v[58:61], v[0:1], off offset:2560
	v_mfma_f32_16x16x32_f16 v[102:105], v[94:97], v[106:109], v[102:105]
	v_mfma_f32_16x16x32_f16 v[24:27], v[94:97], v[110:113], v[24:27]
	v_mfma_f32_16x16x32_f16 v[114:117], v[118:121], v[106:109], v[114:117]
	v_mfma_f32_16x16x32_f16 v[40:43], v[118:121], v[110:113], v[40:43]
	v_mfma_f32_16x16x32_f16 v[70:73], v[122:125], v[106:109], v[70:73]
	global_load_dwordx4 v[106:109], v[2:3], off offset:2560
	global_load_dwordx4 v[134:137], v[4:5], off offset:2560
	global_load_dwordx4 v[158:161], v[14:15], off offset:2560
	global_load_dwordx4 v[94:97], v[10:11], off offset:2560
	global_load_dwordx4 v[162:165], v[12:13], off offset:2560
	global_load_dwordx4 v[166:169], v[8:9], off offset:2560
	global_load_dwordx4 v[190:193], v[6:7], off offset:2560
	s_waitcnt lgkmcnt(0)
	s_barrier
	v_mfma_f32_16x16x32_f16 v[48:51], v[122:125], v[110:113], v[48:51]
	ds_read_b128 v[62:65], v16 offset:49152
	ds_read_b128 v[90:93], v21 offset:16384
	s_waitcnt lgkmcnt(0)
	v_mfma_f32_16x16x32_f16 v[36:39], v[62:65], v[90:93], v[36:39]
	ds_read_b128 v[74:77], v16 offset:51200
	ds_read_b128 v[110:113], v21 offset:18432
	s_waitcnt lgkmcnt(0)
	v_mfma_f32_16x16x32_f16 v[66:69], v[62:65], v[110:113], v[66:69]
	ds_read_b128 v[118:121], v16 offset:53248
	v_mfma_f32_16x16x32_f16 v[44:47], v[74:77], v[90:93], v[44:47]
	ds_read_b128 v[122:125], v16 offset:55296
	v_mfma_f32_16x16x32_f16 v[78:81], v[74:77], v[110:113], v[78:81]
	s_waitcnt vmcnt(7)
	ds_write_b128 v17, v[58:61]
	s_waitcnt lgkmcnt(2)
	v_mfma_f32_16x16x32_f16 v[82:85], v[118:121], v[90:93], v[82:85]
	s_waitcnt vmcnt(6)
	ds_write_b128 v18, v[106:109]
	v_mfma_f32_16x16x32_f16 v[86:89], v[118:121], v[110:113], v[86:89]
	s_waitcnt vmcnt(5)
	ds_write_b128 v19, v[134:137]
	s_waitcnt lgkmcnt(3)
	v_mfma_f32_16x16x32_f16 v[28:31], v[122:125], v[90:93], v[28:31]
	ds_read_b128 v[90:93], v21 offset:20480
	v_mfma_f32_16x16x32_f16 v[32:35], v[122:125], v[110:113], v[32:35]
	ds_read_b128 v[110:113], v21 offset:22528
	s_waitcnt lgkmcnt(1)
	v_mfma_f32_16x16x32_f16 v[98:101], v[62:65], v[90:93], v[98:101]
	s_waitcnt vmcnt(4)
	ds_write_b128 v20, v[158:161]
	s_waitcnt lgkmcnt(1)
	v_mfma_f32_16x16x32_f16 v[52:55], v[62:65], v[110:113], v[52:55]
	ds_read_b128 v[62:65], v22 offset:49152
	v_mfma_f32_16x16x32_f16 v[102:105], v[74:77], v[90:93], v[102:105]
	s_waitcnt vmcnt(3)
	ds_write_b128 v17, v[94:97] offset:32768
	v_mfma_f32_16x16x32_f16 v[24:27], v[74:77], v[110:113], v[24:27]
	ds_read_b128 v[74:77], v22 offset:51200
	v_mfma_f32_16x16x32_f16 v[114:117], v[118:121], v[90:93], v[114:117]
	s_waitcnt vmcnt(2)
	ds_write_b128 v18, v[162:165] offset:32768
	v_mfma_f32_16x16x32_f16 v[40:43], v[118:121], v[110:113], v[40:43]
	ds_read_b128 v[118:121], v22 offset:53248
	v_mfma_f32_16x16x32_f16 v[70:73], v[122:125], v[90:93], v[70:73]
	ds_read_b128 v[90:93], v23 offset:16384
	v_mfma_f32_16x16x32_f16 v[48:51], v[122:125], v[110:113], v[48:51]
	ds_read_b128 v[110:113], v23 offset:18432
	s_waitcnt lgkmcnt(1)
	v_mfma_f32_16x16x32_f16 v[36:39], v[62:65], v[90:93], v[36:39]
	ds_read_b128 v[122:125], v22 offset:55296
	s_waitcnt lgkmcnt(1)
	v_mfma_f32_16x16x32_f16 v[66:69], v[62:65], v[110:113], v[66:69]
	s_waitcnt vmcnt(1)
	ds_write_b128 v19, v[166:169] offset:32768
	v_mfma_f32_16x16x32_f16 v[44:47], v[74:77], v[90:93], v[44:47]
	s_waitcnt vmcnt(0)
	ds_write_b128 v20, v[190:193] offset:32768
	v_mfma_f32_16x16x32_f16 v[78:81], v[74:77], v[110:113], v[78:81]
	v_mfma_f32_16x16x32_f16 v[82:85], v[118:121], v[90:93], v[82:85]
	v_mfma_f32_16x16x32_f16 v[86:89], v[118:121], v[110:113], v[86:89]
	s_waitcnt lgkmcnt(2)
	v_mfma_f32_16x16x32_f16 v[28:31], v[122:125], v[90:93], v[28:31]
	ds_read_b128 v[90:93], v23 offset:20480
	v_mfma_f32_16x16x32_f16 v[32:35], v[122:125], v[110:113], v[32:35]
	ds_read_b128 v[110:113], v23 offset:22528
	s_waitcnt lgkmcnt(1)
	v_mfma_f32_16x16x32_f16 v[98:101], v[62:65], v[90:93], v[98:101]
	s_waitcnt lgkmcnt(0)
	v_mfma_f32_16x16x32_f16 v[52:55], v[62:65], v[110:113], v[52:55]
	global_load_dwordx4 v[62:65], v[0:1], off offset:2688
	v_mfma_f32_16x16x32_f16 v[102:105], v[74:77], v[90:93], v[102:105]
	v_mfma_f32_16x16x32_f16 v[24:27], v[74:77], v[110:113], v[24:27]
	v_mfma_f32_16x16x32_f16 v[114:117], v[118:121], v[90:93], v[114:117]
	v_mfma_f32_16x16x32_f16 v[40:43], v[118:121], v[110:113], v[40:43]
	v_mfma_f32_16x16x32_f16 v[70:73], v[122:125], v[90:93], v[70:73]
	global_load_dwordx4 v[90:93], v[2:3], off offset:2688
	global_load_dwordx4 v[126:129], v[4:5], off offset:2688
	global_load_dwordx4 v[130:133], v[14:15], off offset:2688
	global_load_dwordx4 v[74:77], v[10:11], off offset:2688
	global_load_dwordx4 v[138:141], v[12:13], off offset:2688
	global_load_dwordx4 v[142:145], v[8:9], off offset:2688
	global_load_dwordx4 v[154:157], v[6:7], off offset:2688
	s_waitcnt lgkmcnt(0)
	s_barrier
; #define GL_LOAD(s_, kt_) if (VAR != 1) { a##s_##0 = GL_A(0, kt_); a##s_##1 = GL_A(1, kt_); a##s_##2 = GL_A(2, kt_); a##s_##3 = GL_A(3, kt_); b##s_##0 = GL_B(0, kt_); b##s_##1 = GL_B(1, kt_); b##s_##2 = GL_B(2, kt_); b##s_##3 = GL_B(3, kt_); }
; #define LDS_STORE(s_, buf_) if (VAR != 2) { LDS_ST1(sA, 0, buf_, a##s_##0) LDS_ST1(sA, 1, buf_, a##s_##1) LDS_ST1(sA, 2, buf_, a##s_##2) LDS_ST1(sA, 3, buf_, a##s_##3) LDS_ST1(sB, 0, buf_, b##s_##0) LDS_ST1(sB, 1, buf_, b##s_##1) LDS_ST1(sB, 2, buf_, b##s_##2) LDS_ST1(sB, 3, buf_, b##s_##3) }
;     ...
;   GL_LOAD(0, 0)
;   GL_LOAD(1, 1)
;   LDS_STORE(0, 0)
;   if (VAR != 4) __syncthreads();
; #pragma unroll
;   for (int kt = 0; kt < nk; kt += 2) {
;     if (kt + 2 < nk) { GL_LOAD(0, kt + 2) }
;     MMA_TILE(0)
;     LDS_STORE(1, 1)
;     if (VAR != 4) __syncthreads();
;     if (kt + 3 < nk) { GL_LOAD(1, kt + 3) }
;     MMA_TILE(1)
;     if (kt + 2 < nk) { LDS_STORE(0, 0) }
;     if (VAR != 4) __syncthreads();
	v_mfma_f32_16x16x32_f16 v[48:51], v[122:125], v[110:113], v[48:51]
	ds_read_b128 v[58:61], v16 offset:32768
	ds_read_b128 v[106:109], v21
	s_waitcnt lgkmcnt(0)
	v_mfma_f32_16x16x32_f16 v[36:39], v[58:61], v[106:109], v[36:39]
	ds_read_b128 v[94:97], v16 offset:34816
	ds_read_b128 v[110:113], v21 offset:2048
	s_waitcnt lgkmcnt(0)
	v_mfma_f32_16x16x32_f16 v[66:69], v[58:61], v[110:113], v[66:69]
	ds_read_b128 v[118:121], v16 offset:36864
	v_mfma_f32_16x16x32_f16 v[44:47], v[94:97], v[106:109], v[44:47]
	ds_read_b128 v[122:125], v16 offset:38912
	v_mfma_f32_16x16x32_f16 v[78:81], v[94:97], v[110:113], v[78:81]
	s_waitcnt vmcnt(7)
	ds_write_b128 v17, v[62:65] offset:16384
	s_waitcnt lgkmcnt(2)
	v_mfma_f32_16x16x32_f16 v[82:85], v[118:121], v[106:109], v[82:85]
	s_waitcnt vmcnt(6)
	ds_write_b128 v18, v[90:93] offset:16384
	v_mfma_f32_16x16x32_f16 v[86:89], v[118:121], v[110:113], v[86:89]
	s_waitcnt vmcnt(5)
	ds_write_b128 v19, v[126:129] offset:16384
	s_waitcnt lgkmcnt(3)
	v_mfma_f32_16x16x32_f16 v[28:31], v[122:125], v[106:109], v[28:31]
	ds_read_b128 v[106:109], v21 offset:4096
	v_mfma_f32_16x16x32_f16 v[32:35], v[122:125], v[110:113], v[32:35]
	ds_read_b128 v[110:113], v21 offset:6144
	s_waitcnt lgkmcnt(1)
	v_mfma_f32_16x16x32_f16 v[98:101], v[58:61], v[106:109], v[98:101]
	s_waitcnt vmcnt(4)
	ds_write_b128 v20, v[130:133] offset:16384
	s_waitcnt lgkmcnt(1)
	v_mfma_f32_16x16x32_f16 v[52:55], v[58:61], v[110:113], v[52:55]
	ds_read_b128 v[58:61], v22 offset:32768
	v_mfma_f32_16x16x32_f16 v[102:105], v[94:97], v[106:109], v[102:105]
	s_waitcnt vmcnt(3)
	ds_write_b128 v17, v[74:77] offset:49152
	v_mfma_f32_16x16x32_f16 v[24:27], v[94:97], v[110:113], v[24:27]
	ds_read_b128 v[94:97], v22 offset:34816
	v_mfma_f32_16x16x32_f16 v[114:117], v[118:121], v[106:109], v[114:117]
	s_waitcnt vmcnt(2)
	ds_write_b128 v18, v[138:141] offset:49152
	v_mfma_f32_16x16x32_f16 v[40:43], v[118:121], v[110:113], v[40:43]
	ds_read_b128 v[118:121], v22 offset:36864
	v_mfma_f32_16x16x32_f16 v[70:73], v[122:125], v[106:109], v[70:73]
	ds_read_b128 v[106:109], v23
	v_mfma_f32_16x16x32_f16 v[48:51], v[122:125], v[110:113], v[48:51]
	ds_read_b128 v[110:113], v23 offset:2048
	s_waitcnt lgkmcnt(1)
	v_mfma_f32_16x16x32_f16 v[36:39], v[58:61], v[106:109], v[36:39]
	ds_read_b128 v[122:125], v22 offset:38912
	s_waitcnt lgkmcnt(1)
	v_mfma_f32_16x16x32_f16 v[66:69], v[58:61], v[110:113], v[66:69]
	s_waitcnt vmcnt(1)
	ds_write_b128 v19, v[142:145] offset:49152
	v_mfma_f32_16x16x32_f16 v[44:47], v[94:97], v[106:109], v[44:47]
	s_waitcnt vmcnt(0)
	ds_write_b128 v20, v[154:157] offset:49152
	v_mfma_f32_16x16x32_f16 v[78:81], v[94:97], v[110:113], v[78:81]
	v_mfma_f32_16x16x32_f16 v[82:85], v[118:121], v[106:109], v[82:85]
	v_mfma_f32_16x16x32_f16 v[86:89], v[118:121], v[110:113], v[86:89]
	s_waitcnt lgkmcnt(2)
	v_mfma_f32_16x16x32_f16 v[28:31], v[122:125], v[106:109], v[28:31]
	ds_read_b128 v[106:109], v23 offset:4096
	v_mfma_f32_16x16x32_f16 v[32:35], v[122:125], v[110:113], v[32:35]
	ds_read_b128 v[110:113], v23 offset:6144
	s_waitcnt lgkmcnt(1)
	v_mfma_f32_16x16x32_f16 v[98:101], v[58:61], v[106:109], v[98:101]
	s_waitcnt lgkmcnt(0)
	v_mfma_f32_16x16x32_f16 v[52:55], v[58:61], v[110:113], v[52:55]
	global_load_dwordx4 v[58:61], v[0:1], off offset:2816
	v_mfma_f32_16x16x32_f16 v[102:105], v[94:97], v[106:109], v[102:105]
	v_mfma_f32_16x16x32_f16 v[24:27], v[94:97], v[110:113], v[24:27]
	v_mfma_f32_16x16x32_f16 v[114:117], v[118:121], v[106:109], v[114:117]
	v_mfma_f32_16x16x32_f16 v[40:43], v[118:121], v[110:113], v[40:43]
	v_mfma_f32_16x16x32_f16 v[70:73], v[122:125], v[106:109], v[70:73]
	global_load_dwordx4 v[106:109], v[2:3], off offset:2816
	global_load_dwordx4 v[134:137], v[4:5], off offset:2816
	global_load_dwordx4 v[158:161], v[14:15], off offset:2816
	global_load_dwordx4 v[94:97], v[10:11], off offset:2816
	global_load_dwordx4 v[162:165], v[12:13], off offset:2816
	global_load_dwordx4 v[166:169], v[8:9], off offset:2816
	global_load_dwordx4 v[190:193], v[6:7], off offset:2816
	s_waitcnt lgkmcnt(0)
	s_barrier
	v_mfma_f32_16x16x32_f16 v[48:51], v[122:125], v[110:113], v[48:51]
	ds_read_b128 v[62:65], v16 offset:49152
	ds_read_b128 v[90:93], v21 offset:16384
	s_waitcnt lgkmcnt(0)
	v_mfma_f32_16x16x32_f16 v[36:39], v[62:65], v[90:93], v[36:39]
	ds_read_b128 v[74:77], v16 offset:51200
	ds_read_b128 v[110:113], v21 offset:18432
	s_waitcnt lgkmcnt(0)
	v_mfma_f32_16x16x32_f16 v[66:69], v[62:65], v[110:113], v[66:69]
	ds_read_b128 v[118:121], v16 offset:53248
	v_mfma_f32_16x16x32_f16 v[44:47], v[74:77], v[90:93], v[44:47]
	ds_read_b128 v[122:125], v16 offset:55296
	v_mfma_f32_16x16x32_f16 v[78:81], v[74:77], v[110:113], v[78:81]
	s_waitcnt vmcnt(7)
	ds_write_b128 v17, v[58:61]
	s_waitcnt lgkmcnt(2)
	v_mfma_f32_16x16x32_f16 v[82:85], v[118:121], v[90:93], v[82:85]
	s_waitcnt vmcnt(6)
	ds_write_b128 v18, v[106:109]
	v_mfma_f32_16x16x32_f16 v[86:89], v[118:121], v[110:113], v[86:89]
	s_waitcnt vmcnt(5)
	ds_write_b128 v19, v[134:137]
	s_waitcnt lgkmcnt(3)
	v_mfma_f32_16x16x32_f16 v[28:31], v[122:125], v[90:93], v[28:31]
	ds_read_b128 v[90:93], v21 offset:20480
	v_mfma_f32_16x16x32_f16 v[32:35], v[122:125], v[110:113], v[32:35]
	ds_read_b128 v[110:113], v21 offset:22528
	s_waitcnt lgkmcnt(1)
	v_mfma_f32_16x16x32_f16 v[98:101], v[62:65], v[90:93], v[98:101]
	s_waitcnt vmcnt(4)
	ds_write_b128 v20, v[158:161]
	s_waitcnt lgkmcnt(1)
	v_mfma_f32_16x16x32_f16 v[52:55], v[62:65], v[110:113], v[52:55]
	ds_read_b128 v[62:65], v22 offset:49152
	v_mfma_f32_16x16x32_f16 v[102:105], v[74:77], v[90:93], v[102:105]
	s_waitcnt vmcnt(3)
; #define GL_LOAD(s_, kt_) if (VAR != 1) { a##s_##0 = GL_A(0, kt_); a##s_##1 = GL_A(1, kt_); a##s_##2 = GL_A(2, kt_); a##s_##3 = GL_A(3, kt_); b##s_##0 = GL_B(0, kt_); b##s_##1 = GL_B(1, kt_); b##s_##2 = GL_B(2, kt_); b##s_##3 = GL_B(3, kt_); }
; #define LDS_STORE(s_, buf_) if (VAR != 2) { LDS_ST1(sA, 0, buf_, a##s_##0) LDS_ST1(sA, 1, buf_, a##s_##1) LDS_ST1(sA, 2, buf_, a##s_##2) LDS_ST1(sA, 3, buf_, a##s_##3) LDS_ST1(sB, 0, buf_, b##s_##0) LDS_ST1(sB, 1, buf_, b##s_##1) LDS_ST1(sB, 2, buf_, b##s_##2) LDS_ST1(sB, 3, buf_, b##s_##3) }
;     ...
;   GL_LOAD(0, 0)
;   GL_LOAD(1, 1)
;   LDS_STORE(0, 0)
;   if (VAR != 4) __syncthreads();
; #pragma unroll
;   for (int kt = 0; kt < nk; kt += 2) {
;     if (kt + 2 < nk) { GL_LOAD(0, kt + 2) }
;     MMA_TILE(0)
;     LDS_STORE(1, 1)
;     if (VAR != 4) __syncthreads();
;     if (kt + 3 < nk) { GL_LOAD(1, kt + 3) }
;     MMA_TILE(1)
;     if (kt + 2 < nk) { LDS_STORE(0, 0) }
;     if (VAR != 4) __syncthreads();
	ds_write_b128 v17, v[94:97] offset:32768
	v_mfma_f32_16x16x32_f16 v[24:27], v[74:77], v[110:113], v[24:27]
	ds_read_b128 v[74:77], v22 offset:51200
	v_mfma_f32_16x16x32_f16 v[114:117], v[118:121], v[90:93], v[114:117]
	s_waitcnt vmcnt(2)
	ds_write_b128 v18, v[162:165] offset:32768
	v_mfma_f32_16x16x32_f16 v[40:43], v[118:121], v[110:113], v[40:43]
	ds_read_b128 v[118:121], v22 offset:53248
	v_mfma_f32_16x16x32_f16 v[70:73], v[122:125], v[90:93], v[70:73]
	ds_read_b128 v[90:93], v23 offset:16384
	v_mfma_f32_16x16x32_f16 v[48:51], v[122:125], v[110:113], v[48:51]
	ds_read_b128 v[110:113], v23 offset:18432
	s_waitcnt lgkmcnt(1)
	v_mfma_f32_16x16x32_f16 v[36:39], v[62:65], v[90:93], v[36:39]
	ds_read_b128 v[122:125], v22 offset:55296
	s_waitcnt lgkmcnt(1)
	v_mfma_f32_16x16x32_f16 v[66:69], v[62:65], v[110:113], v[66:69]
	s_waitcnt vmcnt(1)
	ds_write_b128 v19, v[166:169] offset:32768
	v_mfma_f32_16x16x32_f16 v[44:47], v[74:77], v[90:93], v[44:47]
	s_waitcnt vmcnt(0)
	ds_write_b128 v20, v[190:193] offset:32768
	v_mfma_f32_16x16x32_f16 v[78:81], v[74:77], v[110:113], v[78:81]
	v_mfma_f32_16x16x32_f16 v[82:85], v[118:121], v[90:93], v[82:85]
	v_mfma_f32_16x16x32_f16 v[86:89], v[118:121], v[110:113], v[86:89]
	s_waitcnt lgkmcnt(2)
	v_mfma_f32_16x16x32_f16 v[28:31], v[122:125], v[90:93], v[28:31]
	ds_read_b128 v[90:93], v23 offset:20480
	v_mfma_f32_16x16x32_f16 v[32:35], v[122:125], v[110:113], v[32:35]
	ds_read_b128 v[110:113], v23 offset:22528
	s_waitcnt lgkmcnt(1)
	v_mfma_f32_16x16x32_f16 v[98:101], v[62:65], v[90:93], v[98:101]
	s_waitcnt lgkmcnt(0)
	v_mfma_f32_16x16x32_f16 v[52:55], v[62:65], v[110:113], v[52:55]
	global_load_dwordx4 v[62:65], v[0:1], off offset:2944
	v_mfma_f32_16x16x32_f16 v[102:105], v[74:77], v[90:93], v[102:105]
	v_mfma_f32_16x16x32_f16 v[24:27], v[74:77], v[110:113], v[24:27]
	v_mfma_f32_16x16x32_f16 v[114:117], v[118:121], v[90:93], v[114:117]
	v_mfma_f32_16x16x32_f16 v[40:43], v[118:121], v[110:113], v[40:43]
	v_mfma_f32_16x16x32_f16 v[70:73], v[122:125], v[90:93], v[70:73]
	global_load_dwordx4 v[90:93], v[2:3], off offset:2944
	global_load_dwordx4 v[126:129], v[4:5], off offset:2944
	global_load_dwordx4 v[130:133], v[14:15], off offset:2944
	global_load_dwordx4 v[74:77], v[10:11], off offset:2944
	global_load_dwordx4 v[138:141], v[12:13], off offset:2944
	global_load_dwordx4 v[142:145], v[8:9], off offset:2944
	global_load_dwordx4 v[154:157], v[6:7], off offset:2944
	s_waitcnt lgkmcnt(0)
	s_barrier
	v_mfma_f32_16x16x32_f16 v[48:51], v[122:125], v[110:113], v[48:51]
	ds_read_b128 v[58:61], v16 offset:32768
	ds_read_b128 v[106:109], v21
	s_waitcnt lgkmcnt(0)
	v_mfma_f32_16x16x32_f16 v[36:39], v[58:61], v[106:109], v[36:39]
	ds_read_b128 v[94:97], v16 offset:34816
	ds_read_b128 v[110:113], v21 offset:2048
	s_waitcnt lgkmcnt(0)
	v_mfma_f32_16x16x32_f16 v[66:69], v[58:61], v[110:113], v[66:69]
	ds_read_b128 v[118:121], v16 offset:36864
	v_mfma_f32_16x16x32_f16 v[44:47], v[94:97], v[106:109], v[44:47]
	ds_read_b128 v[122:125], v16 offset:38912
	v_mfma_f32_16x16x32_f16 v[78:81], v[94:97], v[110:113], v[78:81]
	s_waitcnt vmcnt(7)
	ds_write_b128 v17, v[62:65] offset:16384
	s_waitcnt lgkmcnt(2)
	v_mfma_f32_16x16x32_f16 v[82:85], v[118:121], v[106:109], v[82:85]
	s_waitcnt vmcnt(6)
	ds_write_b128 v18, v[90:93] offset:16384
	v_mfma_f32_16x16x32_f16 v[86:89], v[118:121], v[110:113], v[86:89]
	s_waitcnt vmcnt(5)
	ds_write_b128 v19, v[126:129] offset:16384
	s_waitcnt lgkmcnt(3)
	v_mfma_f32_16x16x32_f16 v[28:31], v[122:125], v[106:109], v[28:31]
	ds_read_b128 v[106:109], v21 offset:4096
	v_mfma_f32_16x16x32_f16 v[32:35], v[122:125], v[110:113], v[32:35]
	ds_read_b128 v[110:113], v21 offset:6144
	s_waitcnt lgkmcnt(1)
	v_mfma_f32_16x16x32_f16 v[98:101], v[58:61], v[106:109], v[98:101]
	s_waitcnt vmcnt(4)
	ds_write_b128 v20, v[130:133] offset:16384
	s_waitcnt lgkmcnt(1)
	v_mfma_f32_16x16x32_f16 v[52:55], v[58:61], v[110:113], v[52:55]
	ds_read_b128 v[58:61], v22 offset:32768
	v_mfma_f32_16x16x32_f16 v[102:105], v[94:97], v[106:109], v[102:105]
	s_waitcnt vmcnt(3)
	ds_write_b128 v17, v[74:77] offset:49152
	v_mfma_f32_16x16x32_f16 v[24:27], v[94:97], v[110:113], v[24:27]
	ds_read_b128 v[94:97], v22 offset:34816
	v_mfma_f32_16x16x32_f16 v[114:117], v[118:121], v[106:109], v[114:117]
	s_waitcnt vmcnt(2)
	ds_write_b128 v18, v[138:141] offset:49152
	v_mfma_f32_16x16x32_f16 v[40:43], v[118:121], v[110:113], v[40:43]
	ds_read_b128 v[118:121], v22 offset:36864
	v_mfma_f32_16x16x32_f16 v[70:73], v[122:125], v[106:109], v[70:73]
	ds_read_b128 v[106:109], v23
	v_mfma_f32_16x16x32_f16 v[48:51], v[122:125], v[110:113], v[48:51]
	ds_read_b128 v[110:113], v23 offset:2048
	s_waitcnt lgkmcnt(1)
	v_mfma_f32_16x16x32_f16 v[36:39], v[58:61], v[106:109], v[36:39]
	ds_read_b128 v[122:125], v22 offset:38912
	s_waitcnt lgkmcnt(1)
	v_mfma_f32_16x16x32_f16 v[66:69], v[58:61], v[110:113], v[66:69]
	s_waitcnt vmcnt(1)
	ds_write_b128 v19, v[142:145] offset:49152
	v_mfma_f32_16x16x32_f16 v[44:47], v[94:97], v[106:109], v[44:47]
	s_waitcnt vmcnt(0)
	ds_write_b128 v20, v[154:157] offset:49152
	v_mfma_f32_16x16x32_f16 v[78:81], v[94:97], v[110:113], v[78:81]
	v_mfma_f32_16x16x32_f16 v[82:85], v[118:121], v[106:109], v[82:85]
	v_mfma_f32_16x16x32_f16 v[86:89], v[118:121], v[110:113], v[86:89]
	s_waitcnt lgkmcnt(2)
	v_mfma_f32_16x16x32_f16 v[28:31], v[122:125], v[106:109], v[28:31]
	ds_read_b128 v[106:109], v23 offset:4096
	v_mfma_f32_16x16x32_f16 v[32:35], v[122:125], v[110:113], v[32:35]
	ds_read_b128 v[110:113], v23 offset:6144
	s_waitcnt lgkmcnt(1)
	v_mfma_f32_16x16x32_f16 v[98:101], v[58:61], v[106:109], v[98:101]
	s_waitcnt lgkmcnt(0)
	v_mfma_f32_16x16x32_f16 v[52:55], v[58:61], v[110:113], v[52:55]
	global_load_dwordx4 v[58:61], v[0:1], off offset:3072
	v_mfma_f32_16x16x32_f16 v[102:105], v[94:97], v[106:109], v[102:105]
	v_mfma_f32_16x16x32_f16 v[24:27], v[94:97], v[110:113], v[24:27]
	v_mfma_f32_16x16x32_f16 v[114:117], v[118:121], v[106:109], v[114:117]
	v_mfma_f32_16x16x32_f16 v[40:43], v[118:121], v[110:113], v[40:43]
	v_mfma_f32_16x16x32_f16 v[70:73], v[122:125], v[106:109], v[70:73]
	global_load_dwordx4 v[106:109], v[2:3], off offset:3072
	global_load_dwordx4 v[134:137], v[4:5], off offset:3072
	global_load_dwordx4 v[158:161], v[14:15], off offset:3072
	global_load_dwordx4 v[94:97], v[10:11], off offset:3072
	global_load_dwordx4 v[162:165], v[12:13], off offset:3072
	global_load_dwordx4 v[166:169], v[8:9], off offset:3072
	global_load_dwordx4 v[190:193], v[6:7], off offset:3072
	s_waitcnt lgkmcnt(0)
	s_barrier
; #define GL_LOAD(s_, kt_) if (VAR != 1) { a##s_##0 = GL_A(0, kt_); a##s_##1 = GL_A(1, kt_); a##s_##2 = GL_A(2, kt_); a##s_##3 = GL_A(3, kt_); b##s_##0 = GL_B(0, kt_); b##s_##1 = GL_B(1, kt_); b##s_##2 = GL_B(2, kt_); b##s_##3 = GL_B(3, kt_); }
; #define LDS_STORE(s_, buf_) if (VAR != 2) { LDS_ST1(sA, 0, buf_, a##s_##0) LDS_ST1(sA, 1, buf_, a##s_##1) LDS_ST1(sA, 2, buf_, a##s_##2) LDS_ST1(sA, 3, buf_, a##s_##3) LDS_ST1(sB, 0, buf_, b##s_##0) LDS_ST1(sB, 1, buf_, b##s_##1) LDS_ST1(sB, 2, buf_, b##s_##2) LDS_ST1(sB, 3, buf_, b##s_##3) }
;     ...
;   GL_LOAD(0, 0)
;   GL_LOAD(1, 1)
;   LDS_STORE(0, 0)
;   if (VAR != 4) __syncthreads();
; #pragma unroll
;   for (int kt = 0; kt < nk; kt += 2) {
;     if (kt + 2 < nk) { GL_LOAD(0, kt + 2) }
;     MMA_TILE(0)
;     LDS_STORE(1, 1)
;     if (VAR != 4) __syncthreads();
;     if (kt + 3 < nk) { GL_LOAD(1, kt + 3) }
;     MMA_TILE(1)
;     if (kt + 2 < nk) { LDS_STORE(0, 0) }
;     if (VAR != 4) __syncthreads();
	v_mfma_f32_16x16x32_f16 v[48:51], v[122:125], v[110:113], v[48:51]
	ds_read_b128 v[62:65], v16 offset:49152
	ds_read_b128 v[90:93], v21 offset:16384
	s_waitcnt lgkmcnt(0)
	v_mfma_f32_16x16x32_f16 v[36:39], v[62:65], v[90:93], v[36:39]
	ds_read_b128 v[74:77], v16 offset:51200
	ds_read_b128 v[110:113], v21 offset:18432
	s_waitcnt lgkmcnt(0)
	v_mfma_f32_16x16x32_f16 v[66:69], v[62:65], v[110:113], v[66:69]
	ds_read_b128 v[118:121], v16 offset:53248
	v_mfma_f32_16x16x32_f16 v[44:47], v[74:77], v[90:93], v[44:47]
	ds_read_b128 v[122:125], v16 offset:55296
	v_mfma_f32_16x16x32_f16 v[78:81], v[74:77], v[110:113], v[78:81]
	s_waitcnt vmcnt(7)
	ds_write_b128 v17, v[58:61]
	s_waitcnt lgkmcnt(2)
	v_mfma_f32_16x16x32_f16 v[82:85], v[118:121], v[90:93], v[82:85]
	s_waitcnt vmcnt(6)
	ds_write_b128 v18, v[106:109]
	v_mfma_f32_16x16x32_f16 v[86:89], v[118:121], v[110:113], v[86:89]
	s_waitcnt vmcnt(5)
	ds_write_b128 v19, v[134:137]
	s_waitcnt lgkmcnt(3)
	v_mfma_f32_16x16x32_f16 v[28:31], v[122:125], v[90:93], v[28:31]
	ds_read_b128 v[90:93], v21 offset:20480
	v_mfma_f32_16x16x32_f16 v[32:35], v[122:125], v[110:113], v[32:35]
	ds_read_b128 v[110:113], v21 offset:22528
	s_waitcnt lgkmcnt(1)
	v_mfma_f32_16x16x32_f16 v[98:101], v[62:65], v[90:93], v[98:101]
	s_waitcnt vmcnt(4)
	ds_write_b128 v20, v[158:161]
	s_waitcnt lgkmcnt(1)
	v_mfma_f32_16x16x32_f16 v[52:55], v[62:65], v[110:113], v[52:55]
	ds_read_b128 v[62:65], v22 offset:49152
	v_mfma_f32_16x16x32_f16 v[102:105], v[74:77], v[90:93], v[102:105]
	s_waitcnt vmcnt(3)
	ds_write_b128 v17, v[94:97] offset:32768
	v_mfma_f32_16x16x32_f16 v[24:27], v[74:77], v[110:113], v[24:27]
	ds_read_b128 v[74:77], v22 offset:51200
	v_mfma_f32_16x16x32_f16 v[114:117], v[118:121], v[90:93], v[114:117]
	s_waitcnt vmcnt(2)
	ds_write_b128 v18, v[162:165] offset:32768
	v_mfma_f32_16x16x32_f16 v[40:43], v[118:121], v[110:113], v[40:43]
	ds_read_b128 v[118:121], v22 offset:53248
	v_mfma_f32_16x16x32_f16 v[70:73], v[122:125], v[90:93], v[70:73]
	ds_read_b128 v[90:93], v23 offset:16384
	v_mfma_f32_16x16x32_f16 v[48:51], v[122:125], v[110:113], v[48:51]
	ds_read_b128 v[110:113], v23 offset:18432
	s_waitcnt lgkmcnt(1)
	v_mfma_f32_16x16x32_f16 v[36:39], v[62:65], v[90:93], v[36:39]
	ds_read_b128 v[122:125], v22 offset:55296
	s_waitcnt lgkmcnt(1)
	v_mfma_f32_16x16x32_f16 v[66:69], v[62:65], v[110:113], v[66:69]
	s_waitcnt vmcnt(1)
	ds_write_b128 v19, v[166:169] offset:32768
	v_mfma_f32_16x16x32_f16 v[44:47], v[74:77], v[90:93], v[44:47]
	s_waitcnt vmcnt(0)
	ds_write_b128 v20, v[190:193] offset:32768
	v_mfma_f32_16x16x32_f16 v[78:81], v[74:77], v[110:113], v[78:81]
	v_mfma_f32_16x16x32_f16 v[82:85], v[118:121], v[90:93], v[82:85]
	v_mfma_f32_16x16x32_f16 v[86:89], v[118:121], v[110:113], v[86:89]
	s_waitcnt lgkmcnt(2)
	v_mfma_f32_16x16x32_f16 v[28:31], v[122:125], v[90:93], v[28:31]
	ds_read_b128 v[90:93], v23 offset:20480
	v_mfma_f32_16x16x32_f16 v[32:35], v[122:125], v[110:113], v[32:35]
	ds_read_b128 v[110:113], v23 offset:22528
	s_waitcnt lgkmcnt(1)
	v_mfma_f32_16x16x32_f16 v[98:101], v[62:65], v[90:93], v[98:101]
	s_waitcnt lgkmcnt(0)
	v_mfma_f32_16x16x32_f16 v[52:55], v[62:65], v[110:113], v[52:55]
	global_load_dwordx4 v[62:65], v[0:1], off offset:3200
	v_mfma_f32_16x16x32_f16 v[102:105], v[74:77], v[90:93], v[102:105]
	v_mfma_f32_16x16x32_f16 v[24:27], v[74:77], v[110:113], v[24:27]
	v_mfma_f32_16x16x32_f16 v[114:117], v[118:121], v[90:93], v[114:117]
	v_mfma_f32_16x16x32_f16 v[40:43], v[118:121], v[110:113], v[40:43]
	v_mfma_f32_16x16x32_f16 v[70:73], v[122:125], v[90:93], v[70:73]
	global_load_dwordx4 v[90:93], v[2:3], off offset:3200
	global_load_dwordx4 v[126:129], v[4:5], off offset:3200
	global_load_dwordx4 v[130:133], v[14:15], off offset:3200
	global_load_dwordx4 v[74:77], v[10:11], off offset:3200
	global_load_dwordx4 v[138:141], v[12:13], off offset:3200
	global_load_dwordx4 v[142:145], v[8:9], off offset:3200
	global_load_dwordx4 v[154:157], v[6:7], off offset:3200
	s_waitcnt lgkmcnt(0)
	s_barrier
	v_mfma_f32_16x16x32_f16 v[48:51], v[122:125], v[110:113], v[48:51]
	ds_read_b128 v[58:61], v16 offset:32768
	ds_read_b128 v[106:109], v21
	s_waitcnt lgkmcnt(0)
	v_mfma_f32_16x16x32_f16 v[36:39], v[58:61], v[106:109], v[36:39]
	ds_read_b128 v[94:97], v16 offset:34816
	ds_read_b128 v[110:113], v21 offset:2048
	s_waitcnt lgkmcnt(0)
	v_mfma_f32_16x16x32_f16 v[66:69], v[58:61], v[110:113], v[66:69]
	ds_read_b128 v[118:121], v16 offset:36864
	v_mfma_f32_16x16x32_f16 v[44:47], v[94:97], v[106:109], v[44:47]
	ds_read_b128 v[122:125], v16 offset:38912
	v_mfma_f32_16x16x32_f16 v[78:81], v[94:97], v[110:113], v[78:81]
	s_waitcnt vmcnt(7)
	ds_write_b128 v17, v[62:65] offset:16384
	s_waitcnt lgkmcnt(2)
	v_mfma_f32_16x16x32_f16 v[82:85], v[118:121], v[106:109], v[82:85]
	s_waitcnt vmcnt(6)
	ds_write_b128 v18, v[90:93] offset:16384
	v_mfma_f32_16x16x32_f16 v[86:89], v[118:121], v[110:113], v[86:89]
	s_waitcnt vmcnt(5)
	ds_write_b128 v19, v[126:129] offset:16384
	s_waitcnt lgkmcnt(3)
	v_mfma_f32_16x16x32_f16 v[28:31], v[122:125], v[106:109], v[28:31]
	ds_read_b128 v[106:109], v21 offset:4096
	v_mfma_f32_16x16x32_f16 v[32:35], v[122:125], v[110:113], v[32:35]
	ds_read_b128 v[110:113], v21 offset:6144
	s_waitcnt lgkmcnt(1)
	v_mfma_f32_16x16x32_f16 v[98:101], v[58:61], v[106:109], v[98:101]
	s_waitcnt vmcnt(4)
	ds_write_b128 v20, v[130:133] offset:16384
	s_waitcnt lgkmcnt(1)
	v_mfma_f32_16x16x32_f16 v[52:55], v[58:61], v[110:113], v[52:55]
	ds_read_b128 v[58:61], v22 offset:32768
	v_mfma_f32_16x16x32_f16 v[102:105], v[94:97], v[106:109], v[102:105]
	s_waitcnt vmcnt(3)
; #define GL_LOAD(s_, kt_) if (VAR != 1) { a##s_##0 = GL_A(0, kt_); a##s_##1 = GL_A(1, kt_); a##s_##2 = GL_A(2, kt_); a##s_##3 = GL_A(3, kt_); b##s_##0 = GL_B(0, kt_); b##s_##1 = GL_B(1, kt_); b##s_##2 = GL_B(2, kt_); b##s_##3 = GL_B(3, kt_); }
; #define LDS_STORE(s_, buf_) if (VAR != 2) { LDS_ST1(sA, 0, buf_, a##s_##0) LDS_ST1(sA, 1, buf_, a##s_##1) LDS_ST1(sA, 2, buf_, a##s_##2) LDS_ST1(sA, 3, buf_, a##s_##3) LDS_ST1(sB, 0, buf_, b##s_##0) LDS_ST1(sB, 1, buf_, b##s_##1) LDS_ST1(sB, 2, buf_, b##s_##2) LDS_ST1(sB, 3, buf_, b##s_##3) }
;     ...
;   GL_LOAD(0, 0)
;   GL_LOAD(1, 1)
;   LDS_STORE(0, 0)
;   if (VAR != 4) __syncthreads();
; #pragma unroll
;   for (int kt = 0; kt < nk; kt += 2) {
;     if (kt + 2 < nk) { GL_LOAD(0, kt + 2) }
;     MMA_TILE(0)
;     LDS_STORE(1, 1)
;     if (VAR != 4) __syncthreads();
;     if (kt + 3 < nk) { GL_LOAD(1, kt + 3) }
;     MMA_TILE(1)
;     if (kt + 2 < nk) { LDS_STORE(0, 0) }
;     if (VAR != 4) __syncthreads();
	ds_write_b128 v17, v[74:77] offset:49152
	v_mfma_f32_16x16x32_f16 v[24:27], v[94:97], v[110:113], v[24:27]
	ds_read_b128 v[94:97], v22 offset:34816
	v_mfma_f32_16x16x32_f16 v[114:117], v[118:121], v[106:109], v[114:117]
	s_waitcnt vmcnt(2)
	ds_write_b128 v18, v[138:141] offset:49152
	v_mfma_f32_16x16x32_f16 v[40:43], v[118:121], v[110:113], v[40:43]
	ds_read_b128 v[118:121], v22 offset:36864
	v_mfma_f32_16x16x32_f16 v[70:73], v[122:125], v[106:109], v[70:73]
	ds_read_b128 v[106:109], v23
	v_mfma_f32_16x16x32_f16 v[48:51], v[122:125], v[110:113], v[48:51]
	ds_read_b128 v[110:113], v23 offset:2048
	s_waitcnt lgkmcnt(1)
	v_mfma_f32_16x16x32_f16 v[36:39], v[58:61], v[106:109], v[36:39]
	ds_read_b128 v[122:125], v22 offset:38912
	s_waitcnt lgkmcnt(1)
	v_mfma_f32_16x16x32_f16 v[66:69], v[58:61], v[110:113], v[66:69]
	s_waitcnt vmcnt(1)
	ds_write_b128 v19, v[142:145] offset:49152
	v_mfma_f32_16x16x32_f16 v[44:47], v[94:97], v[106:109], v[44:47]
	s_waitcnt vmcnt(0)
	ds_write_b128 v20, v[154:157] offset:49152
	v_mfma_f32_16x16x32_f16 v[78:81], v[94:97], v[110:113], v[78:81]
	v_mfma_f32_16x16x32_f16 v[82:85], v[118:121], v[106:109], v[82:85]
	v_mfma_f32_16x16x32_f16 v[86:89], v[118:121], v[110:113], v[86:89]
	s_waitcnt lgkmcnt(2)
	v_mfma_f32_16x16x32_f16 v[28:31], v[122:125], v[106:109], v[28:31]
	ds_read_b128 v[106:109], v23 offset:4096
	v_mfma_f32_16x16x32_f16 v[32:35], v[122:125], v[110:113], v[32:35]
	ds_read_b128 v[110:113], v23 offset:6144
	s_waitcnt lgkmcnt(1)
	v_mfma_f32_16x16x32_f16 v[98:101], v[58:61], v[106:109], v[98:101]
	s_waitcnt lgkmcnt(0)
	v_mfma_f32_16x16x32_f16 v[52:55], v[58:61], v[110:113], v[52:55]
	global_load_dwordx4 v[58:61], v[0:1], off offset:3328
	v_mfma_f32_16x16x32_f16 v[102:105], v[94:97], v[106:109], v[102:105]
	v_mfma_f32_16x16x32_f16 v[24:27], v[94:97], v[110:113], v[24:27]
	v_mfma_f32_16x16x32_f16 v[114:117], v[118:121], v[106:109], v[114:117]
	v_mfma_f32_16x16x32_f16 v[40:43], v[118:121], v[110:113], v[40:43]
	v_mfma_f32_16x16x32_f16 v[70:73], v[122:125], v[106:109], v[70:73]
	global_load_dwordx4 v[106:109], v[2:3], off offset:3328
	global_load_dwordx4 v[134:137], v[4:5], off offset:3328
	global_load_dwordx4 v[158:161], v[14:15], off offset:3328
	global_load_dwordx4 v[94:97], v[10:11], off offset:3328
	global_load_dwordx4 v[162:165], v[12:13], off offset:3328
	global_load_dwordx4 v[166:169], v[8:9], off offset:3328
	global_load_dwordx4 v[190:193], v[6:7], off offset:3328
	s_waitcnt lgkmcnt(0)
	s_barrier
	v_mfma_f32_16x16x32_f16 v[48:51], v[122:125], v[110:113], v[48:51]
	ds_read_b128 v[62:65], v16 offset:49152
	ds_read_b128 v[90:93], v21 offset:16384
	s_waitcnt lgkmcnt(0)
	v_mfma_f32_16x16x32_f16 v[36:39], v[62:65], v[90:93], v[36:39]
	ds_read_b128 v[74:77], v16 offset:51200
	ds_read_b128 v[110:113], v21 offset:18432
	s_waitcnt lgkmcnt(0)
	v_mfma_f32_16x16x32_f16 v[66:69], v[62:65], v[110:113], v[66:69]
	ds_read_b128 v[118:121], v16 offset:53248
	v_mfma_f32_16x16x32_f16 v[44:47], v[74:77], v[90:93], v[44:47]
	ds_read_b128 v[122:125], v16 offset:55296
	v_mfma_f32_16x16x32_f16 v[78:81], v[74:77], v[110:113], v[78:81]
	s_waitcnt vmcnt(7)
	ds_write_b128 v17, v[58:61]
	s_waitcnt lgkmcnt(2)
	v_mfma_f32_16x16x32_f16 v[82:85], v[118:121], v[90:93], v[82:85]
	s_waitcnt vmcnt(6)
	ds_write_b128 v18, v[106:109]
	v_mfma_f32_16x16x32_f16 v[86:89], v[118:121], v[110:113], v[86:89]
	s_waitcnt vmcnt(5)
	ds_write_b128 v19, v[134:137]
	s_waitcnt lgkmcnt(3)
	v_mfma_f32_16x16x32_f16 v[28:31], v[122:125], v[90:93], v[28:31]
	ds_read_b128 v[90:93], v21 offset:20480
	v_mfma_f32_16x16x32_f16 v[32:35], v[122:125], v[110:113], v[32:35]
	ds_read_b128 v[110:113], v21 offset:22528
	s_waitcnt lgkmcnt(1)
	v_mfma_f32_16x16x32_f16 v[98:101], v[62:65], v[90:93], v[98:101]
	s_waitcnt vmcnt(4)
	ds_write_b128 v20, v[158:161]
	s_waitcnt lgkmcnt(1)
	v_mfma_f32_16x16x32_f16 v[52:55], v[62:65], v[110:113], v[52:55]
	ds_read_b128 v[62:65], v22 offset:49152
	v_mfma_f32_16x16x32_f16 v[102:105], v[74:77], v[90:93], v[102:105]
	s_waitcnt vmcnt(3)
	ds_write_b128 v17, v[94:97] offset:32768
	v_mfma_f32_16x16x32_f16 v[24:27], v[74:77], v[110:113], v[24:27]
	ds_read_b128 v[74:77], v22 offset:51200
	v_mfma_f32_16x16x32_f16 v[114:117], v[118:121], v[90:93], v[114:117]
	s_waitcnt vmcnt(2)
	ds_write_b128 v18, v[162:165] offset:32768
	v_mfma_f32_16x16x32_f16 v[40:43], v[118:121], v[110:113], v[40:43]
	ds_read_b128 v[118:121], v22 offset:53248
	v_mfma_f32_16x16x32_f16 v[70:73], v[122:125], v[90:93], v[70:73]
	ds_read_b128 v[90:93], v23 offset:16384
	v_mfma_f32_16x16x32_f16 v[48:51], v[122:125], v[110:113], v[48:51]
	ds_read_b128 v[110:113], v23 offset:18432
	s_waitcnt lgkmcnt(1)
	v_mfma_f32_16x16x32_f16 v[36:39], v[62:65], v[90:93], v[36:39]
	ds_read_b128 v[122:125], v22 offset:55296
	s_waitcnt lgkmcnt(1)
	v_mfma_f32_16x16x32_f16 v[66:69], v[62:65], v[110:113], v[66:69]
	s_waitcnt vmcnt(1)
	ds_write_b128 v19, v[166:169] offset:32768
	v_mfma_f32_16x16x32_f16 v[44:47], v[74:77], v[90:93], v[44:47]
	s_waitcnt vmcnt(0)
	ds_write_b128 v20, v[190:193] offset:32768
	v_mfma_f32_16x16x32_f16 v[78:81], v[74:77], v[110:113], v[78:81]
	v_mfma_f32_16x16x32_f16 v[82:85], v[118:121], v[90:93], v[82:85]
	v_mfma_f32_16x16x32_f16 v[86:89], v[118:121], v[110:113], v[86:89]
	s_waitcnt lgkmcnt(2)
	v_mfma_f32_16x16x32_f16 v[28:31], v[122:125], v[90:93], v[28:31]
	ds_read_b128 v[90:93], v23 offset:20480
	v_mfma_f32_16x16x32_f16 v[32:35], v[122:125], v[110:113], v[32:35]
	ds_read_b128 v[110:113], v23 offset:22528
	s_waitcnt lgkmcnt(1)
	v_mfma_f32_16x16x32_f16 v[98:101], v[62:65], v[90:93], v[98:101]
	s_waitcnt lgkmcnt(0)
	v_mfma_f32_16x16x32_f16 v[52:55], v[62:65], v[110:113], v[52:55]
	global_load_dwordx4 v[62:65], v[0:1], off offset:3456
	v_mfma_f32_16x16x32_f16 v[102:105], v[74:77], v[90:93], v[102:105]
	v_mfma_f32_16x16x32_f16 v[24:27], v[74:77], v[110:113], v[24:27]
	v_mfma_f32_16x16x32_f16 v[114:117], v[118:121], v[90:93], v[114:117]
	v_mfma_f32_16x16x32_f16 v[40:43], v[118:121], v[110:113], v[40:43]
	v_mfma_f32_16x16x32_f16 v[70:73], v[122:125], v[90:93], v[70:73]
	global_load_dwordx4 v[90:93], v[2:3], off offset:3456
	global_load_dwordx4 v[126:129], v[4:5], off offset:3456
	global_load_dwordx4 v[130:133], v[14:15], off offset:3456
	global_load_dwordx4 v[74:77], v[10:11], off offset:3456
	global_load_dwordx4 v[138:141], v[12:13], off offset:3456
	global_load_dwordx4 v[142:145], v[8:9], off offset:3456
	global_load_dwordx4 v[154:157], v[6:7], off offset:3456
	s_waitcnt lgkmcnt(0)
	s_barrier
; #define GL_LOAD(s_, kt_) if (VAR != 1) { a##s_##0 = GL_A(0, kt_); a##s_##1 = GL_A(1, kt_); a##s_##2 = GL_A(2, kt_); a##s_##3 = GL_A(3, kt_); b##s_##0 = GL_B(0, kt_); b##s_##1 = GL_B(1, kt_); b##s_##2 = GL_B(2, kt_); b##s_##3 = GL_B(3, kt_); }
; #define LDS_STORE(s_, buf_) if (VAR != 2) { LDS_ST1(sA, 0, buf_, a##s_##0) LDS_ST1(sA, 1, buf_, a##s_##1) LDS_ST1(sA, 2, buf_, a##s_##2) LDS_ST1(sA, 3, buf_, a##s_##3) LDS_ST1(sB, 0, buf_, b##s_##0) LDS_ST1(sB, 1, buf_, b##s_##1) LDS_ST1(sB, 2, buf_, b##s_##2) LDS_ST1(sB, 3, buf_, b##s_##3) }
;     ...
;   GL_LOAD(0, 0)
;   GL_LOAD(1, 1)
;   LDS_STORE(0, 0)
;   if (VAR != 4) __syncthreads();
; #pragma unroll
;   for (int kt = 0; kt < nk; kt += 2) {
;     if (kt + 2 < nk) { GL_LOAD(0, kt + 2) }
;     MMA_TILE(0)
;     LDS_STORE(1, 1)
;     if (VAR != 4) __syncthreads();
;     if (kt + 3 < nk) { GL_LOAD(1, kt + 3) }
;     MMA_TILE(1)
;     if (kt + 2 < nk) { LDS_STORE(0, 0) }
;     if (VAR != 4) __syncthreads();
	v_mfma_f32_16x16x32_f16 v[48:51], v[122:125], v[110:113], v[48:51]
	ds_read_b128 v[58:61], v16 offset:32768
	ds_read_b128 v[106:109], v21
	s_waitcnt lgkmcnt(0)
	v_mfma_f32_16x16x32_f16 v[36:39], v[58:61], v[106:109], v[36:39]
	ds_read_b128 v[94:97], v16 offset:34816
	ds_read_b128 v[110:113], v21 offset:2048
	s_waitcnt lgkmcnt(0)
	v_mfma_f32_16x16x32_f16 v[66:69], v[58:61], v[110:113], v[66:69]
	ds_read_b128 v[118:121], v16 offset:36864
	v_mfma_f32_16x16x32_f16 v[44:47], v[94:97], v[106:109], v[44:47]
	ds_read_b128 v[122:125], v16 offset:38912
	v_mfma_f32_16x16x32_f16 v[78:81], v[94:97], v[110:113], v[78:81]
	s_waitcnt vmcnt(7)
	ds_write_b128 v17, v[62:65] offset:16384
	s_waitcnt lgkmcnt(2)
	v_mfma_f32_16x16x32_f16 v[82:85], v[118:121], v[106:109], v[82:85]
	s_waitcnt vmcnt(6)
	ds_write_b128 v18, v[90:93] offset:16384
	v_mfma_f32_16x16x32_f16 v[86:89], v[118:121], v[110:113], v[86:89]
	s_waitcnt vmcnt(5)
	ds_write_b128 v19, v[126:129] offset:16384
	s_waitcnt lgkmcnt(3)
	v_mfma_f32_16x16x32_f16 v[28:31], v[122:125], v[106:109], v[28:31]
	ds_read_b128 v[106:109], v21 offset:4096
	v_mfma_f32_16x16x32_f16 v[32:35], v[122:125], v[110:113], v[32:35]
	ds_read_b128 v[110:113], v21 offset:6144
	s_waitcnt lgkmcnt(1)
	v_mfma_f32_16x16x32_f16 v[98:101], v[58:61], v[106:109], v[98:101]
	s_waitcnt vmcnt(4)
	ds_write_b128 v20, v[130:133] offset:16384
	s_waitcnt lgkmcnt(1)
	v_mfma_f32_16x16x32_f16 v[52:55], v[58:61], v[110:113], v[52:55]
	ds_read_b128 v[58:61], v22 offset:32768
	v_mfma_f32_16x16x32_f16 v[102:105], v[94:97], v[106:109], v[102:105]
	s_waitcnt vmcnt(3)
	ds_write_b128 v17, v[74:77] offset:49152
	v_mfma_f32_16x16x32_f16 v[24:27], v[94:97], v[110:113], v[24:27]
	ds_read_b128 v[94:97], v22 offset:34816
	v_mfma_f32_16x16x32_f16 v[114:117], v[118:121], v[106:109], v[114:117]
	s_waitcnt vmcnt(2)
	ds_write_b128 v18, v[138:141] offset:49152
	v_mfma_f32_16x16x32_f16 v[40:43], v[118:121], v[110:113], v[40:43]
	ds_read_b128 v[118:121], v22 offset:36864
	v_mfma_f32_16x16x32_f16 v[70:73], v[122:125], v[106:109], v[70:73]
	ds_read_b128 v[106:109], v23
	v_mfma_f32_16x16x32_f16 v[48:51], v[122:125], v[110:113], v[48:51]
	ds_read_b128 v[110:113], v23 offset:2048
	s_waitcnt lgkmcnt(1)
	v_mfma_f32_16x16x32_f16 v[36:39], v[58:61], v[106:109], v[36:39]
	ds_read_b128 v[122:125], v22 offset:38912
	s_waitcnt lgkmcnt(1)
	v_mfma_f32_16x16x32_f16 v[66:69], v[58:61], v[110:113], v[66:69]
	s_waitcnt vmcnt(1)
	ds_write_b128 v19, v[142:145] offset:49152
	v_mfma_f32_16x16x32_f16 v[44:47], v[94:97], v[106:109], v[44:47]
	s_waitcnt vmcnt(0)
	ds_write_b128 v20, v[154:157] offset:49152
	v_mfma_f32_16x16x32_f16 v[78:81], v[94:97], v[110:113], v[78:81]
	v_mfma_f32_16x16x32_f16 v[82:85], v[118:121], v[106:109], v[82:85]
	v_mfma_f32_16x16x32_f16 v[86:89], v[118:121], v[110:113], v[86:89]
	s_waitcnt lgkmcnt(2)
	v_mfma_f32_16x16x32_f16 v[28:31], v[122:125], v[106:109], v[28:31]
	ds_read_b128 v[106:109], v23 offset:4096
	v_mfma_f32_16x16x32_f16 v[32:35], v[122:125], v[110:113], v[32:35]
	ds_read_b128 v[110:113], v23 offset:6144
	s_waitcnt lgkmcnt(1)
	v_mfma_f32_16x16x32_f16 v[98:101], v[58:61], v[106:109], v[98:101]
	s_waitcnt lgkmcnt(0)
	v_mfma_f32_16x16x32_f16 v[52:55], v[58:61], v[110:113], v[52:55]
	global_load_dwordx4 v[58:61], v[0:1], off offset:3584
	v_mfma_f32_16x16x32_f16 v[102:105], v[94:97], v[106:109], v[102:105]
	v_mfma_f32_16x16x32_f16 v[24:27], v[94:97], v[110:113], v[24:27]
	v_mfma_f32_16x16x32_f16 v[114:117], v[118:121], v[106:109], v[114:117]
	v_mfma_f32_16x16x32_f16 v[40:43], v[118:121], v[110:113], v[40:43]
	v_mfma_f32_16x16x32_f16 v[70:73], v[122:125], v[106:109], v[70:73]
	global_load_dwordx4 v[106:109], v[2:3], off offset:3584
	global_load_dwordx4 v[134:137], v[4:5], off offset:3584
	global_load_dwordx4 v[158:161], v[14:15], off offset:3584
	global_load_dwordx4 v[94:97], v[10:11], off offset:3584
	global_load_dwordx4 v[162:165], v[12:13], off offset:3584
	global_load_dwordx4 v[166:169], v[8:9], off offset:3584
	global_load_dwordx4 v[190:193], v[6:7], off offset:3584
	s_waitcnt lgkmcnt(0)
	s_barrier
	v_mfma_f32_16x16x32_f16 v[48:51], v[122:125], v[110:113], v[48:51]
	ds_read_b128 v[62:65], v16 offset:49152
	ds_read_b128 v[90:93], v21 offset:16384
	s_waitcnt lgkmcnt(0)
	v_mfma_f32_16x16x32_f16 v[36:39], v[62:65], v[90:93], v[36:39]
	ds_read_b128 v[74:77], v16 offset:51200
	ds_read_b128 v[110:113], v21 offset:18432
	s_waitcnt lgkmcnt(0)
	v_mfma_f32_16x16x32_f16 v[66:69], v[62:65], v[110:113], v[66:69]
	ds_read_b128 v[118:121], v16 offset:53248
	v_mfma_f32_16x16x32_f16 v[44:47], v[74:77], v[90:93], v[44:47]
	ds_read_b128 v[122:125], v16 offset:55296
	v_mfma_f32_16x16x32_f16 v[78:81], v[74:77], v[110:113], v[78:81]
	s_waitcnt vmcnt(7)
	ds_write_b128 v17, v[58:61]
	s_waitcnt lgkmcnt(2)
	v_mfma_f32_16x16x32_f16 v[82:85], v[118:121], v[90:93], v[82:85]
	s_waitcnt vmcnt(6)
	ds_write_b128 v18, v[106:109]
	v_mfma_f32_16x16x32_f16 v[86:89], v[118:121], v[110:113], v[86:89]
	s_waitcnt vmcnt(5)
	ds_write_b128 v19, v[134:137]
	s_waitcnt lgkmcnt(3)
	v_mfma_f32_16x16x32_f16 v[28:31], v[122:125], v[90:93], v[28:31]
	ds_read_b128 v[90:93], v21 offset:20480
	v_mfma_f32_16x16x32_f16 v[32:35], v[122:125], v[110:113], v[32:35]
	ds_read_b128 v[110:113], v21 offset:22528
	s_waitcnt lgkmcnt(1)
	v_mfma_f32_16x16x32_f16 v[98:101], v[62:65], v[90:93], v[98:101]
	s_waitcnt vmcnt(4)
	ds_write_b128 v20, v[158:161]
	s_waitcnt lgkmcnt(1)
	v_mfma_f32_16x16x32_f16 v[52:55], v[62:65], v[110:113], v[52:55]
	ds_read_b128 v[62:65], v22 offset:49152
	v_mfma_f32_16x16x32_f16 v[102:105], v[74:77], v[90:93], v[102:105]
	s_waitcnt vmcnt(3)
; #define GL_LOAD(s_, kt_) if (VAR != 1) { a##s_##0 = GL_A(0, kt_); a##s_##1 = GL_A(1, kt_); a##s_##2 = GL_A(2, kt_); a##s_##3 = GL_A(3, kt_); b##s_##0 = GL_B(0, kt_); b##s_##1 = GL_B(1, kt_); b##s_##2 = GL_B(2, kt_); b##s_##3 = GL_B(3, kt_); }
; #define LDS_STORE(s_, buf_) if (VAR != 2) { LDS_ST1(sA, 0, buf_, a##s_##0) LDS_ST1(sA, 1, buf_, a##s_##1) LDS_ST1(sA, 2, buf_, a##s_##2) LDS_ST1(sA, 3, buf_, a##s_##3) LDS_ST1(sB, 0, buf_, b##s_##0) LDS_ST1(sB, 1, buf_, b##s_##1) LDS_ST1(sB, 2, buf_, b##s_##2) LDS_ST1(sB, 3, buf_, b##s_##3) }
;     ...
;   GL_LOAD(0, 0)
;   GL_LOAD(1, 1)
;   LDS_STORE(0, 0)
;   if (VAR != 4) __syncthreads();
; #pragma unroll
;   for (int kt = 0; kt < nk; kt += 2) {
;     if (kt + 2 < nk) { GL_LOAD(0, kt + 2) }
;     MMA_TILE(0)
;     LDS_STORE(1, 1)
;     if (VAR != 4) __syncthreads();
;     if (kt + 3 < nk) { GL_LOAD(1, kt + 3) }
;     MMA_TILE(1)
;     if (kt + 2 < nk) { LDS_STORE(0, 0) }
;     if (VAR != 4) __syncthreads();
	ds_write_b128 v17, v[94:97] offset:32768
	v_mfma_f32_16x16x32_f16 v[24:27], v[74:77], v[110:113], v[24:27]
	ds_read_b128 v[74:77], v22 offset:51200
	v_mfma_f32_16x16x32_f16 v[114:117], v[118:121], v[90:93], v[114:117]
	s_waitcnt vmcnt(2)
	ds_write_b128 v18, v[162:165] offset:32768
	v_mfma_f32_16x16x32_f16 v[40:43], v[118:121], v[110:113], v[40:43]
	ds_read_b128 v[118:121], v22 offset:53248
	v_mfma_f32_16x16x32_f16 v[70:73], v[122:125], v[90:93], v[70:73]
	ds_read_b128 v[90:93], v23 offset:16384
	v_mfma_f32_16x16x32_f16 v[48:51], v[122:125], v[110:113], v[48:51]
	ds_read_b128 v[110:113], v23 offset:18432
	s_waitcnt lgkmcnt(1)
	v_mfma_f32_16x16x32_f16 v[36:39], v[62:65], v[90:93], v[36:39]
	ds_read_b128 v[122:125], v22 offset:55296
	s_waitcnt lgkmcnt(1)
	v_mfma_f32_16x16x32_f16 v[66:69], v[62:65], v[110:113], v[66:69]
	s_waitcnt vmcnt(1)
	ds_write_b128 v19, v[166:169] offset:32768
	v_mfma_f32_16x16x32_f16 v[44:47], v[74:77], v[90:93], v[44:47]
	s_waitcnt vmcnt(0)
	ds_write_b128 v20, v[190:193] offset:32768
	v_mfma_f32_16x16x32_f16 v[78:81], v[74:77], v[110:113], v[78:81]
	v_mfma_f32_16x16x32_f16 v[82:85], v[118:121], v[90:93], v[82:85]
	v_mfma_f32_16x16x32_f16 v[86:89], v[118:121], v[110:113], v[86:89]
	s_waitcnt lgkmcnt(2)
	v_mfma_f32_16x16x32_f16 v[28:31], v[122:125], v[90:93], v[28:31]
	ds_read_b128 v[90:93], v23 offset:20480
	v_mfma_f32_16x16x32_f16 v[32:35], v[122:125], v[110:113], v[32:35]
	ds_read_b128 v[110:113], v23 offset:22528
	s_waitcnt lgkmcnt(1)
	v_mfma_f32_16x16x32_f16 v[98:101], v[62:65], v[90:93], v[98:101]
	s_waitcnt lgkmcnt(0)
	v_mfma_f32_16x16x32_f16 v[52:55], v[62:65], v[110:113], v[52:55]
	global_load_dwordx4 v[62:65], v[0:1], off offset:3712
	v_mfma_f32_16x16x32_f16 v[102:105], v[74:77], v[90:93], v[102:105]
	v_mfma_f32_16x16x32_f16 v[24:27], v[74:77], v[110:113], v[24:27]
	v_mfma_f32_16x16x32_f16 v[114:117], v[118:121], v[90:93], v[114:117]
	v_mfma_f32_16x16x32_f16 v[40:43], v[118:121], v[110:113], v[40:43]
	v_mfma_f32_16x16x32_f16 v[70:73], v[122:125], v[90:93], v[70:73]
	global_load_dwordx4 v[90:93], v[2:3], off offset:3712
	global_load_dwordx4 v[126:129], v[4:5], off offset:3712
	global_load_dwordx4 v[130:133], v[14:15], off offset:3712
	global_load_dwordx4 v[74:77], v[10:11], off offset:3712
	global_load_dwordx4 v[138:141], v[12:13], off offset:3712
	global_load_dwordx4 v[142:145], v[8:9], off offset:3712
	global_load_dwordx4 v[154:157], v[6:7], off offset:3712
	s_waitcnt lgkmcnt(0)
	s_barrier
	v_mfma_f32_16x16x32_f16 v[48:51], v[122:125], v[110:113], v[48:51]
	ds_read_b128 v[58:61], v16 offset:32768
	ds_read_b128 v[106:109], v21
	s_waitcnt lgkmcnt(0)
	v_mfma_f32_16x16x32_f16 v[36:39], v[58:61], v[106:109], v[36:39]
	ds_read_b128 v[94:97], v16 offset:34816
	ds_read_b128 v[110:113], v21 offset:2048
	s_waitcnt lgkmcnt(0)
	v_mfma_f32_16x16x32_f16 v[66:69], v[58:61], v[110:113], v[66:69]
	ds_read_b128 v[118:121], v16 offset:36864
	v_mfma_f32_16x16x32_f16 v[44:47], v[94:97], v[106:109], v[44:47]
	ds_read_b128 v[122:125], v16 offset:38912
	v_mfma_f32_16x16x32_f16 v[78:81], v[94:97], v[110:113], v[78:81]
	s_waitcnt vmcnt(7)
	ds_write_b128 v17, v[62:65] offset:16384
	s_waitcnt lgkmcnt(2)
	v_mfma_f32_16x16x32_f16 v[82:85], v[118:121], v[106:109], v[82:85]
	s_waitcnt vmcnt(6)
	ds_write_b128 v18, v[90:93] offset:16384
	v_mfma_f32_16x16x32_f16 v[86:89], v[118:121], v[110:113], v[86:89]
	s_waitcnt vmcnt(5)
	ds_write_b128 v19, v[126:129] offset:16384
	s_waitcnt lgkmcnt(3)
	v_mfma_f32_16x16x32_f16 v[28:31], v[122:125], v[106:109], v[28:31]
	ds_read_b128 v[106:109], v21 offset:4096
	v_mfma_f32_16x16x32_f16 v[32:35], v[122:125], v[110:113], v[32:35]
	ds_read_b128 v[110:113], v21 offset:6144
	s_waitcnt lgkmcnt(1)
	v_mfma_f32_16x16x32_f16 v[98:101], v[58:61], v[106:109], v[98:101]
	s_waitcnt vmcnt(4)
	ds_write_b128 v20, v[130:133] offset:16384
	s_waitcnt lgkmcnt(1)
	v_mfma_f32_16x16x32_f16 v[52:55], v[58:61], v[110:113], v[52:55]
	ds_read_b128 v[58:61], v22 offset:32768
	v_mfma_f32_16x16x32_f16 v[102:105], v[94:97], v[106:109], v[102:105]
	s_waitcnt vmcnt(3)
	ds_write_b128 v17, v[74:77] offset:49152
	v_mfma_f32_16x16x32_f16 v[24:27], v[94:97], v[110:113], v[24:27]
	ds_read_b128 v[94:97], v22 offset:34816
	v_mfma_f32_16x16x32_f16 v[114:117], v[118:121], v[106:109], v[114:117]
	s_waitcnt vmcnt(2)
	ds_write_b128 v18, v[138:141] offset:49152
	v_mfma_f32_16x16x32_f16 v[40:43], v[118:121], v[110:113], v[40:43]
	ds_read_b128 v[118:121], v22 offset:36864
	v_mfma_f32_16x16x32_f16 v[70:73], v[122:125], v[106:109], v[70:73]
	ds_read_b128 v[106:109], v23
	v_mfma_f32_16x16x32_f16 v[48:51], v[122:125], v[110:113], v[48:51]
	ds_read_b128 v[110:113], v23 offset:2048
	s_waitcnt lgkmcnt(1)
	v_mfma_f32_16x16x32_f16 v[36:39], v[58:61], v[106:109], v[36:39]
	ds_read_b128 v[122:125], v22 offset:38912
	s_waitcnt lgkmcnt(1)
	v_mfma_f32_16x16x32_f16 v[66:69], v[58:61], v[110:113], v[66:69]
	s_waitcnt vmcnt(1)
	ds_write_b128 v19, v[142:145] offset:49152
	v_mfma_f32_16x16x32_f16 v[44:47], v[94:97], v[106:109], v[44:47]
	s_waitcnt vmcnt(0)
	ds_write_b128 v20, v[154:157] offset:49152
	v_mfma_f32_16x16x32_f16 v[78:81], v[94:97], v[110:113], v[78:81]
	v_mfma_f32_16x16x32_f16 v[82:85], v[118:121], v[106:109], v[82:85]
	v_mfma_f32_16x16x32_f16 v[86:89], v[118:121], v[110:113], v[86:89]
	s_waitcnt lgkmcnt(2)
	v_mfma_f32_16x16x32_f16 v[28:31], v[122:125], v[106:109], v[28:31]
	ds_read_b128 v[106:109], v23 offset:4096
	v_mfma_f32_16x16x32_f16 v[32:35], v[122:125], v[110:113], v[32:35]
	ds_read_b128 v[110:113], v23 offset:6144
	s_waitcnt lgkmcnt(1)
	v_mfma_f32_16x16x32_f16 v[98:101], v[58:61], v[106:109], v[98:101]
	s_waitcnt lgkmcnt(0)
	v_mfma_f32_16x16x32_f16 v[52:55], v[58:61], v[110:113], v[52:55]
	global_load_dwordx4 v[58:61], v[0:1], off offset:3840
	v_mfma_f32_16x16x32_f16 v[102:105], v[94:97], v[106:109], v[102:105]
	v_mfma_f32_16x16x32_f16 v[24:27], v[94:97], v[110:113], v[24:27]
	v_mfma_f32_16x16x32_f16 v[114:117], v[118:121], v[106:109], v[114:117]
	v_mfma_f32_16x16x32_f16 v[40:43], v[118:121], v[110:113], v[40:43]
	v_mfma_f32_16x16x32_f16 v[70:73], v[122:125], v[106:109], v[70:73]
	global_load_dwordx4 v[106:109], v[2:3], off offset:3840
	global_load_dwordx4 v[134:137], v[4:5], off offset:3840
	global_load_dwordx4 v[158:161], v[14:15], off offset:3840
	global_load_dwordx4 v[94:97], v[10:11], off offset:3840
	global_load_dwordx4 v[162:165], v[12:13], off offset:3840
	global_load_dwordx4 v[166:169], v[8:9], off offset:3840
	global_load_dwordx4 v[190:193], v[6:7], off offset:3840
	s_waitcnt lgkmcnt(0)
	s_barrier
; #define GL_LOAD(s_, kt_) if (VAR != 1) { a##s_##0 = GL_A(0, kt_); a##s_##1 = GL_A(1, kt_); a##s_##2 = GL_A(2, kt_); a##s_##3 = GL_A(3, kt_); b##s_##0 = GL_B(0, kt_); b##s_##1 = GL_B(1, kt_); b##s_##2 = GL_B(2, kt_); b##s_##3 = GL_B(3, kt_); }
; #define LDS_STORE(s_, buf_) if (VAR != 2) { LDS_ST1(sA, 0, buf_, a##s_##0) LDS_ST1(sA, 1, buf_, a##s_##1) LDS_ST1(sA, 2, buf_, a##s_##2) LDS_ST1(sA, 3, buf_, a##s_##3) LDS_ST1(sB, 0, buf_, b##s_##0) LDS_ST1(sB, 1, buf_, b##s_##1) LDS_ST1(sB, 2, buf_, b##s_##2) LDS_ST1(sB, 3, buf_, b##s_##3) }
;     ...
;   GL_LOAD(0, 0)
;   GL_LOAD(1, 1)
;   LDS_STORE(0, 0)
;   if (VAR != 4) __syncthreads();
; #pragma unroll
;   for (int kt = 0; kt < nk; kt += 2) {
;     if (kt + 2 < nk) { GL_LOAD(0, kt + 2) }
;     MMA_TILE(0)
;     LDS_STORE(1, 1)
;     if (VAR != 4) __syncthreads();
;     if (kt + 3 < nk) { GL_LOAD(1, kt + 3) }
;     MMA_TILE(1)
;     if (kt + 2 < nk) { LDS_STORE(0, 0) }
;     if (VAR != 4) __syncthreads();
	v_mfma_f32_16x16x32_f16 v[48:51], v[122:125], v[110:113], v[48:51]
	ds_read_b128 v[62:65], v16 offset:49152
	ds_read_b128 v[90:93], v21 offset:16384
	s_waitcnt lgkmcnt(0)
	v_mfma_f32_16x16x32_f16 v[36:39], v[62:65], v[90:93], v[36:39]
	ds_read_b128 v[74:77], v16 offset:51200
	ds_read_b128 v[110:113], v21 offset:18432
	s_waitcnt lgkmcnt(0)
	v_mfma_f32_16x16x32_f16 v[66:69], v[62:65], v[110:113], v[66:69]
	ds_read_b128 v[118:121], v16 offset:53248
	v_mfma_f32_16x16x32_f16 v[44:47], v[74:77], v[90:93], v[44:47]
	ds_read_b128 v[122:125], v16 offset:55296
	v_mfma_f32_16x16x32_f16 v[78:81], v[74:77], v[110:113], v[78:81]
	s_waitcnt vmcnt(7)
	ds_write_b128 v17, v[58:61]
	s_waitcnt lgkmcnt(2)
	v_mfma_f32_16x16x32_f16 v[82:85], v[118:121], v[90:93], v[82:85]
	s_waitcnt vmcnt(6)
	ds_write_b128 v18, v[106:109]
	v_mfma_f32_16x16x32_f16 v[86:89], v[118:121], v[110:113], v[86:89]
	s_waitcnt vmcnt(5)
	ds_write_b128 v19, v[134:137]
	s_waitcnt lgkmcnt(3)
	v_mfma_f32_16x16x32_f16 v[28:31], v[122:125], v[90:93], v[28:31]
	ds_read_b128 v[90:93], v21 offset:20480
	v_mfma_f32_16x16x32_f16 v[32:35], v[122:125], v[110:113], v[32:35]
	ds_read_b128 v[110:113], v21 offset:22528
	s_waitcnt lgkmcnt(1)
	v_mfma_f32_16x16x32_f16 v[98:101], v[62:65], v[90:93], v[98:101]
	s_waitcnt vmcnt(4)
	ds_write_b128 v20, v[158:161]
	s_waitcnt lgkmcnt(1)
	v_mfma_f32_16x16x32_f16 v[52:55], v[62:65], v[110:113], v[52:55]
	ds_read_b128 v[62:65], v22 offset:49152
	v_mfma_f32_16x16x32_f16 v[102:105], v[74:77], v[90:93], v[102:105]
	s_waitcnt vmcnt(3)
	ds_write_b128 v17, v[94:97] offset:32768
	v_mfma_f32_16x16x32_f16 v[24:27], v[74:77], v[110:113], v[24:27]
	ds_read_b128 v[74:77], v22 offset:51200
	v_mfma_f32_16x16x32_f16 v[114:117], v[118:121], v[90:93], v[114:117]
	s_waitcnt vmcnt(2)
	ds_write_b128 v18, v[162:165] offset:32768
	v_mfma_f32_16x16x32_f16 v[40:43], v[118:121], v[110:113], v[40:43]
	ds_read_b128 v[118:121], v22 offset:53248
	v_mfma_f32_16x16x32_f16 v[70:73], v[122:125], v[90:93], v[70:73]
	ds_read_b128 v[90:93], v23 offset:16384
	v_mfma_f32_16x16x32_f16 v[48:51], v[122:125], v[110:113], v[48:51]
	ds_read_b128 v[110:113], v23 offset:18432
	s_waitcnt lgkmcnt(1)
	v_mfma_f32_16x16x32_f16 v[36:39], v[62:65], v[90:93], v[36:39]
	ds_read_b128 v[122:125], v22 offset:55296
	s_waitcnt lgkmcnt(1)
	v_mfma_f32_16x16x32_f16 v[66:69], v[62:65], v[110:113], v[66:69]
	s_waitcnt vmcnt(1)
	ds_write_b128 v19, v[166:169] offset:32768
	v_mfma_f32_16x16x32_f16 v[44:47], v[74:77], v[90:93], v[44:47]
	s_waitcnt vmcnt(0)
	ds_write_b128 v20, v[190:193] offset:32768
	v_mfma_f32_16x16x32_f16 v[78:81], v[74:77], v[110:113], v[78:81]
	v_mfma_f32_16x16x32_f16 v[82:85], v[118:121], v[90:93], v[82:85]
	v_mfma_f32_16x16x32_f16 v[86:89], v[118:121], v[110:113], v[86:89]
	s_waitcnt lgkmcnt(2)
	v_mfma_f32_16x16x32_f16 v[28:31], v[122:125], v[90:93], v[28:31]
	ds_read_b128 v[90:93], v23 offset:20480
	v_mfma_f32_16x16x32_f16 v[32:35], v[122:125], v[110:113], v[32:35]
	ds_read_b128 v[110:113], v23 offset:22528
	s_waitcnt lgkmcnt(1)
	v_mfma_f32_16x16x32_f16 v[98:101], v[62:65], v[90:93], v[98:101]
	s_waitcnt lgkmcnt(0)
	v_mfma_f32_16x16x32_f16 v[52:55], v[62:65], v[110:113], v[52:55]
	global_load_dwordx4 v[62:65], v[0:1], off offset:3968
	v_add_co_u32_e32 v0, vcc, s1, v0
	v_mfma_f32_16x16x32_f16 v[102:105], v[74:77], v[90:93], v[102:105]
	v_mfma_f32_16x16x32_f16 v[24:27], v[74:77], v[110:113], v[24:27]
	v_mfma_f32_16x16x32_f16 v[114:117], v[118:121], v[90:93], v[114:117]
	v_mfma_f32_16x16x32_f16 v[40:43], v[118:121], v[110:113], v[40:43]
	v_mfma_f32_16x16x32_f16 v[70:73], v[122:125], v[90:93], v[70:73]
	global_load_dwordx4 v[90:93], v[2:3], off offset:3968
	global_load_dwordx4 v[126:129], v[4:5], off offset:3968
	global_load_dwordx4 v[130:133], v[14:15], off offset:3968
	global_load_dwordx4 v[74:77], v[10:11], off offset:3968
	global_load_dwordx4 v[138:141], v[12:13], off offset:3968
	global_load_dwordx4 v[142:145], v[8:9], off offset:3968
	global_load_dwordx4 v[154:157], v[6:7], off offset:3968
	s_waitcnt lgkmcnt(0)
	s_barrier
	v_mfma_f32_16x16x32_f16 v[48:51], v[122:125], v[110:113], v[48:51]
	ds_read_b128 v[58:61], v16 offset:32768
	ds_read_b128 v[106:109], v21
	s_waitcnt lgkmcnt(0)
	v_mfma_f32_16x16x32_f16 v[36:39], v[58:61], v[106:109], v[36:39]
	ds_read_b128 v[94:97], v16 offset:34816
	ds_read_b128 v[110:113], v21 offset:2048
	s_waitcnt lgkmcnt(0)
	v_mfma_f32_16x16x32_f16 v[66:69], v[58:61], v[110:113], v[66:69]
	ds_read_b128 v[118:121], v16 offset:36864
	v_mfma_f32_16x16x32_f16 v[44:47], v[94:97], v[106:109], v[44:47]
	ds_read_b128 v[122:125], v16 offset:38912
	v_mfma_f32_16x16x32_f16 v[78:81], v[94:97], v[110:113], v[78:81]
	ds_read_b128 v[158:161], v23 offset:6144
	s_waitcnt lgkmcnt(2)
	v_mfma_f32_16x16x32_f16 v[82:85], v[118:121], v[106:109], v[82:85]
	v_addc_co_u32_e32 v1, vcc, 0, v1, vcc
	v_mfma_f32_16x16x32_f16 v[86:89], v[118:121], v[110:113], v[86:89]
	v_add_co_u32_e32 v2, vcc, s1, v2
	s_waitcnt lgkmcnt(1)
	v_mfma_f32_16x16x32_f16 v[28:31], v[122:125], v[106:109], v[28:31]
	ds_read_b128 v[106:109], v21 offset:4096
	v_mfma_f32_16x16x32_f16 v[32:35], v[122:125], v[110:113], v[32:35]
	ds_read_b128 v[110:113], v21 offset:6144
	s_waitcnt lgkmcnt(1)
	v_mfma_f32_16x16x32_f16 v[98:101], v[58:61], v[106:109], v[98:101]
	v_addc_co_u32_e32 v3, vcc, 0, v3, vcc
	s_waitcnt lgkmcnt(0)
; #define GL_LOAD(s_, kt_) if (VAR != 1) { a##s_##0 = GL_A(0, kt_); a##s_##1 = GL_A(1, kt_); a##s_##2 = GL_A(2, kt_); a##s_##3 = GL_A(3, kt_); b##s_##0 = GL_B(0, kt_); b##s_##1 = GL_B(1, kt_); b##s_##2 = GL_B(2, kt_); b##s_##3 = GL_B(3, kt_); }
; #define LDS_STORE(s_, buf_) if (VAR != 2) { LDS_ST1(sA, 0, buf_, a##s_##0) LDS_ST1(sA, 1, buf_, a##s_##1) LDS_ST1(sA, 2, buf_, a##s_##2) LDS_ST1(sA, 3, buf_, a##s_##3) LDS_ST1(sB, 0, buf_, b##s_##0) LDS_ST1(sB, 1, buf_, b##s_##1) LDS_ST1(sB, 2, buf_, b##s_##2) LDS_ST1(sB, 3, buf_, b##s_##3) }
;     ...
;   GL_LOAD(0, 0)
;   GL_LOAD(1, 1)
;   LDS_STORE(0, 0)
;   if (VAR != 4) __syncthreads();
; #pragma unroll
;   for (int kt = 0; kt < nk; kt += 2) {
;     if (kt + 2 < nk) { GL_LOAD(0, kt + 2) }
;     MMA_TILE(0)
;     LDS_STORE(1, 1)
;     if (VAR != 4) __syncthreads();
;     if (kt + 3 < nk) { GL_LOAD(1, kt + 3) }
;     MMA_TILE(1)
;     if (kt + 2 < nk) { LDS_STORE(0, 0) }
;     if (VAR != 4) __syncthreads();
	v_mfma_f32_16x16x32_f16 v[52:55], v[58:61], v[110:113], v[52:55]
	ds_read_b128 v[58:61], v22 offset:32768
	v_mfma_f32_16x16x32_f16 v[102:105], v[94:97], v[106:109], v[102:105]
	v_add_co_u32_e32 v4, vcc, s1, v4
	v_mfma_f32_16x16x32_f16 v[24:27], v[94:97], v[110:113], v[24:27]
	ds_read_b128 v[94:97], v22 offset:34816
	v_addc_co_u32_e32 v5, vcc, 0, v5, vcc
	v_mfma_f32_16x16x32_f16 v[114:117], v[118:121], v[106:109], v[114:117]
	v_add_co_u32_e32 v14, vcc, s1, v14
	s_nop 1
	v_addc_co_u32_e32 v15, vcc, 0, v15, vcc
	v_mfma_f32_16x16x32_f16 v[40:43], v[118:121], v[110:113], v[40:43]
	ds_read_b128 v[118:121], v22 offset:36864
	v_add_co_u32_e32 v10, vcc, s1, v10
	v_mfma_f32_16x16x32_f16 v[70:73], v[122:125], v[106:109], v[70:73]
	ds_read_b128 v[106:109], v23
	v_addc_co_u32_e32 v11, vcc, 0, v11, vcc
	v_mfma_f32_16x16x32_f16 v[48:51], v[122:125], v[110:113], v[48:51]
	ds_read_b128 v[110:113], v23 offset:2048
	ds_read_b128 v[122:125], v22 offset:38912
	s_waitcnt lgkmcnt(2)
	v_mfma_f32_16x16x32_f16 v[36:39], v[58:61], v[106:109], v[36:39]
	v_add_co_u32_e32 v12, vcc, s1, v12
	s_nop 1
	v_addc_co_u32_e32 v13, vcc, 0, v13, vcc
	s_waitcnt lgkmcnt(1)
	v_mfma_f32_16x16x32_f16 v[66:69], v[58:61], v[110:113], v[66:69]
	v_add_co_u32_e32 v8, vcc, s1, v8
	s_nop 1
	v_addc_co_u32_e32 v9, vcc, 0, v9, vcc
	v_mfma_f32_16x16x32_f16 v[44:47], v[94:97], v[106:109], v[44:47]
	v_add_co_u32_e32 v6, vcc, s1, v6
	s_nop 1
	v_addc_co_u32_e32 v7, vcc, 0, v7, vcc
	v_mfma_f32_16x16x32_f16 v[78:81], v[94:97], v[110:113], v[78:81]
	s_waitcnt vmcnt(7)
	ds_write_b128 v17, v[62:65] offset:16384
	s_waitcnt vmcnt(6)
	ds_write_b128 v18, v[90:93] offset:16384
	v_mfma_f32_16x16x32_f16 v[52:55], v[58:61], v[158:161], v[52:55]
	s_waitcnt vmcnt(5)
	ds_write_b128 v19, v[126:129] offset:16384
	s_waitcnt vmcnt(4)
	ds_write_b128 v20, v[130:133] offset:16384
	v_mfma_f32_16x16x32_f16 v[24:27], v[94:97], v[158:161], v[24:27]
	s_waitcnt vmcnt(3)
	ds_write_b128 v17, v[74:77] offset:49152
	s_waitcnt vmcnt(2)
	ds_write_b128 v18, v[138:141] offset:49152
	v_mfma_f32_16x16x32_f16 v[82:85], v[118:121], v[106:109], v[82:85]
	s_waitcnt vmcnt(1)
	ds_write_b128 v19, v[142:145] offset:49152
	s_waitcnt vmcnt(0)
	ds_write_b128 v20, v[154:157] offset:49152
	v_mfma_f32_16x16x32_f16 v[86:89], v[118:121], v[110:113], v[86:89]
	s_waitcnt lgkmcnt(8)
	v_mfma_f32_16x16x32_f16 v[28:31], v[122:125], v[106:109], v[28:31]
	ds_read_b128 v[106:109], v23 offset:4096
	v_mfma_f32_16x16x32_f16 v[32:35], v[122:125], v[110:113], v[32:35]
	global_load_dwordx4 v[110:113], v[0:1], off
	global_load_dwordx4 v[134:137], v[2:3], off
	v_mfma_f32_16x16x32_f16 v[40:43], v[118:121], v[158:161], v[40:43]
	global_load_dwordx4 v[162:165], v[4:5], off
	s_waitcnt lgkmcnt(0)
	v_mfma_f32_16x16x32_f16 v[98:101], v[58:61], v[106:109], v[98:101]
	global_load_dwordx4 v[166:169], v[14:15], off
	v_mfma_f32_16x16x32_f16 v[102:105], v[94:97], v[106:109], v[102:105]
	v_mfma_f32_16x16x32_f16 v[114:117], v[118:121], v[106:109], v[114:117]
	v_mfma_f32_16x16x32_f16 v[70:73], v[122:125], v[106:109], v[70:73]
	global_load_dwordx4 v[106:109], v[10:11], off
	global_load_dwordx4 v[190:193], v[12:13], off
	global_load_dwordx4 v[58:61], v[8:9], off
	global_load_dwordx4 v[94:97], v[6:7], off
	s_waitcnt lgkmcnt(0)
	s_barrier
	v_mfma_f32_16x16x32_f16 v[48:51], v[122:125], v[158:161], v[48:51]
	ds_read_b128 v[62:65], v16 offset:49152
	ds_read_b128 v[90:93], v21 offset:16384
	s_waitcnt lgkmcnt(0)
	v_mfma_f32_16x16x32_f16 v[36:39], v[62:65], v[90:93], v[36:39]
	ds_read_b128 v[74:77], v16 offset:51200
	ds_read_b128 v[118:121], v21 offset:18432
	s_waitcnt lgkmcnt(0)
	v_mfma_f32_16x16x32_f16 v[66:69], v[62:65], v[118:121], v[66:69]
	ds_read_b128 v[122:125], v16 offset:53248
	v_mfma_f32_16x16x32_f16 v[44:47], v[74:77], v[90:93], v[44:47]
	ds_read_b128 v[126:129], v16 offset:55296
	v_mfma_f32_16x16x32_f16 v[78:81], v[74:77], v[118:121], v[78:81]
	s_waitcnt vmcnt(7)
	ds_write_b128 v17, v[110:113]
	s_waitcnt lgkmcnt(2)
	v_mfma_f32_16x16x32_f16 v[82:85], v[122:125], v[90:93], v[82:85]
	s_waitcnt vmcnt(6)
	ds_write_b128 v18, v[134:137]
	v_mfma_f32_16x16x32_f16 v[86:89], v[122:125], v[118:121], v[86:89]
	s_waitcnt vmcnt(5)
	ds_write_b128 v19, v[162:165]
	s_waitcnt lgkmcnt(3)
	v_mfma_f32_16x16x32_f16 v[28:31], v[126:129], v[90:93], v[28:31]
	ds_read_b128 v[90:93], v21 offset:20480
	v_mfma_f32_16x16x32_f16 v[32:35], v[126:129], v[118:121], v[32:35]
	ds_read_b128 v[118:121], v21 offset:22528
	s_waitcnt lgkmcnt(1)
	v_mfma_f32_16x16x32_f16 v[98:101], v[62:65], v[90:93], v[98:101]
	s_waitcnt vmcnt(4)
	ds_write_b128 v20, v[166:169]
	s_waitcnt lgkmcnt(1)
	v_mfma_f32_16x16x32_f16 v[52:55], v[62:65], v[118:121], v[52:55]
	ds_read_b128 v[62:65], v22 offset:49152
	v_mfma_f32_16x16x32_f16 v[102:105], v[74:77], v[90:93], v[102:105]
	s_waitcnt vmcnt(3)
	ds_write_b128 v17, v[106:109] offset:32768
	v_mfma_f32_16x16x32_f16 v[24:27], v[74:77], v[118:121], v[24:27]
	ds_read_b128 v[74:77], v22 offset:51200
	v_mfma_f32_16x16x32_f16 v[114:117], v[122:125], v[90:93], v[114:117]
	s_waitcnt vmcnt(2)
	ds_write_b128 v18, v[190:193] offset:32768
	v_mfma_f32_16x16x32_f16 v[40:43], v[122:125], v[118:121], v[40:43]
	ds_read_b128 v[122:125], v22 offset:53248
	v_mfma_f32_16x16x32_f16 v[70:73], v[126:129], v[90:93], v[70:73]
	ds_read_b128 v[90:93], v23 offset:16384
	v_mfma_f32_16x16x32_f16 v[48:51], v[126:129], v[118:121], v[48:51]
	ds_read_b128 v[118:121], v23 offset:18432
	s_waitcnt lgkmcnt(1)
	v_mfma_f32_16x16x32_f16 v[36:39], v[62:65], v[90:93], v[36:39]
	ds_read_b128 v[126:129], v22 offset:55296
	s_waitcnt lgkmcnt(1)
	v_mfma_f32_16x16x32_f16 v[66:69], v[62:65], v[118:121], v[66:69]
	s_waitcnt vmcnt(1)
; #define GL_LOAD(s_, kt_) if (VAR != 1) { a##s_##0 = GL_A(0, kt_); a##s_##1 = GL_A(1, kt_); a##s_##2 = GL_A(2, kt_); a##s_##3 = GL_A(3, kt_); b##s_##0 = GL_B(0, kt_); b##s_##1 = GL_B(1, kt_); b##s_##2 = GL_B(2, kt_); b##s_##3 = GL_B(3, kt_); }
; #define LDS_STORE(s_, buf_) if (VAR != 2) { LDS_ST1(sA, 0, buf_, a##s_##0) LDS_ST1(sA, 1, buf_, a##s_##1) LDS_ST1(sA, 2, buf_, a##s_##2) LDS_ST1(sA, 3, buf_, a##s_##3) LDS_ST1(sB, 0, buf_, b##s_##0) LDS_ST1(sB, 1, buf_, b##s_##1) LDS_ST1(sB, 2, buf_, b##s_##2) LDS_ST1(sB, 3, buf_, b##s_##3) }
;     ...
;   GL_LOAD(0, 0)
;   GL_LOAD(1, 1)
;   LDS_STORE(0, 0)
;   if (VAR != 4) __syncthreads();
; #pragma unroll
;   for (int kt = 0; kt < nk; kt += 2) {
;     if (kt + 2 < nk) { GL_LOAD(0, kt + 2) }
;     MMA_TILE(0)
;     LDS_STORE(1, 1)
;     if (VAR != 4) __syncthreads();
;     if (kt + 3 < nk) { GL_LOAD(1, kt + 3) }
;     MMA_TILE(1)
;     if (kt + 2 < nk) { LDS_STORE(0, 0) }
;     if (VAR != 4) __syncthreads();
	ds_write_b128 v19, v[58:61] offset:32768
	v_mfma_f32_16x16x32_f16 v[44:47], v[74:77], v[90:93], v[44:47]
	s_waitcnt vmcnt(0)
	ds_write_b128 v20, v[94:97] offset:32768
	v_mfma_f32_16x16x32_f16 v[78:81], v[74:77], v[118:121], v[78:81]
	v_mfma_f32_16x16x32_f16 v[82:85], v[122:125], v[90:93], v[82:85]
	v_mfma_f32_16x16x32_f16 v[86:89], v[122:125], v[118:121], v[86:89]
	s_waitcnt lgkmcnt(2)
	v_mfma_f32_16x16x32_f16 v[28:31], v[126:129], v[90:93], v[28:31]
	ds_read_b128 v[90:93], v23 offset:20480
	v_mfma_f32_16x16x32_f16 v[32:35], v[126:129], v[118:121], v[32:35]
	ds_read_b128 v[118:121], v23 offset:22528
	s_waitcnt lgkmcnt(1)
	v_mfma_f32_16x16x32_f16 v[98:101], v[62:65], v[90:93], v[98:101]
	s_waitcnt lgkmcnt(0)
	v_mfma_f32_16x16x32_f16 v[52:55], v[62:65], v[118:121], v[52:55]
	global_load_dwordx4 v[62:65], v[0:1], off offset:128
	v_mfma_f32_16x16x32_f16 v[102:105], v[74:77], v[90:93], v[102:105]
	v_mfma_f32_16x16x32_f16 v[24:27], v[74:77], v[118:121], v[24:27]
	v_mfma_f32_16x16x32_f16 v[114:117], v[122:125], v[90:93], v[114:117]
	v_mfma_f32_16x16x32_f16 v[40:43], v[122:125], v[118:121], v[40:43]
	v_mfma_f32_16x16x32_f16 v[70:73], v[126:129], v[90:93], v[70:73]
	global_load_dwordx4 v[90:93], v[2:3], off offset:128
	global_load_dwordx4 v[130:133], v[4:5], off offset:128
	global_load_dwordx4 v[138:141], v[14:15], off offset:128
	global_load_dwordx4 v[74:77], v[10:11], off offset:128
	global_load_dwordx4 v[142:145], v[12:13], off offset:128
	global_load_dwordx4 v[154:157], v[8:9], off offset:128
	global_load_dwordx4 v[158:161], v[6:7], off offset:128
	s_waitcnt lgkmcnt(0)
	s_barrier
	v_mfma_f32_16x16x32_f16 v[48:51], v[126:129], v[118:121], v[48:51]
	ds_read_b128 v[58:61], v16 offset:32768
	ds_read_b128 v[106:109], v21
	s_waitcnt lgkmcnt(0)
	v_mfma_f32_16x16x32_f16 v[36:39], v[58:61], v[106:109], v[36:39]
	ds_read_b128 v[94:97], v16 offset:34816
	ds_read_b128 v[110:113], v21 offset:2048
	s_waitcnt lgkmcnt(0)
	v_mfma_f32_16x16x32_f16 v[66:69], v[58:61], v[110:113], v[66:69]
	ds_read_b128 v[118:121], v16 offset:36864
	v_mfma_f32_16x16x32_f16 v[44:47], v[94:97], v[106:109], v[44:47]
	ds_read_b128 v[122:125], v16 offset:38912
	v_mfma_f32_16x16x32_f16 v[78:81], v[94:97], v[110:113], v[78:81]
	s_waitcnt vmcnt(7)
	ds_write_b128 v17, v[62:65] offset:16384
	s_waitcnt lgkmcnt(2)
	v_mfma_f32_16x16x32_f16 v[82:85], v[118:121], v[106:109], v[82:85]
	s_waitcnt vmcnt(6)
	ds_write_b128 v18, v[90:93] offset:16384
	v_mfma_f32_16x16x32_f16 v[86:89], v[118:121], v[110:113], v[86:89]
	s_waitcnt vmcnt(5)
	ds_write_b128 v19, v[130:133] offset:16384
	s_waitcnt lgkmcnt(3)
	v_mfma_f32_16x16x32_f16 v[28:31], v[122:125], v[106:109], v[28:31]
	ds_read_b128 v[106:109], v21 offset:4096
	v_mfma_f32_16x16x32_f16 v[32:35], v[122:125], v[110:113], v[32:35]
	ds_read_b128 v[110:113], v21 offset:6144
	s_waitcnt lgkmcnt(1)
	v_mfma_f32_16x16x32_f16 v[98:101], v[58:61], v[106:109], v[98:101]
	s_waitcnt vmcnt(4)
	ds_write_b128 v20, v[138:141] offset:16384
	s_waitcnt lgkmcnt(1)
	v_mfma_f32_16x16x32_f16 v[52:55], v[58:61], v[110:113], v[52:55]
	ds_read_b128 v[58:61], v22 offset:32768
	v_mfma_f32_16x16x32_f16 v[102:105], v[94:97], v[106:109], v[102:105]
	s_waitcnt vmcnt(3)
	ds_write_b128 v17, v[74:77] offset:49152
	v_mfma_f32_16x16x32_f16 v[24:27], v[94:97], v[110:113], v[24:27]
	ds_read_b128 v[94:97], v22 offset:34816
	v_mfma_f32_16x16x32_f16 v[114:117], v[118:121], v[106:109], v[114:117]
	s_waitcnt vmcnt(2)
	ds_write_b128 v18, v[142:145] offset:49152
	v_mfma_f32_16x16x32_f16 v[40:43], v[118:121], v[110:113], v[40:43]
	ds_read_b128 v[118:121], v22 offset:36864
	v_mfma_f32_16x16x32_f16 v[70:73], v[122:125], v[106:109], v[70:73]
	ds_read_b128 v[106:109], v23
	v_mfma_f32_16x16x32_f16 v[48:51], v[122:125], v[110:113], v[48:51]
	ds_read_b128 v[110:113], v23 offset:2048
	s_waitcnt lgkmcnt(1)
	v_mfma_f32_16x16x32_f16 v[36:39], v[58:61], v[106:109], v[36:39]
	ds_read_b128 v[122:125], v22 offset:38912
	s_waitcnt lgkmcnt(1)
	v_mfma_f32_16x16x32_f16 v[66:69], v[58:61], v[110:113], v[66:69]
	s_waitcnt vmcnt(1)
	ds_write_b128 v19, v[154:157] offset:49152
	v_mfma_f32_16x16x32_f16 v[44:47], v[94:97], v[106:109], v[44:47]
	s_waitcnt vmcnt(0)
	ds_write_b128 v20, v[158:161] offset:49152
	v_mfma_f32_16x16x32_f16 v[78:81], v[94:97], v[110:113], v[78:81]
	v_mfma_f32_16x16x32_f16 v[82:85], v[118:121], v[106:109], v[82:85]
	v_mfma_f32_16x16x32_f16 v[86:89], v[118:121], v[110:113], v[86:89]
	s_waitcnt lgkmcnt(2)
	v_mfma_f32_16x16x32_f16 v[28:31], v[122:125], v[106:109], v[28:31]
	ds_read_b128 v[106:109], v23 offset:4096
	v_mfma_f32_16x16x32_f16 v[32:35], v[122:125], v[110:113], v[32:35]
	ds_read_b128 v[110:113], v23 offset:6144
	s_waitcnt lgkmcnt(1)
	v_mfma_f32_16x16x32_f16 v[98:101], v[58:61], v[106:109], v[98:101]
	s_waitcnt lgkmcnt(0)
	v_mfma_f32_16x16x32_f16 v[52:55], v[58:61], v[110:113], v[52:55]
	global_load_dwordx4 v[58:61], v[0:1], off offset:256
	v_mfma_f32_16x16x32_f16 v[102:105], v[94:97], v[106:109], v[102:105]
	v_mfma_f32_16x16x32_f16 v[24:27], v[94:97], v[110:113], v[24:27]
	v_mfma_f32_16x16x32_f16 v[114:117], v[118:121], v[106:109], v[114:117]
	v_mfma_f32_16x16x32_f16 v[40:43], v[118:121], v[110:113], v[40:43]
	v_mfma_f32_16x16x32_f16 v[70:73], v[122:125], v[106:109], v[70:73]
	global_load_dwordx4 v[106:109], v[2:3], off offset:256
	global_load_dwordx4 v[126:129], v[4:5], off offset:256
	global_load_dwordx4 v[134:137], v[14:15], off offset:256
	global_load_dwordx4 v[94:97], v[10:11], off offset:256
	global_load_dwordx4 v[162:165], v[12:13], off offset:256
	global_load_dwordx4 v[166:169], v[8:9], off offset:256
	global_load_dwordx4 v[190:193], v[6:7], off offset:256
	s_waitcnt lgkmcnt(0)
	s_barrier
; #define GL_LOAD(s_, kt_) if (VAR != 1) { a##s_##0 = GL_A(0, kt_); a##s_##1 = GL_A(1, kt_); a##s_##2 = GL_A(2, kt_); a##s_##3 = GL_A(3, kt_); b##s_##0 = GL_B(0, kt_); b##s_##1 = GL_B(1, kt_); b##s_##2 = GL_B(2, kt_); b##s_##3 = GL_B(3, kt_); }
; #define LDS_STORE(s_, buf_) if (VAR != 2) { LDS_ST1(sA, 0, buf_, a##s_##0) LDS_ST1(sA, 1, buf_, a##s_##1) LDS_ST1(sA, 2, buf_, a##s_##2) LDS_ST1(sA, 3, buf_, a##s_##3) LDS_ST1(sB, 0, buf_, b##s_##0) LDS_ST1(sB, 1, buf_, b##s_##1) LDS_ST1(sB, 2, buf_, b##s_##2) LDS_ST1(sB, 3, buf_, b##s_##3) }
;     ...
;   GL_LOAD(0, 0)
;   GL_LOAD(1, 1)
;   LDS_STORE(0, 0)
;   if (VAR != 4) __syncthreads();
; #pragma unroll
;   for (int kt = 0; kt < nk; kt += 2) {
;     if (kt + 2 < nk) { GL_LOAD(0, kt + 2) }
;     MMA_TILE(0)
;     LDS_STORE(1, 1)
;     if (VAR != 4) __syncthreads();
;     if (kt + 3 < nk) { GL_LOAD(1, kt + 3) }
;     MMA_TILE(1)
;     if (kt + 2 < nk) { LDS_STORE(0, 0) }
;     if (VAR != 4) __syncthreads();
	v_mfma_f32_16x16x32_f16 v[48:51], v[122:125], v[110:113], v[48:51]
	ds_read_b128 v[62:65], v16 offset:49152
	ds_read_b128 v[90:93], v21 offset:16384
	s_waitcnt lgkmcnt(0)
	v_mfma_f32_16x16x32_f16 v[36:39], v[62:65], v[90:93], v[36:39]
	ds_read_b128 v[74:77], v16 offset:51200
	ds_read_b128 v[110:113], v21 offset:18432
	s_waitcnt lgkmcnt(0)
	v_mfma_f32_16x16x32_f16 v[66:69], v[62:65], v[110:113], v[66:69]
	ds_read_b128 v[118:121], v16 offset:53248
	v_mfma_f32_16x16x32_f16 v[44:47], v[74:77], v[90:93], v[44:47]
	ds_read_b128 v[122:125], v16 offset:55296
	v_mfma_f32_16x16x32_f16 v[78:81], v[74:77], v[110:113], v[78:81]
	s_waitcnt vmcnt(7)
	ds_write_b128 v17, v[58:61]
	s_waitcnt lgkmcnt(2)
	v_mfma_f32_16x16x32_f16 v[82:85], v[118:121], v[90:93], v[82:85]
	s_waitcnt vmcnt(6)
	ds_write_b128 v18, v[106:109]
	v_mfma_f32_16x16x32_f16 v[86:89], v[118:121], v[110:113], v[86:89]
	s_waitcnt vmcnt(5)
	ds_write_b128 v19, v[126:129]
	s_waitcnt lgkmcnt(3)
	v_mfma_f32_16x16x32_f16 v[28:31], v[122:125], v[90:93], v[28:31]
	ds_read_b128 v[90:93], v21 offset:20480
	v_mfma_f32_16x16x32_f16 v[32:35], v[122:125], v[110:113], v[32:35]
	ds_read_b128 v[110:113], v21 offset:22528
	s_waitcnt lgkmcnt(1)
	v_mfma_f32_16x16x32_f16 v[98:101], v[62:65], v[90:93], v[98:101]
	s_waitcnt vmcnt(4)
	ds_write_b128 v20, v[134:137]
	s_waitcnt lgkmcnt(1)
	v_mfma_f32_16x16x32_f16 v[52:55], v[62:65], v[110:113], v[52:55]
	ds_read_b128 v[62:65], v22 offset:49152
	v_mfma_f32_16x16x32_f16 v[102:105], v[74:77], v[90:93], v[102:105]
	s_waitcnt vmcnt(3)
	ds_write_b128 v17, v[94:97] offset:32768
	v_mfma_f32_16x16x32_f16 v[24:27], v[74:77], v[110:113], v[24:27]
	ds_read_b128 v[74:77], v22 offset:51200
	v_mfma_f32_16x16x32_f16 v[114:117], v[118:121], v[90:93], v[114:117]
	s_waitcnt vmcnt(2)
	ds_write_b128 v18, v[162:165] offset:32768
	v_mfma_f32_16x16x32_f16 v[40:43], v[118:121], v[110:113], v[40:43]
	ds_read_b128 v[118:121], v22 offset:53248
	v_mfma_f32_16x16x32_f16 v[70:73], v[122:125], v[90:93], v[70:73]
	ds_read_b128 v[90:93], v23 offset:16384
	v_mfma_f32_16x16x32_f16 v[48:51], v[122:125], v[110:113], v[48:51]
	ds_read_b128 v[110:113], v23 offset:18432
	s_waitcnt lgkmcnt(1)
	v_mfma_f32_16x16x32_f16 v[36:39], v[62:65], v[90:93], v[36:39]
	ds_read_b128 v[122:125], v22 offset:55296
	s_waitcnt lgkmcnt(1)
	v_mfma_f32_16x16x32_f16 v[66:69], v[62:65], v[110:113], v[66:69]
	s_waitcnt vmcnt(1)
	ds_write_b128 v19, v[166:169] offset:32768
	v_mfma_f32_16x16x32_f16 v[44:47], v[74:77], v[90:93], v[44:47]
	s_waitcnt vmcnt(0)
	ds_write_b128 v20, v[190:193] offset:32768
	v_mfma_f32_16x16x32_f16 v[78:81], v[74:77], v[110:113], v[78:81]
	v_mfma_f32_16x16x32_f16 v[82:85], v[118:121], v[90:93], v[82:85]
	v_mfma_f32_16x16x32_f16 v[86:89], v[118:121], v[110:113], v[86:89]
	s_waitcnt lgkmcnt(2)
	v_mfma_f32_16x16x32_f16 v[28:31], v[122:125], v[90:93], v[28:31]
	ds_read_b128 v[90:93], v23 offset:20480
	v_mfma_f32_16x16x32_f16 v[32:35], v[122:125], v[110:113], v[32:35]
	ds_read_b128 v[110:113], v23 offset:22528
	s_waitcnt lgkmcnt(1)
	v_mfma_f32_16x16x32_f16 v[98:101], v[62:65], v[90:93], v[98:101]
	s_waitcnt lgkmcnt(0)
	v_mfma_f32_16x16x32_f16 v[52:55], v[62:65], v[110:113], v[52:55]
	global_load_dwordx4 v[62:65], v[0:1], off offset:384
	v_mfma_f32_16x16x32_f16 v[102:105], v[74:77], v[90:93], v[102:105]
	v_mfma_f32_16x16x32_f16 v[24:27], v[74:77], v[110:113], v[24:27]
	v_mfma_f32_16x16x32_f16 v[114:117], v[118:121], v[90:93], v[114:117]
	v_mfma_f32_16x16x32_f16 v[40:43], v[118:121], v[110:113], v[40:43]
	v_mfma_f32_16x16x32_f16 v[70:73], v[122:125], v[90:93], v[70:73]
	global_load_dwordx4 v[90:93], v[2:3], off offset:384
	global_load_dwordx4 v[130:133], v[4:5], off offset:384
	global_load_dwordx4 v[138:141], v[14:15], off offset:384
	global_load_dwordx4 v[74:77], v[10:11], off offset:384
	global_load_dwordx4 v[142:145], v[12:13], off offset:384
	global_load_dwordx4 v[154:157], v[8:9], off offset:384
	global_load_dwordx4 v[158:161], v[6:7], off offset:384
	s_waitcnt lgkmcnt(0)
	s_barrier
	v_mfma_f32_16x16x32_f16 v[48:51], v[122:125], v[110:113], v[48:51]
	ds_read_b128 v[58:61], v16 offset:32768
	ds_read_b128 v[106:109], v21
	s_waitcnt lgkmcnt(0)
	v_mfma_f32_16x16x32_f16 v[36:39], v[58:61], v[106:109], v[36:39]
	ds_read_b128 v[94:97], v16 offset:34816
	ds_read_b128 v[110:113], v21 offset:2048
	s_waitcnt lgkmcnt(0)
	v_mfma_f32_16x16x32_f16 v[66:69], v[58:61], v[110:113], v[66:69]
	ds_read_b128 v[118:121], v16 offset:36864
	v_mfma_f32_16x16x32_f16 v[44:47], v[94:97], v[106:109], v[44:47]
	ds_read_b128 v[122:125], v16 offset:38912
	v_mfma_f32_16x16x32_f16 v[78:81], v[94:97], v[110:113], v[78:81]
	s_waitcnt vmcnt(7)
	ds_write_b128 v17, v[62:65] offset:16384
	s_waitcnt lgkmcnt(2)
	v_mfma_f32_16x16x32_f16 v[82:85], v[118:121], v[106:109], v[82:85]
	s_waitcnt vmcnt(6)
	ds_write_b128 v18, v[90:93] offset:16384
	v_mfma_f32_16x16x32_f16 v[86:89], v[118:121], v[110:113], v[86:89]
	s_waitcnt vmcnt(5)
	ds_write_b128 v19, v[130:133] offset:16384
	s_waitcnt lgkmcnt(3)
	v_mfma_f32_16x16x32_f16 v[28:31], v[122:125], v[106:109], v[28:31]
	ds_read_b128 v[106:109], v21 offset:4096
	v_mfma_f32_16x16x32_f16 v[32:35], v[122:125], v[110:113], v[32:35]
	ds_read_b128 v[110:113], v21 offset:6144
	s_waitcnt lgkmcnt(1)
	v_mfma_f32_16x16x32_f16 v[98:101], v[58:61], v[106:109], v[98:101]
	s_waitcnt vmcnt(4)
	ds_write_b128 v20, v[138:141] offset:16384
	s_waitcnt lgkmcnt(1)
	v_mfma_f32_16x16x32_f16 v[52:55], v[58:61], v[110:113], v[52:55]
	ds_read_b128 v[58:61], v22 offset:32768
	v_mfma_f32_16x16x32_f16 v[102:105], v[94:97], v[106:109], v[102:105]
	s_waitcnt vmcnt(3)
; #define GL_LOAD(s_, kt_) if (VAR != 1) { a##s_##0 = GL_A(0, kt_); a##s_##1 = GL_A(1, kt_); a##s_##2 = GL_A(2, kt_); a##s_##3 = GL_A(3, kt_); b##s_##0 = GL_B(0, kt_); b##s_##1 = GL_B(1, kt_); b##s_##2 = GL_B(2, kt_); b##s_##3 = GL_B(3, kt_); }
; #define LDS_STORE(s_, buf_) if (VAR != 2) { LDS_ST1(sA, 0, buf_, a##s_##0) LDS_ST1(sA, 1, buf_, a##s_##1) LDS_ST1(sA, 2, buf_, a##s_##2) LDS_ST1(sA, 3, buf_, a##s_##3) LDS_ST1(sB, 0, buf_, b##s_##0) LDS_ST1(sB, 1, buf_, b##s_##1) LDS_ST1(sB, 2, buf_, b##s_##2) LDS_ST1(sB, 3, buf_, b##s_##3) }
;     ...
;   GL_LOAD(0, 0)
;   GL_LOAD(1, 1)
;   LDS_STORE(0, 0)
;   if (VAR != 4) __syncthreads();
; #pragma unroll
;   for (int kt = 0; kt < nk; kt += 2) {
;     if (kt + 2 < nk) { GL_LOAD(0, kt + 2) }
;     MMA_TILE(0)
;     LDS_STORE(1, 1)
;     if (VAR != 4) __syncthreads();
;     if (kt + 3 < nk) { GL_LOAD(1, kt + 3) }
;     MMA_TILE(1)
;     if (kt + 2 < nk) { LDS_STORE(0, 0) }
;     if (VAR != 4) __syncthreads();
	ds_write_b128 v17, v[74:77] offset:49152
	v_mfma_f32_16x16x32_f16 v[24:27], v[94:97], v[110:113], v[24:27]
	ds_read_b128 v[94:97], v22 offset:34816
	v_mfma_f32_16x16x32_f16 v[114:117], v[118:121], v[106:109], v[114:117]
	s_waitcnt vmcnt(2)
	ds_write_b128 v18, v[142:145] offset:49152
	v_mfma_f32_16x16x32_f16 v[40:43], v[118:121], v[110:113], v[40:43]
	ds_read_b128 v[118:121], v22 offset:36864
	v_mfma_f32_16x16x32_f16 v[70:73], v[122:125], v[106:109], v[70:73]
	ds_read_b128 v[106:109], v23
	v_mfma_f32_16x16x32_f16 v[48:51], v[122:125], v[110:113], v[48:51]
	ds_read_b128 v[110:113], v23 offset:2048
	s_waitcnt lgkmcnt(1)
	v_mfma_f32_16x16x32_f16 v[36:39], v[58:61], v[106:109], v[36:39]
	ds_read_b128 v[122:125], v22 offset:38912
	s_waitcnt lgkmcnt(1)
	v_mfma_f32_16x16x32_f16 v[66:69], v[58:61], v[110:113], v[66:69]
	s_waitcnt vmcnt(1)
	ds_write_b128 v19, v[154:157] offset:49152
	v_mfma_f32_16x16x32_f16 v[44:47], v[94:97], v[106:109], v[44:47]
	s_waitcnt vmcnt(0)
	ds_write_b128 v20, v[158:161] offset:49152
	v_mfma_f32_16x16x32_f16 v[78:81], v[94:97], v[110:113], v[78:81]
	v_mfma_f32_16x16x32_f16 v[82:85], v[118:121], v[106:109], v[82:85]
	v_mfma_f32_16x16x32_f16 v[86:89], v[118:121], v[110:113], v[86:89]
	s_waitcnt lgkmcnt(2)
	v_mfma_f32_16x16x32_f16 v[28:31], v[122:125], v[106:109], v[28:31]
	ds_read_b128 v[106:109], v23 offset:4096
	v_mfma_f32_16x16x32_f16 v[32:35], v[122:125], v[110:113], v[32:35]
	ds_read_b128 v[110:113], v23 offset:6144
	s_waitcnt lgkmcnt(1)
	v_mfma_f32_16x16x32_f16 v[98:101], v[58:61], v[106:109], v[98:101]
	s_waitcnt lgkmcnt(0)
	v_mfma_f32_16x16x32_f16 v[52:55], v[58:61], v[110:113], v[52:55]
	global_load_dwordx4 v[58:61], v[0:1], off offset:512
	v_mfma_f32_16x16x32_f16 v[102:105], v[94:97], v[106:109], v[102:105]
	v_mfma_f32_16x16x32_f16 v[24:27], v[94:97], v[110:113], v[24:27]
	v_mfma_f32_16x16x32_f16 v[114:117], v[118:121], v[106:109], v[114:117]
	v_mfma_f32_16x16x32_f16 v[40:43], v[118:121], v[110:113], v[40:43]
	v_mfma_f32_16x16x32_f16 v[70:73], v[122:125], v[106:109], v[70:73]
	global_load_dwordx4 v[106:109], v[2:3], off offset:512
	global_load_dwordx4 v[126:129], v[4:5], off offset:512
	global_load_dwordx4 v[134:137], v[14:15], off offset:512
	global_load_dwordx4 v[94:97], v[10:11], off offset:512
	global_load_dwordx4 v[162:165], v[12:13], off offset:512
	global_load_dwordx4 v[166:169], v[8:9], off offset:512
	global_load_dwordx4 v[190:193], v[6:7], off offset:512
	s_waitcnt lgkmcnt(0)
	s_barrier
	v_mfma_f32_16x16x32_f16 v[48:51], v[122:125], v[110:113], v[48:51]
	ds_read_b128 v[62:65], v16 offset:49152
	ds_read_b128 v[90:93], v21 offset:16384
	s_waitcnt lgkmcnt(0)
	v_mfma_f32_16x16x32_f16 v[36:39], v[62:65], v[90:93], v[36:39]
	ds_read_b128 v[74:77], v16 offset:51200
	ds_read_b128 v[110:113], v21 offset:18432
	s_waitcnt lgkmcnt(0)
	v_mfma_f32_16x16x32_f16 v[66:69], v[62:65], v[110:113], v[66:69]
	ds_read_b128 v[118:121], v16 offset:53248
	v_mfma_f32_16x16x32_f16 v[44:47], v[74:77], v[90:93], v[44:47]
	ds_read_b128 v[122:125], v16 offset:55296
	v_mfma_f32_16x16x32_f16 v[78:81], v[74:77], v[110:113], v[78:81]
	s_waitcnt vmcnt(7)
	ds_write_b128 v17, v[58:61]
	s_waitcnt lgkmcnt(2)
	v_mfma_f32_16x16x32_f16 v[82:85], v[118:121], v[90:93], v[82:85]
	s_waitcnt vmcnt(6)
	ds_write_b128 v18, v[106:109]
	v_mfma_f32_16x16x32_f16 v[86:89], v[118:121], v[110:113], v[86:89]
	s_waitcnt vmcnt(5)
	ds_write_b128 v19, v[126:129]
	s_waitcnt lgkmcnt(3)
	v_mfma_f32_16x16x32_f16 v[28:31], v[122:125], v[90:93], v[28:31]
	ds_read_b128 v[90:93], v21 offset:20480
	v_mfma_f32_16x16x32_f16 v[32:35], v[122:125], v[110:113], v[32:35]
	ds_read_b128 v[110:113], v21 offset:22528
	s_waitcnt lgkmcnt(1)
	v_mfma_f32_16x16x32_f16 v[98:101], v[62:65], v[90:93], v[98:101]
	s_waitcnt vmcnt(4)
	ds_write_b128 v20, v[134:137]
	s_waitcnt lgkmcnt(1)
	v_mfma_f32_16x16x32_f16 v[52:55], v[62:65], v[110:113], v[52:55]
	ds_read_b128 v[62:65], v22 offset:49152
	v_mfma_f32_16x16x32_f16 v[102:105], v[74:77], v[90:93], v[102:105]
	s_waitcnt vmcnt(3)
	ds_write_b128 v17, v[94:97] offset:32768
	v_mfma_f32_16x16x32_f16 v[24:27], v[74:77], v[110:113], v[24:27]
	ds_read_b128 v[74:77], v22 offset:51200
	v_mfma_f32_16x16x32_f16 v[114:117], v[118:121], v[90:93], v[114:117]
	s_waitcnt vmcnt(2)
	ds_write_b128 v18, v[162:165] offset:32768
	v_mfma_f32_16x16x32_f16 v[40:43], v[118:121], v[110:113], v[40:43]
	ds_read_b128 v[118:121], v22 offset:53248
	v_mfma_f32_16x16x32_f16 v[70:73], v[122:125], v[90:93], v[70:73]
	ds_read_b128 v[90:93], v23 offset:16384
	v_mfma_f32_16x16x32_f16 v[48:51], v[122:125], v[110:113], v[48:51]
	ds_read_b128 v[110:113], v23 offset:18432
	s_waitcnt lgkmcnt(1)
	v_mfma_f32_16x16x32_f16 v[36:39], v[62:65], v[90:93], v[36:39]
	ds_read_b128 v[122:125], v22 offset:55296
	s_waitcnt lgkmcnt(1)
	v_mfma_f32_16x16x32_f16 v[66:69], v[62:65], v[110:113], v[66:69]
	s_waitcnt vmcnt(1)
	ds_write_b128 v19, v[166:169] offset:32768
	v_mfma_f32_16x16x32_f16 v[44:47], v[74:77], v[90:93], v[44:47]
	s_waitcnt vmcnt(0)
	ds_write_b128 v20, v[190:193] offset:32768
	v_mfma_f32_16x16x32_f16 v[78:81], v[74:77], v[110:113], v[78:81]
	v_mfma_f32_16x16x32_f16 v[82:85], v[118:121], v[90:93], v[82:85]
	v_mfma_f32_16x16x32_f16 v[86:89], v[118:121], v[110:113], v[86:89]
	s_waitcnt lgkmcnt(2)
	v_mfma_f32_16x16x32_f16 v[28:31], v[122:125], v[90:93], v[28:31]
	ds_read_b128 v[90:93], v23 offset:20480
	v_mfma_f32_16x16x32_f16 v[32:35], v[122:125], v[110:113], v[32:35]
	ds_read_b128 v[110:113], v23 offset:22528
	s_waitcnt lgkmcnt(1)
	v_mfma_f32_16x16x32_f16 v[98:101], v[62:65], v[90:93], v[98:101]
	s_waitcnt lgkmcnt(0)
	v_mfma_f32_16x16x32_f16 v[52:55], v[62:65], v[110:113], v[52:55]
	global_load_dwordx4 v[62:65], v[0:1], off offset:640
	v_mfma_f32_16x16x32_f16 v[102:105], v[74:77], v[90:93], v[102:105]
	v_mfma_f32_16x16x32_f16 v[24:27], v[74:77], v[110:113], v[24:27]
	v_mfma_f32_16x16x32_f16 v[114:117], v[118:121], v[90:93], v[114:117]
	v_mfma_f32_16x16x32_f16 v[40:43], v[118:121], v[110:113], v[40:43]
	v_mfma_f32_16x16x32_f16 v[70:73], v[122:125], v[90:93], v[70:73]
	global_load_dwordx4 v[90:93], v[2:3], off offset:640
	global_load_dwordx4 v[130:133], v[4:5], off offset:640
	global_load_dwordx4 v[138:141], v[14:15], off offset:640
	global_load_dwordx4 v[74:77], v[10:11], off offset:640
	global_load_dwordx4 v[142:145], v[12:13], off offset:640
	global_load_dwordx4 v[154:157], v[8:9], off offset:640
	global_load_dwordx4 v[158:161], v[6:7], off offset:640
	s_waitcnt lgkmcnt(0)
	s_barrier
; #define GL_LOAD(s_, kt_) if (VAR != 1) { a##s_##0 = GL_A(0, kt_); a##s_##1 = GL_A(1, kt_); a##s_##2 = GL_A(2, kt_); a##s_##3 = GL_A(3, kt_); b##s_##0 = GL_B(0, kt_); b##s_##1 = GL_B(1, kt_); b##s_##2 = GL_B(2, kt_); b##s_##3 = GL_B(3, kt_); }
; #define LDS_STORE(s_, buf_) if (VAR != 2) { LDS_ST1(sA, 0, buf_, a##s_##0) LDS_ST1(sA, 1, buf_, a##s_##1) LDS_ST1(sA, 2, buf_, a##s_##2) LDS_ST1(sA, 3, buf_, a##s_##3) LDS_ST1(sB, 0, buf_, b##s_##0) LDS_ST1(sB, 1, buf_, b##s_##1) LDS_ST1(sB, 2, buf_, b##s_##2) LDS_ST1(sB, 3, buf_, b##s_##3) }
;     ...
;   GL_LOAD(0, 0)
;   GL_LOAD(1, 1)
;   LDS_STORE(0, 0)
;   if (VAR != 4) __syncthreads();
; #pragma unroll
;   for (int kt = 0; kt < nk; kt += 2) {
;     if (kt + 2 < nk) { GL_LOAD(0, kt + 2) }
;     MMA_TILE(0)
;     LDS_STORE(1, 1)
;     if (VAR != 4) __syncthreads();
;     if (kt + 3 < nk) { GL_LOAD(1, kt + 3) }
;     MMA_TILE(1)
;     if (kt + 2 < nk) { LDS_STORE(0, 0) }
;     if (VAR != 4) __syncthreads();
	v_mfma_f32_16x16x32_f16 v[48:51], v[122:125], v[110:113], v[48:51]
	ds_read_b128 v[58:61], v16 offset:32768
	ds_read_b128 v[106:109], v21
	s_waitcnt lgkmcnt(0)
	v_mfma_f32_16x16x32_f16 v[36:39], v[58:61], v[106:109], v[36:39]
	ds_read_b128 v[94:97], v16 offset:34816
	ds_read_b128 v[110:113], v21 offset:2048
	s_waitcnt lgkmcnt(0)
	v_mfma_f32_16x16x32_f16 v[66:69], v[58:61], v[110:113], v[66:69]
	ds_read_b128 v[118:121], v16 offset:36864
	v_mfma_f32_16x16x32_f16 v[44:47], v[94:97], v[106:109], v[44:47]
	ds_read_b128 v[122:125], v16 offset:38912
	v_mfma_f32_16x16x32_f16 v[78:81], v[94:97], v[110:113], v[78:81]
	s_waitcnt vmcnt(7)
	ds_write_b128 v17, v[62:65] offset:16384
	s_waitcnt lgkmcnt(2)
	v_mfma_f32_16x16x32_f16 v[82:85], v[118:121], v[106:109], v[82:85]
	s_waitcnt vmcnt(6)
	ds_write_b128 v18, v[90:93] offset:16384
	v_mfma_f32_16x16x32_f16 v[86:89], v[118:121], v[110:113], v[86:89]
	s_waitcnt vmcnt(5)
	ds_write_b128 v19, v[130:133] offset:16384
	s_waitcnt lgkmcnt(3)
	v_mfma_f32_16x16x32_f16 v[28:31], v[122:125], v[106:109], v[28:31]
	ds_read_b128 v[106:109], v21 offset:4096
	v_mfma_f32_16x16x32_f16 v[32:35], v[122:125], v[110:113], v[32:35]
	ds_read_b128 v[110:113], v21 offset:6144
	s_waitcnt lgkmcnt(1)
	v_mfma_f32_16x16x32_f16 v[98:101], v[58:61], v[106:109], v[98:101]
	s_waitcnt vmcnt(4)
	ds_write_b128 v20, v[138:141] offset:16384
	s_waitcnt lgkmcnt(1)
	v_mfma_f32_16x16x32_f16 v[52:55], v[58:61], v[110:113], v[52:55]
	ds_read_b128 v[58:61], v22 offset:32768
	v_mfma_f32_16x16x32_f16 v[102:105], v[94:97], v[106:109], v[102:105]
	s_waitcnt vmcnt(3)
	ds_write_b128 v17, v[74:77] offset:49152
	v_mfma_f32_16x16x32_f16 v[24:27], v[94:97], v[110:113], v[24:27]
	ds_read_b128 v[94:97], v22 offset:34816
	v_mfma_f32_16x16x32_f16 v[114:117], v[118:121], v[106:109], v[114:117]
	s_waitcnt vmcnt(2)
	ds_write_b128 v18, v[142:145] offset:49152
	v_mfma_f32_16x16x32_f16 v[40:43], v[118:121], v[110:113], v[40:43]
	ds_read_b128 v[118:121], v22 offset:36864
	v_mfma_f32_16x16x32_f16 v[70:73], v[122:125], v[106:109], v[70:73]
	ds_read_b128 v[106:109], v23
	v_mfma_f32_16x16x32_f16 v[48:51], v[122:125], v[110:113], v[48:51]
	ds_read_b128 v[110:113], v23 offset:2048
	s_waitcnt lgkmcnt(1)
	v_mfma_f32_16x16x32_f16 v[36:39], v[58:61], v[106:109], v[36:39]
	ds_read_b128 v[122:125], v22 offset:38912
	s_waitcnt lgkmcnt(1)
	v_mfma_f32_16x16x32_f16 v[66:69], v[58:61], v[110:113], v[66:69]
	s_waitcnt vmcnt(1)
	ds_write_b128 v19, v[154:157] offset:49152
	v_mfma_f32_16x16x32_f16 v[44:47], v[94:97], v[106:109], v[44:47]
	s_waitcnt vmcnt(0)
	ds_write_b128 v20, v[158:161] offset:49152
	v_mfma_f32_16x16x32_f16 v[78:81], v[94:97], v[110:113], v[78:81]
	v_mfma_f32_16x16x32_f16 v[82:85], v[118:121], v[106:109], v[82:85]
	v_mfma_f32_16x16x32_f16 v[86:89], v[118:121], v[110:113], v[86:89]
	s_waitcnt lgkmcnt(2)
	v_mfma_f32_16x16x32_f16 v[28:31], v[122:125], v[106:109], v[28:31]
	ds_read_b128 v[106:109], v23 offset:4096
	v_mfma_f32_16x16x32_f16 v[32:35], v[122:125], v[110:113], v[32:35]
	ds_read_b128 v[110:113], v23 offset:6144
	s_waitcnt lgkmcnt(1)
	v_mfma_f32_16x16x32_f16 v[98:101], v[58:61], v[106:109], v[98:101]
	s_waitcnt lgkmcnt(0)
	v_mfma_f32_16x16x32_f16 v[52:55], v[58:61], v[110:113], v[52:55]
	global_load_dwordx4 v[58:61], v[0:1], off offset:768
	v_mfma_f32_16x16x32_f16 v[102:105], v[94:97], v[106:109], v[102:105]
	v_mfma_f32_16x16x32_f16 v[24:27], v[94:97], v[110:113], v[24:27]
	v_mfma_f32_16x16x32_f16 v[114:117], v[118:121], v[106:109], v[114:117]
	v_mfma_f32_16x16x32_f16 v[40:43], v[118:121], v[110:113], v[40:43]
	v_mfma_f32_16x16x32_f16 v[70:73], v[122:125], v[106:109], v[70:73]
	global_load_dwordx4 v[106:109], v[2:3], off offset:768
	global_load_dwordx4 v[126:129], v[4:5], off offset:768
	global_load_dwordx4 v[134:137], v[14:15], off offset:768
	global_load_dwordx4 v[94:97], v[10:11], off offset:768
	global_load_dwordx4 v[162:165], v[12:13], off offset:768
	global_load_dwordx4 v[166:169], v[8:9], off offset:768
	global_load_dwordx4 v[190:193], v[6:7], off offset:768
	s_waitcnt lgkmcnt(0)
	s_barrier
	v_mfma_f32_16x16x32_f16 v[48:51], v[122:125], v[110:113], v[48:51]
	ds_read_b128 v[62:65], v16 offset:49152
	ds_read_b128 v[90:93], v21 offset:16384
	s_waitcnt lgkmcnt(0)
	v_mfma_f32_16x16x32_f16 v[36:39], v[62:65], v[90:93], v[36:39]
	ds_read_b128 v[74:77], v16 offset:51200
	ds_read_b128 v[110:113], v21 offset:18432
	s_waitcnt lgkmcnt(0)
	v_mfma_f32_16x16x32_f16 v[66:69], v[62:65], v[110:113], v[66:69]
	ds_read_b128 v[118:121], v16 offset:53248
	v_mfma_f32_16x16x32_f16 v[44:47], v[74:77], v[90:93], v[44:47]
	ds_read_b128 v[122:125], v16 offset:55296
	v_mfma_f32_16x16x32_f16 v[78:81], v[74:77], v[110:113], v[78:81]
	s_waitcnt vmcnt(7)
	ds_write_b128 v17, v[58:61]
	s_waitcnt lgkmcnt(2)
	v_mfma_f32_16x16x32_f16 v[82:85], v[118:121], v[90:93], v[82:85]
	s_waitcnt vmcnt(6)
	ds_write_b128 v18, v[106:109]
	v_mfma_f32_16x16x32_f16 v[86:89], v[118:121], v[110:113], v[86:89]
	s_waitcnt vmcnt(5)
	ds_write_b128 v19, v[126:129]
	s_waitcnt lgkmcnt(3)
	v_mfma_f32_16x16x32_f16 v[28:31], v[122:125], v[90:93], v[28:31]
	ds_read_b128 v[90:93], v21 offset:20480
	v_mfma_f32_16x16x32_f16 v[32:35], v[122:125], v[110:113], v[32:35]
	ds_read_b128 v[110:113], v21 offset:22528
	s_waitcnt lgkmcnt(1)
	v_mfma_f32_16x16x32_f16 v[98:101], v[62:65], v[90:93], v[98:101]
	s_waitcnt vmcnt(4)
	ds_write_b128 v20, v[134:137]
	s_waitcnt lgkmcnt(1)
	v_mfma_f32_16x16x32_f16 v[52:55], v[62:65], v[110:113], v[52:55]
	ds_read_b128 v[62:65], v22 offset:49152
	v_mfma_f32_16x16x32_f16 v[102:105], v[74:77], v[90:93], v[102:105]
	s_waitcnt vmcnt(3)
; #define GL_LOAD(s_, kt_) if (VAR != 1) { a##s_##0 = GL_A(0, kt_); a##s_##1 = GL_A(1, kt_); a##s_##2 = GL_A(2, kt_); a##s_##3 = GL_A(3, kt_); b##s_##0 = GL_B(0, kt_); b##s_##1 = GL_B(1, kt_); b##s_##2 = GL_B(2, kt_); b##s_##3 = GL_B(3, kt_); }
; #define LDS_STORE(s_, buf_) if (VAR != 2) { LDS_ST1(sA, 0, buf_, a##s_##0) LDS_ST1(sA, 1, buf_, a##s_##1) LDS_ST1(sA, 2, buf_, a##s_##2) LDS_ST1(sA, 3, buf_, a##s_##3) LDS_ST1(sB, 0, buf_, b##s_##0) LDS_ST1(sB, 1, buf_, b##s_##1) LDS_ST1(sB, 2, buf_, b##s_##2) LDS_ST1(sB, 3, buf_, b##s_##3) }
;     ...
;   GL_LOAD(0, 0)
;   GL_LOAD(1, 1)
;   LDS_STORE(0, 0)
;   if (VAR != 4) __syncthreads();
; #pragma unroll
;   for (int kt = 0; kt < nk; kt += 2) {
;     if (kt + 2 < nk) { GL_LOAD(0, kt + 2) }
;     MMA_TILE(0)
;     LDS_STORE(1, 1)
;     if (VAR != 4) __syncthreads();
;     if (kt + 3 < nk) { GL_LOAD(1, kt + 3) }
;     MMA_TILE(1)
;     if (kt + 2 < nk) { LDS_STORE(0, 0) }
;     if (VAR != 4) __syncthreads();
	ds_write_b128 v17, v[94:97] offset:32768
	v_mfma_f32_16x16x32_f16 v[24:27], v[74:77], v[110:113], v[24:27]
	ds_read_b128 v[74:77], v22 offset:51200
	v_mfma_f32_16x16x32_f16 v[114:117], v[118:121], v[90:93], v[114:117]
	s_waitcnt vmcnt(2)
	ds_write_b128 v18, v[162:165] offset:32768
	v_mfma_f32_16x16x32_f16 v[40:43], v[118:121], v[110:113], v[40:43]
	ds_read_b128 v[118:121], v22 offset:53248
	v_mfma_f32_16x16x32_f16 v[70:73], v[122:125], v[90:93], v[70:73]
	ds_read_b128 v[90:93], v23 offset:16384
	v_mfma_f32_16x16x32_f16 v[48:51], v[122:125], v[110:113], v[48:51]
	ds_read_b128 v[110:113], v23 offset:18432
	s_waitcnt lgkmcnt(1)
	v_mfma_f32_16x16x32_f16 v[36:39], v[62:65], v[90:93], v[36:39]
	ds_read_b128 v[122:125], v22 offset:55296
	s_waitcnt lgkmcnt(1)
	v_mfma_f32_16x16x32_f16 v[66:69], v[62:65], v[110:113], v[66:69]
	s_waitcnt vmcnt(1)
	ds_write_b128 v19, v[166:169] offset:32768
	v_mfma_f32_16x16x32_f16 v[44:47], v[74:77], v[90:93], v[44:47]
	s_waitcnt vmcnt(0)
	ds_write_b128 v20, v[190:193] offset:32768
	v_mfma_f32_16x16x32_f16 v[78:81], v[74:77], v[110:113], v[78:81]
	v_mfma_f32_16x16x32_f16 v[82:85], v[118:121], v[90:93], v[82:85]
	v_mfma_f32_16x16x32_f16 v[86:89], v[118:121], v[110:113], v[86:89]
	s_waitcnt lgkmcnt(2)
	v_mfma_f32_16x16x32_f16 v[28:31], v[122:125], v[90:93], v[28:31]
	ds_read_b128 v[90:93], v23 offset:20480
	v_mfma_f32_16x16x32_f16 v[32:35], v[122:125], v[110:113], v[32:35]
	ds_read_b128 v[110:113], v23 offset:22528
	s_waitcnt lgkmcnt(1)
	v_mfma_f32_16x16x32_f16 v[98:101], v[62:65], v[90:93], v[98:101]
	s_waitcnt lgkmcnt(0)
	v_mfma_f32_16x16x32_f16 v[52:55], v[62:65], v[110:113], v[52:55]
	global_load_dwordx4 v[62:65], v[0:1], off offset:896
	v_mfma_f32_16x16x32_f16 v[102:105], v[74:77], v[90:93], v[102:105]
	v_mfma_f32_16x16x32_f16 v[24:27], v[74:77], v[110:113], v[24:27]
	v_mfma_f32_16x16x32_f16 v[114:117], v[118:121], v[90:93], v[114:117]
	v_mfma_f32_16x16x32_f16 v[40:43], v[118:121], v[110:113], v[40:43]
	v_mfma_f32_16x16x32_f16 v[70:73], v[122:125], v[90:93], v[70:73]
	global_load_dwordx4 v[90:93], v[2:3], off offset:896
	global_load_dwordx4 v[130:133], v[4:5], off offset:896
	global_load_dwordx4 v[138:141], v[14:15], off offset:896
	global_load_dwordx4 v[74:77], v[10:11], off offset:896
	global_load_dwordx4 v[142:145], v[12:13], off offset:896
	global_load_dwordx4 v[154:157], v[8:9], off offset:896
	global_load_dwordx4 v[158:161], v[6:7], off offset:896
	s_waitcnt lgkmcnt(0)
	s_barrier
	v_mfma_f32_16x16x32_f16 v[48:51], v[122:125], v[110:113], v[48:51]
	ds_read_b128 v[58:61], v16 offset:32768
	ds_read_b128 v[106:109], v21
	s_waitcnt lgkmcnt(0)
	v_mfma_f32_16x16x32_f16 v[36:39], v[58:61], v[106:109], v[36:39]
	ds_read_b128 v[94:97], v16 offset:34816
	ds_read_b128 v[110:113], v21 offset:2048
	s_waitcnt lgkmcnt(0)
	v_mfma_f32_16x16x32_f16 v[66:69], v[58:61], v[110:113], v[66:69]
	ds_read_b128 v[118:121], v16 offset:36864
	v_mfma_f32_16x16x32_f16 v[44:47], v[94:97], v[106:109], v[44:47]
	ds_read_b128 v[122:125], v16 offset:38912
	v_mfma_f32_16x16x32_f16 v[78:81], v[94:97], v[110:113], v[78:81]
	s_waitcnt vmcnt(7)
	ds_write_b128 v17, v[62:65] offset:16384
	s_waitcnt lgkmcnt(2)
	v_mfma_f32_16x16x32_f16 v[82:85], v[118:121], v[106:109], v[82:85]
	s_waitcnt vmcnt(6)
	ds_write_b128 v18, v[90:93] offset:16384
	v_mfma_f32_16x16x32_f16 v[86:89], v[118:121], v[110:113], v[86:89]
	s_waitcnt vmcnt(5)
	ds_write_b128 v19, v[130:133] offset:16384
	s_waitcnt lgkmcnt(3)
	v_mfma_f32_16x16x32_f16 v[28:31], v[122:125], v[106:109], v[28:31]
	ds_read_b128 v[106:109], v21 offset:4096
	v_mfma_f32_16x16x32_f16 v[32:35], v[122:125], v[110:113], v[32:35]
	ds_read_b128 v[110:113], v21 offset:6144
	s_waitcnt lgkmcnt(1)
	v_mfma_f32_16x16x32_f16 v[98:101], v[58:61], v[106:109], v[98:101]
	s_waitcnt vmcnt(4)
	ds_write_b128 v20, v[138:141] offset:16384
	s_waitcnt lgkmcnt(1)
	v_mfma_f32_16x16x32_f16 v[52:55], v[58:61], v[110:113], v[52:55]
	ds_read_b128 v[58:61], v22 offset:32768
	v_mfma_f32_16x16x32_f16 v[102:105], v[94:97], v[106:109], v[102:105]
	s_waitcnt vmcnt(3)
	ds_write_b128 v17, v[74:77] offset:49152
	v_mfma_f32_16x16x32_f16 v[24:27], v[94:97], v[110:113], v[24:27]
	ds_read_b128 v[94:97], v22 offset:34816
	v_mfma_f32_16x16x32_f16 v[114:117], v[118:121], v[106:109], v[114:117]
	s_waitcnt vmcnt(2)
	ds_write_b128 v18, v[142:145] offset:49152
	v_mfma_f32_16x16x32_f16 v[40:43], v[118:121], v[110:113], v[40:43]
	ds_read_b128 v[118:121], v22 offset:36864
	v_mfma_f32_16x16x32_f16 v[70:73], v[122:125], v[106:109], v[70:73]
	ds_read_b128 v[106:109], v23
	v_mfma_f32_16x16x32_f16 v[48:51], v[122:125], v[110:113], v[48:51]
	ds_read_b128 v[110:113], v23 offset:2048
	s_waitcnt lgkmcnt(1)
	v_mfma_f32_16x16x32_f16 v[36:39], v[58:61], v[106:109], v[36:39]
	ds_read_b128 v[122:125], v22 offset:38912
	s_waitcnt lgkmcnt(1)
	v_mfma_f32_16x16x32_f16 v[66:69], v[58:61], v[110:113], v[66:69]
	s_waitcnt vmcnt(1)
	ds_write_b128 v19, v[154:157] offset:49152
	v_mfma_f32_16x16x32_f16 v[44:47], v[94:97], v[106:109], v[44:47]
	s_waitcnt vmcnt(0)
	ds_write_b128 v20, v[158:161] offset:49152
	v_mfma_f32_16x16x32_f16 v[78:81], v[94:97], v[110:113], v[78:81]
	v_mfma_f32_16x16x32_f16 v[82:85], v[118:121], v[106:109], v[82:85]
	v_mfma_f32_16x16x32_f16 v[86:89], v[118:121], v[110:113], v[86:89]
	s_waitcnt lgkmcnt(2)
	v_mfma_f32_16x16x32_f16 v[28:31], v[122:125], v[106:109], v[28:31]
	ds_read_b128 v[106:109], v23 offset:4096
	v_mfma_f32_16x16x32_f16 v[32:35], v[122:125], v[110:113], v[32:35]
	ds_read_b128 v[110:113], v23 offset:6144
	s_waitcnt lgkmcnt(1)
	v_mfma_f32_16x16x32_f16 v[98:101], v[58:61], v[106:109], v[98:101]
	s_waitcnt lgkmcnt(0)
	v_mfma_f32_16x16x32_f16 v[52:55], v[58:61], v[110:113], v[52:55]
	global_load_dwordx4 v[58:61], v[0:1], off offset:1024
	v_mfma_f32_16x16x32_f16 v[102:105], v[94:97], v[106:109], v[102:105]
	v_mfma_f32_16x16x32_f16 v[24:27], v[94:97], v[110:113], v[24:27]
	v_mfma_f32_16x16x32_f16 v[114:117], v[118:121], v[106:109], v[114:117]
	v_mfma_f32_16x16x32_f16 v[40:43], v[118:121], v[110:113], v[40:43]
	v_mfma_f32_16x16x32_f16 v[70:73], v[122:125], v[106:109], v[70:73]
	global_load_dwordx4 v[106:109], v[2:3], off offset:1024
	global_load_dwordx4 v[126:129], v[4:5], off offset:1024
	global_load_dwordx4 v[134:137], v[14:15], off offset:1024
	global_load_dwordx4 v[94:97], v[10:11], off offset:1024
	global_load_dwordx4 v[162:165], v[12:13], off offset:1024
	global_load_dwordx4 v[166:169], v[8:9], off offset:1024
	global_load_dwordx4 v[190:193], v[6:7], off offset:1024
	s_waitcnt lgkmcnt(0)
	s_barrier
; #define GL_LOAD(s_, kt_) if (VAR != 1) { a##s_##0 = GL_A(0, kt_); a##s_##1 = GL_A(1, kt_); a##s_##2 = GL_A(2, kt_); a##s_##3 = GL_A(3, kt_); b##s_##0 = GL_B(0, kt_); b##s_##1 = GL_B(1, kt_); b##s_##2 = GL_B(2, kt_); b##s_##3 = GL_B(3, kt_); }
; #define LDS_STORE(s_, buf_) if (VAR != 2) { LDS_ST1(sA, 0, buf_, a##s_##0) LDS_ST1(sA, 1, buf_, a##s_##1) LDS_ST1(sA, 2, buf_, a##s_##2) LDS_ST1(sA, 3, buf_, a##s_##3) LDS_ST1(sB, 0, buf_, b##s_##0) LDS_ST1(sB, 1, buf_, b##s_##1) LDS_ST1(sB, 2, buf_, b##s_##2) LDS_ST1(sB, 3, buf_, b##s_##3) }
;     ...
;   GL_LOAD(0, 0)
;   GL_LOAD(1, 1)
;   LDS_STORE(0, 0)
;   if (VAR != 4) __syncthreads();
; #pragma unroll
;   for (int kt = 0; kt < nk; kt += 2) {
;     if (kt + 2 < nk) { GL_LOAD(0, kt + 2) }
;     MMA_TILE(0)
;     LDS_STORE(1, 1)
;     if (VAR != 4) __syncthreads();
;     if (kt + 3 < nk) { GL_LOAD(1, kt + 3) }
;     MMA_TILE(1)
;     if (kt + 2 < nk) { LDS_STORE(0, 0) }
;     if (VAR != 4) __syncthreads();
	v_mfma_f32_16x16x32_f16 v[48:51], v[122:125], v[110:113], v[48:51]
	ds_read_b128 v[62:65], v16 offset:49152
	ds_read_b128 v[90:93], v21 offset:16384
	s_waitcnt lgkmcnt(0)
	v_mfma_f32_16x16x32_f16 v[36:39], v[62:65], v[90:93], v[36:39]
	ds_read_b128 v[74:77], v16 offset:51200
	ds_read_b128 v[110:113], v21 offset:18432
	s_waitcnt lgkmcnt(0)
	v_mfma_f32_16x16x32_f16 v[66:69], v[62:65], v[110:113], v[66:69]
	ds_read_b128 v[118:121], v16 offset:53248
	v_mfma_f32_16x16x32_f16 v[44:47], v[74:77], v[90:93], v[44:47]
	ds_read_b128 v[122:125], v16 offset:55296
	v_mfma_f32_16x16x32_f16 v[78:81], v[74:77], v[110:113], v[78:81]
	s_waitcnt vmcnt(7)
	ds_write_b128 v17, v[58:61]
	s_waitcnt lgkmcnt(2)
	v_mfma_f32_16x16x32_f16 v[82:85], v[118:121], v[90:93], v[82:85]
	s_waitcnt vmcnt(6)
	ds_write_b128 v18, v[106:109]
	v_mfma_f32_16x16x32_f16 v[86:89], v[118:121], v[110:113], v[86:89]
	s_waitcnt vmcnt(5)
	ds_write_b128 v19, v[126:129]
	s_waitcnt lgkmcnt(3)
	v_mfma_f32_16x16x32_f16 v[28:31], v[122:125], v[90:93], v[28:31]
	ds_read_b128 v[90:93], v21 offset:20480
	v_mfma_f32_16x16x32_f16 v[32:35], v[122:125], v[110:113], v[32:35]
	ds_read_b128 v[110:113], v21 offset:22528
	s_waitcnt lgkmcnt(1)
	v_mfma_f32_16x16x32_f16 v[98:101], v[62:65], v[90:93], v[98:101]
	s_waitcnt vmcnt(4)
	ds_write_b128 v20, v[134:137]
	s_waitcnt lgkmcnt(1)
	v_mfma_f32_16x16x32_f16 v[52:55], v[62:65], v[110:113], v[52:55]
	ds_read_b128 v[62:65], v22 offset:49152
	v_mfma_f32_16x16x32_f16 v[102:105], v[74:77], v[90:93], v[102:105]
	s_waitcnt vmcnt(3)
	ds_write_b128 v17, v[94:97] offset:32768
	v_mfma_f32_16x16x32_f16 v[24:27], v[74:77], v[110:113], v[24:27]
	ds_read_b128 v[74:77], v22 offset:51200
	v_mfma_f32_16x16x32_f16 v[114:117], v[118:121], v[90:93], v[114:117]
	s_waitcnt vmcnt(2)
	ds_write_b128 v18, v[162:165] offset:32768
	v_mfma_f32_16x16x32_f16 v[40:43], v[118:121], v[110:113], v[40:43]
	ds_read_b128 v[118:121], v22 offset:53248
	v_mfma_f32_16x16x32_f16 v[70:73], v[122:125], v[90:93], v[70:73]
	ds_read_b128 v[90:93], v23 offset:16384
	v_mfma_f32_16x16x32_f16 v[48:51], v[122:125], v[110:113], v[48:51]
	ds_read_b128 v[110:113], v23 offset:18432
	s_waitcnt lgkmcnt(1)
	v_mfma_f32_16x16x32_f16 v[36:39], v[62:65], v[90:93], v[36:39]
	ds_read_b128 v[122:125], v22 offset:55296
	s_waitcnt lgkmcnt(1)
	v_mfma_f32_16x16x32_f16 v[66:69], v[62:65], v[110:113], v[66:69]
	s_waitcnt vmcnt(1)
	ds_write_b128 v19, v[166:169] offset:32768
	v_mfma_f32_16x16x32_f16 v[44:47], v[74:77], v[90:93], v[44:47]
	s_waitcnt vmcnt(0)
	ds_write_b128 v20, v[190:193] offset:32768
	v_mfma_f32_16x16x32_f16 v[78:81], v[74:77], v[110:113], v[78:81]
	v_mfma_f32_16x16x32_f16 v[82:85], v[118:121], v[90:93], v[82:85]
	v_mfma_f32_16x16x32_f16 v[86:89], v[118:121], v[110:113], v[86:89]
	s_waitcnt lgkmcnt(2)
	v_mfma_f32_16x16x32_f16 v[28:31], v[122:125], v[90:93], v[28:31]
	ds_read_b128 v[90:93], v23 offset:20480
	v_mfma_f32_16x16x32_f16 v[32:35], v[122:125], v[110:113], v[32:35]
	ds_read_b128 v[110:113], v23 offset:22528
	s_waitcnt lgkmcnt(1)
	v_mfma_f32_16x16x32_f16 v[98:101], v[62:65], v[90:93], v[98:101]
	s_waitcnt lgkmcnt(0)
	v_mfma_f32_16x16x32_f16 v[52:55], v[62:65], v[110:113], v[52:55]
	global_load_dwordx4 v[62:65], v[0:1], off offset:1152
	v_mfma_f32_16x16x32_f16 v[102:105], v[74:77], v[90:93], v[102:105]
	v_mfma_f32_16x16x32_f16 v[24:27], v[74:77], v[110:113], v[24:27]
	v_mfma_f32_16x16x32_f16 v[114:117], v[118:121], v[90:93], v[114:117]
	v_mfma_f32_16x16x32_f16 v[40:43], v[118:121], v[110:113], v[40:43]
	v_mfma_f32_16x16x32_f16 v[70:73], v[122:125], v[90:93], v[70:73]
	global_load_dwordx4 v[90:93], v[2:3], off offset:1152
	global_load_dwordx4 v[130:133], v[4:5], off offset:1152
	global_load_dwordx4 v[138:141], v[14:15], off offset:1152
	global_load_dwordx4 v[74:77], v[10:11], off offset:1152
	global_load_dwordx4 v[142:145], v[12:13], off offset:1152
	global_load_dwordx4 v[154:157], v[8:9], off offset:1152
	global_load_dwordx4 v[158:161], v[6:7], off offset:1152
	s_waitcnt lgkmcnt(0)
	s_barrier
	v_mfma_f32_16x16x32_f16 v[48:51], v[122:125], v[110:113], v[48:51]
	ds_read_b128 v[58:61], v16 offset:32768
	ds_read_b128 v[106:109], v21
	s_waitcnt lgkmcnt(0)
	v_mfma_f32_16x16x32_f16 v[36:39], v[58:61], v[106:109], v[36:39]
	ds_read_b128 v[94:97], v16 offset:34816
	ds_read_b128 v[110:113], v21 offset:2048
	s_waitcnt lgkmcnt(0)
	v_mfma_f32_16x16x32_f16 v[66:69], v[58:61], v[110:113], v[66:69]
	ds_read_b128 v[118:121], v16 offset:36864
	v_mfma_f32_16x16x32_f16 v[44:47], v[94:97], v[106:109], v[44:47]
	ds_read_b128 v[122:125], v16 offset:38912
	v_mfma_f32_16x16x32_f16 v[78:81], v[94:97], v[110:113], v[78:81]
	s_waitcnt vmcnt(7)
	ds_write_b128 v17, v[62:65] offset:16384
	s_waitcnt lgkmcnt(2)
	v_mfma_f32_16x16x32_f16 v[82:85], v[118:121], v[106:109], v[82:85]
	s_waitcnt vmcnt(6)
	ds_write_b128 v18, v[90:93] offset:16384
	v_mfma_f32_16x16x32_f16 v[86:89], v[118:121], v[110:113], v[86:89]
	s_waitcnt vmcnt(5)
	ds_write_b128 v19, v[130:133] offset:16384
	s_waitcnt lgkmcnt(3)
	v_mfma_f32_16x16x32_f16 v[28:31], v[122:125], v[106:109], v[28:31]
	ds_read_b128 v[106:109], v21 offset:4096
	v_mfma_f32_16x16x32_f16 v[32:35], v[122:125], v[110:113], v[32:35]
	ds_read_b128 v[110:113], v21 offset:6144
	s_waitcnt lgkmcnt(1)
	v_mfma_f32_16x16x32_f16 v[98:101], v[58:61], v[106:109], v[98:101]
	s_waitcnt vmcnt(4)
	ds_write_b128 v20, v[138:141] offset:16384
	s_waitcnt lgkmcnt(1)
	v_mfma_f32_16x16x32_f16 v[52:55], v[58:61], v[110:113], v[52:55]
	ds_read_b128 v[58:61], v22 offset:32768
	v_mfma_f32_16x16x32_f16 v[102:105], v[94:97], v[106:109], v[102:105]
	s_waitcnt vmcnt(3)
; #define GL_LOAD(s_, kt_) if (VAR != 1) { a##s_##0 = GL_A(0, kt_); a##s_##1 = GL_A(1, kt_); a##s_##2 = GL_A(2, kt_); a##s_##3 = GL_A(3, kt_); b##s_##0 = GL_B(0, kt_); b##s_##1 = GL_B(1, kt_); b##s_##2 = GL_B(2, kt_); b##s_##3 = GL_B(3, kt_); }
; #define LDS_STORE(s_, buf_) if (VAR != 2) { LDS_ST1(sA, 0, buf_, a##s_##0) LDS_ST1(sA, 1, buf_, a##s_##1) LDS_ST1(sA, 2, buf_, a##s_##2) LDS_ST1(sA, 3, buf_, a##s_##3) LDS_ST1(sB, 0, buf_, b##s_##0) LDS_ST1(sB, 1, buf_, b##s_##1) LDS_ST1(sB, 2, buf_, b##s_##2) LDS_ST1(sB, 3, buf_, b##s_##3) }
;     ...
;   GL_LOAD(0, 0)
;   GL_LOAD(1, 1)
;   LDS_STORE(0, 0)
;   if (VAR != 4) __syncthreads();
; #pragma unroll
;   for (int kt = 0; kt < nk; kt += 2) {
;     if (kt + 2 < nk) { GL_LOAD(0, kt + 2) }
;     MMA_TILE(0)
;     LDS_STORE(1, 1)
;     if (VAR != 4) __syncthreads();
;     if (kt + 3 < nk) { GL_LOAD(1, kt + 3) }
;     MMA_TILE(1)
;     if (kt + 2 < nk) { LDS_STORE(0, 0) }
;     if (VAR != 4) __syncthreads();
	ds_write_b128 v17, v[74:77] offset:49152
	v_mfma_f32_16x16x32_f16 v[24:27], v[94:97], v[110:113], v[24:27]
	ds_read_b128 v[94:97], v22 offset:34816
	v_mfma_f32_16x16x32_f16 v[114:117], v[118:121], v[106:109], v[114:117]
	s_waitcnt vmcnt(2)
	ds_write_b128 v18, v[142:145] offset:49152
	v_mfma_f32_16x16x32_f16 v[40:43], v[118:121], v[110:113], v[40:43]
	ds_read_b128 v[118:121], v22 offset:36864
	v_mfma_f32_16x16x32_f16 v[70:73], v[122:125], v[106:109], v[70:73]
	ds_read_b128 v[106:109], v23
	v_mfma_f32_16x16x32_f16 v[48:51], v[122:125], v[110:113], v[48:51]
	ds_read_b128 v[110:113], v23 offset:2048
	s_waitcnt lgkmcnt(1)
	v_mfma_f32_16x16x32_f16 v[36:39], v[58:61], v[106:109], v[36:39]
	ds_read_b128 v[122:125], v22 offset:38912
	s_waitcnt lgkmcnt(1)
	v_mfma_f32_16x16x32_f16 v[66:69], v[58:61], v[110:113], v[66:69]
	s_waitcnt vmcnt(1)
	ds_write_b128 v19, v[154:157] offset:49152
	v_mfma_f32_16x16x32_f16 v[44:47], v[94:97], v[106:109], v[44:47]
	s_waitcnt vmcnt(0)
	ds_write_b128 v20, v[158:161] offset:49152
	v_mfma_f32_16x16x32_f16 v[78:81], v[94:97], v[110:113], v[78:81]
	v_mfma_f32_16x16x32_f16 v[82:85], v[118:121], v[106:109], v[82:85]
	v_mfma_f32_16x16x32_f16 v[86:89], v[118:121], v[110:113], v[86:89]
	s_waitcnt lgkmcnt(2)
	v_mfma_f32_16x16x32_f16 v[28:31], v[122:125], v[106:109], v[28:31]
	ds_read_b128 v[106:109], v23 offset:4096
	v_mfma_f32_16x16x32_f16 v[32:35], v[122:125], v[110:113], v[32:35]
	ds_read_b128 v[110:113], v23 offset:6144
	s_waitcnt lgkmcnt(1)
	v_mfma_f32_16x16x32_f16 v[98:101], v[58:61], v[106:109], v[98:101]
	s_waitcnt lgkmcnt(0)
	v_mfma_f32_16x16x32_f16 v[52:55], v[58:61], v[110:113], v[52:55]
	global_load_dwordx4 v[58:61], v[0:1], off offset:1280
	v_mfma_f32_16x16x32_f16 v[102:105], v[94:97], v[106:109], v[102:105]
	v_mfma_f32_16x16x32_f16 v[24:27], v[94:97], v[110:113], v[24:27]
	v_mfma_f32_16x16x32_f16 v[114:117], v[118:121], v[106:109], v[114:117]
	v_mfma_f32_16x16x32_f16 v[40:43], v[118:121], v[110:113], v[40:43]
	v_mfma_f32_16x16x32_f16 v[70:73], v[122:125], v[106:109], v[70:73]
	global_load_dwordx4 v[106:109], v[2:3], off offset:1280
	global_load_dwordx4 v[126:129], v[4:5], off offset:1280
	global_load_dwordx4 v[134:137], v[14:15], off offset:1280
	global_load_dwordx4 v[94:97], v[10:11], off offset:1280
	global_load_dwordx4 v[162:165], v[12:13], off offset:1280
	global_load_dwordx4 v[166:169], v[8:9], off offset:1280
	global_load_dwordx4 v[190:193], v[6:7], off offset:1280
	s_waitcnt lgkmcnt(0)
	s_barrier
	v_mfma_f32_16x16x32_f16 v[48:51], v[122:125], v[110:113], v[48:51]
	ds_read_b128 v[62:65], v16 offset:49152
	ds_read_b128 v[90:93], v21 offset:16384
	s_waitcnt lgkmcnt(0)
	v_mfma_f32_16x16x32_f16 v[36:39], v[62:65], v[90:93], v[36:39]
	ds_read_b128 v[74:77], v16 offset:51200
	ds_read_b128 v[110:113], v21 offset:18432
	s_waitcnt lgkmcnt(0)
	v_mfma_f32_16x16x32_f16 v[66:69], v[62:65], v[110:113], v[66:69]
	ds_read_b128 v[118:121], v16 offset:53248
	v_mfma_f32_16x16x32_f16 v[44:47], v[74:77], v[90:93], v[44:47]
	ds_read_b128 v[122:125], v16 offset:55296
	v_mfma_f32_16x16x32_f16 v[78:81], v[74:77], v[110:113], v[78:81]
	s_waitcnt vmcnt(7)
	ds_write_b128 v17, v[58:61]
	s_waitcnt lgkmcnt(2)
	v_mfma_f32_16x16x32_f16 v[82:85], v[118:121], v[90:93], v[82:85]
	s_waitcnt vmcnt(6)
	ds_write_b128 v18, v[106:109]
	v_mfma_f32_16x16x32_f16 v[86:89], v[118:121], v[110:113], v[86:89]
	s_waitcnt vmcnt(5)
	ds_write_b128 v19, v[126:129]
	s_waitcnt lgkmcnt(3)
	v_mfma_f32_16x16x32_f16 v[28:31], v[122:125], v[90:93], v[28:31]
	ds_read_b128 v[90:93], v21 offset:20480
	v_mfma_f32_16x16x32_f16 v[32:35], v[122:125], v[110:113], v[32:35]
	ds_read_b128 v[110:113], v21 offset:22528
	s_waitcnt lgkmcnt(1)
	v_mfma_f32_16x16x32_f16 v[98:101], v[62:65], v[90:93], v[98:101]
	s_waitcnt vmcnt(4)
	ds_write_b128 v20, v[134:137]
	s_waitcnt lgkmcnt(1)
	v_mfma_f32_16x16x32_f16 v[52:55], v[62:65], v[110:113], v[52:55]
	ds_read_b128 v[62:65], v22 offset:49152
	v_mfma_f32_16x16x32_f16 v[102:105], v[74:77], v[90:93], v[102:105]
	s_waitcnt vmcnt(3)
	ds_write_b128 v17, v[94:97] offset:32768
	v_mfma_f32_16x16x32_f16 v[24:27], v[74:77], v[110:113], v[24:27]
	ds_read_b128 v[74:77], v22 offset:51200
	v_mfma_f32_16x16x32_f16 v[114:117], v[118:121], v[90:93], v[114:117]
	s_waitcnt vmcnt(2)
	ds_write_b128 v18, v[162:165] offset:32768
	v_mfma_f32_16x16x32_f16 v[40:43], v[118:121], v[110:113], v[40:43]
	ds_read_b128 v[118:121], v22 offset:53248
	v_mfma_f32_16x16x32_f16 v[70:73], v[122:125], v[90:93], v[70:73]
	ds_read_b128 v[90:93], v23 offset:16384
	v_mfma_f32_16x16x32_f16 v[48:51], v[122:125], v[110:113], v[48:51]
	ds_read_b128 v[110:113], v23 offset:18432
	s_waitcnt lgkmcnt(1)
	v_mfma_f32_16x16x32_f16 v[36:39], v[62:65], v[90:93], v[36:39]
	ds_read_b128 v[122:125], v22 offset:55296
	s_waitcnt lgkmcnt(1)
	v_mfma_f32_16x16x32_f16 v[66:69], v[62:65], v[110:113], v[66:69]
	s_waitcnt vmcnt(1)
	ds_write_b128 v19, v[166:169] offset:32768
	v_mfma_f32_16x16x32_f16 v[44:47], v[74:77], v[90:93], v[44:47]
	s_waitcnt vmcnt(0)
	ds_write_b128 v20, v[190:193] offset:32768
	v_mfma_f32_16x16x32_f16 v[78:81], v[74:77], v[110:113], v[78:81]
	v_mfma_f32_16x16x32_f16 v[82:85], v[118:121], v[90:93], v[82:85]
	v_mfma_f32_16x16x32_f16 v[86:89], v[118:121], v[110:113], v[86:89]
	s_waitcnt lgkmcnt(2)
	v_mfma_f32_16x16x32_f16 v[28:31], v[122:125], v[90:93], v[28:31]
	ds_read_b128 v[90:93], v23 offset:20480
	v_mfma_f32_16x16x32_f16 v[32:35], v[122:125], v[110:113], v[32:35]
	ds_read_b128 v[110:113], v23 offset:22528
	s_waitcnt lgkmcnt(1)
	v_mfma_f32_16x16x32_f16 v[98:101], v[62:65], v[90:93], v[98:101]
	s_waitcnt lgkmcnt(0)
	v_mfma_f32_16x16x32_f16 v[52:55], v[62:65], v[110:113], v[52:55]
	global_load_dwordx4 v[62:65], v[0:1], off offset:1408
	v_mfma_f32_16x16x32_f16 v[102:105], v[74:77], v[90:93], v[102:105]
	v_mfma_f32_16x16x32_f16 v[24:27], v[74:77], v[110:113], v[24:27]
	v_mfma_f32_16x16x32_f16 v[114:117], v[118:121], v[90:93], v[114:117]
	v_mfma_f32_16x16x32_f16 v[40:43], v[118:121], v[110:113], v[40:43]
	v_mfma_f32_16x16x32_f16 v[70:73], v[122:125], v[90:93], v[70:73]
	global_load_dwordx4 v[90:93], v[2:3], off offset:1408
	global_load_dwordx4 v[130:133], v[4:5], off offset:1408
	global_load_dwordx4 v[138:141], v[14:15], off offset:1408
	global_load_dwordx4 v[74:77], v[10:11], off offset:1408
	global_load_dwordx4 v[142:145], v[12:13], off offset:1408
	global_load_dwordx4 v[154:157], v[8:9], off offset:1408
	global_load_dwordx4 v[158:161], v[6:7], off offset:1408
	s_waitcnt lgkmcnt(0)
	s_barrier
; #define GL_LOAD(s_, kt_) if (VAR != 1) { a##s_##0 = GL_A(0, kt_); a##s_##1 = GL_A(1, kt_); a##s_##2 = GL_A(2, kt_); a##s_##3 = GL_A(3, kt_); b##s_##0 = GL_B(0, kt_); b##s_##1 = GL_B(1, kt_); b##s_##2 = GL_B(2, kt_); b##s_##3 = GL_B(3, kt_); }
; #define LDS_STORE(s_, buf_) if (VAR != 2) { LDS_ST1(sA, 0, buf_, a##s_##0) LDS_ST1(sA, 1, buf_, a##s_##1) LDS_ST1(sA, 2, buf_, a##s_##2) LDS_ST1(sA, 3, buf_, a##s_##3) LDS_ST1(sB, 0, buf_, b##s_##0) LDS_ST1(sB, 1, buf_, b##s_##1) LDS_ST1(sB, 2, buf_, b##s_##2) LDS_ST1(sB, 3, buf_, b##s_##3) }
;     ...
;   for (int kt = 0; kt < nk; kt += 2) {
;     if (kt + 2 < nk) { GL_LOAD(0, kt + 2) }
;     MMA_TILE(0)
;     LDS_STORE(1, 1)
;     if (VAR != 4) __syncthreads();
;     if (kt + 3 < nk) { GL_LOAD(1, kt + 3) }
;     MMA_TILE(1)
;     if (kt + 2 < nk) { LDS_STORE(0, 0) }
;     if (VAR != 4) __syncthreads();
	v_mfma_f32_16x16x32_f16 v[48:51], v[122:125], v[110:113], v[48:51]
	ds_read_b128 v[58:61], v16 offset:32768
	ds_read_b128 v[106:109], v21
	s_waitcnt lgkmcnt(0)
	v_mfma_f32_16x16x32_f16 v[36:39], v[58:61], v[106:109], v[36:39]
	ds_read_b128 v[94:97], v16 offset:34816
	ds_read_b128 v[110:113], v21 offset:2048
	s_waitcnt lgkmcnt(0)
	v_mfma_f32_16x16x32_f16 v[66:69], v[58:61], v[110:113], v[66:69]
	ds_read_b128 v[118:121], v16 offset:36864
	v_mfma_f32_16x16x32_f16 v[44:47], v[94:97], v[106:109], v[44:47]
	ds_read_b128 v[122:125], v16 offset:38912
	v_mfma_f32_16x16x32_f16 v[78:81], v[94:97], v[110:113], v[78:81]
	s_waitcnt vmcnt(7)
	ds_write_b128 v17, v[62:65] offset:16384
	s_waitcnt lgkmcnt(2)
	v_mfma_f32_16x16x32_f16 v[82:85], v[118:121], v[106:109], v[82:85]
	s_waitcnt vmcnt(6)
	ds_write_b128 v18, v[90:93] offset:16384
	v_mfma_f32_16x16x32_f16 v[86:89], v[118:121], v[110:113], v[86:89]
	s_waitcnt vmcnt(5)
	ds_write_b128 v19, v[130:133] offset:16384
	s_waitcnt lgkmcnt(3)
	v_mfma_f32_16x16x32_f16 v[28:31], v[122:125], v[106:109], v[28:31]
	ds_read_b128 v[106:109], v21 offset:4096
	v_mfma_f32_16x16x32_f16 v[32:35], v[122:125], v[110:113], v[32:35]
	ds_read_b128 v[110:113], v21 offset:6144
	s_waitcnt lgkmcnt(1)
	v_mfma_f32_16x16x32_f16 v[98:101], v[58:61], v[106:109], v[98:101]
	s_waitcnt vmcnt(4)
	ds_write_b128 v20, v[138:141] offset:16384
	s_waitcnt lgkmcnt(1)
	v_mfma_f32_16x16x32_f16 v[52:55], v[58:61], v[110:113], v[52:55]
	ds_read_b128 v[58:61], v22 offset:32768
	v_mfma_f32_16x16x32_f16 v[102:105], v[94:97], v[106:109], v[102:105]
	s_waitcnt vmcnt(3)
	ds_write_b128 v17, v[74:77] offset:49152
	v_mfma_f32_16x16x32_f16 v[24:27], v[94:97], v[110:113], v[24:27]
	ds_read_b128 v[94:97], v22 offset:34816
	v_mfma_f32_16x16x32_f16 v[114:117], v[118:121], v[106:109], v[114:117]
	s_waitcnt vmcnt(2)
	ds_write_b128 v18, v[142:145] offset:49152
	v_mfma_f32_16x16x32_f16 v[40:43], v[118:121], v[110:113], v[40:43]
	ds_read_b128 v[118:121], v22 offset:36864
	v_mfma_f32_16x16x32_f16 v[70:73], v[122:125], v[106:109], v[70:73]
	ds_read_b128 v[106:109], v23
	v_mfma_f32_16x16x32_f16 v[48:51], v[122:125], v[110:113], v[48:51]
	ds_read_b128 v[110:113], v23 offset:2048
	s_waitcnt lgkmcnt(1)
	v_mfma_f32_16x16x32_f16 v[36:39], v[58:61], v[106:109], v[36:39]
	ds_read_b128 v[122:125], v22 offset:38912
	s_waitcnt lgkmcnt(1)
	v_mfma_f32_16x16x32_f16 v[66:69], v[58:61], v[110:113], v[66:69]
	s_waitcnt vmcnt(1)
	ds_write_b128 v19, v[154:157] offset:49152
	v_mfma_f32_16x16x32_f16 v[44:47], v[94:97], v[106:109], v[44:47]
	s_waitcnt vmcnt(0)
	ds_write_b128 v20, v[158:161] offset:49152
	v_mfma_f32_16x16x32_f16 v[78:81], v[94:97], v[110:113], v[78:81]
	v_mfma_f32_16x16x32_f16 v[82:85], v[118:121], v[106:109], v[82:85]
	v_mfma_f32_16x16x32_f16 v[86:89], v[118:121], v[110:113], v[86:89]
	s_waitcnt lgkmcnt(2)
	v_mfma_f32_16x16x32_f16 v[28:31], v[122:125], v[106:109], v[28:31]
	ds_read_b128 v[106:109], v23 offset:4096
	v_mfma_f32_16x16x32_f16 v[32:35], v[122:125], v[110:113], v[32:35]
	ds_read_b128 v[110:113], v23 offset:6144
	s_waitcnt lgkmcnt(1)
	v_mfma_f32_16x16x32_f16 v[98:101], v[58:61], v[106:109], v[98:101]
	s_waitcnt lgkmcnt(0)
	v_mfma_f32_16x16x32_f16 v[52:55], v[58:61], v[110:113], v[52:55]
	global_load_dwordx4 v[58:61], v[0:1], off offset:1536
	v_mfma_f32_16x16x32_f16 v[102:105], v[94:97], v[106:109], v[102:105]
	v_mfma_f32_16x16x32_f16 v[24:27], v[94:97], v[110:113], v[24:27]
	v_mfma_f32_16x16x32_f16 v[114:117], v[118:121], v[106:109], v[114:117]
	v_mfma_f32_16x16x32_f16 v[40:43], v[118:121], v[110:113], v[40:43]
	v_mfma_f32_16x16x32_f16 v[70:73], v[122:125], v[106:109], v[70:73]
	global_load_dwordx4 v[106:109], v[2:3], off offset:1536
	global_load_dwordx4 v[126:129], v[4:5], off offset:1536
	global_load_dwordx4 v[134:137], v[14:15], off offset:1536
	global_load_dwordx4 v[94:97], v[10:11], off offset:1536
	global_load_dwordx4 v[162:165], v[12:13], off offset:1536
	global_load_dwordx4 v[166:169], v[8:9], off offset:1536
	global_load_dwordx4 v[190:193], v[6:7], off offset:1536
	s_waitcnt lgkmcnt(0)
	s_barrier
	v_mfma_f32_16x16x32_f16 v[48:51], v[122:125], v[110:113], v[48:51]
	ds_read_b128 v[62:65], v16 offset:49152
	ds_read_b128 v[90:93], v21 offset:16384
	s_waitcnt lgkmcnt(0)
	v_mfma_f32_16x16x32_f16 v[36:39], v[62:65], v[90:93], v[36:39]
	ds_read_b128 v[74:77], v16 offset:51200
	ds_read_b128 v[110:113], v21 offset:18432
	s_waitcnt lgkmcnt(0)
	v_mfma_f32_16x16x32_f16 v[66:69], v[62:65], v[110:113], v[66:69]
	ds_read_b128 v[118:121], v16 offset:53248
	v_mfma_f32_16x16x32_f16 v[44:47], v[74:77], v[90:93], v[44:47]
	ds_read_b128 v[122:125], v16 offset:55296
	v_mfma_f32_16x16x32_f16 v[78:81], v[74:77], v[110:113], v[78:81]
	s_waitcnt vmcnt(7)
	ds_write_b128 v17, v[58:61]
	s_waitcnt lgkmcnt(2)
	v_mfma_f32_16x16x32_f16 v[82:85], v[118:121], v[90:93], v[82:85]
	s_waitcnt vmcnt(6)
	ds_write_b128 v18, v[106:109]
	v_mfma_f32_16x16x32_f16 v[86:89], v[118:121], v[110:113], v[86:89]
	s_waitcnt vmcnt(5)
	ds_write_b128 v19, v[126:129]
	s_waitcnt lgkmcnt(3)
	v_mfma_f32_16x16x32_f16 v[28:31], v[122:125], v[90:93], v[28:31]
	ds_read_b128 v[90:93], v21 offset:20480
	v_mfma_f32_16x16x32_f16 v[32:35], v[122:125], v[110:113], v[32:35]
	ds_read_b128 v[110:113], v21 offset:22528
	s_waitcnt lgkmcnt(1)
	v_mfma_f32_16x16x32_f16 v[98:101], v[62:65], v[90:93], v[98:101]
	s_waitcnt vmcnt(4)
	ds_write_b128 v20, v[134:137]
	s_waitcnt lgkmcnt(1)
	v_mfma_f32_16x16x32_f16 v[52:55], v[62:65], v[110:113], v[52:55]
	ds_read_b128 v[62:65], v22 offset:49152
	v_mfma_f32_16x16x32_f16 v[102:105], v[74:77], v[90:93], v[102:105]
	s_waitcnt vmcnt(3)
; #define GL_LOAD(s_, kt_) if (VAR != 1) { a##s_##0 = GL_A(0, kt_); a##s_##1 = GL_A(1, kt_); a##s_##2 = GL_A(2, kt_); a##s_##3 = GL_A(3, kt_); b##s_##0 = GL_B(0, kt_); b##s_##1 = GL_B(1, kt_); b##s_##2 = GL_B(2, kt_); b##s_##3 = GL_B(3, kt_); }
; #define LDS_STORE(s_, buf_) if (VAR != 2) { LDS_ST1(sA, 0, buf_, a##s_##0) LDS_ST1(sA, 1, buf_, a##s_##1) LDS_ST1(sA, 2, buf_, a##s_##2) LDS_ST1(sA, 3, buf_, a##s_##3) LDS_ST1(sB, 0, buf_, b##s_##0) LDS_ST1(sB, 1, buf_, b##s_##1) LDS_ST1(sB, 2, buf_, b##s_##2) LDS_ST1(sB, 3, buf_, b##s_##3) }
;     ...
;   for (int kt = 0; kt < nk; kt += 2) {
;     if (kt + 2 < nk) { GL_LOAD(0, kt + 2) }
;     MMA_TILE(0)
;     LDS_STORE(1, 1)
;     if (VAR != 4) __syncthreads();
;     if (kt + 3 < nk) { GL_LOAD(1, kt + 3) }
;     MMA_TILE(1)
;     if (kt + 2 < nk) { LDS_STORE(0, 0) }
;     if (VAR != 4) __syncthreads();
	ds_write_b128 v17, v[94:97] offset:32768
	v_mfma_f32_16x16x32_f16 v[24:27], v[74:77], v[110:113], v[24:27]
	ds_read_b128 v[74:77], v22 offset:51200
	v_mfma_f32_16x16x32_f16 v[114:117], v[118:121], v[90:93], v[114:117]
	s_waitcnt vmcnt(2)
	ds_write_b128 v18, v[162:165] offset:32768
	v_mfma_f32_16x16x32_f16 v[40:43], v[118:121], v[110:113], v[40:43]
	ds_read_b128 v[118:121], v22 offset:53248
	v_mfma_f32_16x16x32_f16 v[70:73], v[122:125], v[90:93], v[70:73]
	ds_read_b128 v[90:93], v23 offset:16384
	v_mfma_f32_16x16x32_f16 v[48:51], v[122:125], v[110:113], v[48:51]
	ds_read_b128 v[110:113], v23 offset:18432
	s_waitcnt lgkmcnt(1)
	v_mfma_f32_16x16x32_f16 v[36:39], v[62:65], v[90:93], v[36:39]
	ds_read_b128 v[122:125], v22 offset:55296
	s_waitcnt lgkmcnt(1)
	v_mfma_f32_16x16x32_f16 v[66:69], v[62:65], v[110:113], v[66:69]
	s_waitcnt vmcnt(1)
	ds_write_b128 v19, v[166:169] offset:32768
	v_mfma_f32_16x16x32_f16 v[44:47], v[74:77], v[90:93], v[44:47]
	s_waitcnt vmcnt(0)
	ds_write_b128 v20, v[190:193] offset:32768
	v_mfma_f32_16x16x32_f16 v[78:81], v[74:77], v[110:113], v[78:81]
	v_mfma_f32_16x16x32_f16 v[82:85], v[118:121], v[90:93], v[82:85]
	v_mfma_f32_16x16x32_f16 v[86:89], v[118:121], v[110:113], v[86:89]
	s_waitcnt lgkmcnt(2)
	v_mfma_f32_16x16x32_f16 v[28:31], v[122:125], v[90:93], v[28:31]
	ds_read_b128 v[90:93], v23 offset:20480
	v_mfma_f32_16x16x32_f16 v[32:35], v[122:125], v[110:113], v[32:35]
	ds_read_b128 v[110:113], v23 offset:22528
	s_waitcnt lgkmcnt(1)
	v_mfma_f32_16x16x32_f16 v[98:101], v[62:65], v[90:93], v[98:101]
	s_waitcnt lgkmcnt(0)
	v_mfma_f32_16x16x32_f16 v[52:55], v[62:65], v[110:113], v[52:55]
	global_load_dwordx4 v[62:65], v[0:1], off offset:1664
	v_mfma_f32_16x16x32_f16 v[102:105], v[74:77], v[90:93], v[102:105]
	v_mfma_f32_16x16x32_f16 v[24:27], v[74:77], v[110:113], v[24:27]
	v_mfma_f32_16x16x32_f16 v[114:117], v[118:121], v[90:93], v[114:117]
	v_mfma_f32_16x16x32_f16 v[40:43], v[118:121], v[110:113], v[40:43]
	v_mfma_f32_16x16x32_f16 v[70:73], v[122:125], v[90:93], v[70:73]
	global_load_dwordx4 v[90:93], v[2:3], off offset:1664
	global_load_dwordx4 v[130:133], v[4:5], off offset:1664
	global_load_dwordx4 v[138:141], v[14:15], off offset:1664
	global_load_dwordx4 v[74:77], v[10:11], off offset:1664
	global_load_dwordx4 v[142:145], v[12:13], off offset:1664
	global_load_dwordx4 v[154:157], v[8:9], off offset:1664
	global_load_dwordx4 v[158:161], v[6:7], off offset:1664
	s_waitcnt lgkmcnt(0)
	s_barrier
	v_mfma_f32_16x16x32_f16 v[48:51], v[122:125], v[110:113], v[48:51]
	ds_read_b128 v[58:61], v16 offset:32768
	ds_read_b128 v[106:109], v21
	s_waitcnt lgkmcnt(0)
	v_mfma_f32_16x16x32_f16 v[36:39], v[58:61], v[106:109], v[36:39]
	ds_read_b128 v[94:97], v16 offset:34816
	ds_read_b128 v[110:113], v21 offset:2048
	s_waitcnt lgkmcnt(0)
	v_mfma_f32_16x16x32_f16 v[66:69], v[58:61], v[110:113], v[66:69]
	ds_read_b128 v[118:121], v16 offset:36864
	v_mfma_f32_16x16x32_f16 v[44:47], v[94:97], v[106:109], v[44:47]
	ds_read_b128 v[122:125], v16 offset:38912
	v_mfma_f32_16x16x32_f16 v[78:81], v[94:97], v[110:113], v[78:81]
	s_waitcnt vmcnt(7)
	ds_write_b128 v17, v[62:65] offset:16384
	s_waitcnt lgkmcnt(2)
	v_mfma_f32_16x16x32_f16 v[82:85], v[118:121], v[106:109], v[82:85]
	s_waitcnt vmcnt(6)
	ds_write_b128 v18, v[90:93] offset:16384
	v_mfma_f32_16x16x32_f16 v[86:89], v[118:121], v[110:113], v[86:89]
	s_waitcnt vmcnt(5)
	ds_write_b128 v19, v[130:133] offset:16384
	s_waitcnt lgkmcnt(3)
	v_mfma_f32_16x16x32_f16 v[28:31], v[122:125], v[106:109], v[28:31]
	ds_read_b128 v[106:109], v21 offset:4096
	v_mfma_f32_16x16x32_f16 v[32:35], v[122:125], v[110:113], v[32:35]
	ds_read_b128 v[110:113], v21 offset:6144
	s_waitcnt lgkmcnt(1)
	v_mfma_f32_16x16x32_f16 v[98:101], v[58:61], v[106:109], v[98:101]
	s_waitcnt vmcnt(4)
	ds_write_b128 v20, v[138:141] offset:16384
	s_waitcnt lgkmcnt(1)
	v_mfma_f32_16x16x32_f16 v[52:55], v[58:61], v[110:113], v[52:55]
	ds_read_b128 v[58:61], v22 offset:32768
	v_mfma_f32_16x16x32_f16 v[102:105], v[94:97], v[106:109], v[102:105]
	s_waitcnt vmcnt(3)
	ds_write_b128 v17, v[74:77] offset:49152
	v_mfma_f32_16x16x32_f16 v[24:27], v[94:97], v[110:113], v[24:27]
	ds_read_b128 v[94:97], v22 offset:34816
	v_mfma_f32_16x16x32_f16 v[114:117], v[118:121], v[106:109], v[114:117]
	s_waitcnt vmcnt(2)
	ds_write_b128 v18, v[142:145] offset:49152
	v_mfma_f32_16x16x32_f16 v[40:43], v[118:121], v[110:113], v[40:43]
	ds_read_b128 v[118:121], v22 offset:36864
	v_mfma_f32_16x16x32_f16 v[70:73], v[122:125], v[106:109], v[70:73]
	ds_read_b128 v[106:109], v23
	v_mfma_f32_16x16x32_f16 v[48:51], v[122:125], v[110:113], v[48:51]
	ds_read_b128 v[110:113], v23 offset:2048
	s_waitcnt lgkmcnt(1)
	v_mfma_f32_16x16x32_f16 v[36:39], v[58:61], v[106:109], v[36:39]
	ds_read_b128 v[122:125], v22 offset:38912
	s_waitcnt lgkmcnt(1)
	v_mfma_f32_16x16x32_f16 v[66:69], v[58:61], v[110:113], v[66:69]
	s_waitcnt vmcnt(1)
	ds_write_b128 v19, v[154:157] offset:49152
	v_mfma_f32_16x16x32_f16 v[44:47], v[94:97], v[106:109], v[44:47]
	s_waitcnt vmcnt(0)
	ds_write_b128 v20, v[158:161] offset:49152
	v_mfma_f32_16x16x32_f16 v[78:81], v[94:97], v[110:113], v[78:81]
	v_mfma_f32_16x16x32_f16 v[82:85], v[118:121], v[106:109], v[82:85]
	v_mfma_f32_16x16x32_f16 v[86:89], v[118:121], v[110:113], v[86:89]
	s_waitcnt lgkmcnt(2)
	v_mfma_f32_16x16x32_f16 v[28:31], v[122:125], v[106:109], v[28:31]
	ds_read_b128 v[106:109], v23 offset:4096
	v_mfma_f32_16x16x32_f16 v[32:35], v[122:125], v[110:113], v[32:35]
	ds_read_b128 v[110:113], v23 offset:6144
	s_waitcnt lgkmcnt(1)
	v_mfma_f32_16x16x32_f16 v[98:101], v[58:61], v[106:109], v[98:101]
	s_waitcnt lgkmcnt(0)
	v_mfma_f32_16x16x32_f16 v[52:55], v[58:61], v[110:113], v[52:55]
	global_load_dwordx4 v[58:61], v[0:1], off offset:1792
	v_mfma_f32_16x16x32_f16 v[102:105], v[94:97], v[106:109], v[102:105]
	v_mfma_f32_16x16x32_f16 v[24:27], v[94:97], v[110:113], v[24:27]
	v_mfma_f32_16x16x32_f16 v[114:117], v[118:121], v[106:109], v[114:117]
	v_mfma_f32_16x16x32_f16 v[40:43], v[118:121], v[110:113], v[40:43]
	v_mfma_f32_16x16x32_f16 v[70:73], v[122:125], v[106:109], v[70:73]
	global_load_dwordx4 v[106:109], v[2:3], off offset:1792
	global_load_dwordx4 v[126:129], v[4:5], off offset:1792
	global_load_dwordx4 v[134:137], v[14:15], off offset:1792
	global_load_dwordx4 v[94:97], v[10:11], off offset:1792
	global_load_dwordx4 v[162:165], v[12:13], off offset:1792
	global_load_dwordx4 v[166:169], v[8:9], off offset:1792
	global_load_dwordx4 v[190:193], v[6:7], off offset:1792
	s_waitcnt lgkmcnt(0)
	s_barrier
; #define GL_LOAD(s_, kt_) if (VAR != 1) { a##s_##0 = GL_A(0, kt_); a##s_##1 = GL_A(1, kt_); a##s_##2 = GL_A(2, kt_); a##s_##3 = GL_A(3, kt_); b##s_##0 = GL_B(0, kt_); b##s_##1 = GL_B(1, kt_); b##s_##2 = GL_B(2, kt_); b##s_##3 = GL_B(3, kt_); }
; #define LDS_STORE(s_, buf_) if (VAR != 2) { LDS_ST1(sA, 0, buf_, a##s_##0) LDS_ST1(sA, 1, buf_, a##s_##1) LDS_ST1(sA, 2, buf_, a##s_##2) LDS_ST1(sA, 3, buf_, a##s_##3) LDS_ST1(sB, 0, buf_, b##s_##0) LDS_ST1(sB, 1, buf_, b##s_##1) LDS_ST1(sB, 2, buf_, b##s_##2) LDS_ST1(sB, 3, buf_, b##s_##3) }
;     ...
;   for (int kt = 0; kt < nk; kt += 2) {
;     if (kt + 2 < nk) { GL_LOAD(0, kt + 2) }
;     MMA_TILE(0)
;     LDS_STORE(1, 1)
;     if (VAR != 4) __syncthreads();
;     if (kt + 3 < nk) { GL_LOAD(1, kt + 3) }
;     MMA_TILE(1)
;     if (kt + 2 < nk) { LDS_STORE(0, 0) }
;     if (VAR != 4) __syncthreads();
	v_mfma_f32_16x16x32_f16 v[48:51], v[122:125], v[110:113], v[48:51]
	ds_read_b128 v[62:65], v16 offset:49152
	ds_read_b128 v[90:93], v21 offset:16384
	s_waitcnt lgkmcnt(0)
	v_mfma_f32_16x16x32_f16 v[36:39], v[62:65], v[90:93], v[36:39]
	ds_read_b128 v[74:77], v16 offset:51200
	ds_read_b128 v[110:113], v21 offset:18432
	s_waitcnt lgkmcnt(0)
	v_mfma_f32_16x16x32_f16 v[66:69], v[62:65], v[110:113], v[66:69]
	ds_read_b128 v[118:121], v16 offset:53248
	v_mfma_f32_16x16x32_f16 v[44:47], v[74:77], v[90:93], v[44:47]
	ds_read_b128 v[122:125], v16 offset:55296
	v_mfma_f32_16x16x32_f16 v[78:81], v[74:77], v[110:113], v[78:81]
	s_waitcnt vmcnt(7)
	ds_write_b128 v17, v[58:61]
	s_waitcnt lgkmcnt(2)
	v_mfma_f32_16x16x32_f16 v[82:85], v[118:121], v[90:93], v[82:85]
	s_waitcnt vmcnt(6)
	ds_write_b128 v18, v[106:109]
	v_mfma_f32_16x16x32_f16 v[86:89], v[118:121], v[110:113], v[86:89]
	s_waitcnt vmcnt(5)
	ds_write_b128 v19, v[126:129]
	s_waitcnt lgkmcnt(3)
	v_mfma_f32_16x16x32_f16 v[28:31], v[122:125], v[90:93], v[28:31]
	ds_read_b128 v[90:93], v21 offset:20480
	v_mfma_f32_16x16x32_f16 v[32:35], v[122:125], v[110:113], v[32:35]
	ds_read_b128 v[110:113], v21 offset:22528
	s_waitcnt lgkmcnt(1)
	v_mfma_f32_16x16x32_f16 v[98:101], v[62:65], v[90:93], v[98:101]
	s_waitcnt vmcnt(4)
	ds_write_b128 v20, v[134:137]
	s_waitcnt lgkmcnt(1)
	v_mfma_f32_16x16x32_f16 v[52:55], v[62:65], v[110:113], v[52:55]
	ds_read_b128 v[62:65], v22 offset:49152
	v_mfma_f32_16x16x32_f16 v[102:105], v[74:77], v[90:93], v[102:105]
	s_waitcnt vmcnt(3)
	ds_write_b128 v17, v[94:97] offset:32768
	v_mfma_f32_16x16x32_f16 v[24:27], v[74:77], v[110:113], v[24:27]
	ds_read_b128 v[74:77], v22 offset:51200
	v_mfma_f32_16x16x32_f16 v[114:117], v[118:121], v[90:93], v[114:117]
	s_waitcnt vmcnt(2)
	ds_write_b128 v18, v[162:165] offset:32768
	v_mfma_f32_16x16x32_f16 v[40:43], v[118:121], v[110:113], v[40:43]
	ds_read_b128 v[118:121], v22 offset:53248
	v_mfma_f32_16x16x32_f16 v[70:73], v[122:125], v[90:93], v[70:73]
	ds_read_b128 v[90:93], v23 offset:16384
	v_mfma_f32_16x16x32_f16 v[48:51], v[122:125], v[110:113], v[48:51]
	ds_read_b128 v[110:113], v23 offset:18432
	s_waitcnt lgkmcnt(1)
	v_mfma_f32_16x16x32_f16 v[36:39], v[62:65], v[90:93], v[36:39]
	ds_read_b128 v[122:125], v22 offset:55296
	s_waitcnt lgkmcnt(1)
	v_mfma_f32_16x16x32_f16 v[66:69], v[62:65], v[110:113], v[66:69]
	s_waitcnt vmcnt(1)
	ds_write_b128 v19, v[166:169] offset:32768
	v_mfma_f32_16x16x32_f16 v[44:47], v[74:77], v[90:93], v[44:47]
	s_waitcnt vmcnt(0)
	ds_write_b128 v20, v[190:193] offset:32768
	v_mfma_f32_16x16x32_f16 v[78:81], v[74:77], v[110:113], v[78:81]
	v_mfma_f32_16x16x32_f16 v[82:85], v[118:121], v[90:93], v[82:85]
	v_mfma_f32_16x16x32_f16 v[86:89], v[118:121], v[110:113], v[86:89]
	s_waitcnt lgkmcnt(2)
	v_mfma_f32_16x16x32_f16 v[28:31], v[122:125], v[90:93], v[28:31]
	ds_read_b128 v[90:93], v23 offset:20480
	v_mfma_f32_16x16x32_f16 v[32:35], v[122:125], v[110:113], v[32:35]
	ds_read_b128 v[110:113], v23 offset:22528
	s_waitcnt lgkmcnt(1)
	v_mfma_f32_16x16x32_f16 v[98:101], v[62:65], v[90:93], v[98:101]
	s_waitcnt lgkmcnt(0)
	v_mfma_f32_16x16x32_f16 v[52:55], v[62:65], v[110:113], v[52:55]
	global_load_dwordx4 v[62:65], v[0:1], off offset:1920
	v_mfma_f32_16x16x32_f16 v[102:105], v[74:77], v[90:93], v[102:105]
	v_mfma_f32_16x16x32_f16 v[24:27], v[74:77], v[110:113], v[24:27]
	v_mfma_f32_16x16x32_f16 v[114:117], v[118:121], v[90:93], v[114:117]
	v_mfma_f32_16x16x32_f16 v[40:43], v[118:121], v[110:113], v[40:43]
	v_mfma_f32_16x16x32_f16 v[70:73], v[122:125], v[90:93], v[70:73]
	global_load_dwordx4 v[90:93], v[2:3], off offset:1920
	global_load_dwordx4 v[130:133], v[4:5], off offset:1920
	global_load_dwordx4 v[138:141], v[14:15], off offset:1920
	global_load_dwordx4 v[74:77], v[10:11], off offset:1920
	global_load_dwordx4 v[142:145], v[12:13], off offset:1920
	global_load_dwordx4 v[154:157], v[8:9], off offset:1920
	global_load_dwordx4 v[158:161], v[6:7], off offset:1920
	s_waitcnt lgkmcnt(0)
	s_barrier
	v_mfma_f32_16x16x32_f16 v[48:51], v[122:125], v[110:113], v[48:51]
	ds_read_b128 v[58:61], v16 offset:32768
	ds_read_b128 v[106:109], v21
	s_waitcnt lgkmcnt(0)
	v_mfma_f32_16x16x32_f16 v[36:39], v[58:61], v[106:109], v[36:39]
	ds_read_b128 v[94:97], v16 offset:34816
	ds_read_b128 v[110:113], v21 offset:2048
	s_waitcnt lgkmcnt(0)
	v_mfma_f32_16x16x32_f16 v[66:69], v[58:61], v[110:113], v[66:69]
	ds_read_b128 v[118:121], v16 offset:36864
	v_mfma_f32_16x16x32_f16 v[44:47], v[94:97], v[106:109], v[44:47]
	ds_read_b128 v[122:125], v16 offset:38912
	v_mfma_f32_16x16x32_f16 v[78:81], v[94:97], v[110:113], v[78:81]
	s_waitcnt vmcnt(7)
	ds_write_b128 v17, v[62:65] offset:16384
	s_waitcnt lgkmcnt(2)
	v_mfma_f32_16x16x32_f16 v[82:85], v[118:121], v[106:109], v[82:85]
	s_waitcnt vmcnt(6)
	ds_write_b128 v18, v[90:93] offset:16384
	v_mfma_f32_16x16x32_f16 v[86:89], v[118:121], v[110:113], v[86:89]
	s_waitcnt vmcnt(5)
	ds_write_b128 v19, v[130:133] offset:16384
	s_waitcnt lgkmcnt(3)
	v_mfma_f32_16x16x32_f16 v[28:31], v[122:125], v[106:109], v[28:31]
	ds_read_b128 v[106:109], v21 offset:4096
	v_mfma_f32_16x16x32_f16 v[32:35], v[122:125], v[110:113], v[32:35]
	ds_read_b128 v[110:113], v21 offset:6144
	s_waitcnt lgkmcnt(1)
	v_mfma_f32_16x16x32_f16 v[98:101], v[58:61], v[106:109], v[98:101]
	s_waitcnt vmcnt(4)
	ds_write_b128 v20, v[138:141] offset:16384
	s_waitcnt lgkmcnt(1)
	v_mfma_f32_16x16x32_f16 v[52:55], v[58:61], v[110:113], v[52:55]
	ds_read_b128 v[58:61], v22 offset:32768
	v_mfma_f32_16x16x32_f16 v[102:105], v[94:97], v[106:109], v[102:105]
	s_waitcnt vmcnt(3)
; #define GL_LOAD(s_, kt_) if (VAR != 1) { a##s_##0 = GL_A(0, kt_); a##s_##1 = GL_A(1, kt_); a##s_##2 = GL_A(2, kt_); a##s_##3 = GL_A(3, kt_); b##s_##0 = GL_B(0, kt_); b##s_##1 = GL_B(1, kt_); b##s_##2 = GL_B(2, kt_); b##s_##3 = GL_B(3, kt_); }
; #define LDS_STORE(s_, buf_) if (VAR != 2) { LDS_ST1(sA, 0, buf_, a##s_##0) LDS_ST1(sA, 1, buf_, a##s_##1) LDS_ST1(sA, 2, buf_, a##s_##2) LDS_ST1(sA, 3, buf_, a##s_##3) LDS_ST1(sB, 0, buf_, b##s_##0) LDS_ST1(sB, 1, buf_, b##s_##1) LDS_ST1(sB, 2, buf_, b##s_##2) LDS_ST1(sB, 3, buf_, b##s_##3) }
;     ...
;   for (int kt = 0; kt < nk; kt += 2) {
;     if (kt + 2 < nk) { GL_LOAD(0, kt + 2) }
;     MMA_TILE(0)
;     LDS_STORE(1, 1)
;     if (VAR != 4) __syncthreads();
;     if (kt + 3 < nk) { GL_LOAD(1, kt + 3) }
;     MMA_TILE(1)
;     if (kt + 2 < nk) { LDS_STORE(0, 0) }
;     if (VAR != 4) __syncthreads();
	ds_write_b128 v17, v[74:77] offset:49152
	v_mfma_f32_16x16x32_f16 v[24:27], v[94:97], v[110:113], v[24:27]
	ds_read_b128 v[94:97], v22 offset:34816
	v_mfma_f32_16x16x32_f16 v[114:117], v[118:121], v[106:109], v[114:117]
	s_waitcnt vmcnt(2)
	ds_write_b128 v18, v[142:145] offset:49152
	v_mfma_f32_16x16x32_f16 v[40:43], v[118:121], v[110:113], v[40:43]
	ds_read_b128 v[118:121], v22 offset:36864
	v_mfma_f32_16x16x32_f16 v[70:73], v[122:125], v[106:109], v[70:73]
	ds_read_b128 v[106:109], v23
	v_mfma_f32_16x16x32_f16 v[48:51], v[122:125], v[110:113], v[48:51]
	ds_read_b128 v[110:113], v23 offset:2048
	s_waitcnt lgkmcnt(1)
	v_mfma_f32_16x16x32_f16 v[36:39], v[58:61], v[106:109], v[36:39]
	ds_read_b128 v[122:125], v22 offset:38912
	s_waitcnt lgkmcnt(1)
	v_mfma_f32_16x16x32_f16 v[66:69], v[58:61], v[110:113], v[66:69]
	s_waitcnt vmcnt(1)
	ds_write_b128 v19, v[154:157] offset:49152
	v_mfma_f32_16x16x32_f16 v[44:47], v[94:97], v[106:109], v[44:47]
	s_waitcnt vmcnt(0)
	ds_write_b128 v20, v[158:161] offset:49152
	v_mfma_f32_16x16x32_f16 v[78:81], v[94:97], v[110:113], v[78:81]
	v_mfma_f32_16x16x32_f16 v[82:85], v[118:121], v[106:109], v[82:85]
	v_mfma_f32_16x16x32_f16 v[86:89], v[118:121], v[110:113], v[86:89]
	s_waitcnt lgkmcnt(2)
	v_mfma_f32_16x16x32_f16 v[28:31], v[122:125], v[106:109], v[28:31]
	ds_read_b128 v[106:109], v23 offset:4096
	v_mfma_f32_16x16x32_f16 v[32:35], v[122:125], v[110:113], v[32:35]
	ds_read_b128 v[110:113], v23 offset:6144
	s_waitcnt lgkmcnt(1)
	v_mfma_f32_16x16x32_f16 v[98:101], v[58:61], v[106:109], v[98:101]
	s_waitcnt lgkmcnt(0)
	v_mfma_f32_16x16x32_f16 v[52:55], v[58:61], v[110:113], v[52:55]
	global_load_dwordx4 v[58:61], v[0:1], off offset:2048
	v_mfma_f32_16x16x32_f16 v[102:105], v[94:97], v[106:109], v[102:105]
	v_mfma_f32_16x16x32_f16 v[24:27], v[94:97], v[110:113], v[24:27]
	v_mfma_f32_16x16x32_f16 v[114:117], v[118:121], v[106:109], v[114:117]
	v_mfma_f32_16x16x32_f16 v[40:43], v[118:121], v[110:113], v[40:43]
	v_mfma_f32_16x16x32_f16 v[70:73], v[122:125], v[106:109], v[70:73]
	global_load_dwordx4 v[106:109], v[2:3], off offset:2048
	global_load_dwordx4 v[126:129], v[4:5], off offset:2048
	global_load_dwordx4 v[134:137], v[14:15], off offset:2048
	global_load_dwordx4 v[94:97], v[10:11], off offset:2048
	global_load_dwordx4 v[162:165], v[12:13], off offset:2048
	global_load_dwordx4 v[166:169], v[8:9], off offset:2048
	global_load_dwordx4 v[190:193], v[6:7], off offset:2048
	s_waitcnt lgkmcnt(0)
	s_barrier
	v_mfma_f32_16x16x32_f16 v[48:51], v[122:125], v[110:113], v[48:51]
	ds_read_b128 v[62:65], v16 offset:49152
	ds_read_b128 v[90:93], v21 offset:16384
	s_waitcnt lgkmcnt(0)
	v_mfma_f32_16x16x32_f16 v[36:39], v[62:65], v[90:93], v[36:39]
	ds_read_b128 v[74:77], v16 offset:51200
	ds_read_b128 v[110:113], v21 offset:18432
	s_waitcnt lgkmcnt(0)
	v_mfma_f32_16x16x32_f16 v[66:69], v[62:65], v[110:113], v[66:69]
	ds_read_b128 v[118:121], v16 offset:53248
	v_mfma_f32_16x16x32_f16 v[44:47], v[74:77], v[90:93], v[44:47]
	ds_read_b128 v[122:125], v16 offset:55296
	v_mfma_f32_16x16x32_f16 v[78:81], v[74:77], v[110:113], v[78:81]
	s_waitcnt vmcnt(7)
	ds_write_b128 v17, v[58:61]
	s_waitcnt lgkmcnt(2)
	v_mfma_f32_16x16x32_f16 v[82:85], v[118:121], v[90:93], v[82:85]
	s_waitcnt vmcnt(6)
	ds_write_b128 v18, v[106:109]
	v_mfma_f32_16x16x32_f16 v[86:89], v[118:121], v[110:113], v[86:89]
	s_waitcnt vmcnt(5)
	ds_write_b128 v19, v[126:129]
	s_waitcnt lgkmcnt(3)
	v_mfma_f32_16x16x32_f16 v[28:31], v[122:125], v[90:93], v[28:31]
	ds_read_b128 v[90:93], v21 offset:20480
	v_mfma_f32_16x16x32_f16 v[32:35], v[122:125], v[110:113], v[32:35]
	ds_read_b128 v[110:113], v21 offset:22528
	s_waitcnt lgkmcnt(1)
	v_mfma_f32_16x16x32_f16 v[98:101], v[62:65], v[90:93], v[98:101]
	s_waitcnt vmcnt(4)
	ds_write_b128 v20, v[134:137]
	s_waitcnt lgkmcnt(1)
	v_mfma_f32_16x16x32_f16 v[52:55], v[62:65], v[110:113], v[52:55]
	ds_read_b128 v[62:65], v22 offset:49152
	v_mfma_f32_16x16x32_f16 v[102:105], v[74:77], v[90:93], v[102:105]
	s_waitcnt vmcnt(3)
	ds_write_b128 v17, v[94:97] offset:32768
	v_mfma_f32_16x16x32_f16 v[24:27], v[74:77], v[110:113], v[24:27]
	ds_read_b128 v[74:77], v22 offset:51200
	v_mfma_f32_16x16x32_f16 v[114:117], v[118:121], v[90:93], v[114:117]
	s_waitcnt vmcnt(2)
	ds_write_b128 v18, v[162:165] offset:32768
	v_mfma_f32_16x16x32_f16 v[40:43], v[118:121], v[110:113], v[40:43]
	ds_read_b128 v[118:121], v22 offset:53248
	v_mfma_f32_16x16x32_f16 v[70:73], v[122:125], v[90:93], v[70:73]
	ds_read_b128 v[90:93], v23 offset:16384
	v_mfma_f32_16x16x32_f16 v[48:51], v[122:125], v[110:113], v[48:51]
	ds_read_b128 v[110:113], v23 offset:18432
	s_waitcnt lgkmcnt(1)
	v_mfma_f32_16x16x32_f16 v[36:39], v[62:65], v[90:93], v[36:39]
	ds_read_b128 v[122:125], v22 offset:55296
	s_waitcnt lgkmcnt(1)
	v_mfma_f32_16x16x32_f16 v[66:69], v[62:65], v[110:113], v[66:69]
	s_waitcnt vmcnt(1)
	ds_write_b128 v19, v[166:169] offset:32768
	v_mfma_f32_16x16x32_f16 v[44:47], v[74:77], v[90:93], v[44:47]
	s_waitcnt vmcnt(0)
	ds_write_b128 v20, v[190:193] offset:32768
	v_mfma_f32_16x16x32_f16 v[78:81], v[74:77], v[110:113], v[78:81]
	v_mfma_f32_16x16x32_f16 v[82:85], v[118:121], v[90:93], v[82:85]
	v_mfma_f32_16x16x32_f16 v[86:89], v[118:121], v[110:113], v[86:89]
	s_waitcnt lgkmcnt(2)
	v_mfma_f32_16x16x32_f16 v[28:31], v[122:125], v[90:93], v[28:31]
	ds_read_b128 v[90:93], v23 offset:20480
	v_mfma_f32_16x16x32_f16 v[32:35], v[122:125], v[110:113], v[32:35]
	ds_read_b128 v[110:113], v23 offset:22528
	s_waitcnt lgkmcnt(1)
	v_mfma_f32_16x16x32_f16 v[98:101], v[62:65], v[90:93], v[98:101]
	s_waitcnt lgkmcnt(0)
	v_mfma_f32_16x16x32_f16 v[52:55], v[62:65], v[110:113], v[52:55]
	global_load_dwordx4 v[62:65], v[0:1], off offset:2176
	v_mfma_f32_16x16x32_f16 v[102:105], v[74:77], v[90:93], v[102:105]
	v_mfma_f32_16x16x32_f16 v[24:27], v[74:77], v[110:113], v[24:27]
	v_mfma_f32_16x16x32_f16 v[114:117], v[118:121], v[90:93], v[114:117]
	v_mfma_f32_16x16x32_f16 v[40:43], v[118:121], v[110:113], v[40:43]
	v_mfma_f32_16x16x32_f16 v[70:73], v[122:125], v[90:93], v[70:73]
	global_load_dwordx4 v[90:93], v[2:3], off offset:2176
	global_load_dwordx4 v[130:133], v[4:5], off offset:2176
	global_load_dwordx4 v[138:141], v[14:15], off offset:2176
	global_load_dwordx4 v[74:77], v[10:11], off offset:2176
	global_load_dwordx4 v[142:145], v[12:13], off offset:2176
	global_load_dwordx4 v[154:157], v[8:9], off offset:2176
	global_load_dwordx4 v[158:161], v[6:7], off offset:2176
	s_waitcnt lgkmcnt(0)
	s_barrier
; #define GL_LOAD(s_, kt_) if (VAR != 1) { a##s_##0 = GL_A(0, kt_); a##s_##1 = GL_A(1, kt_); a##s_##2 = GL_A(2, kt_); a##s_##3 = GL_A(3, kt_); b##s_##0 = GL_B(0, kt_); b##s_##1 = GL_B(1, kt_); b##s_##2 = GL_B(2, kt_); b##s_##3 = GL_B(3, kt_); }
; #define LDS_STORE(s_, buf_) if (VAR != 2) { LDS_ST1(sA, 0, buf_, a##s_##0) LDS_ST1(sA, 1, buf_, a##s_##1) LDS_ST1(sA, 2, buf_, a##s_##2) LDS_ST1(sA, 3, buf_, a##s_##3) LDS_ST1(sB, 0, buf_, b##s_##0) LDS_ST1(sB, 1, buf_, b##s_##1) LDS_ST1(sB, 2, buf_, b##s_##2) LDS_ST1(sB, 3, buf_, b##s_##3) }
;     ...
;   for (int kt = 0; kt < nk; kt += 2) {
;     if (kt + 2 < nk) { GL_LOAD(0, kt + 2) }
;     MMA_TILE(0)
;     LDS_STORE(1, 1)
;     if (VAR != 4) __syncthreads();
;     if (kt + 3 < nk) { GL_LOAD(1, kt + 3) }
;     MMA_TILE(1)
;     if (kt + 2 < nk) { LDS_STORE(0, 0) }
;     if (VAR != 4) __syncthreads();
	v_mfma_f32_16x16x32_f16 v[48:51], v[122:125], v[110:113], v[48:51]
	ds_read_b128 v[58:61], v16 offset:32768
	ds_read_b128 v[106:109], v21
	s_waitcnt lgkmcnt(0)
	v_mfma_f32_16x16x32_f16 v[36:39], v[58:61], v[106:109], v[36:39]
	ds_read_b128 v[94:97], v16 offset:34816
	ds_read_b128 v[110:113], v21 offset:2048
	s_waitcnt lgkmcnt(0)
	v_mfma_f32_16x16x32_f16 v[66:69], v[58:61], v[110:113], v[66:69]
	ds_read_b128 v[118:121], v16 offset:36864
	v_mfma_f32_16x16x32_f16 v[44:47], v[94:97], v[106:109], v[44:47]
	ds_read_b128 v[122:125], v16 offset:38912
	v_mfma_f32_16x16x32_f16 v[78:81], v[94:97], v[110:113], v[78:81]
	s_waitcnt vmcnt(7)
	ds_write_b128 v17, v[62:65] offset:16384
	s_waitcnt lgkmcnt(2)
	v_mfma_f32_16x16x32_f16 v[82:85], v[118:121], v[106:109], v[82:85]
	s_waitcnt vmcnt(6)
	ds_write_b128 v18, v[90:93] offset:16384
	v_mfma_f32_16x16x32_f16 v[86:89], v[118:121], v[110:113], v[86:89]
	s_waitcnt vmcnt(5)
	ds_write_b128 v19, v[130:133] offset:16384
	s_waitcnt lgkmcnt(3)
	v_mfma_f32_16x16x32_f16 v[28:31], v[122:125], v[106:109], v[28:31]
	ds_read_b128 v[106:109], v21 offset:4096
	v_mfma_f32_16x16x32_f16 v[32:35], v[122:125], v[110:113], v[32:35]
	ds_read_b128 v[110:113], v21 offset:6144
	s_waitcnt lgkmcnt(1)
	v_mfma_f32_16x16x32_f16 v[98:101], v[58:61], v[106:109], v[98:101]
	s_waitcnt vmcnt(4)
	ds_write_b128 v20, v[138:141] offset:16384
	s_waitcnt lgkmcnt(1)
	v_mfma_f32_16x16x32_f16 v[52:55], v[58:61], v[110:113], v[52:55]
	ds_read_b128 v[58:61], v22 offset:32768
	v_mfma_f32_16x16x32_f16 v[102:105], v[94:97], v[106:109], v[102:105]
	s_waitcnt vmcnt(3)
	ds_write_b128 v17, v[74:77] offset:49152
	v_mfma_f32_16x16x32_f16 v[24:27], v[94:97], v[110:113], v[24:27]
	ds_read_b128 v[94:97], v22 offset:34816
	v_mfma_f32_16x16x32_f16 v[114:117], v[118:121], v[106:109], v[114:117]
	s_waitcnt vmcnt(2)
	ds_write_b128 v18, v[142:145] offset:49152
	v_mfma_f32_16x16x32_f16 v[40:43], v[118:121], v[110:113], v[40:43]
	ds_read_b128 v[118:121], v22 offset:36864
	v_mfma_f32_16x16x32_f16 v[70:73], v[122:125], v[106:109], v[70:73]
	ds_read_b128 v[106:109], v23
	v_mfma_f32_16x16x32_f16 v[48:51], v[122:125], v[110:113], v[48:51]
	ds_read_b128 v[110:113], v23 offset:2048
	s_waitcnt lgkmcnt(1)
	v_mfma_f32_16x16x32_f16 v[36:39], v[58:61], v[106:109], v[36:39]
	ds_read_b128 v[122:125], v22 offset:38912
	s_waitcnt lgkmcnt(1)
	v_mfma_f32_16x16x32_f16 v[66:69], v[58:61], v[110:113], v[66:69]
	s_waitcnt vmcnt(1)
	ds_write_b128 v19, v[154:157] offset:49152
	v_mfma_f32_16x16x32_f16 v[44:47], v[94:97], v[106:109], v[44:47]
	s_waitcnt vmcnt(0)
	ds_write_b128 v20, v[158:161] offset:49152
	v_mfma_f32_16x16x32_f16 v[78:81], v[94:97], v[110:113], v[78:81]
	v_mfma_f32_16x16x32_f16 v[82:85], v[118:121], v[106:109], v[82:85]
	v_mfma_f32_16x16x32_f16 v[86:89], v[118:121], v[110:113], v[86:89]
	s_waitcnt lgkmcnt(2)
	v_mfma_f32_16x16x32_f16 v[28:31], v[122:125], v[106:109], v[28:31]
	ds_read_b128 v[106:109], v23 offset:4096
	v_mfma_f32_16x16x32_f16 v[32:35], v[122:125], v[110:113], v[32:35]
	ds_read_b128 v[110:113], v23 offset:6144
	s_waitcnt lgkmcnt(1)
	v_mfma_f32_16x16x32_f16 v[98:101], v[58:61], v[106:109], v[98:101]
	s_waitcnt lgkmcnt(0)
	v_mfma_f32_16x16x32_f16 v[52:55], v[58:61], v[110:113], v[52:55]
	global_load_dwordx4 v[58:61], v[0:1], off offset:2304
	v_mfma_f32_16x16x32_f16 v[102:105], v[94:97], v[106:109], v[102:105]
	v_mfma_f32_16x16x32_f16 v[24:27], v[94:97], v[110:113], v[24:27]
	v_mfma_f32_16x16x32_f16 v[114:117], v[118:121], v[106:109], v[114:117]
	v_mfma_f32_16x16x32_f16 v[40:43], v[118:121], v[110:113], v[40:43]
	v_mfma_f32_16x16x32_f16 v[70:73], v[122:125], v[106:109], v[70:73]
	global_load_dwordx4 v[106:109], v[2:3], off offset:2304
	global_load_dwordx4 v[126:129], v[4:5], off offset:2304
	global_load_dwordx4 v[134:137], v[14:15], off offset:2304
	global_load_dwordx4 v[94:97], v[10:11], off offset:2304
	global_load_dwordx4 v[162:165], v[12:13], off offset:2304
	global_load_dwordx4 v[166:169], v[8:9], off offset:2304
	global_load_dwordx4 v[190:193], v[6:7], off offset:2304
	s_waitcnt lgkmcnt(0)
	s_barrier
	v_mfma_f32_16x16x32_f16 v[48:51], v[122:125], v[110:113], v[48:51]
	ds_read_b128 v[62:65], v16 offset:49152
	ds_read_b128 v[90:93], v21 offset:16384
	s_waitcnt lgkmcnt(0)
	v_mfma_f32_16x16x32_f16 v[36:39], v[62:65], v[90:93], v[36:39]
	ds_read_b128 v[74:77], v16 offset:51200
	ds_read_b128 v[110:113], v21 offset:18432
	s_waitcnt lgkmcnt(0)
	v_mfma_f32_16x16x32_f16 v[66:69], v[62:65], v[110:113], v[66:69]
	ds_read_b128 v[118:121], v16 offset:53248
	v_mfma_f32_16x16x32_f16 v[44:47], v[74:77], v[90:93], v[44:47]
	ds_read_b128 v[122:125], v16 offset:55296
	v_mfma_f32_16x16x32_f16 v[78:81], v[74:77], v[110:113], v[78:81]
	s_waitcnt vmcnt(7)
	ds_write_b128 v17, v[58:61]
	s_waitcnt lgkmcnt(2)
	v_mfma_f32_16x16x32_f16 v[82:85], v[118:121], v[90:93], v[82:85]
	s_waitcnt vmcnt(6)
	ds_write_b128 v18, v[106:109]
	v_mfma_f32_16x16x32_f16 v[86:89], v[118:121], v[110:113], v[86:89]
	s_waitcnt vmcnt(5)
	ds_write_b128 v19, v[126:129]
	s_waitcnt lgkmcnt(3)
	v_mfma_f32_16x16x32_f16 v[28:31], v[122:125], v[90:93], v[28:31]
	ds_read_b128 v[90:93], v21 offset:20480
	v_mfma_f32_16x16x32_f16 v[32:35], v[122:125], v[110:113], v[32:35]
	ds_read_b128 v[110:113], v21 offset:22528
	s_waitcnt lgkmcnt(1)
	v_mfma_f32_16x16x32_f16 v[98:101], v[62:65], v[90:93], v[98:101]
	s_waitcnt vmcnt(4)
	ds_write_b128 v20, v[134:137]
	s_waitcnt lgkmcnt(1)
	v_mfma_f32_16x16x32_f16 v[52:55], v[62:65], v[110:113], v[52:55]
	ds_read_b128 v[62:65], v22 offset:49152
	v_mfma_f32_16x16x32_f16 v[102:105], v[74:77], v[90:93], v[102:105]
	s_waitcnt vmcnt(3)
; #define GL_LOAD(s_, kt_) if (VAR != 1) { a##s_##0 = GL_A(0, kt_); a##s_##1 = GL_A(1, kt_); a##s_##2 = GL_A(2, kt_); a##s_##3 = GL_A(3, kt_); b##s_##0 = GL_B(0, kt_); b##s_##1 = GL_B(1, kt_); b##s_##2 = GL_B(2, kt_); b##s_##3 = GL_B(3, kt_); }
; #define LDS_STORE(s_, buf_) if (VAR != 2) { LDS_ST1(sA, 0, buf_, a##s_##0) LDS_ST1(sA, 1, buf_, a##s_##1) LDS_ST1(sA, 2, buf_, a##s_##2) LDS_ST1(sA, 3, buf_, a##s_##3) LDS_ST1(sB, 0, buf_, b##s_##0) LDS_ST1(sB, 1, buf_, b##s_##1) LDS_ST1(sB, 2, buf_, b##s_##2) LDS_ST1(sB, 3, buf_, b##s_##3) }
;     ...
;   for (int kt = 0; kt < nk; kt += 2) {
;     if (kt + 2 < nk) { GL_LOAD(0, kt + 2) }
;     MMA_TILE(0)
;     LDS_STORE(1, 1)
;     if (VAR != 4) __syncthreads();
;     if (kt + 3 < nk) { GL_LOAD(1, kt + 3) }
;     MMA_TILE(1)
;     if (kt + 2 < nk) { LDS_STORE(0, 0) }
;     if (VAR != 4) __syncthreads();
	ds_write_b128 v17, v[94:97] offset:32768
	v_mfma_f32_16x16x32_f16 v[24:27], v[74:77], v[110:113], v[24:27]
	ds_read_b128 v[74:77], v22 offset:51200
	v_mfma_f32_16x16x32_f16 v[114:117], v[118:121], v[90:93], v[114:117]
	s_waitcnt vmcnt(2)
	ds_write_b128 v18, v[162:165] offset:32768
	v_mfma_f32_16x16x32_f16 v[40:43], v[118:121], v[110:113], v[40:43]
	ds_read_b128 v[118:121], v22 offset:53248
	v_mfma_f32_16x16x32_f16 v[70:73], v[122:125], v[90:93], v[70:73]
	ds_read_b128 v[90:93], v23 offset:16384
	v_mfma_f32_16x16x32_f16 v[48:51], v[122:125], v[110:113], v[48:51]
	ds_read_b128 v[110:113], v23 offset:18432
	s_waitcnt lgkmcnt(1)
	v_mfma_f32_16x16x32_f16 v[36:39], v[62:65], v[90:93], v[36:39]
	ds_read_b128 v[122:125], v22 offset:55296
	s_waitcnt lgkmcnt(1)
	v_mfma_f32_16x16x32_f16 v[66:69], v[62:65], v[110:113], v[66:69]
	s_waitcnt vmcnt(1)
	ds_write_b128 v19, v[166:169] offset:32768
	v_mfma_f32_16x16x32_f16 v[44:47], v[74:77], v[90:93], v[44:47]
	s_waitcnt vmcnt(0)
	ds_write_b128 v20, v[190:193] offset:32768
	v_mfma_f32_16x16x32_f16 v[78:81], v[74:77], v[110:113], v[78:81]
	v_mfma_f32_16x16x32_f16 v[82:85], v[118:121], v[90:93], v[82:85]
	v_mfma_f32_16x16x32_f16 v[86:89], v[118:121], v[110:113], v[86:89]
	s_waitcnt lgkmcnt(2)
	v_mfma_f32_16x16x32_f16 v[28:31], v[122:125], v[90:93], v[28:31]
	ds_read_b128 v[90:93], v23 offset:20480
	v_mfma_f32_16x16x32_f16 v[32:35], v[122:125], v[110:113], v[32:35]
	ds_read_b128 v[110:113], v23 offset:22528
	s_waitcnt lgkmcnt(1)
	v_mfma_f32_16x16x32_f16 v[98:101], v[62:65], v[90:93], v[98:101]
	s_waitcnt lgkmcnt(0)
	v_mfma_f32_16x16x32_f16 v[52:55], v[62:65], v[110:113], v[52:55]
	global_load_dwordx4 v[62:65], v[0:1], off offset:2432
	v_mfma_f32_16x16x32_f16 v[102:105], v[74:77], v[90:93], v[102:105]
	v_mfma_f32_16x16x32_f16 v[24:27], v[74:77], v[110:113], v[24:27]
	v_mfma_f32_16x16x32_f16 v[114:117], v[118:121], v[90:93], v[114:117]
	v_mfma_f32_16x16x32_f16 v[40:43], v[118:121], v[110:113], v[40:43]
	v_mfma_f32_16x16x32_f16 v[70:73], v[122:125], v[90:93], v[70:73]
	global_load_dwordx4 v[90:93], v[2:3], off offset:2432
	global_load_dwordx4 v[130:133], v[4:5], off offset:2432
	global_load_dwordx4 v[138:141], v[14:15], off offset:2432
	global_load_dwordx4 v[74:77], v[10:11], off offset:2432
	global_load_dwordx4 v[142:145], v[12:13], off offset:2432
	global_load_dwordx4 v[154:157], v[8:9], off offset:2432
	global_load_dwordx4 v[158:161], v[6:7], off offset:2432
	s_waitcnt lgkmcnt(0)
	s_barrier
	v_mfma_f32_16x16x32_f16 v[48:51], v[122:125], v[110:113], v[48:51]
	ds_read_b128 v[58:61], v16 offset:32768
	ds_read_b128 v[106:109], v21
	s_waitcnt lgkmcnt(0)
	v_mfma_f32_16x16x32_f16 v[36:39], v[58:61], v[106:109], v[36:39]
	ds_read_b128 v[94:97], v16 offset:34816
	ds_read_b128 v[110:113], v21 offset:2048
	s_waitcnt lgkmcnt(0)
	v_mfma_f32_16x16x32_f16 v[66:69], v[58:61], v[110:113], v[66:69]
	ds_read_b128 v[118:121], v16 offset:36864
	v_mfma_f32_16x16x32_f16 v[44:47], v[94:97], v[106:109], v[44:47]
	ds_read_b128 v[122:125], v16 offset:38912
	v_mfma_f32_16x16x32_f16 v[78:81], v[94:97], v[110:113], v[78:81]
	s_waitcnt vmcnt(7)
	ds_write_b128 v17, v[62:65] offset:16384
	s_waitcnt lgkmcnt(2)
	v_mfma_f32_16x16x32_f16 v[82:85], v[118:121], v[106:109], v[82:85]
	s_waitcnt vmcnt(6)
	ds_write_b128 v18, v[90:93] offset:16384
	v_mfma_f32_16x16x32_f16 v[86:89], v[118:121], v[110:113], v[86:89]
	s_waitcnt vmcnt(5)
	ds_write_b128 v19, v[130:133] offset:16384
	s_waitcnt lgkmcnt(3)
	v_mfma_f32_16x16x32_f16 v[28:31], v[122:125], v[106:109], v[28:31]
	ds_read_b128 v[106:109], v21 offset:4096
	v_mfma_f32_16x16x32_f16 v[32:35], v[122:125], v[110:113], v[32:35]
	ds_read_b128 v[110:113], v21 offset:6144
	s_waitcnt lgkmcnt(1)
	v_mfma_f32_16x16x32_f16 v[98:101], v[58:61], v[106:109], v[98:101]
	s_waitcnt vmcnt(4)
	ds_write_b128 v20, v[138:141] offset:16384
	s_waitcnt lgkmcnt(1)
	v_mfma_f32_16x16x32_f16 v[52:55], v[58:61], v[110:113], v[52:55]
	ds_read_b128 v[58:61], v22 offset:32768
	v_mfma_f32_16x16x32_f16 v[102:105], v[94:97], v[106:109], v[102:105]
	s_waitcnt vmcnt(3)
	ds_write_b128 v17, v[74:77] offset:49152
	v_mfma_f32_16x16x32_f16 v[24:27], v[94:97], v[110:113], v[24:27]
	ds_read_b128 v[94:97], v22 offset:34816
	v_mfma_f32_16x16x32_f16 v[114:117], v[118:121], v[106:109], v[114:117]
	s_waitcnt vmcnt(2)
	ds_write_b128 v18, v[142:145] offset:49152
	v_mfma_f32_16x16x32_f16 v[40:43], v[118:121], v[110:113], v[40:43]
	ds_read_b128 v[118:121], v22 offset:36864
	v_mfma_f32_16x16x32_f16 v[70:73], v[122:125], v[106:109], v[70:73]
	ds_read_b128 v[106:109], v23
	v_mfma_f32_16x16x32_f16 v[48:51], v[122:125], v[110:113], v[48:51]
	ds_read_b128 v[110:113], v23 offset:2048
	s_waitcnt lgkmcnt(1)
	v_mfma_f32_16x16x32_f16 v[36:39], v[58:61], v[106:109], v[36:39]
	ds_read_b128 v[122:125], v22 offset:38912
	s_waitcnt lgkmcnt(1)
	v_mfma_f32_16x16x32_f16 v[66:69], v[58:61], v[110:113], v[66:69]
	s_waitcnt vmcnt(1)
	ds_write_b128 v19, v[154:157] offset:49152
	v_mfma_f32_16x16x32_f16 v[44:47], v[94:97], v[106:109], v[44:47]
	s_waitcnt vmcnt(0)
	ds_write_b128 v20, v[158:161] offset:49152
	v_mfma_f32_16x16x32_f16 v[78:81], v[94:97], v[110:113], v[78:81]
	v_mfma_f32_16x16x32_f16 v[82:85], v[118:121], v[106:109], v[82:85]
	v_mfma_f32_16x16x32_f16 v[86:89], v[118:121], v[110:113], v[86:89]
	s_waitcnt lgkmcnt(2)
	v_mfma_f32_16x16x32_f16 v[28:31], v[122:125], v[106:109], v[28:31]
	ds_read_b128 v[106:109], v23 offset:4096
	v_mfma_f32_16x16x32_f16 v[32:35], v[122:125], v[110:113], v[32:35]
	ds_read_b128 v[110:113], v23 offset:6144
	s_waitcnt lgkmcnt(1)
	v_mfma_f32_16x16x32_f16 v[98:101], v[58:61], v[106:109], v[98:101]
	s_waitcnt lgkmcnt(0)
	v_mfma_f32_16x16x32_f16 v[52:55], v[58:61], v[110:113], v[52:55]
	global_load_dwordx4 v[58:61], v[0:1], off offset:2560
	v_mfma_f32_16x16x32_f16 v[102:105], v[94:97], v[106:109], v[102:105]
	v_mfma_f32_16x16x32_f16 v[24:27], v[94:97], v[110:113], v[24:27]
	v_mfma_f32_16x16x32_f16 v[114:117], v[118:121], v[106:109], v[114:117]
	v_mfma_f32_16x16x32_f16 v[40:43], v[118:121], v[110:113], v[40:43]
	v_mfma_f32_16x16x32_f16 v[70:73], v[122:125], v[106:109], v[70:73]
	global_load_dwordx4 v[106:109], v[2:3], off offset:2560
	global_load_dwordx4 v[126:129], v[4:5], off offset:2560
	global_load_dwordx4 v[134:137], v[14:15], off offset:2560
	global_load_dwordx4 v[94:97], v[10:11], off offset:2560
	global_load_dwordx4 v[162:165], v[12:13], off offset:2560
	global_load_dwordx4 v[166:169], v[8:9], off offset:2560
	global_load_dwordx4 v[190:193], v[6:7], off offset:2560
	s_waitcnt lgkmcnt(0)
	s_barrier
; #define GL_LOAD(s_, kt_) if (VAR != 1) { a##s_##0 = GL_A(0, kt_); a##s_##1 = GL_A(1, kt_); a##s_##2 = GL_A(2, kt_); a##s_##3 = GL_A(3, kt_); b##s_##0 = GL_B(0, kt_); b##s_##1 = GL_B(1, kt_); b##s_##2 = GL_B(2, kt_); b##s_##3 = GL_B(3, kt_); }
; #define LDS_STORE(s_, buf_) if (VAR != 2) { LDS_ST1(sA, 0, buf_, a##s_##0) LDS_ST1(sA, 1, buf_, a##s_##1) LDS_ST1(sA, 2, buf_, a##s_##2) LDS_ST1(sA, 3, buf_, a##s_##3) LDS_ST1(sB, 0, buf_, b##s_##0) LDS_ST1(sB, 1, buf_, b##s_##1) LDS_ST1(sB, 2, buf_, b##s_##2) LDS_ST1(sB, 3, buf_, b##s_##3) }
;     ...
;   for (int kt = 0; kt < nk; kt += 2) {
;     if (kt + 2 < nk) { GL_LOAD(0, kt + 2) }
;     MMA_TILE(0)
;     LDS_STORE(1, 1)
;     if (VAR != 4) __syncthreads();
;     if (kt + 3 < nk) { GL_LOAD(1, kt + 3) }
;     MMA_TILE(1)
;     if (kt + 2 < nk) { LDS_STORE(0, 0) }
;     if (VAR != 4) __syncthreads();
	v_mfma_f32_16x16x32_f16 v[48:51], v[122:125], v[110:113], v[48:51]
	ds_read_b128 v[62:65], v16 offset:49152
	ds_read_b128 v[90:93], v21 offset:16384
	s_waitcnt lgkmcnt(0)
	v_mfma_f32_16x16x32_f16 v[36:39], v[62:65], v[90:93], v[36:39]
	ds_read_b128 v[74:77], v16 offset:51200
	ds_read_b128 v[110:113], v21 offset:18432
	s_waitcnt lgkmcnt(0)
	v_mfma_f32_16x16x32_f16 v[66:69], v[62:65], v[110:113], v[66:69]
	ds_read_b128 v[118:121], v16 offset:53248
	v_mfma_f32_16x16x32_f16 v[44:47], v[74:77], v[90:93], v[44:47]
	ds_read_b128 v[122:125], v16 offset:55296
	v_mfma_f32_16x16x32_f16 v[78:81], v[74:77], v[110:113], v[78:81]
	s_waitcnt vmcnt(7)
	ds_write_b128 v17, v[58:61]
	s_waitcnt lgkmcnt(2)
	v_mfma_f32_16x16x32_f16 v[82:85], v[118:121], v[90:93], v[82:85]
	s_waitcnt vmcnt(6)
	ds_write_b128 v18, v[106:109]
	v_mfma_f32_16x16x32_f16 v[86:89], v[118:121], v[110:113], v[86:89]
	s_waitcnt vmcnt(5)
	ds_write_b128 v19, v[126:129]
	s_waitcnt lgkmcnt(3)
	v_mfma_f32_16x16x32_f16 v[28:31], v[122:125], v[90:93], v[28:31]
	ds_read_b128 v[90:93], v21 offset:20480
	v_mfma_f32_16x16x32_f16 v[32:35], v[122:125], v[110:113], v[32:35]
	ds_read_b128 v[110:113], v21 offset:22528
	s_waitcnt lgkmcnt(1)
	v_mfma_f32_16x16x32_f16 v[98:101], v[62:65], v[90:93], v[98:101]
	s_waitcnt vmcnt(4)
	ds_write_b128 v20, v[134:137]
	s_waitcnt lgkmcnt(1)
	v_mfma_f32_16x16x32_f16 v[52:55], v[62:65], v[110:113], v[52:55]
	ds_read_b128 v[62:65], v22 offset:49152
	v_mfma_f32_16x16x32_f16 v[102:105], v[74:77], v[90:93], v[102:105]
	s_waitcnt vmcnt(3)
	ds_write_b128 v17, v[94:97] offset:32768
	v_mfma_f32_16x16x32_f16 v[24:27], v[74:77], v[110:113], v[24:27]
	ds_read_b128 v[74:77], v22 offset:51200
	v_mfma_f32_16x16x32_f16 v[114:117], v[118:121], v[90:93], v[114:117]
	s_waitcnt vmcnt(2)
	ds_write_b128 v18, v[162:165] offset:32768
	v_mfma_f32_16x16x32_f16 v[40:43], v[118:121], v[110:113], v[40:43]
	ds_read_b128 v[118:121], v22 offset:53248
	v_mfma_f32_16x16x32_f16 v[70:73], v[122:125], v[90:93], v[70:73]
	ds_read_b128 v[90:93], v23 offset:16384
	v_mfma_f32_16x16x32_f16 v[48:51], v[122:125], v[110:113], v[48:51]
	ds_read_b128 v[110:113], v23 offset:18432
	s_waitcnt lgkmcnt(1)
	v_mfma_f32_16x16x32_f16 v[36:39], v[62:65], v[90:93], v[36:39]
	ds_read_b128 v[122:125], v22 offset:55296
	s_waitcnt lgkmcnt(1)
	v_mfma_f32_16x16x32_f16 v[66:69], v[62:65], v[110:113], v[66:69]
	s_waitcnt vmcnt(1)
	ds_write_b128 v19, v[166:169] offset:32768
	v_mfma_f32_16x16x32_f16 v[44:47], v[74:77], v[90:93], v[44:47]
	s_waitcnt vmcnt(0)
	ds_write_b128 v20, v[190:193] offset:32768
	v_mfma_f32_16x16x32_f16 v[78:81], v[74:77], v[110:113], v[78:81]
	v_mfma_f32_16x16x32_f16 v[82:85], v[118:121], v[90:93], v[82:85]
	v_mfma_f32_16x16x32_f16 v[86:89], v[118:121], v[110:113], v[86:89]
	s_waitcnt lgkmcnt(2)
	v_mfma_f32_16x16x32_f16 v[28:31], v[122:125], v[90:93], v[28:31]
	ds_read_b128 v[90:93], v23 offset:20480
	v_mfma_f32_16x16x32_f16 v[32:35], v[122:125], v[110:113], v[32:35]
	ds_read_b128 v[110:113], v23 offset:22528
	s_waitcnt lgkmcnt(1)
	v_mfma_f32_16x16x32_f16 v[98:101], v[62:65], v[90:93], v[98:101]
	s_waitcnt lgkmcnt(0)
	v_mfma_f32_16x16x32_f16 v[52:55], v[62:65], v[110:113], v[52:55]
	global_load_dwordx4 v[62:65], v[0:1], off offset:2688
	v_mfma_f32_16x16x32_f16 v[102:105], v[74:77], v[90:93], v[102:105]
	v_mfma_f32_16x16x32_f16 v[24:27], v[74:77], v[110:113], v[24:27]
	v_mfma_f32_16x16x32_f16 v[114:117], v[118:121], v[90:93], v[114:117]
	v_mfma_f32_16x16x32_f16 v[40:43], v[118:121], v[110:113], v[40:43]
	v_mfma_f32_16x16x32_f16 v[70:73], v[122:125], v[90:93], v[70:73]
	global_load_dwordx4 v[90:93], v[2:3], off offset:2688
	global_load_dwordx4 v[130:133], v[4:5], off offset:2688
	global_load_dwordx4 v[138:141], v[14:15], off offset:2688
	global_load_dwordx4 v[74:77], v[10:11], off offset:2688
	global_load_dwordx4 v[142:145], v[12:13], off offset:2688
	global_load_dwordx4 v[154:157], v[8:9], off offset:2688
	global_load_dwordx4 v[158:161], v[6:7], off offset:2688
	s_waitcnt lgkmcnt(0)
	s_barrier
	v_mfma_f32_16x16x32_f16 v[48:51], v[122:125], v[110:113], v[48:51]
	ds_read_b128 v[58:61], v16 offset:32768
	ds_read_b128 v[106:109], v21
	s_waitcnt lgkmcnt(0)
	v_mfma_f32_16x16x32_f16 v[36:39], v[58:61], v[106:109], v[36:39]
	ds_read_b128 v[94:97], v16 offset:34816
	ds_read_b128 v[110:113], v21 offset:2048
	s_waitcnt lgkmcnt(0)
	v_mfma_f32_16x16x32_f16 v[66:69], v[58:61], v[110:113], v[66:69]
	ds_read_b128 v[118:121], v16 offset:36864
	v_mfma_f32_16x16x32_f16 v[44:47], v[94:97], v[106:109], v[44:47]
	ds_read_b128 v[122:125], v16 offset:38912
	v_mfma_f32_16x16x32_f16 v[78:81], v[94:97], v[110:113], v[78:81]
	s_waitcnt vmcnt(7)
	ds_write_b128 v17, v[62:65] offset:16384
	s_waitcnt lgkmcnt(2)
	v_mfma_f32_16x16x32_f16 v[82:85], v[118:121], v[106:109], v[82:85]
	s_waitcnt vmcnt(6)
	ds_write_b128 v18, v[90:93] offset:16384
	v_mfma_f32_16x16x32_f16 v[86:89], v[118:121], v[110:113], v[86:89]
	s_waitcnt vmcnt(5)
	ds_write_b128 v19, v[130:133] offset:16384
	s_waitcnt lgkmcnt(3)
	v_mfma_f32_16x16x32_f16 v[28:31], v[122:125], v[106:109], v[28:31]
	ds_read_b128 v[106:109], v21 offset:4096
	v_mfma_f32_16x16x32_f16 v[32:35], v[122:125], v[110:113], v[32:35]
	ds_read_b128 v[110:113], v21 offset:6144
	s_waitcnt lgkmcnt(1)
	v_mfma_f32_16x16x32_f16 v[98:101], v[58:61], v[106:109], v[98:101]
	s_waitcnt vmcnt(4)
	ds_write_b128 v20, v[138:141] offset:16384
	s_waitcnt lgkmcnt(1)
	v_mfma_f32_16x16x32_f16 v[52:55], v[58:61], v[110:113], v[52:55]
	ds_read_b128 v[58:61], v22 offset:32768
	v_mfma_f32_16x16x32_f16 v[102:105], v[94:97], v[106:109], v[102:105]
	s_waitcnt vmcnt(3)
; #define GL_LOAD(s_, kt_) if (VAR != 1) { a##s_##0 = GL_A(0, kt_); a##s_##1 = GL_A(1, kt_); a##s_##2 = GL_A(2, kt_); a##s_##3 = GL_A(3, kt_); b##s_##0 = GL_B(0, kt_); b##s_##1 = GL_B(1, kt_); b##s_##2 = GL_B(2, kt_); b##s_##3 = GL_B(3, kt_); }
; #define LDS_STORE(s_, buf_) if (VAR != 2) { LDS_ST1(sA, 0, buf_, a##s_##0) LDS_ST1(sA, 1, buf_, a##s_##1) LDS_ST1(sA, 2, buf_, a##s_##2) LDS_ST1(sA, 3, buf_, a##s_##3) LDS_ST1(sB, 0, buf_, b##s_##0) LDS_ST1(sB, 1, buf_, b##s_##1) LDS_ST1(sB, 2, buf_, b##s_##2) LDS_ST1(sB, 3, buf_, b##s_##3) }
;     ...
;   for (int kt = 0; kt < nk; kt += 2) {
;     if (kt + 2 < nk) { GL_LOAD(0, kt + 2) }
;     MMA_TILE(0)
;     LDS_STORE(1, 1)
;     if (VAR != 4) __syncthreads();
;     if (kt + 3 < nk) { GL_LOAD(1, kt + 3) }
;     MMA_TILE(1)
;     if (kt + 2 < nk) { LDS_STORE(0, 0) }
;     if (VAR != 4) __syncthreads();
	ds_write_b128 v17, v[74:77] offset:49152
	v_mfma_f32_16x16x32_f16 v[24:27], v[94:97], v[110:113], v[24:27]
	ds_read_b128 v[94:97], v22 offset:34816
	v_mfma_f32_16x16x32_f16 v[114:117], v[118:121], v[106:109], v[114:117]
	s_waitcnt vmcnt(2)
	ds_write_b128 v18, v[142:145] offset:49152
	v_mfma_f32_16x16x32_f16 v[40:43], v[118:121], v[110:113], v[40:43]
	ds_read_b128 v[118:121], v22 offset:36864
	v_mfma_f32_16x16x32_f16 v[70:73], v[122:125], v[106:109], v[70:73]
	ds_read_b128 v[106:109], v23
	v_mfma_f32_16x16x32_f16 v[48:51], v[122:125], v[110:113], v[48:51]
	ds_read_b128 v[110:113], v23 offset:2048
	s_waitcnt lgkmcnt(1)
	v_mfma_f32_16x16x32_f16 v[36:39], v[58:61], v[106:109], v[36:39]
	ds_read_b128 v[122:125], v22 offset:38912
	s_waitcnt lgkmcnt(1)
	v_mfma_f32_16x16x32_f16 v[66:69], v[58:61], v[110:113], v[66:69]
	s_waitcnt vmcnt(1)
	ds_write_b128 v19, v[154:157] offset:49152
	v_mfma_f32_16x16x32_f16 v[44:47], v[94:97], v[106:109], v[44:47]
	s_waitcnt vmcnt(0)
	ds_write_b128 v20, v[158:161] offset:49152
	v_mfma_f32_16x16x32_f16 v[78:81], v[94:97], v[110:113], v[78:81]
	v_mfma_f32_16x16x32_f16 v[82:85], v[118:121], v[106:109], v[82:85]
	v_mfma_f32_16x16x32_f16 v[86:89], v[118:121], v[110:113], v[86:89]
	s_waitcnt lgkmcnt(2)
	v_mfma_f32_16x16x32_f16 v[28:31], v[122:125], v[106:109], v[28:31]
	ds_read_b128 v[106:109], v23 offset:4096
	v_mfma_f32_16x16x32_f16 v[32:35], v[122:125], v[110:113], v[32:35]
	ds_read_b128 v[110:113], v23 offset:6144
	s_waitcnt lgkmcnt(1)
	v_mfma_f32_16x16x32_f16 v[98:101], v[58:61], v[106:109], v[98:101]
	s_waitcnt lgkmcnt(0)
	v_mfma_f32_16x16x32_f16 v[52:55], v[58:61], v[110:113], v[52:55]
	global_load_dwordx4 v[58:61], v[0:1], off offset:2816
	v_mfma_f32_16x16x32_f16 v[102:105], v[94:97], v[106:109], v[102:105]
	v_mfma_f32_16x16x32_f16 v[24:27], v[94:97], v[110:113], v[24:27]
	v_mfma_f32_16x16x32_f16 v[114:117], v[118:121], v[106:109], v[114:117]
	v_mfma_f32_16x16x32_f16 v[40:43], v[118:121], v[110:113], v[40:43]
	v_mfma_f32_16x16x32_f16 v[70:73], v[122:125], v[106:109], v[70:73]
	global_load_dwordx4 v[106:109], v[2:3], off offset:2816
	global_load_dwordx4 v[126:129], v[4:5], off offset:2816
	global_load_dwordx4 v[134:137], v[14:15], off offset:2816
	global_load_dwordx4 v[94:97], v[10:11], off offset:2816
	global_load_dwordx4 v[162:165], v[12:13], off offset:2816
	global_load_dwordx4 v[166:169], v[8:9], off offset:2816
	global_load_dwordx4 v[190:193], v[6:7], off offset:2816
	s_waitcnt lgkmcnt(0)
	s_barrier
	v_mfma_f32_16x16x32_f16 v[48:51], v[122:125], v[110:113], v[48:51]
	ds_read_b128 v[62:65], v16 offset:49152
	ds_read_b128 v[90:93], v21 offset:16384
	s_waitcnt lgkmcnt(0)
	v_mfma_f32_16x16x32_f16 v[36:39], v[62:65], v[90:93], v[36:39]
	ds_read_b128 v[74:77], v16 offset:51200
	ds_read_b128 v[110:113], v21 offset:18432
	s_waitcnt lgkmcnt(0)
	v_mfma_f32_16x16x32_f16 v[66:69], v[62:65], v[110:113], v[66:69]
	ds_read_b128 v[118:121], v16 offset:53248
	v_mfma_f32_16x16x32_f16 v[44:47], v[74:77], v[90:93], v[44:47]
	ds_read_b128 v[122:125], v16 offset:55296
	v_mfma_f32_16x16x32_f16 v[78:81], v[74:77], v[110:113], v[78:81]
	s_waitcnt vmcnt(7)
	ds_write_b128 v17, v[58:61]
	s_waitcnt lgkmcnt(2)
	v_mfma_f32_16x16x32_f16 v[82:85], v[118:121], v[90:93], v[82:85]
	s_waitcnt vmcnt(6)
	ds_write_b128 v18, v[106:109]
	v_mfma_f32_16x16x32_f16 v[86:89], v[118:121], v[110:113], v[86:89]
	s_waitcnt vmcnt(5)
	ds_write_b128 v19, v[126:129]
	s_waitcnt lgkmcnt(3)
	v_mfma_f32_16x16x32_f16 v[28:31], v[122:125], v[90:93], v[28:31]
	ds_read_b128 v[90:93], v21 offset:20480
	v_mfma_f32_16x16x32_f16 v[32:35], v[122:125], v[110:113], v[32:35]
	ds_read_b128 v[110:113], v21 offset:22528
	s_waitcnt lgkmcnt(1)
	v_mfma_f32_16x16x32_f16 v[98:101], v[62:65], v[90:93], v[98:101]
	s_waitcnt vmcnt(4)
	ds_write_b128 v20, v[134:137]
	s_waitcnt lgkmcnt(1)
	v_mfma_f32_16x16x32_f16 v[52:55], v[62:65], v[110:113], v[52:55]
	ds_read_b128 v[62:65], v22 offset:49152
	v_mfma_f32_16x16x32_f16 v[102:105], v[74:77], v[90:93], v[102:105]
	s_waitcnt vmcnt(3)
	ds_write_b128 v17, v[94:97] offset:32768
	v_mfma_f32_16x16x32_f16 v[24:27], v[74:77], v[110:113], v[24:27]
	ds_read_b128 v[74:77], v22 offset:51200
	v_mfma_f32_16x16x32_f16 v[114:117], v[118:121], v[90:93], v[114:117]
	s_waitcnt vmcnt(2)
	ds_write_b128 v18, v[162:165] offset:32768
	v_mfma_f32_16x16x32_f16 v[40:43], v[118:121], v[110:113], v[40:43]
	ds_read_b128 v[118:121], v22 offset:53248
	v_mfma_f32_16x16x32_f16 v[70:73], v[122:125], v[90:93], v[70:73]
	ds_read_b128 v[90:93], v23 offset:16384
	v_mfma_f32_16x16x32_f16 v[48:51], v[122:125], v[110:113], v[48:51]
	ds_read_b128 v[110:113], v23 offset:18432
	s_waitcnt lgkmcnt(1)
	v_mfma_f32_16x16x32_f16 v[36:39], v[62:65], v[90:93], v[36:39]
	ds_read_b128 v[122:125], v22 offset:55296
	s_waitcnt lgkmcnt(1)
	v_mfma_f32_16x16x32_f16 v[66:69], v[62:65], v[110:113], v[66:69]
	s_waitcnt vmcnt(1)
	ds_write_b128 v19, v[166:169] offset:32768
	v_mfma_f32_16x16x32_f16 v[44:47], v[74:77], v[90:93], v[44:47]
	s_waitcnt vmcnt(0)
	ds_write_b128 v20, v[190:193] offset:32768
	v_mfma_f32_16x16x32_f16 v[78:81], v[74:77], v[110:113], v[78:81]
	v_mfma_f32_16x16x32_f16 v[82:85], v[118:121], v[90:93], v[82:85]
	v_mfma_f32_16x16x32_f16 v[86:89], v[118:121], v[110:113], v[86:89]
	s_waitcnt lgkmcnt(2)
	v_mfma_f32_16x16x32_f16 v[28:31], v[122:125], v[90:93], v[28:31]
	ds_read_b128 v[90:93], v23 offset:20480
	v_mfma_f32_16x16x32_f16 v[32:35], v[122:125], v[110:113], v[32:35]
	ds_read_b128 v[110:113], v23 offset:22528
	s_waitcnt lgkmcnt(1)
	v_mfma_f32_16x16x32_f16 v[98:101], v[62:65], v[90:93], v[98:101]
	s_waitcnt lgkmcnt(0)
	v_mfma_f32_16x16x32_f16 v[52:55], v[62:65], v[110:113], v[52:55]
	global_load_dwordx4 v[62:65], v[0:1], off offset:2944
	v_mfma_f32_16x16x32_f16 v[102:105], v[74:77], v[90:93], v[102:105]
	v_mfma_f32_16x16x32_f16 v[24:27], v[74:77], v[110:113], v[24:27]
	v_mfma_f32_16x16x32_f16 v[114:117], v[118:121], v[90:93], v[114:117]
	v_mfma_f32_16x16x32_f16 v[40:43], v[118:121], v[110:113], v[40:43]
	v_mfma_f32_16x16x32_f16 v[70:73], v[122:125], v[90:93], v[70:73]
	global_load_dwordx4 v[90:93], v[2:3], off offset:2944
	global_load_dwordx4 v[130:133], v[4:5], off offset:2944
	global_load_dwordx4 v[138:141], v[14:15], off offset:2944
	global_load_dwordx4 v[74:77], v[10:11], off offset:2944
	global_load_dwordx4 v[142:145], v[12:13], off offset:2944
	global_load_dwordx4 v[154:157], v[8:9], off offset:2944
	global_load_dwordx4 v[158:161], v[6:7], off offset:2944
	s_waitcnt lgkmcnt(0)
	s_barrier
; #define GL_LOAD(s_, kt_) if (VAR != 1) { a##s_##0 = GL_A(0, kt_); a##s_##1 = GL_A(1, kt_); a##s_##2 = GL_A(2, kt_); a##s_##3 = GL_A(3, kt_); b##s_##0 = GL_B(0, kt_); b##s_##1 = GL_B(1, kt_); b##s_##2 = GL_B(2, kt_); b##s_##3 = GL_B(3, kt_); }
; #define LDS_STORE(s_, buf_) if (VAR != 2) { LDS_ST1(sA, 0, buf_, a##s_##0) LDS_ST1(sA, 1, buf_, a##s_##1) LDS_ST1(sA, 2, buf_, a##s_##2) LDS_ST1(sA, 3, buf_, a##s_##3) LDS_ST1(sB, 0, buf_, b##s_##0) LDS_ST1(sB, 1, buf_, b##s_##1) LDS_ST1(sB, 2, buf_, b##s_##2) LDS_ST1(sB, 3, buf_, b##s_##3) }
;     ...
;   for (int kt = 0; kt < nk; kt += 2) {
;     if (kt + 2 < nk) { GL_LOAD(0, kt + 2) }
;     MMA_TILE(0)
;     LDS_STORE(1, 1)
;     if (VAR != 4) __syncthreads();
;     if (kt + 3 < nk) { GL_LOAD(1, kt + 3) }
;     MMA_TILE(1)
;     if (kt + 2 < nk) { LDS_STORE(0, 0) }
;     if (VAR != 4) __syncthreads();
	v_mfma_f32_16x16x32_f16 v[48:51], v[122:125], v[110:113], v[48:51]
	ds_read_b128 v[58:61], v16 offset:32768
	ds_read_b128 v[106:109], v21
	s_waitcnt lgkmcnt(0)
	v_mfma_f32_16x16x32_f16 v[36:39], v[58:61], v[106:109], v[36:39]
	ds_read_b128 v[94:97], v16 offset:34816
	ds_read_b128 v[110:113], v21 offset:2048
	s_waitcnt lgkmcnt(0)
	v_mfma_f32_16x16x32_f16 v[66:69], v[58:61], v[110:113], v[66:69]
	ds_read_b128 v[118:121], v16 offset:36864
	v_mfma_f32_16x16x32_f16 v[44:47], v[94:97], v[106:109], v[44:47]
	ds_read_b128 v[122:125], v16 offset:38912
	v_mfma_f32_16x16x32_f16 v[78:81], v[94:97], v[110:113], v[78:81]
	s_waitcnt vmcnt(7)
	ds_write_b128 v17, v[62:65] offset:16384
	s_waitcnt lgkmcnt(2)
	v_mfma_f32_16x16x32_f16 v[82:85], v[118:121], v[106:109], v[82:85]
	s_waitcnt vmcnt(6)
	ds_write_b128 v18, v[90:93] offset:16384
	v_mfma_f32_16x16x32_f16 v[86:89], v[118:121], v[110:113], v[86:89]
	s_waitcnt vmcnt(5)
	ds_write_b128 v19, v[130:133] offset:16384
	s_waitcnt lgkmcnt(3)
	v_mfma_f32_16x16x32_f16 v[28:31], v[122:125], v[106:109], v[28:31]
	ds_read_b128 v[106:109], v21 offset:4096
	v_mfma_f32_16x16x32_f16 v[32:35], v[122:125], v[110:113], v[32:35]
	ds_read_b128 v[110:113], v21 offset:6144
	s_waitcnt lgkmcnt(1)
	v_mfma_f32_16x16x32_f16 v[98:101], v[58:61], v[106:109], v[98:101]
	s_waitcnt vmcnt(4)
	ds_write_b128 v20, v[138:141] offset:16384
	s_waitcnt lgkmcnt(1)
	v_mfma_f32_16x16x32_f16 v[52:55], v[58:61], v[110:113], v[52:55]
	ds_read_b128 v[58:61], v22 offset:32768
	v_mfma_f32_16x16x32_f16 v[102:105], v[94:97], v[106:109], v[102:105]
	s_waitcnt vmcnt(3)
	ds_write_b128 v17, v[74:77] offset:49152
	v_mfma_f32_16x16x32_f16 v[24:27], v[94:97], v[110:113], v[24:27]
	ds_read_b128 v[94:97], v22 offset:34816
	v_mfma_f32_16x16x32_f16 v[114:117], v[118:121], v[106:109], v[114:117]
	s_waitcnt vmcnt(2)
	ds_write_b128 v18, v[142:145] offset:49152
	v_mfma_f32_16x16x32_f16 v[40:43], v[118:121], v[110:113], v[40:43]
	ds_read_b128 v[118:121], v22 offset:36864
	v_mfma_f32_16x16x32_f16 v[70:73], v[122:125], v[106:109], v[70:73]
	ds_read_b128 v[106:109], v23
	v_mfma_f32_16x16x32_f16 v[48:51], v[122:125], v[110:113], v[48:51]
	ds_read_b128 v[110:113], v23 offset:2048
	s_waitcnt lgkmcnt(1)
	v_mfma_f32_16x16x32_f16 v[36:39], v[58:61], v[106:109], v[36:39]
	ds_read_b128 v[122:125], v22 offset:38912
	s_waitcnt lgkmcnt(1)
	v_mfma_f32_16x16x32_f16 v[66:69], v[58:61], v[110:113], v[66:69]
	s_waitcnt vmcnt(1)
	ds_write_b128 v19, v[154:157] offset:49152
	v_mfma_f32_16x16x32_f16 v[44:47], v[94:97], v[106:109], v[44:47]
	s_waitcnt vmcnt(0)
	ds_write_b128 v20, v[158:161] offset:49152
	v_mfma_f32_16x16x32_f16 v[78:81], v[94:97], v[110:113], v[78:81]
	v_mfma_f32_16x16x32_f16 v[82:85], v[118:121], v[106:109], v[82:85]
	v_mfma_f32_16x16x32_f16 v[86:89], v[118:121], v[110:113], v[86:89]
	s_waitcnt lgkmcnt(2)
	v_mfma_f32_16x16x32_f16 v[28:31], v[122:125], v[106:109], v[28:31]
	ds_read_b128 v[106:109], v23 offset:4096
	v_mfma_f32_16x16x32_f16 v[32:35], v[122:125], v[110:113], v[32:35]
	ds_read_b128 v[110:113], v23 offset:6144
	s_waitcnt lgkmcnt(1)
	v_mfma_f32_16x16x32_f16 v[98:101], v[58:61], v[106:109], v[98:101]
	s_waitcnt lgkmcnt(0)
	v_mfma_f32_16x16x32_f16 v[52:55], v[58:61], v[110:113], v[52:55]
	global_load_dwordx4 v[58:61], v[0:1], off offset:3072
	v_mfma_f32_16x16x32_f16 v[102:105], v[94:97], v[106:109], v[102:105]
	v_mfma_f32_16x16x32_f16 v[24:27], v[94:97], v[110:113], v[24:27]
	v_mfma_f32_16x16x32_f16 v[114:117], v[118:121], v[106:109], v[114:117]
	v_mfma_f32_16x16x32_f16 v[40:43], v[118:121], v[110:113], v[40:43]
	v_mfma_f32_16x16x32_f16 v[70:73], v[122:125], v[106:109], v[70:73]
	global_load_dwordx4 v[106:109], v[2:3], off offset:3072
	global_load_dwordx4 v[126:129], v[4:5], off offset:3072
	global_load_dwordx4 v[134:137], v[14:15], off offset:3072
	global_load_dwordx4 v[94:97], v[10:11], off offset:3072
	global_load_dwordx4 v[162:165], v[12:13], off offset:3072
	global_load_dwordx4 v[166:169], v[8:9], off offset:3072
	global_load_dwordx4 v[190:193], v[6:7], off offset:3072
	s_waitcnt lgkmcnt(0)
	s_barrier
	v_mfma_f32_16x16x32_f16 v[48:51], v[122:125], v[110:113], v[48:51]
	ds_read_b128 v[62:65], v16 offset:49152
	ds_read_b128 v[90:93], v21 offset:16384
	s_waitcnt lgkmcnt(0)
	v_mfma_f32_16x16x32_f16 v[36:39], v[62:65], v[90:93], v[36:39]
	ds_read_b128 v[74:77], v16 offset:51200
	ds_read_b128 v[110:113], v21 offset:18432
	s_waitcnt lgkmcnt(0)
	v_mfma_f32_16x16x32_f16 v[66:69], v[62:65], v[110:113], v[66:69]
	ds_read_b128 v[118:121], v16 offset:53248
	v_mfma_f32_16x16x32_f16 v[44:47], v[74:77], v[90:93], v[44:47]
	ds_read_b128 v[122:125], v16 offset:55296
	v_mfma_f32_16x16x32_f16 v[78:81], v[74:77], v[110:113], v[78:81]
	s_waitcnt vmcnt(7)
	ds_write_b128 v17, v[58:61]
	s_waitcnt lgkmcnt(2)
	v_mfma_f32_16x16x32_f16 v[82:85], v[118:121], v[90:93], v[82:85]
	s_waitcnt vmcnt(6)
	ds_write_b128 v18, v[106:109]
	v_mfma_f32_16x16x32_f16 v[86:89], v[118:121], v[110:113], v[86:89]
	s_waitcnt vmcnt(5)
	ds_write_b128 v19, v[126:129]
	s_waitcnt lgkmcnt(3)
	v_mfma_f32_16x16x32_f16 v[28:31], v[122:125], v[90:93], v[28:31]
	ds_read_b128 v[90:93], v21 offset:20480
	v_mfma_f32_16x16x32_f16 v[32:35], v[122:125], v[110:113], v[32:35]
	ds_read_b128 v[110:113], v21 offset:22528
	s_waitcnt lgkmcnt(1)
	v_mfma_f32_16x16x32_f16 v[98:101], v[62:65], v[90:93], v[98:101]
	s_waitcnt vmcnt(4)
	ds_write_b128 v20, v[134:137]
	s_waitcnt lgkmcnt(1)
	v_mfma_f32_16x16x32_f16 v[52:55], v[62:65], v[110:113], v[52:55]
	ds_read_b128 v[62:65], v22 offset:49152
	v_mfma_f32_16x16x32_f16 v[102:105], v[74:77], v[90:93], v[102:105]
	s_waitcnt vmcnt(3)
; #define GL_LOAD(s_, kt_) if (VAR != 1) { a##s_##0 = GL_A(0, kt_); a##s_##1 = GL_A(1, kt_); a##s_##2 = GL_A(2, kt_); a##s_##3 = GL_A(3, kt_); b##s_##0 = GL_B(0, kt_); b##s_##1 = GL_B(1, kt_); b##s_##2 = GL_B(2, kt_); b##s_##3 = GL_B(3, kt_); }
; #define LDS_STORE(s_, buf_) if (VAR != 2) { LDS_ST1(sA, 0, buf_, a##s_##0) LDS_ST1(sA, 1, buf_, a##s_##1) LDS_ST1(sA, 2, buf_, a##s_##2) LDS_ST1(sA, 3, buf_, a##s_##3) LDS_ST1(sB, 0, buf_, b##s_##0) LDS_ST1(sB, 1, buf_, b##s_##1) LDS_ST1(sB, 2, buf_, b##s_##2) LDS_ST1(sB, 3, buf_, b##s_##3) }
;     ...
;   for (int kt = 0; kt < nk; kt += 2) {
;     if (kt + 2 < nk) { GL_LOAD(0, kt + 2) }
;     MMA_TILE(0)
;     LDS_STORE(1, 1)
;     if (VAR != 4) __syncthreads();
;     if (kt + 3 < nk) { GL_LOAD(1, kt + 3) }
;     MMA_TILE(1)
;     if (kt + 2 < nk) { LDS_STORE(0, 0) }
;     if (VAR != 4) __syncthreads();
	ds_write_b128 v17, v[94:97] offset:32768
	v_mfma_f32_16x16x32_f16 v[24:27], v[74:77], v[110:113], v[24:27]
	ds_read_b128 v[74:77], v22 offset:51200
	v_mfma_f32_16x16x32_f16 v[114:117], v[118:121], v[90:93], v[114:117]
	s_waitcnt vmcnt(2)
	ds_write_b128 v18, v[162:165] offset:32768
	v_mfma_f32_16x16x32_f16 v[40:43], v[118:121], v[110:113], v[40:43]
	ds_read_b128 v[118:121], v22 offset:53248
	v_mfma_f32_16x16x32_f16 v[70:73], v[122:125], v[90:93], v[70:73]
	ds_read_b128 v[90:93], v23 offset:16384
	v_mfma_f32_16x16x32_f16 v[48:51], v[122:125], v[110:113], v[48:51]
	ds_read_b128 v[110:113], v23 offset:18432
	s_waitcnt lgkmcnt(1)
	v_mfma_f32_16x16x32_f16 v[36:39], v[62:65], v[90:93], v[36:39]
	ds_read_b128 v[122:125], v22 offset:55296
	s_waitcnt lgkmcnt(1)
	v_mfma_f32_16x16x32_f16 v[66:69], v[62:65], v[110:113], v[66:69]
	s_waitcnt vmcnt(1)
	ds_write_b128 v19, v[166:169] offset:32768
	v_mfma_f32_16x16x32_f16 v[44:47], v[74:77], v[90:93], v[44:47]
	s_waitcnt vmcnt(0)
	ds_write_b128 v20, v[190:193] offset:32768
	v_mfma_f32_16x16x32_f16 v[78:81], v[74:77], v[110:113], v[78:81]
	v_mfma_f32_16x16x32_f16 v[82:85], v[118:121], v[90:93], v[82:85]
	v_mfma_f32_16x16x32_f16 v[86:89], v[118:121], v[110:113], v[86:89]
	s_waitcnt lgkmcnt(2)
	v_mfma_f32_16x16x32_f16 v[28:31], v[122:125], v[90:93], v[28:31]
	ds_read_b128 v[90:93], v23 offset:20480
	v_mfma_f32_16x16x32_f16 v[32:35], v[122:125], v[110:113], v[32:35]
	ds_read_b128 v[110:113], v23 offset:22528
	s_waitcnt lgkmcnt(1)
	v_mfma_f32_16x16x32_f16 v[98:101], v[62:65], v[90:93], v[98:101]
	s_waitcnt lgkmcnt(0)
	v_mfma_f32_16x16x32_f16 v[52:55], v[62:65], v[110:113], v[52:55]
	global_load_dwordx4 v[62:65], v[0:1], off offset:3200
	v_mfma_f32_16x16x32_f16 v[102:105], v[74:77], v[90:93], v[102:105]
	v_mfma_f32_16x16x32_f16 v[24:27], v[74:77], v[110:113], v[24:27]
	v_mfma_f32_16x16x32_f16 v[114:117], v[118:121], v[90:93], v[114:117]
	v_mfma_f32_16x16x32_f16 v[40:43], v[118:121], v[110:113], v[40:43]
	v_mfma_f32_16x16x32_f16 v[70:73], v[122:125], v[90:93], v[70:73]
	global_load_dwordx4 v[90:93], v[2:3], off offset:3200
	global_load_dwordx4 v[130:133], v[4:5], off offset:3200
	global_load_dwordx4 v[138:141], v[14:15], off offset:3200
	global_load_dwordx4 v[74:77], v[10:11], off offset:3200
	global_load_dwordx4 v[142:145], v[12:13], off offset:3200
	global_load_dwordx4 v[154:157], v[8:9], off offset:3200
	global_load_dwordx4 v[158:161], v[6:7], off offset:3200
	s_waitcnt lgkmcnt(0)
	s_barrier
	v_mfma_f32_16x16x32_f16 v[48:51], v[122:125], v[110:113], v[48:51]
	ds_read_b128 v[58:61], v16 offset:32768
	ds_read_b128 v[106:109], v21
	s_waitcnt lgkmcnt(0)
	v_mfma_f32_16x16x32_f16 v[36:39], v[58:61], v[106:109], v[36:39]
	ds_read_b128 v[94:97], v16 offset:34816
	ds_read_b128 v[110:113], v21 offset:2048
	s_waitcnt lgkmcnt(0)
	v_mfma_f32_16x16x32_f16 v[66:69], v[58:61], v[110:113], v[66:69]
	ds_read_b128 v[118:121], v16 offset:36864
	v_mfma_f32_16x16x32_f16 v[44:47], v[94:97], v[106:109], v[44:47]
	ds_read_b128 v[122:125], v16 offset:38912
	v_mfma_f32_16x16x32_f16 v[78:81], v[94:97], v[110:113], v[78:81]
	s_waitcnt vmcnt(7)
	ds_write_b128 v17, v[62:65] offset:16384
	s_waitcnt lgkmcnt(2)
	v_mfma_f32_16x16x32_f16 v[82:85], v[118:121], v[106:109], v[82:85]
	s_waitcnt vmcnt(6)
	ds_write_b128 v18, v[90:93] offset:16384
	v_mfma_f32_16x16x32_f16 v[86:89], v[118:121], v[110:113], v[86:89]
	s_waitcnt vmcnt(5)
	ds_write_b128 v19, v[130:133] offset:16384
	s_waitcnt lgkmcnt(3)
	v_mfma_f32_16x16x32_f16 v[28:31], v[122:125], v[106:109], v[28:31]
	ds_read_b128 v[106:109], v21 offset:4096
	v_mfma_f32_16x16x32_f16 v[32:35], v[122:125], v[110:113], v[32:35]
	ds_read_b128 v[110:113], v21 offset:6144
	s_waitcnt lgkmcnt(1)
	v_mfma_f32_16x16x32_f16 v[98:101], v[58:61], v[106:109], v[98:101]
	s_waitcnt vmcnt(4)
	ds_write_b128 v20, v[138:141] offset:16384
	s_waitcnt lgkmcnt(1)
	v_mfma_f32_16x16x32_f16 v[52:55], v[58:61], v[110:113], v[52:55]
	ds_read_b128 v[58:61], v22 offset:32768
	v_mfma_f32_16x16x32_f16 v[102:105], v[94:97], v[106:109], v[102:105]
	s_waitcnt vmcnt(3)
	ds_write_b128 v17, v[74:77] offset:49152
	v_mfma_f32_16x16x32_f16 v[24:27], v[94:97], v[110:113], v[24:27]
	ds_read_b128 v[94:97], v22 offset:34816
	v_mfma_f32_16x16x32_f16 v[114:117], v[118:121], v[106:109], v[114:117]
	s_waitcnt vmcnt(2)
	ds_write_b128 v18, v[142:145] offset:49152
	v_mfma_f32_16x16x32_f16 v[40:43], v[118:121], v[110:113], v[40:43]
	ds_read_b128 v[118:121], v22 offset:36864
	v_mfma_f32_16x16x32_f16 v[70:73], v[122:125], v[106:109], v[70:73]
	ds_read_b128 v[106:109], v23
	v_mfma_f32_16x16x32_f16 v[48:51], v[122:125], v[110:113], v[48:51]
	ds_read_b128 v[110:113], v23 offset:2048
	s_waitcnt lgkmcnt(1)
	v_mfma_f32_16x16x32_f16 v[36:39], v[58:61], v[106:109], v[36:39]
	ds_read_b128 v[122:125], v22 offset:38912
	s_waitcnt lgkmcnt(1)
	v_mfma_f32_16x16x32_f16 v[66:69], v[58:61], v[110:113], v[66:69]
	s_waitcnt vmcnt(1)
	ds_write_b128 v19, v[154:157] offset:49152
	v_mfma_f32_16x16x32_f16 v[44:47], v[94:97], v[106:109], v[44:47]
	s_waitcnt vmcnt(0)
	ds_write_b128 v20, v[158:161] offset:49152
	v_mfma_f32_16x16x32_f16 v[78:81], v[94:97], v[110:113], v[78:81]
	v_mfma_f32_16x16x32_f16 v[82:85], v[118:121], v[106:109], v[82:85]
	v_mfma_f32_16x16x32_f16 v[86:89], v[118:121], v[110:113], v[86:89]
	s_waitcnt lgkmcnt(2)
	v_mfma_f32_16x16x32_f16 v[28:31], v[122:125], v[106:109], v[28:31]
	ds_read_b128 v[106:109], v23 offset:4096
	v_mfma_f32_16x16x32_f16 v[32:35], v[122:125], v[110:113], v[32:35]
	ds_read_b128 v[110:113], v23 offset:6144
	s_waitcnt lgkmcnt(1)
	v_mfma_f32_16x16x32_f16 v[98:101], v[58:61], v[106:109], v[98:101]
	s_waitcnt lgkmcnt(0)
	v_mfma_f32_16x16x32_f16 v[52:55], v[58:61], v[110:113], v[52:55]
	global_load_dwordx4 v[58:61], v[0:1], off offset:3328
	v_mfma_f32_16x16x32_f16 v[102:105], v[94:97], v[106:109], v[102:105]
	v_mfma_f32_16x16x32_f16 v[24:27], v[94:97], v[110:113], v[24:27]
	v_mfma_f32_16x16x32_f16 v[114:117], v[118:121], v[106:109], v[114:117]
	v_mfma_f32_16x16x32_f16 v[40:43], v[118:121], v[110:113], v[40:43]
	v_mfma_f32_16x16x32_f16 v[70:73], v[122:125], v[106:109], v[70:73]
	global_load_dwordx4 v[106:109], v[2:3], off offset:3328
	global_load_dwordx4 v[126:129], v[4:5], off offset:3328
	global_load_dwordx4 v[134:137], v[14:15], off offset:3328
	global_load_dwordx4 v[94:97], v[10:11], off offset:3328
	global_load_dwordx4 v[162:165], v[12:13], off offset:3328
	global_load_dwordx4 v[166:169], v[8:9], off offset:3328
	global_load_dwordx4 v[190:193], v[6:7], off offset:3328
	s_waitcnt lgkmcnt(0)
	s_barrier
; #define GL_LOAD(s_, kt_) if (VAR != 1) { a##s_##0 = GL_A(0, kt_); a##s_##1 = GL_A(1, kt_); a##s_##2 = GL_A(2, kt_); a##s_##3 = GL_A(3, kt_); b##s_##0 = GL_B(0, kt_); b##s_##1 = GL_B(1, kt_); b##s_##2 = GL_B(2, kt_); b##s_##3 = GL_B(3, kt_); }
; #define LDS_STORE(s_, buf_) if (VAR != 2) { LDS_ST1(sA, 0, buf_, a##s_##0) LDS_ST1(sA, 1, buf_, a##s_##1) LDS_ST1(sA, 2, buf_, a##s_##2) LDS_ST1(sA, 3, buf_, a##s_##3) LDS_ST1(sB, 0, buf_, b##s_##0) LDS_ST1(sB, 1, buf_, b##s_##1) LDS_ST1(sB, 2, buf_, b##s_##2) LDS_ST1(sB, 3, buf_, b##s_##3) }
;     ...
;   for (int kt = 0; kt < nk; kt += 2) {
;     if (kt + 2 < nk) { GL_LOAD(0, kt + 2) }
;     MMA_TILE(0)
;     LDS_STORE(1, 1)
;     if (VAR != 4) __syncthreads();
;     if (kt + 3 < nk) { GL_LOAD(1, kt + 3) }
;     MMA_TILE(1)
;     if (kt + 2 < nk) { LDS_STORE(0, 0) }
;     if (VAR != 4) __syncthreads();
	v_mfma_f32_16x16x32_f16 v[48:51], v[122:125], v[110:113], v[48:51]
	ds_read_b128 v[62:65], v16 offset:49152
	ds_read_b128 v[90:93], v21 offset:16384
	s_waitcnt lgkmcnt(0)
	v_mfma_f32_16x16x32_f16 v[36:39], v[62:65], v[90:93], v[36:39]
	ds_read_b128 v[74:77], v16 offset:51200
	ds_read_b128 v[110:113], v21 offset:18432
	s_waitcnt lgkmcnt(0)
	v_mfma_f32_16x16x32_f16 v[66:69], v[62:65], v[110:113], v[66:69]
	ds_read_b128 v[118:121], v16 offset:53248
	v_mfma_f32_16x16x32_f16 v[44:47], v[74:77], v[90:93], v[44:47]
	ds_read_b128 v[122:125], v16 offset:55296
	v_mfma_f32_16x16x32_f16 v[78:81], v[74:77], v[110:113], v[78:81]
	s_waitcnt vmcnt(7)
	ds_write_b128 v17, v[58:61]
	s_waitcnt lgkmcnt(2)
	v_mfma_f32_16x16x32_f16 v[82:85], v[118:121], v[90:93], v[82:85]
	s_waitcnt vmcnt(6)
	ds_write_b128 v18, v[106:109]
	v_mfma_f32_16x16x32_f16 v[86:89], v[118:121], v[110:113], v[86:89]
	s_waitcnt vmcnt(5)
	ds_write_b128 v19, v[126:129]
	s_waitcnt lgkmcnt(3)
	v_mfma_f32_16x16x32_f16 v[28:31], v[122:125], v[90:93], v[28:31]
	ds_read_b128 v[90:93], v21 offset:20480
	v_mfma_f32_16x16x32_f16 v[32:35], v[122:125], v[110:113], v[32:35]
	ds_read_b128 v[110:113], v21 offset:22528
	s_waitcnt lgkmcnt(1)
	v_mfma_f32_16x16x32_f16 v[98:101], v[62:65], v[90:93], v[98:101]
	s_waitcnt vmcnt(4)
	ds_write_b128 v20, v[134:137]
	s_waitcnt lgkmcnt(1)
	v_mfma_f32_16x16x32_f16 v[52:55], v[62:65], v[110:113], v[52:55]
	ds_read_b128 v[62:65], v22 offset:49152
	v_mfma_f32_16x16x32_f16 v[102:105], v[74:77], v[90:93], v[102:105]
	s_waitcnt vmcnt(3)
	ds_write_b128 v17, v[94:97] offset:32768
	v_mfma_f32_16x16x32_f16 v[24:27], v[74:77], v[110:113], v[24:27]
	ds_read_b128 v[74:77], v22 offset:51200
	v_mfma_f32_16x16x32_f16 v[114:117], v[118:121], v[90:93], v[114:117]
	s_waitcnt vmcnt(2)
	ds_write_b128 v18, v[162:165] offset:32768
	v_mfma_f32_16x16x32_f16 v[40:43], v[118:121], v[110:113], v[40:43]
	ds_read_b128 v[118:121], v22 offset:53248
	v_mfma_f32_16x16x32_f16 v[70:73], v[122:125], v[90:93], v[70:73]
	ds_read_b128 v[90:93], v23 offset:16384
	v_mfma_f32_16x16x32_f16 v[48:51], v[122:125], v[110:113], v[48:51]
	ds_read_b128 v[110:113], v23 offset:18432
	s_waitcnt lgkmcnt(1)
	v_mfma_f32_16x16x32_f16 v[36:39], v[62:65], v[90:93], v[36:39]
	ds_read_b128 v[122:125], v22 offset:55296
	s_waitcnt lgkmcnt(1)
	v_mfma_f32_16x16x32_f16 v[66:69], v[62:65], v[110:113], v[66:69]
	s_waitcnt vmcnt(1)
	ds_write_b128 v19, v[166:169] offset:32768
	v_mfma_f32_16x16x32_f16 v[44:47], v[74:77], v[90:93], v[44:47]
	s_waitcnt vmcnt(0)
	ds_write_b128 v20, v[190:193] offset:32768
	v_mfma_f32_16x16x32_f16 v[78:81], v[74:77], v[110:113], v[78:81]
	v_mfma_f32_16x16x32_f16 v[82:85], v[118:121], v[90:93], v[82:85]
	v_mfma_f32_16x16x32_f16 v[86:89], v[118:121], v[110:113], v[86:89]
	s_waitcnt lgkmcnt(2)
	v_mfma_f32_16x16x32_f16 v[28:31], v[122:125], v[90:93], v[28:31]
	ds_read_b128 v[90:93], v23 offset:20480
	v_mfma_f32_16x16x32_f16 v[32:35], v[122:125], v[110:113], v[32:35]
	ds_read_b128 v[110:113], v23 offset:22528
	s_waitcnt lgkmcnt(1)
	v_mfma_f32_16x16x32_f16 v[98:101], v[62:65], v[90:93], v[98:101]
	s_waitcnt lgkmcnt(0)
	v_mfma_f32_16x16x32_f16 v[52:55], v[62:65], v[110:113], v[52:55]
	global_load_dwordx4 v[62:65], v[0:1], off offset:3456
	v_mfma_f32_16x16x32_f16 v[102:105], v[74:77], v[90:93], v[102:105]
	v_mfma_f32_16x16x32_f16 v[24:27], v[74:77], v[110:113], v[24:27]
	v_mfma_f32_16x16x32_f16 v[114:117], v[118:121], v[90:93], v[114:117]
	v_mfma_f32_16x16x32_f16 v[40:43], v[118:121], v[110:113], v[40:43]
	v_mfma_f32_16x16x32_f16 v[70:73], v[122:125], v[90:93], v[70:73]
	global_load_dwordx4 v[90:93], v[2:3], off offset:3456
	global_load_dwordx4 v[130:133], v[4:5], off offset:3456
	global_load_dwordx4 v[138:141], v[14:15], off offset:3456
	global_load_dwordx4 v[74:77], v[10:11], off offset:3456
	global_load_dwordx4 v[142:145], v[12:13], off offset:3456
	global_load_dwordx4 v[154:157], v[8:9], off offset:3456
	global_load_dwordx4 v[158:161], v[6:7], off offset:3456
	s_waitcnt lgkmcnt(0)
	s_barrier
	v_mfma_f32_16x16x32_f16 v[48:51], v[122:125], v[110:113], v[48:51]
	ds_read_b128 v[58:61], v16 offset:32768
	ds_read_b128 v[106:109], v21
	s_waitcnt lgkmcnt(0)
	v_mfma_f32_16x16x32_f16 v[36:39], v[58:61], v[106:109], v[36:39]
	ds_read_b128 v[94:97], v16 offset:34816
	ds_read_b128 v[110:113], v21 offset:2048
	s_waitcnt lgkmcnt(0)
	v_mfma_f32_16x16x32_f16 v[66:69], v[58:61], v[110:113], v[66:69]
	ds_read_b128 v[118:121], v16 offset:36864
	v_mfma_f32_16x16x32_f16 v[44:47], v[94:97], v[106:109], v[44:47]
	ds_read_b128 v[122:125], v16 offset:38912
	v_mfma_f32_16x16x32_f16 v[78:81], v[94:97], v[110:113], v[78:81]
	s_waitcnt vmcnt(7)
	ds_write_b128 v17, v[62:65] offset:16384
	s_waitcnt lgkmcnt(2)
	v_mfma_f32_16x16x32_f16 v[82:85], v[118:121], v[106:109], v[82:85]
	s_waitcnt vmcnt(6)
	ds_write_b128 v18, v[90:93] offset:16384
	v_mfma_f32_16x16x32_f16 v[86:89], v[118:121], v[110:113], v[86:89]
	s_waitcnt vmcnt(5)
	ds_write_b128 v19, v[130:133] offset:16384
	s_waitcnt lgkmcnt(3)
	v_mfma_f32_16x16x32_f16 v[28:31], v[122:125], v[106:109], v[28:31]
	ds_read_b128 v[106:109], v21 offset:4096
	v_mfma_f32_16x16x32_f16 v[32:35], v[122:125], v[110:113], v[32:35]
	ds_read_b128 v[110:113], v21 offset:6144
	s_waitcnt lgkmcnt(1)
	v_mfma_f32_16x16x32_f16 v[98:101], v[58:61], v[106:109], v[98:101]
	s_waitcnt vmcnt(4)
	ds_write_b128 v20, v[138:141] offset:16384
	s_waitcnt lgkmcnt(1)
	v_mfma_f32_16x16x32_f16 v[52:55], v[58:61], v[110:113], v[52:55]
	ds_read_b128 v[58:61], v22 offset:32768
	v_mfma_f32_16x16x32_f16 v[102:105], v[94:97], v[106:109], v[102:105]
	s_waitcnt vmcnt(3)
; #define GL_LOAD(s_, kt_) if (VAR != 1) { a##s_##0 = GL_A(0, kt_); a##s_##1 = GL_A(1, kt_); a##s_##2 = GL_A(2, kt_); a##s_##3 = GL_A(3, kt_); b##s_##0 = GL_B(0, kt_); b##s_##1 = GL_B(1, kt_); b##s_##2 = GL_B(2, kt_); b##s_##3 = GL_B(3, kt_); }
; #define LDS_STORE(s_, buf_) if (VAR != 2) { LDS_ST1(sA, 0, buf_, a##s_##0) LDS_ST1(sA, 1, buf_, a##s_##1) LDS_ST1(sA, 2, buf_, a##s_##2) LDS_ST1(sA, 3, buf_, a##s_##3) LDS_ST1(sB, 0, buf_, b##s_##0) LDS_ST1(sB, 1, buf_, b##s_##1) LDS_ST1(sB, 2, buf_, b##s_##2) LDS_ST1(sB, 3, buf_, b##s_##3) }
;     ...
;   for (int kt = 0; kt < nk; kt += 2) {
;     if (kt + 2 < nk) { GL_LOAD(0, kt + 2) }
;     MMA_TILE(0)
;     LDS_STORE(1, 1)
;     if (VAR != 4) __syncthreads();
;     if (kt + 3 < nk) { GL_LOAD(1, kt + 3) }
;     MMA_TILE(1)
;     if (kt + 2 < nk) { LDS_STORE(0, 0) }
;     if (VAR != 4) __syncthreads();
	ds_write_b128 v17, v[74:77] offset:49152
	v_mfma_f32_16x16x32_f16 v[24:27], v[94:97], v[110:113], v[24:27]
	ds_read_b128 v[94:97], v22 offset:34816
	v_mfma_f32_16x16x32_f16 v[114:117], v[118:121], v[106:109], v[114:117]
	s_waitcnt vmcnt(2)
	ds_write_b128 v18, v[142:145] offset:49152
	v_mfma_f32_16x16x32_f16 v[40:43], v[118:121], v[110:113], v[40:43]
	ds_read_b128 v[118:121], v22 offset:36864
	v_mfma_f32_16x16x32_f16 v[70:73], v[122:125], v[106:109], v[70:73]
	ds_read_b128 v[106:109], v23
	v_mfma_f32_16x16x32_f16 v[48:51], v[122:125], v[110:113], v[48:51]
	ds_read_b128 v[110:113], v23 offset:2048
	s_waitcnt lgkmcnt(1)
	v_mfma_f32_16x16x32_f16 v[36:39], v[58:61], v[106:109], v[36:39]
	ds_read_b128 v[122:125], v22 offset:38912
	s_waitcnt lgkmcnt(1)
	v_mfma_f32_16x16x32_f16 v[66:69], v[58:61], v[110:113], v[66:69]
	s_waitcnt vmcnt(1)
	ds_write_b128 v19, v[154:157] offset:49152
	v_mfma_f32_16x16x32_f16 v[44:47], v[94:97], v[106:109], v[44:47]
	s_waitcnt vmcnt(0)
	ds_write_b128 v20, v[158:161] offset:49152
	v_mfma_f32_16x16x32_f16 v[78:81], v[94:97], v[110:113], v[78:81]
	v_mfma_f32_16x16x32_f16 v[82:85], v[118:121], v[106:109], v[82:85]
	v_mfma_f32_16x16x32_f16 v[86:89], v[118:121], v[110:113], v[86:89]
	s_waitcnt lgkmcnt(2)
	v_mfma_f32_16x16x32_f16 v[28:31], v[122:125], v[106:109], v[28:31]
	ds_read_b128 v[106:109], v23 offset:4096
	v_mfma_f32_16x16x32_f16 v[32:35], v[122:125], v[110:113], v[32:35]
	ds_read_b128 v[110:113], v23 offset:6144
	s_waitcnt lgkmcnt(1)
	v_mfma_f32_16x16x32_f16 v[98:101], v[58:61], v[106:109], v[98:101]
	s_waitcnt lgkmcnt(0)
	v_mfma_f32_16x16x32_f16 v[52:55], v[58:61], v[110:113], v[52:55]
	global_load_dwordx4 v[58:61], v[0:1], off offset:3584
	v_mfma_f32_16x16x32_f16 v[102:105], v[94:97], v[106:109], v[102:105]
	v_mfma_f32_16x16x32_f16 v[24:27], v[94:97], v[110:113], v[24:27]
	v_mfma_f32_16x16x32_f16 v[114:117], v[118:121], v[106:109], v[114:117]
	v_mfma_f32_16x16x32_f16 v[40:43], v[118:121], v[110:113], v[40:43]
	v_mfma_f32_16x16x32_f16 v[70:73], v[122:125], v[106:109], v[70:73]
	global_load_dwordx4 v[106:109], v[2:3], off offset:3584
	global_load_dwordx4 v[126:129], v[4:5], off offset:3584
	global_load_dwordx4 v[134:137], v[14:15], off offset:3584
	global_load_dwordx4 v[94:97], v[10:11], off offset:3584
	global_load_dwordx4 v[162:165], v[12:13], off offset:3584
	global_load_dwordx4 v[166:169], v[8:9], off offset:3584
	global_load_dwordx4 v[190:193], v[6:7], off offset:3584
	s_waitcnt lgkmcnt(0)
	s_barrier
	v_mfma_f32_16x16x32_f16 v[48:51], v[122:125], v[110:113], v[48:51]
	ds_read_b128 v[62:65], v16 offset:49152
	ds_read_b128 v[90:93], v21 offset:16384
	s_waitcnt lgkmcnt(0)
	v_mfma_f32_16x16x32_f16 v[36:39], v[62:65], v[90:93], v[36:39]
	ds_read_b128 v[74:77], v16 offset:51200
	ds_read_b128 v[110:113], v21 offset:18432
	s_waitcnt lgkmcnt(0)
	v_mfma_f32_16x16x32_f16 v[66:69], v[62:65], v[110:113], v[66:69]
	ds_read_b128 v[118:121], v16 offset:53248
	v_mfma_f32_16x16x32_f16 v[44:47], v[74:77], v[90:93], v[44:47]
	ds_read_b128 v[122:125], v16 offset:55296
	v_mfma_f32_16x16x32_f16 v[78:81], v[74:77], v[110:113], v[78:81]
	s_waitcnt vmcnt(7)
	ds_write_b128 v17, v[58:61]
	s_waitcnt lgkmcnt(2)
	v_mfma_f32_16x16x32_f16 v[82:85], v[118:121], v[90:93], v[82:85]
	s_waitcnt vmcnt(6)
	ds_write_b128 v18, v[106:109]
	v_mfma_f32_16x16x32_f16 v[86:89], v[118:121], v[110:113], v[86:89]
	s_waitcnt vmcnt(5)
	ds_write_b128 v19, v[126:129]
	s_waitcnt lgkmcnt(3)
	v_mfma_f32_16x16x32_f16 v[28:31], v[122:125], v[90:93], v[28:31]
	ds_read_b128 v[90:93], v21 offset:20480
	v_mfma_f32_16x16x32_f16 v[32:35], v[122:125], v[110:113], v[32:35]
	ds_read_b128 v[110:113], v21 offset:22528
	s_waitcnt lgkmcnt(1)
	v_mfma_f32_16x16x32_f16 v[98:101], v[62:65], v[90:93], v[98:101]
	s_waitcnt vmcnt(4)
	ds_write_b128 v20, v[134:137]
	s_waitcnt lgkmcnt(1)
	v_mfma_f32_16x16x32_f16 v[52:55], v[62:65], v[110:113], v[52:55]
	ds_read_b128 v[62:65], v22 offset:49152
	v_mfma_f32_16x16x32_f16 v[102:105], v[74:77], v[90:93], v[102:105]
	s_waitcnt vmcnt(3)
	ds_write_b128 v17, v[94:97] offset:32768
	v_mfma_f32_16x16x32_f16 v[24:27], v[74:77], v[110:113], v[24:27]
	ds_read_b128 v[74:77], v22 offset:51200
	v_mfma_f32_16x16x32_f16 v[114:117], v[118:121], v[90:93], v[114:117]
	s_waitcnt vmcnt(2)
	ds_write_b128 v18, v[162:165] offset:32768
	v_mfma_f32_16x16x32_f16 v[40:43], v[118:121], v[110:113], v[40:43]
	ds_read_b128 v[118:121], v22 offset:53248
	v_mfma_f32_16x16x32_f16 v[70:73], v[122:125], v[90:93], v[70:73]
	ds_read_b128 v[90:93], v23 offset:16384
	v_mfma_f32_16x16x32_f16 v[48:51], v[122:125], v[110:113], v[48:51]
	ds_read_b128 v[110:113], v23 offset:18432
	s_waitcnt lgkmcnt(1)
	v_mfma_f32_16x16x32_f16 v[36:39], v[62:65], v[90:93], v[36:39]
	ds_read_b128 v[122:125], v22 offset:55296
	s_waitcnt lgkmcnt(1)
	v_mfma_f32_16x16x32_f16 v[66:69], v[62:65], v[110:113], v[66:69]
	s_waitcnt vmcnt(1)
	ds_write_b128 v19, v[166:169] offset:32768
	v_mfma_f32_16x16x32_f16 v[44:47], v[74:77], v[90:93], v[44:47]
	s_waitcnt vmcnt(0)
	ds_write_b128 v20, v[190:193] offset:32768
	v_mfma_f32_16x16x32_f16 v[78:81], v[74:77], v[110:113], v[78:81]
	v_mfma_f32_16x16x32_f16 v[82:85], v[118:121], v[90:93], v[82:85]
	v_mfma_f32_16x16x32_f16 v[86:89], v[118:121], v[110:113], v[86:89]
	s_waitcnt lgkmcnt(2)
	v_mfma_f32_16x16x32_f16 v[28:31], v[122:125], v[90:93], v[28:31]
	ds_read_b128 v[90:93], v23 offset:20480
	v_mfma_f32_16x16x32_f16 v[32:35], v[122:125], v[110:113], v[32:35]
	ds_read_b128 v[110:113], v23 offset:22528
	s_waitcnt lgkmcnt(1)
	v_mfma_f32_16x16x32_f16 v[98:101], v[62:65], v[90:93], v[98:101]
	s_waitcnt lgkmcnt(0)
	v_mfma_f32_16x16x32_f16 v[52:55], v[62:65], v[110:113], v[52:55]
	global_load_dwordx4 v[62:65], v[0:1], off offset:3712
	v_mfma_f32_16x16x32_f16 v[102:105], v[74:77], v[90:93], v[102:105]
	v_mfma_f32_16x16x32_f16 v[24:27], v[74:77], v[110:113], v[24:27]
	v_mfma_f32_16x16x32_f16 v[114:117], v[118:121], v[90:93], v[114:117]
	v_mfma_f32_16x16x32_f16 v[40:43], v[118:121], v[110:113], v[40:43]
	v_mfma_f32_16x16x32_f16 v[70:73], v[122:125], v[90:93], v[70:73]
	global_load_dwordx4 v[90:93], v[2:3], off offset:3712
	global_load_dwordx4 v[130:133], v[4:5], off offset:3712
	global_load_dwordx4 v[138:141], v[14:15], off offset:3712
	global_load_dwordx4 v[74:77], v[10:11], off offset:3712
	global_load_dwordx4 v[142:145], v[12:13], off offset:3712
	global_load_dwordx4 v[154:157], v[8:9], off offset:3712
	global_load_dwordx4 v[158:161], v[6:7], off offset:3712
	s_waitcnt lgkmcnt(0)
	s_barrier
; #define GL_LOAD(s_, kt_) if (VAR != 1) { a##s_##0 = GL_A(0, kt_); a##s_##1 = GL_A(1, kt_); a##s_##2 = GL_A(2, kt_); a##s_##3 = GL_A(3, kt_); b##s_##0 = GL_B(0, kt_); b##s_##1 = GL_B(1, kt_); b##s_##2 = GL_B(2, kt_); b##s_##3 = GL_B(3, kt_); }
; #define LDS_STORE(s_, buf_) if (VAR != 2) { LDS_ST1(sA, 0, buf_, a##s_##0) LDS_ST1(sA, 1, buf_, a##s_##1) LDS_ST1(sA, 2, buf_, a##s_##2) LDS_ST1(sA, 3, buf_, a##s_##3) LDS_ST1(sB, 0, buf_, b##s_##0) LDS_ST1(sB, 1, buf_, b##s_##1) LDS_ST1(sB, 2, buf_, b##s_##2) LDS_ST1(sB, 3, buf_, b##s_##3) }
;     ...
;   for (int kt = 0; kt < nk; kt += 2) {
;     if (kt + 2 < nk) { GL_LOAD(0, kt + 2) }
;     MMA_TILE(0)
;     LDS_STORE(1, 1)
;     if (VAR != 4) __syncthreads();
;     if (kt + 3 < nk) { GL_LOAD(1, kt + 3) }
;     MMA_TILE(1)
;     if (kt + 2 < nk) { LDS_STORE(0, 0) }
;     if (VAR != 4) __syncthreads();
	v_mfma_f32_16x16x32_f16 v[48:51], v[122:125], v[110:113], v[48:51]
	ds_read_b128 v[58:61], v16 offset:32768
	ds_read_b128 v[106:109], v21
	s_waitcnt lgkmcnt(0)
	v_mfma_f32_16x16x32_f16 v[36:39], v[58:61], v[106:109], v[36:39]
	ds_read_b128 v[94:97], v16 offset:34816
	ds_read_b128 v[110:113], v21 offset:2048
	s_waitcnt lgkmcnt(0)
	v_mfma_f32_16x16x32_f16 v[66:69], v[58:61], v[110:113], v[66:69]
	ds_read_b128 v[118:121], v16 offset:36864
	v_mfma_f32_16x16x32_f16 v[44:47], v[94:97], v[106:109], v[44:47]
	ds_read_b128 v[122:125], v16 offset:38912
	v_mfma_f32_16x16x32_f16 v[78:81], v[94:97], v[110:113], v[78:81]
	s_waitcnt vmcnt(7)
	ds_write_b128 v17, v[62:65] offset:16384
	s_waitcnt lgkmcnt(2)
	v_mfma_f32_16x16x32_f16 v[82:85], v[118:121], v[106:109], v[82:85]
	s_waitcnt vmcnt(6)
	ds_write_b128 v18, v[90:93] offset:16384
	v_mfma_f32_16x16x32_f16 v[86:89], v[118:121], v[110:113], v[86:89]
	s_waitcnt vmcnt(5)
	ds_write_b128 v19, v[130:133] offset:16384
	s_waitcnt lgkmcnt(3)
	v_mfma_f32_16x16x32_f16 v[28:31], v[122:125], v[106:109], v[28:31]
	ds_read_b128 v[106:109], v21 offset:4096
	v_mfma_f32_16x16x32_f16 v[32:35], v[122:125], v[110:113], v[32:35]
	ds_read_b128 v[110:113], v21 offset:6144
	s_waitcnt lgkmcnt(1)
	v_mfma_f32_16x16x32_f16 v[98:101], v[58:61], v[106:109], v[98:101]
	s_waitcnt vmcnt(4)
	ds_write_b128 v20, v[138:141] offset:16384
	s_waitcnt lgkmcnt(1)
	v_mfma_f32_16x16x32_f16 v[52:55], v[58:61], v[110:113], v[52:55]
	ds_read_b128 v[58:61], v22 offset:32768
	v_mfma_f32_16x16x32_f16 v[102:105], v[94:97], v[106:109], v[102:105]
	s_waitcnt vmcnt(3)
	ds_write_b128 v17, v[74:77] offset:49152
	v_mfma_f32_16x16x32_f16 v[24:27], v[94:97], v[110:113], v[24:27]
	ds_read_b128 v[94:97], v22 offset:34816
	v_mfma_f32_16x16x32_f16 v[114:117], v[118:121], v[106:109], v[114:117]
	s_waitcnt vmcnt(2)
	ds_write_b128 v18, v[142:145] offset:49152
	v_mfma_f32_16x16x32_f16 v[40:43], v[118:121], v[110:113], v[40:43]
	ds_read_b128 v[118:121], v22 offset:36864
	v_mfma_f32_16x16x32_f16 v[70:73], v[122:125], v[106:109], v[70:73]
	ds_read_b128 v[106:109], v23
	v_mfma_f32_16x16x32_f16 v[48:51], v[122:125], v[110:113], v[48:51]
	ds_read_b128 v[110:113], v23 offset:2048
	s_waitcnt lgkmcnt(1)
	v_mfma_f32_16x16x32_f16 v[36:39], v[58:61], v[106:109], v[36:39]
	ds_read_b128 v[122:125], v22 offset:38912
	s_waitcnt lgkmcnt(1)
	v_mfma_f32_16x16x32_f16 v[66:69], v[58:61], v[110:113], v[66:69]
	s_waitcnt vmcnt(1)
	ds_write_b128 v19, v[154:157] offset:49152
	v_mfma_f32_16x16x32_f16 v[44:47], v[94:97], v[106:109], v[44:47]
	s_waitcnt vmcnt(0)
	ds_write_b128 v20, v[158:161] offset:49152
	v_mfma_f32_16x16x32_f16 v[78:81], v[94:97], v[110:113], v[78:81]
	v_mfma_f32_16x16x32_f16 v[82:85], v[118:121], v[106:109], v[82:85]
	v_mfma_f32_16x16x32_f16 v[86:89], v[118:121], v[110:113], v[86:89]
	s_waitcnt lgkmcnt(2)
	v_mfma_f32_16x16x32_f16 v[28:31], v[122:125], v[106:109], v[28:31]
	ds_read_b128 v[106:109], v23 offset:4096
	v_mfma_f32_16x16x32_f16 v[32:35], v[122:125], v[110:113], v[32:35]
	ds_read_b128 v[110:113], v23 offset:6144
	s_waitcnt lgkmcnt(1)
	v_mfma_f32_16x16x32_f16 v[98:101], v[58:61], v[106:109], v[98:101]
	s_waitcnt lgkmcnt(0)
	v_mfma_f32_16x16x32_f16 v[52:55], v[58:61], v[110:113], v[52:55]
	global_load_dwordx4 v[58:61], v[0:1], off offset:3840
	v_mfma_f32_16x16x32_f16 v[102:105], v[94:97], v[106:109], v[102:105]
	v_mfma_f32_16x16x32_f16 v[24:27], v[94:97], v[110:113], v[24:27]
	v_mfma_f32_16x16x32_f16 v[114:117], v[118:121], v[106:109], v[114:117]
	v_mfma_f32_16x16x32_f16 v[40:43], v[118:121], v[110:113], v[40:43]
	v_mfma_f32_16x16x32_f16 v[70:73], v[122:125], v[106:109], v[70:73]
	global_load_dwordx4 v[106:109], v[2:3], off offset:3840
	global_load_dwordx4 v[126:129], v[4:5], off offset:3840
	global_load_dwordx4 v[134:137], v[14:15], off offset:3840
	global_load_dwordx4 v[94:97], v[10:11], off offset:3840
	global_load_dwordx4 v[162:165], v[12:13], off offset:3840
	global_load_dwordx4 v[166:169], v[8:9], off offset:3840
	global_load_dwordx4 v[190:193], v[6:7], off offset:3840
	s_waitcnt lgkmcnt(0)
	s_barrier
	v_mfma_f32_16x16x32_f16 v[48:51], v[122:125], v[110:113], v[48:51]
	ds_read_b128 v[62:65], v16 offset:49152
	ds_read_b128 v[90:93], v21 offset:16384
	s_waitcnt lgkmcnt(0)
	v_mfma_f32_16x16x32_f16 v[36:39], v[62:65], v[90:93], v[36:39]
	ds_read_b128 v[74:77], v16 offset:51200
	ds_read_b128 v[110:113], v21 offset:18432
	s_waitcnt lgkmcnt(0)
	v_mfma_f32_16x16x32_f16 v[66:69], v[62:65], v[110:113], v[66:69]
	ds_read_b128 v[118:121], v16 offset:53248
	v_mfma_f32_16x16x32_f16 v[44:47], v[74:77], v[90:93], v[44:47]
	ds_read_b128 v[122:125], v16 offset:55296
	v_mfma_f32_16x16x32_f16 v[78:81], v[74:77], v[110:113], v[78:81]
	s_waitcnt vmcnt(7)
	ds_write_b128 v17, v[58:61]
	s_waitcnt lgkmcnt(2)
	v_mfma_f32_16x16x32_f16 v[82:85], v[118:121], v[90:93], v[82:85]
	s_waitcnt vmcnt(6)
	ds_write_b128 v18, v[106:109]
	v_mfma_f32_16x16x32_f16 v[86:89], v[118:121], v[110:113], v[86:89]
	s_waitcnt vmcnt(5)
	ds_write_b128 v19, v[126:129]
	s_waitcnt lgkmcnt(3)
	v_mfma_f32_16x16x32_f16 v[28:31], v[122:125], v[90:93], v[28:31]
	ds_read_b128 v[90:93], v21 offset:20480
	v_mfma_f32_16x16x32_f16 v[32:35], v[122:125], v[110:113], v[32:35]
	ds_read_b128 v[110:113], v21 offset:22528
	s_waitcnt lgkmcnt(1)
	v_mfma_f32_16x16x32_f16 v[98:101], v[62:65], v[90:93], v[98:101]
	s_waitcnt vmcnt(4)
	ds_write_b128 v20, v[134:137]
	s_waitcnt lgkmcnt(1)
	v_mfma_f32_16x16x32_f16 v[52:55], v[62:65], v[110:113], v[52:55]
	ds_read_b128 v[62:65], v22 offset:49152
	v_mfma_f32_16x16x32_f16 v[102:105], v[74:77], v[90:93], v[102:105]
	s_waitcnt vmcnt(3)
; #define GL_LOAD(s_, kt_) if (VAR != 1) { a##s_##0 = GL_A(0, kt_); a##s_##1 = GL_A(1, kt_); a##s_##2 = GL_A(2, kt_); a##s_##3 = GL_A(3, kt_); b##s_##0 = GL_B(0, kt_); b##s_##1 = GL_B(1, kt_); b##s_##2 = GL_B(2, kt_); b##s_##3 = GL_B(3, kt_); }
; #define LDS_STORE(s_, buf_) if (VAR != 2) { LDS_ST1(sA, 0, buf_, a##s_##0) LDS_ST1(sA, 1, buf_, a##s_##1) LDS_ST1(sA, 2, buf_, a##s_##2) LDS_ST1(sA, 3, buf_, a##s_##3) LDS_ST1(sB, 0, buf_, b##s_##0) LDS_ST1(sB, 1, buf_, b##s_##1) LDS_ST1(sB, 2, buf_, b##s_##2) LDS_ST1(sB, 3, buf_, b##s_##3) }
;     ...
;   for (int kt = 0; kt < nk; kt += 2) {
;     if (kt + 2 < nk) { GL_LOAD(0, kt + 2) }
;     MMA_TILE(0)
;     LDS_STORE(1, 1)
;     if (VAR != 4) __syncthreads();
;     if (kt + 3 < nk) { GL_LOAD(1, kt + 3) }
;     MMA_TILE(1)
;     if (kt + 2 < nk) { LDS_STORE(0, 0) }
;     if (VAR != 4) __syncthreads();
	ds_write_b128 v17, v[94:97] offset:32768
	v_mfma_f32_16x16x32_f16 v[24:27], v[74:77], v[110:113], v[24:27]
	ds_read_b128 v[74:77], v22 offset:51200
	v_mfma_f32_16x16x32_f16 v[114:117], v[118:121], v[90:93], v[114:117]
	s_waitcnt vmcnt(2)
	ds_write_b128 v18, v[162:165] offset:32768
	v_mfma_f32_16x16x32_f16 v[40:43], v[118:121], v[110:113], v[40:43]
	ds_read_b128 v[118:121], v22 offset:53248
	v_mfma_f32_16x16x32_f16 v[70:73], v[122:125], v[90:93], v[70:73]
	ds_read_b128 v[90:93], v23 offset:16384
	v_mfma_f32_16x16x32_f16 v[48:51], v[122:125], v[110:113], v[48:51]
	ds_read_b128 v[110:113], v23 offset:18432
	s_waitcnt lgkmcnt(1)
	v_mfma_f32_16x16x32_f16 v[36:39], v[62:65], v[90:93], v[36:39]
	ds_read_b128 v[122:125], v22 offset:55296
	s_waitcnt lgkmcnt(1)
	v_mfma_f32_16x16x32_f16 v[66:69], v[62:65], v[110:113], v[66:69]
	s_waitcnt vmcnt(1)
	ds_write_b128 v19, v[166:169] offset:32768
	v_mfma_f32_16x16x32_f16 v[44:47], v[74:77], v[90:93], v[44:47]
	s_waitcnt vmcnt(0)
	ds_write_b128 v20, v[190:193] offset:32768
	v_mfma_f32_16x16x32_f16 v[78:81], v[74:77], v[110:113], v[78:81]
	v_mfma_f32_16x16x32_f16 v[82:85], v[118:121], v[90:93], v[82:85]
	v_mfma_f32_16x16x32_f16 v[86:89], v[118:121], v[110:113], v[86:89]
	s_waitcnt lgkmcnt(2)
	v_mfma_f32_16x16x32_f16 v[28:31], v[122:125], v[90:93], v[28:31]
	ds_read_b128 v[90:93], v23 offset:20480
	v_mfma_f32_16x16x32_f16 v[32:35], v[122:125], v[110:113], v[32:35]
	ds_read_b128 v[110:113], v23 offset:22528
	s_waitcnt lgkmcnt(1)
	v_mfma_f32_16x16x32_f16 v[98:101], v[62:65], v[90:93], v[98:101]
	s_waitcnt lgkmcnt(0)
	v_mfma_f32_16x16x32_f16 v[52:55], v[62:65], v[110:113], v[52:55]
	global_load_dwordx4 v[62:65], v[0:1], off offset:3968
	global_load_dwordx4 v[0:3], v[2:3], off offset:3968
	v_mfma_f32_16x16x32_f16 v[102:105], v[74:77], v[90:93], v[102:105]
	v_mfma_f32_16x16x32_f16 v[24:27], v[74:77], v[110:113], v[24:27]
	v_mfma_f32_16x16x32_f16 v[114:117], v[118:121], v[90:93], v[114:117]
	v_mfma_f32_16x16x32_f16 v[40:43], v[118:121], v[110:113], v[40:43]
	v_mfma_f32_16x16x32_f16 v[70:73], v[122:125], v[90:93], v[70:73]
	global_load_dwordx4 v[90:93], v[4:5], off offset:3968
	global_load_dwordx4 v[130:133], v[14:15], off offset:3968
	global_load_dwordx4 v[74:77], v[10:11], off offset:3968
	global_load_dwordx4 v[10:13], v[12:13], off offset:3968
	global_load_dwordx4 v[138:141], v[8:9], off offset:3968
	global_load_dwordx4 v[4:7], v[6:7], off offset:3968
	s_waitcnt lgkmcnt(0)
	s_barrier
	ds_read_b128 v[58:61], v16 offset:32768
	v_mfma_f32_16x16x32_f16 v[48:51], v[122:125], v[110:113], v[48:51]
	ds_read_b128 v[94:97], v16 offset:34816
	ds_read_b128 v[106:109], v21
	ds_read_b128 v[110:113], v21 offset:2048
	ds_read_b128 v[118:121], v16 offset:36864
	ds_read_b128 v[122:125], v16 offset:38912
	s_waitcnt lgkmcnt(3)
	v_mfma_f32_16x16x32_f16 v[36:39], v[58:61], v[106:109], v[36:39]
	v_mfma_f32_16x16x32_f16 v[44:47], v[94:97], v[106:109], v[44:47]
	s_waitcnt lgkmcnt(1)
	v_mfma_f32_16x16x32_f16 v[82:85], v[118:121], v[106:109], v[82:85]
	s_waitcnt lgkmcnt(0)
	v_mfma_f32_16x16x32_f16 v[28:31], v[122:125], v[106:109], v[28:31]
	v_mfma_f32_16x16x32_f16 v[66:69], v[58:61], v[110:113], v[66:69]
	v_mfma_f32_16x16x32_f16 v[78:81], v[94:97], v[110:113], v[78:81]
	v_mfma_f32_16x16x32_f16 v[86:89], v[118:121], v[110:113], v[86:89]
	v_mfma_f32_16x16x32_f16 v[32:35], v[122:125], v[110:113], v[32:35]
	ds_read_b128 v[106:109], v21 offset:4096
	ds_read_b128 v[110:113], v21 offset:6144
	s_waitcnt lgkmcnt(1)
	v_mfma_f32_16x16x32_f16 v[98:101], v[58:61], v[106:109], v[98:101]
	v_mfma_f32_16x16x32_f16 v[102:105], v[94:97], v[106:109], v[102:105]
	v_mfma_f32_16x16x32_f16 v[114:117], v[118:121], v[106:109], v[114:117]
	v_mfma_f32_16x16x32_f16 v[70:73], v[122:125], v[106:109], v[70:73]
	s_waitcnt lgkmcnt(0)
	v_mfma_f32_16x16x32_f16 v[52:55], v[58:61], v[110:113], v[52:55]
	ds_read_b128 v[58:61], v22 offset:32768
	v_mfma_f32_16x16x32_f16 v[24:27], v[94:97], v[110:113], v[24:27]
	v_mfma_f32_16x16x32_f16 v[40:43], v[118:121], v[110:113], v[40:43]
	v_mfma_f32_16x16x32_f16 v[48:51], v[122:125], v[110:113], v[48:51]
	ds_read_b128 v[94:97], v22 offset:34816
	ds_read_b128 v[106:109], v23
	ds_read_b128 v[110:113], v23 offset:2048
	ds_read_b128 v[118:121], v22 offset:36864
	ds_read_b128 v[122:125], v22 offset:38912
	s_waitcnt lgkmcnt(3)
	v_mfma_f32_16x16x32_f16 v[36:39], v[58:61], v[106:109], v[36:39]
	v_mfma_f32_16x16x32_f16 v[44:47], v[94:97], v[106:109], v[44:47]
	s_waitcnt lgkmcnt(1)
	v_mfma_f32_16x16x32_f16 v[82:85], v[118:121], v[106:109], v[82:85]
	s_waitcnt lgkmcnt(0)
	v_mfma_f32_16x16x32_f16 v[28:31], v[122:125], v[106:109], v[28:31]
	v_mfma_f32_16x16x32_f16 v[66:69], v[58:61], v[110:113], v[66:69]
	v_mfma_f32_16x16x32_f16 v[78:81], v[94:97], v[110:113], v[78:81]
	v_mfma_f32_16x16x32_f16 v[86:89], v[118:121], v[110:113], v[86:89]
	v_mfma_f32_16x16x32_f16 v[32:35], v[122:125], v[110:113], v[32:35]
	ds_read_b128 v[106:109], v23 offset:4096
	ds_read_b128 v[110:113], v23 offset:6144
	s_waitcnt vmcnt(7)
	ds_write_b128 v17, v[62:65] offset:16384
	s_waitcnt vmcnt(6)
	ds_write_b128 v18, v[0:3] offset:16384
	s_waitcnt vmcnt(5)
	ds_write_b128 v19, v[90:93] offset:16384
	s_waitcnt vmcnt(4)
	ds_write_b128 v20, v[130:133] offset:16384
	s_waitcnt lgkmcnt(5)
	v_mfma_f32_16x16x32_f16 v[98:101], v[58:61], v[106:109], v[98:101]
	s_waitcnt vmcnt(3)
	ds_write_b128 v17, v[74:77] offset:49152
	s_waitcnt vmcnt(2)
	ds_write_b128 v18, v[10:13] offset:49152
	s_waitcnt vmcnt(1)
	ds_write_b128 v19, v[138:141] offset:49152
	s_waitcnt vmcnt(0)
	ds_write_b128 v20, v[4:7] offset:49152
	s_waitcnt lgkmcnt(0)
	s_barrier
; DI int TIDX() { int t = threadIdx.x; asm volatile("" : "+v"(t)); return t; }
; DI unsigned pack2(float lo, float hi) { f2_t v = {lo, hi}; h2_t b = __builtin_convertvector(v, h2_t); return __builtin_bit_cast(unsigned, b); }
; #define GL_LOAD(s_, kt_) if (VAR != 1) { a##s_##0 = GL_A(0, kt_); a##s_##1 = GL_A(1, kt_); a##s_##2 = GL_A(2, kt_); a##s_##3 = GL_A(3, kt_); b##s_##0 = GL_B(0, kt_); b##s_##1 = GL_B(1, kt_); b##s_##2 = GL_B(2, kt_); b##s_##3 = GL_B(3, kt_); }
; #define LDS_STORE(s_, buf_) if (VAR != 2) { LDS_ST1(sA, 0, buf_, a##s_##0) LDS_ST1(sA, 1, buf_, a##s_##1) LDS_ST1(sA, 2, buf_, a##s_##2) LDS_ST1(sA, 3, buf_, a##s_##3) LDS_ST1(sB, 0, buf_, b##s_##0) LDS_ST1(sB, 1, buf_, b##s_##1) LDS_ST1(sB, 2, buf_, b##s_##2) LDS_ST1(sB, 3, buf_, b##s_##3) }
;     ...
;     MMA_TILE(0)
;     LDS_STORE(1, 1)
;     if (VAR != 4) __syncthreads();
;     if (kt + 3 < nk) { GL_LOAD(1, kt + 3) }
;     MMA_TILE(1)
;     if (kt + 2 < nk) { LDS_STORE(0, 0) }
;     if (VAR != 4) __syncthreads();
; DI void epi_residual(const f32x4 (&v)[4][4], int row0, int col0, const float* xsrc, float* x, bf16_t* xb, float* ssq_out, bool write_xb, bool write_ssq) {
;   const int lane = TIDX() & 63, lr = lane & 15, g = lane >> 4;
; #pragma unroll
;   for (int mt = 0; mt < 4; ++mt) {
;     const int row = row0 + mt * 16 + lr;
;     float ss = 0.f;
; #pragma unroll
;     for (int nt = 0; nt < 4; ++nt) {
;       const int col = col0 + nt * 16 + 4 * g;
;       float4* px = (float4*)(x + (size_t)row * DM + col);
;       float4 o = *(const float4*)(xsrc + (size_t)row * DM + col);
;       o.x += v[mt][nt][0]; o.y += v[mt][nt][1]; o.z += v[mt][nt][2]; o.w += v[mt][nt][3];
;       *px = o;
;       ss += (o.x * o.x + o.y * o.y) + (o.z * o.z + o.w * o.w);
;       if (write_xb) *(uint2*)(xb + (size_t)row * DM + col) = make_uint2(pack2(o.x, o.y), pack2(o.z, o.w));
;     }
	v_mfma_f32_16x16x32_f16 v[52:55], v[58:61], v[110:113], v[52:55]
	ds_read_b128 v[4:7], v16 offset:49152
	v_add_u32_e32 v130, s4, v57
	v_mfma_f32_16x16x32_f16 v[0:3], v[118:121], v[110:113], v[40:43]
	v_readlane_b32 s4, v254, 45
	v_readlane_b32 s5, v254, 46
	v_mfma_f32_16x16x32_f16 v[8:11], v[122:125], v[110:113], v[48:51]
	ds_read_b128 v[12:15], v16 offset:51200
	ds_read_b128 v[40:43], v21 offset:16384
	s_nop 0
	ds_read_b128 v[48:51], v21 offset:18432
	ds_read_b128 v[58:61], v16 offset:53248
	ds_read_b128 v[16:19], v16 offset:55296
	v_mfma_f32_16x16x32_f16 v[102:105], v[94:97], v[106:109], v[102:105]
	v_mfma_f32_16x16x32_f16 v[114:117], v[118:121], v[106:109], v[114:117]
	v_mfma_f32_16x16x32_f16 v[70:73], v[122:125], v[106:109], v[70:73]
	v_mfma_f32_16x16x32_f16 v[24:27], v[94:97], v[110:113], v[24:27]
	s_waitcnt lgkmcnt(3)
	v_mfma_f32_16x16x32_f16 v[36:39], v[4:7], v[40:43], v[36:39]
	v_mfma_f32_16x16x32_f16 v[44:47], v[12:15], v[40:43], v[44:47]
	s_waitcnt lgkmcnt(1)
	v_mfma_f32_16x16x32_f16 v[62:65], v[58:61], v[40:43], v[82:85]
	s_waitcnt lgkmcnt(0)
	v_mfma_f32_16x16x32_f16 v[28:31], v[16:19], v[40:43], v[28:31]
	ds_read_b128 v[40:43], v21 offset:20480
	ds_read_b128 v[74:77], v21 offset:22528
	ds_read_b128 v[82:85], v23 offset:16384
	ds_read_b128 v[90:93], v23 offset:18432
	ds_read_b128 v[94:97], v22 offset:49152
	ds_read_b128 v[106:109], v22 offset:51200
	ds_read_b128 v[110:113], v23 offset:20480
	ds_read_b128 v[118:121], v23 offset:22528
	ds_read_b128 v[122:125], v22 offset:53248
	ds_read_b128 v[126:129], v22 offset:55296
	v_mfma_f32_16x16x32_f16 v[66:69], v[4:7], v[48:51], v[66:69]
	s_waitcnt lgkmcnt(0)
	s_barrier
	s_setprio 0
	v_mfma_f32_16x16x32_f16 v[78:81], v[12:15], v[48:51], v[78:81]
	v_mfma_f32_16x16x32_f16 v[20:23], v[58:61], v[48:51], v[86:89]
	v_mfma_f32_16x16x32_f16 v[32:35], v[16:19], v[48:51], v[32:35]
	v_mov_b32_e32 v49, v148
	v_or_b32_e32 v48, s10, v56
	v_and_or_b32 v50, v49, 15, v130
	v_bfe_u32 v134, v49, 4, 2
	v_ashrrev_i32_e32 v51, 31, v50
	v_mfma_f32_16x16x32_f16 v[86:89], v[4:7], v[40:43], v[98:101]
	v_lshl_or_b32 v135, v134, 2, v48
	v_lshrrev_b32_e32 v150, 4, v48
	v_lshl_add_u64 v[48:49], s[4:5], 0, v[150:151]
	v_mfma_f32_16x16x32_f16 v[98:101], v[12:15], v[40:43], v[102:105]
	v_lshlrev_b32_e32 v150, 2, v135
	v_readlane_b32 s4, v254, 43
	v_readlane_b32 s5, v254, 44
	v_mfma_f32_16x16x32_f16 v[102:105], v[58:61], v[40:43], v[114:117]
	v_cmp_eq_u32_e32 vcc, 0, v134
	s_nop 1
	v_lshlrev_b64 v[114:115], 12, v[50:51]
	v_lshl_add_u64 v[114:115], s[12:13], 0, v[114:115]
	v_lshl_add_u64 v[130:131], v[114:115], 0, v[150:151]
	v_mfma_f32_16x16x32_f16 v[70:73], v[16:19], v[40:43], v[70:73]
	global_load_dwordx4 v[40:43], v[130:131], off
	v_lshlrev_b64 v[114:115], 11, v[50:51]
	v_lshl_add_u64 v[132:133], s[4:5], 0, v[114:115]
	v_mfma_f32_16x16x32_f16 v[36:39], v[94:97], v[82:85], v[36:39]
	v_mfma_f32_16x16x32_f16 v[4:7], v[4:7], v[74:77], v[52:55]
	s_nop 2
	v_lshlrev_b32_e32 v52, 1, v135
	v_mov_b32_e32 v53, v151
	v_lshl_add_u64 v[54:55], v[132:133], 0, v[52:53]
	v_mfma_f32_16x16x32_f16 v[114:117], v[12:15], v[74:77], v[24:27]
	s_waitcnt vmcnt(0)
	v_pk_add_f32 v[36:37], v[36:37], v[40:41]
	v_pk_add_f32 v[38:39], v[38:39], v[42:43]
	v_cvt_pk_f16_f32 v40, v36, v37
	v_cvt_pk_f16_f32 v41, v38, v39
	global_store_dwordx4 v[130:131], v[36:39], off
	v_mov_b32_e32 v136, v40
	v_mov_b32_e32 v137, v41
	global_load_dwordx4 v[24:27], v[130:131], off offset:64
	v_mfma_f32_16x16x32_f16 v[12:15], v[106:109], v[82:85], v[44:47]
	v_mfma_f32_16x16x32_f16 v[0:3], v[58:61], v[74:77], v[0:3]
	v_mfma_f32_16x16x32_f16 v[58:61], v[16:19], v[74:77], v[8:11]
	s_waitcnt vmcnt(0)
	s_nop 4
	v_pk_add_f32 v[12:13], v[12:13], v[24:25]
	v_pk_add_f32 v[14:15], v[14:15], v[26:27]
	v_cvt_pk_f16_f32 v24, v12, v13
	v_cvt_pk_f16_f32 v25, v14, v15
	global_store_dwordx4 v[130:131], v[12:15], off offset:64
	v_mov_b32_e32 v138, v24
	v_mov_b32_e32 v139, v25
	v_and_b32_e32 v144, 16, v148
	v_lshrrev_b32_e32 v145, 1, v144
	v_add_u32_e32 v144, v144, v145
	v_mov_b32_e32 v145, 0
	v_lshl_add_u64 v[144:145], v[144:145], 0, v[54:55]
	v_permlane16_swap_b32_e32 v136, v138
	v_permlane16_swap_b32_e32 v137, v139
	global_store_dwordx4 v[144:145], v[136:139], off
	global_load_dwordx4 v[8:11], v[130:131], off offset:128
	v_mfma_f32_16x16x32_f16 v[16:19], v[122:125], v[82:85], v[62:65]
	v_mul_f32_e64 v12, v12, v12
	v_mul_f32_e64 v13, v13, v13
	v_pk_mul_f32 v[14:15], v[14:15], v[14:15]
	v_add_f32_e32 v12, v12, v13
	v_mfma_f32_16x16x32_f16 v[44:47], v[94:97], v[90:93], v[66:69]
	v_add_f32_e32 v14, v14, v15
	v_add_f32_e32 v12, v12, v14
	s_waitcnt vmcnt(0)
	v_pk_add_f32 v[8:9], v[16:17], v[8:9]
	v_pk_add_f32 v[10:11], v[18:19], v[10:11]
	v_cvt_pk_f16_f32 v24, v8, v9
	v_cvt_pk_f16_f32 v25, v10, v11
	global_store_dwordx4 v[130:131], v[8:11], off offset:128
	v_mov_b32_e32 v140, v24
	v_mov_b32_e32 v141, v25
	global_load_dwordx4 v[24:27], v[130:131], off offset:192
	v_mfma_f32_16x16x32_f16 v[16:19], v[126:129], v[82:85], v[28:31]
	v_mul_f32_e64 v66, v36, v36
	v_mul_f32_e64 v67, v37, v37
	v_pk_mul_f32 v[68:69], v[38:39], v[38:39]
	v_pk_mul_f32 v[8:9], v[8:9], v[8:9]
	v_pk_mul_f32 v[10:11], v[10:11], v[10:11]
	v_add_f32_e32 v8, v8, v9
	v_add_f32_e32 v10, v10, v11
	v_add_f32_e32 v8, v8, v10
	v_mfma_f32_16x16x32_f16 v[40:43], v[106:109], v[90:93], v[78:81]
	s_waitcnt vmcnt(0)
; DI unsigned pack2(float lo, float hi) { f2_t v = {lo, hi}; h2_t b = __builtin_convertvector(v, h2_t); return __builtin_bit_cast(unsigned, b); }
; DI void epi_residual(const f32x4 (&v)[4][4], int row0, int col0, const float* xsrc, float* x, bf16_t* xb, float* ssq_out, bool write_xb, bool write_ssq) {
;     ...
;   for (int mt = 0; mt < 4; ++mt) {
;     const int row = row0 + mt * 16 + lr;
;     float ss = 0.f;
; #pragma unroll
;     for (int nt = 0; nt < 4; ++nt) {
;       const int col = col0 + nt * 16 + 4 * g;
;       float4* px = (float4*)(x + (size_t)row * DM + col);
;       float4 o = *(const float4*)(xsrc + (size_t)row * DM + col);
;       o.x += v[mt][nt][0]; o.y += v[mt][nt][1]; o.z += v[mt][nt][2]; o.w += v[mt][nt][3];
;       *px = o;
;       ss += (o.x * o.x + o.y * o.y) + (o.z * o.z + o.w * o.w);
;       if (write_xb) *(uint2*)(xb + (size_t)row * DM + col) = make_uint2(pack2(o.x, o.y), pack2(o.z, o.w));
;     }
;     if (write_ssq) {
;       ss += __shfl_xor(ss, 16); ss += __shfl_xor(ss, 32);
;       if (g == 0) ssq_out[(size_t)row * 16 + (col0 >> 6)] = ss;
;     }
;   }
	v_pk_add_f32 v[62:63], v[16:17], v[24:25]
	v_add_f32_e32 v16, v68, v69
	v_add_f32_e32 v17, v66, v67
	v_pk_add_f32 v[64:65], v[18:19], v[26:27]
	v_add_f32_e32 v16, v17, v16
	v_pk_mul_f32 v[74:75], v[62:63], v[62:63]
	v_pk_mul_f32 v[76:77], v[64:65], v[64:65]
	v_add_f32_e32 v12, v16, v12
	v_add_f32_e32 v66, v12, v8
	v_mfma_f32_16x16x32_f16 v[12:15], v[94:97], v[118:121], v[4:7]
	global_store_dwordx4 v[130:131], v[62:65], off offset:192
	s_nop 1
	v_add_f32_e32 v4, v76, v77
	v_add_f32_e32 v5, v74, v75
	v_add_f32_e32 v4, v5, v4
	v_add_f32_e32 v66, v66, v4
	ds_bpermute_b32 v67, v189, v66
	v_cvt_pk_f16_f32 v62, v62, v63
	v_cvt_pk_f16_f32 v63, v64, v65
	v_mov_b32_e32 v142, v62
	v_mov_b32_e32 v143, v63
	v_and_b32_e32 v144, 16, v148
	v_lshrrev_b32_e32 v145, 1, v144
	v_add_u32_e32 v144, v144, v145
	v_mov_b32_e32 v145, 0
	v_lshl_add_u64 v[144:145], v[144:145], 0, v[54:55]
	v_permlane16_swap_b32_e32 v140, v142
	v_permlane16_swap_b32_e32 v141, v143
	global_store_dwordx4 v[144:145], v[140:143], off offset:64
	v_mfma_f32_16x16x32_f16 v[36:39], v[122:125], v[90:93], v[20:23]
	s_waitcnt lgkmcnt(0)
	v_add_f32_e32 v54, v66, v67
	ds_bpermute_b32 v55, v188, v54
	v_mfma_f32_16x16x32_f16 v[32:35], v[126:129], v[90:93], v[32:35]
	v_mfma_f32_16x16x32_f16 v[28:31], v[94:97], v[110:113], v[86:89]
	v_mfma_f32_16x16x32_f16 v[24:27], v[106:109], v[110:113], v[98:101]
	v_mfma_f32_16x16x32_f16 v[20:23], v[122:125], v[110:113], v[102:105]
	v_mfma_f32_16x16x32_f16 v[16:19], v[126:129], v[110:113], v[70:73]
	v_mfma_f32_16x16x32_f16 v[8:11], v[106:109], v[118:121], v[114:117]
	v_mfma_f32_16x16x32_f16 v[4:7], v[122:125], v[118:121], v[0:3]
	v_mfma_f32_16x16x32_f16 v[0:3], v[126:129], v[118:121], v[58:61]
	s_and_saveexec_b64 s[4:5], vcc
	s_cbranch_execz .LBB0_1374
	s_waitcnt lgkmcnt(0)
	v_add_f32_e32 v58, v54, v55
	v_lshlrev_b64 v[54:55], 6, v[50:51]
	v_lshl_add_u64 v[54:55], v[48:49], 0, v[54:55]
	global_store_dword v[54:55], v58, off
.LBB0_1374:
	s_or_b64 exec, exec, s[4:5]
	v_or_b32_e32 v54, 16, v50
	s_waitcnt lgkmcnt(0)
	v_ashrrev_i32_e32 v55, 31, v54
	v_readlane_b32 s12, v254, 55
	v_lshlrev_b64 v[58:59], 12, v[54:55]
	v_readlane_b32 s13, v254, 56
	v_readlane_b32 s4, v254, 43
	v_lshlrev_b64 v[64:65], 11, v[54:55]
	v_lshl_add_u64 v[58:59], s[12:13], 0, v[58:59]
	v_lshl_add_u64 v[62:63], v[58:59], 0, v[150:151]
	global_load_dwordx4 v[58:61], v[62:63], off
	v_readlane_b32 s5, v254, 44
	v_readlane_b32 s14, v254, 57
	v_readlane_b32 s15, v254, 58
	v_lshl_add_u64 v[64:65], s[4:5], 0, v[64:65]
	v_lshl_add_u64 v[64:65], v[64:65], 0, v[52:53]
	s_waitcnt vmcnt(0)
	v_pk_add_f32 v[44:45], v[44:45], v[58:59]
	v_pk_add_f32 v[46:47], v[46:47], v[60:61]
	v_cvt_pk_f16_f32 v58, v44, v45
	v_cvt_pk_f16_f32 v59, v46, v47
	global_store_dwordx4 v[62:63], v[44:47], off
	v_mov_b32_e32 v136, v58
	v_mov_b32_e32 v137, v59
	global_load_dwordx4 v[58:61], v[62:63], off offset:64
	v_pk_mul_f32 v[44:45], v[44:45], v[44:45]
	v_pk_mul_f32 v[46:47], v[46:47], v[46:47]
	v_add_f32_e32 v44, v44, v45
	v_add_f32_e32 v46, v46, v47
	v_add_f32_e32 v44, v44, v46
	s_waitcnt vmcnt(0)
	v_pk_add_f32 v[40:41], v[40:41], v[58:59]
	v_pk_add_f32 v[42:43], v[42:43], v[60:61]
	v_cvt_pk_f16_f32 v58, v40, v41
	v_cvt_pk_f16_f32 v59, v42, v43
	global_store_dwordx4 v[62:63], v[40:43], off offset:64
	v_mov_b32_e32 v138, v58
	v_mov_b32_e32 v139, v59
	v_and_b32_e32 v144, 16, v148
	v_lshrrev_b32_e32 v145, 1, v144
	v_add_u32_e32 v144, v144, v145
	v_mov_b32_e32 v145, 0
	v_lshl_add_u64 v[144:145], v[144:145], 0, v[64:65]
	v_permlane16_swap_b32_e32 v136, v138
	v_permlane16_swap_b32_e32 v137, v139
	global_store_dwordx4 v[144:145], v[136:139], off
	global_load_dwordx4 v[58:61], v[62:63], off offset:128
	v_pk_mul_f32 v[40:41], v[40:41], v[40:41]
	v_pk_mul_f32 v[42:43], v[42:43], v[42:43]
	v_add_f32_e32 v40, v40, v41
	v_add_f32_e32 v42, v42, v43
	v_add_f32_e32 v40, v40, v42
	v_add_f32_e32 v40, v44, v40
	s_waitcnt vmcnt(0)
	v_pk_add_f32 v[36:37], v[36:37], v[58:59]
	v_pk_add_f32 v[38:39], v[38:39], v[60:61]
	v_cvt_pk_f16_f32 v58, v36, v37
	v_cvt_pk_f16_f32 v59, v38, v39
	global_store_dwordx4 v[62:63], v[36:39], off offset:128
	v_mov_b32_e32 v140, v58
	v_mov_b32_e32 v141, v59
	global_load_dwordx4 v[58:61], v[62:63], off offset:192
	v_pk_mul_f32 v[36:37], v[36:37], v[36:37]
	v_pk_mul_f32 v[38:39], v[38:39], v[38:39]
	v_add_f32_e32 v36, v36, v37
	v_add_f32_e32 v38, v38, v39
	v_add_f32_e32 v36, v36, v38
	v_add_f32_e32 v40, v40, v36
	s_waitcnt vmcnt(0)
	v_pk_add_f32 v[36:37], v[32:33], v[58:59]
	v_pk_add_f32 v[38:39], v[34:35], v[60:61]
	v_pk_mul_f32 v[32:33], v[36:37], v[36:37]
	v_pk_mul_f32 v[34:35], v[38:39], v[38:39]
	v_add_f32_e32 v32, v32, v33
	v_add_f32_e32 v34, v34, v35
	v_add_f32_e32 v32, v32, v34
	v_add_f32_e32 v32, v40, v32
	ds_bpermute_b32 v33, v189, v32
	v_cvt_pk_f16_f32 v34, v36, v37
	v_cvt_pk_f16_f32 v35, v38, v39
	global_store_dwordx4 v[62:63], v[36:39], off offset:192
	v_mov_b32_e32 v142, v34
	v_mov_b32_e32 v143, v35
	v_and_b32_e32 v144, 16, v148
	v_lshrrev_b32_e32 v145, 1, v144
	v_add_u32_e32 v144, v144, v145
	v_mov_b32_e32 v145, 0
	v_lshl_add_u64 v[144:145], v[144:145], 0, v[64:65]
	v_permlane16_swap_b32_e32 v140, v142
	v_permlane16_swap_b32_e32 v141, v143
	global_store_dwordx4 v[144:145], v[140:143], off offset:64
	s_waitcnt lgkmcnt(0)
	v_add_f32_e32 v32, v32, v33
	ds_bpermute_b32 v33, v188, v32
	s_and_saveexec_b64 s[4:5], vcc
	s_cbranch_execz .LBB0_1376
	s_waitcnt lgkmcnt(0)
	v_add_f32_e32 v34, v32, v33
	v_lshlrev_b64 v[32:33], 6, v[54:55]
	v_lshl_add_u64 v[32:33], v[48:49], 0, v[32:33]
	global_store_dword v[32:33], v34, off
; DI unsigned pack2(float lo, float hi) { f2_t v = {lo, hi}; h2_t b = __builtin_convertvector(v, h2_t); return __builtin_bit_cast(unsigned, b); }
; DI void epi_residual(const f32x4 (&v)[4][4], int row0, int col0, const float* xsrc, float* x, bf16_t* xb, float* ssq_out, bool write_xb, bool write_ssq) {
;     ...
;   for (int mt = 0; mt < 4; ++mt) {
;     const int row = row0 + mt * 16 + lr;
;     float ss = 0.f;
; #pragma unroll
;     for (int nt = 0; nt < 4; ++nt) {
;       const int col = col0 + nt * 16 + 4 * g;
;       float4* px = (float4*)(x + (size_t)row * DM + col);
;       float4 o = *(const float4*)(xsrc + (size_t)row * DM + col);
;       o.x += v[mt][nt][0]; o.y += v[mt][nt][1]; o.z += v[mt][nt][2]; o.w += v[mt][nt][3];
;       *px = o;
;       ss += (o.x * o.x + o.y * o.y) + (o.z * o.z + o.w * o.w);
;       if (write_xb) *(uint2*)(xb + (size_t)row * DM + col) = make_uint2(pack2(o.x, o.y), pack2(o.z, o.w));
;     }
;     if (write_ssq) {
;       ss += __shfl_xor(ss, 16); ss += __shfl_xor(ss, 32);
;       if (g == 0) ssq_out[(size_t)row * 16 + (col0 >> 6)] = ss;
;     }
;   }
.LBB0_1376:
	s_or_b64 exec, exec, s[4:5]
	v_or_b32_e32 v32, 32, v50
	s_waitcnt lgkmcnt(0)
	v_ashrrev_i32_e32 v33, 31, v32
	v_readlane_b32 s12, v254, 55
	v_lshlrev_b64 v[34:35], 12, v[32:33]
	v_readlane_b32 s13, v254, 56
	v_readlane_b32 s4, v254, 43
	v_lshlrev_b64 v[40:41], 11, v[32:33]
	v_lshl_add_u64 v[34:35], s[12:13], 0, v[34:35]
	v_lshl_add_u64 v[38:39], v[34:35], 0, v[150:151]
	global_load_dwordx4 v[34:37], v[38:39], off
	v_readlane_b32 s5, v254, 44
	v_mov_b32_e32 v53, v151
	v_readlane_b32 s14, v254, 57
	v_lshl_add_u64 v[40:41], s[4:5], 0, v[40:41]
	v_lshl_add_u64 v[40:41], v[40:41], 0, v[52:53]
	v_readlane_b32 s15, v254, 58
	s_waitcnt vmcnt(0)
	v_pk_add_f32 v[28:29], v[28:29], v[34:35]
	v_pk_add_f32 v[30:31], v[30:31], v[36:37]
	v_cvt_pk_f16_f32 v34, v28, v29
	v_cvt_pk_f16_f32 v35, v30, v31
	global_store_dwordx4 v[38:39], v[28:31], off
	v_mov_b32_e32 v136, v34
	v_mov_b32_e32 v137, v35
	global_load_dwordx4 v[34:37], v[38:39], off offset:64
	v_pk_mul_f32 v[28:29], v[28:29], v[28:29]
	v_pk_mul_f32 v[30:31], v[30:31], v[30:31]
	v_add_f32_e32 v28, v28, v29
	v_add_f32_e32 v30, v30, v31
	v_add_f32_e32 v28, v28, v30
	s_waitcnt vmcnt(0)
	v_pk_add_f32 v[24:25], v[24:25], v[34:35]
	v_pk_add_f32 v[26:27], v[26:27], v[36:37]
	v_cvt_pk_f16_f32 v34, v24, v25
	v_cvt_pk_f16_f32 v35, v26, v27
	global_store_dwordx4 v[38:39], v[24:27], off offset:64
	v_mov_b32_e32 v138, v34
	v_mov_b32_e32 v139, v35
	v_and_b32_e32 v144, 16, v148
	v_lshrrev_b32_e32 v145, 1, v144
	v_add_u32_e32 v144, v144, v145
	v_mov_b32_e32 v145, 0
	v_lshl_add_u64 v[144:145], v[144:145], 0, v[40:41]
	v_permlane16_swap_b32_e32 v136, v138
	v_permlane16_swap_b32_e32 v137, v139
	global_store_dwordx4 v[144:145], v[136:139], off
	global_load_dwordx4 v[34:37], v[38:39], off offset:128
	v_pk_mul_f32 v[24:25], v[24:25], v[24:25]
	v_pk_mul_f32 v[26:27], v[26:27], v[26:27]
	v_add_f32_e32 v24, v24, v25
	v_add_f32_e32 v26, v26, v27
	v_add_f32_e32 v24, v24, v26
	v_add_f32_e32 v24, v28, v24
	s_waitcnt vmcnt(0)
	v_pk_add_f32 v[20:21], v[20:21], v[34:35]
	v_pk_add_f32 v[22:23], v[22:23], v[36:37]
	v_cvt_pk_f16_f32 v34, v20, v21
	v_cvt_pk_f16_f32 v35, v22, v23
	global_store_dwordx4 v[38:39], v[20:23], off offset:128
	v_mov_b32_e32 v140, v34
	v_mov_b32_e32 v141, v35
	global_load_dwordx4 v[34:37], v[38:39], off offset:192
	v_pk_mul_f32 v[20:21], v[20:21], v[20:21]
	v_pk_mul_f32 v[22:23], v[22:23], v[22:23]
	v_add_f32_e32 v20, v20, v21
	v_add_f32_e32 v22, v22, v23
	v_add_f32_e32 v20, v20, v22
	v_add_f32_e32 v24, v24, v20
	s_waitcnt vmcnt(0)
	v_pk_add_f32 v[20:21], v[16:17], v[34:35]
	v_pk_add_f32 v[22:23], v[18:19], v[36:37]
	v_pk_mul_f32 v[16:17], v[20:21], v[20:21]
	v_pk_mul_f32 v[18:19], v[22:23], v[22:23]
	v_add_f32_e32 v16, v16, v17
	v_add_f32_e32 v18, v18, v19
	v_add_f32_e32 v16, v16, v18
	v_add_f32_e32 v16, v24, v16
	ds_bpermute_b32 v17, v189, v16
	v_cvt_pk_f16_f32 v18, v20, v21
	v_cvt_pk_f16_f32 v19, v22, v23
	global_store_dwordx4 v[38:39], v[20:23], off offset:192
	v_mov_b32_e32 v142, v18
	v_mov_b32_e32 v143, v19
	v_and_b32_e32 v144, 16, v148
	v_lshrrev_b32_e32 v145, 1, v144
	v_add_u32_e32 v144, v144, v145
	v_mov_b32_e32 v145, 0
	v_lshl_add_u64 v[144:145], v[144:145], 0, v[40:41]
	v_permlane16_swap_b32_e32 v140, v142
	v_permlane16_swap_b32_e32 v141, v143
	global_store_dwordx4 v[144:145], v[140:143], off offset:64
	s_waitcnt lgkmcnt(0)
	v_add_f32_e32 v16, v16, v17
	ds_bpermute_b32 v17, v188, v16
	s_and_saveexec_b64 s[4:5], vcc
	s_cbranch_execz .LBB0_1378
	s_waitcnt lgkmcnt(0)
	v_add_f32_e32 v18, v16, v17
	v_lshlrev_b64 v[16:17], 6, v[32:33]
	v_lshl_add_u64 v[16:17], v[48:49], 0, v[16:17]
	global_store_dword v[16:17], v18, off
; DI unsigned pack2(float lo, float hi) { f2_t v = {lo, hi}; h2_t b = __builtin_convertvector(v, h2_t); return __builtin_bit_cast(unsigned, b); }
; DI void epi_residual(const f32x4 (&v)[4][4], int row0, int col0, const float* xsrc, float* x, bf16_t* xb, float* ssq_out, bool write_xb, bool write_ssq) {
;     ...
;   for (int mt = 0; mt < 4; ++mt) {
;     const int row = row0 + mt * 16 + lr;
;     float ss = 0.f;
; #pragma unroll
;     for (int nt = 0; nt < 4; ++nt) {
;       const int col = col0 + nt * 16 + 4 * g;
;       float4* px = (float4*)(x + (size_t)row * DM + col);
;       float4 o = *(const float4*)(xsrc + (size_t)row * DM + col);
;       o.x += v[mt][nt][0]; o.y += v[mt][nt][1]; o.z += v[mt][nt][2]; o.w += v[mt][nt][3];
;       *px = o;
;       ss += (o.x * o.x + o.y * o.y) + (o.z * o.z + o.w * o.w);
;       if (write_xb) *(uint2*)(xb + (size_t)row * DM + col) = make_uint2(pack2(o.x, o.y), pack2(o.z, o.w));
;     }
;     if (write_ssq) {
;       ss += __shfl_xor(ss, 16); ss += __shfl_xor(ss, 32);
;       if (g == 0) ssq_out[(size_t)row * 16 + (col0 >> 6)] = ss;
;     }
;   }
.LBB0_1378:
	s_or_b64 exec, exec, s[4:5]
	v_or_b32_e32 v16, 48, v50
	s_waitcnt lgkmcnt(0)
	v_ashrrev_i32_e32 v17, 31, v16
	v_readlane_b32 s12, v254, 55
	v_lshlrev_b64 v[18:19], 12, v[16:17]
	v_readlane_b32 s13, v254, 56
	v_readlane_b32 s4, v254, 43
	v_lshlrev_b64 v[24:25], 11, v[16:17]
	v_lshl_add_u64 v[18:19], s[12:13], 0, v[18:19]
	v_lshl_add_u64 v[22:23], v[18:19], 0, v[150:151]
	global_load_dwordx4 v[18:21], v[22:23], off
	v_readlane_b32 s5, v254, 44
	v_readlane_b32 s14, v254, 57
	v_readlane_b32 s15, v254, 58
	v_lshl_add_u64 v[24:25], s[4:5], 0, v[24:25]
	v_lshl_add_u64 v[24:25], v[24:25], 0, v[52:53]
	s_waitcnt vmcnt(0)
	v_pk_add_f32 v[12:13], v[12:13], v[18:19]
	v_pk_add_f32 v[14:15], v[14:15], v[20:21]
	v_cvt_pk_f16_f32 v18, v12, v13
	v_cvt_pk_f16_f32 v19, v14, v15
	global_store_dwordx4 v[22:23], v[12:15], off
	v_mov_b32_e32 v136, v18
	v_mov_b32_e32 v137, v19
	global_load_dwordx4 v[18:21], v[22:23], off offset:64
	v_pk_mul_f32 v[12:13], v[12:13], v[12:13]
	v_pk_mul_f32 v[14:15], v[14:15], v[14:15]
	v_add_f32_e32 v12, v12, v13
	v_add_f32_e32 v14, v14, v15
	v_add_f32_e32 v12, v12, v14
	s_waitcnt vmcnt(0)
	v_pk_add_f32 v[8:9], v[8:9], v[18:19]
	v_pk_add_f32 v[10:11], v[10:11], v[20:21]
	v_cvt_pk_f16_f32 v18, v8, v9
	v_cvt_pk_f16_f32 v19, v10, v11
	global_store_dwordx4 v[22:23], v[8:11], off offset:64
	v_mov_b32_e32 v138, v18
	v_mov_b32_e32 v139, v19
	v_and_b32_e32 v144, 16, v148
	v_lshrrev_b32_e32 v145, 1, v144
	v_add_u32_e32 v144, v144, v145
	v_mov_b32_e32 v145, 0
	v_lshl_add_u64 v[144:145], v[144:145], 0, v[24:25]
	v_permlane16_swap_b32_e32 v136, v138
	v_permlane16_swap_b32_e32 v137, v139
	global_store_dwordx4 v[144:145], v[136:139], off
	global_load_dwordx4 v[18:21], v[22:23], off offset:128
	v_pk_mul_f32 v[8:9], v[8:9], v[8:9]
	v_pk_mul_f32 v[10:11], v[10:11], v[10:11]
	v_add_f32_e32 v8, v8, v9
	v_add_f32_e32 v10, v10, v11
	v_add_f32_e32 v8, v8, v10
	v_add_f32_e32 v8, v12, v8
	s_waitcnt vmcnt(0)
	v_pk_add_f32 v[4:5], v[4:5], v[18:19]
	v_pk_add_f32 v[6:7], v[6:7], v[20:21]
	v_cvt_pk_f16_f32 v18, v4, v5
	v_cvt_pk_f16_f32 v19, v6, v7
	global_store_dwordx4 v[22:23], v[4:7], off offset:128
	v_mov_b32_e32 v140, v18
	v_mov_b32_e32 v141, v19
	global_load_dwordx4 v[18:21], v[22:23], off offset:192
	v_pk_mul_f32 v[4:5], v[4:5], v[4:5]
	v_pk_mul_f32 v[6:7], v[6:7], v[6:7]
	v_add_f32_e32 v4, v4, v5
	v_add_f32_e32 v6, v6, v7
	v_add_f32_e32 v4, v4, v6
	v_add_f32_e32 v8, v8, v4
	s_waitcnt vmcnt(0)
	v_pk_add_f32 v[4:5], v[0:1], v[18:19]
	v_pk_add_f32 v[6:7], v[2:3], v[20:21]
	v_pk_mul_f32 v[0:1], v[4:5], v[4:5]
	v_pk_mul_f32 v[2:3], v[6:7], v[6:7]
	v_add_f32_e32 v0, v0, v1
	v_add_f32_e32 v2, v2, v3
	v_add_f32_e32 v0, v0, v2
	v_add_f32_e32 v0, v8, v0
	ds_bpermute_b32 v1, v189, v0
	v_cvt_pk_f16_f32 v2, v4, v5
	v_cvt_pk_f16_f32 v3, v6, v7
	global_store_dwordx4 v[22:23], v[4:7], off offset:192
	v_mov_b32_e32 v142, v2
	v_mov_b32_e32 v143, v3
	v_and_b32_e32 v144, 16, v148
	v_lshrrev_b32_e32 v145, 1, v144
	v_add_u32_e32 v144, v144, v145
	v_mov_b32_e32 v145, 0
	v_lshl_add_u64 v[144:145], v[144:145], 0, v[24:25]
	v_permlane16_swap_b32_e32 v140, v142
	v_permlane16_swap_b32_e32 v141, v143
	global_store_dwordx4 v[144:145], v[140:143], off offset:64
	s_waitcnt lgkmcnt(0)
	v_add_f32_e32 v0, v0, v1
	ds_bpermute_b32 v1, v188, v0
	s_and_saveexec_b64 s[4:5], vcc
	s_cbranch_execz .LBB0_1369
	s_waitcnt lgkmcnt(0)
	v_add_f32_e32 v2, v0, v1
	v_lshlrev_b64 v[0:1], 6, v[16:17]
	v_lshl_add_u64 v[0:1], v[48:49], 0, v[0:1]
	global_store_dword v[0:1], v2, off
	s_branch .LBB0_1369
